# v78 + redundant s_waitcnt lgkmcnt(0) removed at the head of every MMA segment (60 sites): the asm wait before the barrier already covers it
# baseline (speedup 1.0000x reference)
; #define GPROBE_BEGIN(id) do { if (((PROBE_GEMM_SEL >> (id)) & 1) && blockIdx.x == 0 && tid_in < 64 && g.N == 20480) { volatile PG8_LAS unsigned long long* PW_ = (volatile PG8_LAS unsigned long long*)(lds + 163840 - 512 + 64); PW_[0] = __builtin_amdgcn_s_memrealtime(); } } while (0)
; #define PG8_WAIT_V(n) asm volatile("s_waitcnt vmcnt(" #n ")" ::: "memory")
; template <class Epi, class Sched, bool ALIGN_EPI = false, bool SP2 = false, bool KHOOK = false>
; __device__ __forceinline__ void gemm_phase(PG8_LAS unsigned char* lds, const Gemm g, const Sched& S, const Epi& E, const int tid_in) {
;     ...
;         const char* nA = has_next ? (const char*)g.A + (size_t)nxt.pm * tstep + (size_t)nxt.pn * ksl : cA; const char* nB = has_next ? (const char*)g.Bt + (size_t)nxt.pn * bts + (size_t)nxt.pn * ksl + (gdv ? (size_t)(nxt.pm / gdv) * gst : 0) : cB;
;         GPROBE_END(2); GPROBE_BEGIN(1);
;         for (int t = 0; t < nt; t += 2) {
;             const bool last = (t == nt - 2);
;             const char* a1 = cA + (size_t)(t + 1) * kstep;
;             const char* a2 = last ? nA : cA + (size_t)(t + 2) * kstep; const char* b2 = last ? nB : cB + (size_t)(t + 2) * kstep;
;             const char* a3 = a2 + kstep; const char* b3 = b2 + kstep;
;             if (last && has_next) S.a_ready(nxt);
;             if constexpr (SP2) {
;             PG8_LDB(B0, 0, 0); PG8_LDB(B1, 0, 1); PG8_SCHED; PG8_LDA(At, 0, 0); PG8_STAGE(PG8_SA(1, 1), a1 + hstep, voffA);
;             PG8_WAIT_V(8); PG8_WAIT_L(0); PG8_BAR; PG8_MMA(0, 0, At, B0); PG8_MMA(0, 1, At, B1); PG8_BAR; PG8_SCHED;
;             PG8_LDA(At, 0, 1); PG8_STAGE(PG8_SB(0, 0), b2, voffB); PG8_STAGE(PG8_SB(0, 1), b2 + hstep, voffB); PG8_STAGE(PG8_SA(0, 0), a2, voffA);
;             PG8_WAIT_V(8); PG8_WAIT_L(0); PG8_BAR; PG8_MMA(1, 0, At, B0); PG8_MMA(1, 1, At, B1); PG8_BAR; PG8_SCHED;
;             PG8_LDB(B0, 1, 0); PG8_LDB(B1, 1, 1); PG8_SCHED; PG8_LDA(At, 1, 0); PG8_STAGE(PG8_SA(0, 1), a2 + hstep, voffA);
;             PG8_WAIT_V(8); PG8_WAIT_L(0); PG8_BAR; PG8_MMA(0, 0, At, B0); PG8_MMA(0, 1, At, B1); PG8_BAR; PG8_SCHED;
;             PG8_LDA(At, 1, 1); PG8_STAGE(PG8_SB(1, 0), b3, voffB); PG8_STAGE(PG8_SB(1, 1), b3 + hstep, voffB); PG8_STAGE(PG8_SA(1, 0), a3, voffA);
;             PG8_WAIT_V(8); PG8_WAIT_L(0); PG8_BAR; PG8_MMA(1, 0, At, B0); PG8_MMA(1, 1, At, B1); PG8_BAR; PG8_SCHED;
.LBB0_262:
	s_ashr_i32 s17, s16, 31
	s_lshl_b64 s[18:19], s[16:17], 20
	s_add_u32 s26, s78, s18
	s_addc_u32 s27, s79, s19
	s_and_b64 s[18:19], s[22:23], exec
	s_cselect_b32 s11, s27, s49
	s_cselect_b32 s17, s26, s48
	s_ashr_i32 s15, s14, 31
	s_lshl_b64 s[18:19], s[14:15], 20
	v_readlane_b32 s5, v255, 25
	s_add_u32 s30, s5, s18
	v_readlane_b32 s5, v255, 26
	s_addc_u32 s31, s5, s19
	s_and_b64 s[18:19], s[22:23], exec
	s_cselect_b32 s15, s31, s53
	s_cselect_b32 s18, s30, s52
	s_add_u32 s48, s48, 0x80080
	s_addc_u32 s49, s49, 0
	s_add_u32 s19, s52, 0x100
	s_addc_u32 s42, s53, 0
	s_mov_b32 s44, -2
	s_cmp_lg_u32 s60, 0
	s_cbranch_scc1 .Lg1_peel_e1
	s_add_u32 s45, s48, 0xfff80080
	s_addc_u32 s46, s49, -1
	s_add_i32 s47, 0, 0x10000
	s_cmp_eq_u32 s44, 28
	s_cselect_b32 s57, s11, s46
	s_cselect_b32 s56, s17, s45
	s_cselect_b32 s53, s15, s42
	s_cselect_b32 s52, s18, s19
	s_add_i32 s45, 0, 0x14000
	v_add_u32_e32 v156, s47, v141
	v_add_u32_e32 v172, s45, v141
	ds_read_b128 v[144:147], v156
	ds_read_b128 v[148:151], v156 offset:1024
	ds_read_b128 v[152:155], v156 offset:2048
	ds_read_b128 v[156:159], v156 offset:3072
	ds_read_b128 v[160:163], v172
	ds_read_b128 v[164:167], v172 offset:1024
	ds_read_b128 v[168:171], v172 offset:2048
	ds_read_b128 v[172:175], v172 offset:3072
	v_lshl_add_u64 v[192:193], s[48:49], 0, v[136:137]
	s_add_i32 m0, s13, 0xc000
	ds_read_b128 v[176:179], v143
	ds_read_b128 v[180:183], v143 offset:1024
	ds_read_b128 v[184:187], v143 offset:2048
	ds_read_b128 v[188:191], v143 offset:3072
	ds_read_b128 v[198:201], v143 offset:4096
	ds_read_b128 v[202:205], v143 offset:5120
	ds_read_b128 v[206:209], v143 offset:6144
	ds_read_b128 v[210:213], v143 offset:7168
	global_load_lds_dwordx4 v[192:193], off
	s_add_i32 m0, s13, 0xe000
	v_lshl_add_u64 v[192:193], s[48:49], 0, v[138:139]
	global_load_lds_dwordx4 v[192:193], off
	s_waitcnt vmcnt(18)
	s_waitcnt lgkmcnt(0)
	s_barrier
	s_setprio 1
	v_mfma_f32_16x16x32_bf16 v[126:129], v[144:147], v[176:179], 0
	v_mfma_f32_16x16x32_bf16 v[122:125], v[152:155], v[176:179], 0
	v_mfma_f32_16x16x32_bf16 v[118:121], v[144:147], v[184:187], 0
	v_mfma_f32_16x16x32_bf16 v[114:117], v[152:155], v[184:187], 0
	v_mfma_f32_16x16x32_bf16 v[102:105], v[144:147], v[198:201], 0
	v_mfma_f32_16x16x32_bf16 v[98:101], v[152:155], v[198:201], 0
	v_mfma_f32_16x16x32_bf16 v[86:89], v[144:147], v[206:209], 0
	v_mfma_f32_16x16x32_bf16 v[82:85], v[152:155], v[206:209], 0
	v_mfma_f32_16x16x32_bf16 v[126:129], v[148:151], v[180:183], v[126:129]
	v_mfma_f32_16x16x32_bf16 v[122:125], v[156:159], v[180:183], v[122:125]
	v_mfma_f32_16x16x32_bf16 v[118:121], v[148:151], v[188:191], v[118:121]
	v_mfma_f32_16x16x32_bf16 v[114:117], v[156:159], v[188:191], v[114:117]
	v_mfma_f32_16x16x32_bf16 v[102:105], v[148:151], v[202:205], v[102:105]
	v_mfma_f32_16x16x32_bf16 v[98:101], v[156:159], v[202:205], v[98:101]
	v_mfma_f32_16x16x32_bf16 v[86:89], v[148:151], v[210:213], v[86:89]
	v_mfma_f32_16x16x32_bf16 v[82:85], v[156:159], v[210:213], v[82:85]
	s_setprio 0
	s_setprio 1
	v_mfma_f32_16x16x32_bf16 v[110:113], v[160:163], v[176:179], 0
	v_mfma_f32_16x16x32_bf16 v[106:109], v[168:171], v[176:179], 0
	v_mfma_f32_16x16x32_bf16 v[94:97], v[160:163], v[184:187], 0
	v_mfma_f32_16x16x32_bf16 v[90:93], v[168:171], v[184:187], 0
	v_mfma_f32_16x16x32_bf16 v[78:81], v[160:163], v[198:201], 0
	v_mfma_f32_16x16x32_bf16 v[74:77], v[168:171], v[198:201], 0
	v_mfma_f32_16x16x32_bf16 v[70:73], v[160:163], v[206:209], 0
	v_mfma_f32_16x16x32_bf16 v[66:69], v[168:171], v[206:209], 0
	v_mfma_f32_16x16x32_bf16 v[110:113], v[164:167], v[180:183], v[110:113]
	v_mfma_f32_16x16x32_bf16 v[106:109], v[172:175], v[180:183], v[106:109]
	v_mfma_f32_16x16x32_bf16 v[94:97], v[164:167], v[188:191], v[94:97]
	v_mfma_f32_16x16x32_bf16 v[90:93], v[172:175], v[188:191], v[90:93]
	v_mfma_f32_16x16x32_bf16 v[78:81], v[164:167], v[202:205], v[78:81]
	v_mfma_f32_16x16x32_bf16 v[74:77], v[172:175], v[202:205], v[74:77]
	v_mfma_f32_16x16x32_bf16 v[70:73], v[164:167], v[210:213], v[70:73]
	v_mfma_f32_16x16x32_bf16 v[66:69], v[172:175], v[210:213], v[66:69]
	s_setprio 0
	s_barrier
	s_add_i32 s46, s47, s37
	v_lshl_add_u64 v[192:193], s[52:53], 0, v[32:33]
	s_mov_b32 m0, s46
	ds_read_b128 v[176:179], v143 offset:16384
	ds_read_b128 v[180:183], v143 offset:17408
	ds_read_b128 v[184:187], v143 offset:18432
	ds_read_b128 v[188:191], v143 offset:19456
	ds_read_b128 v[198:201], v143 offset:20480
	ds_read_b128 v[202:205], v143 offset:21504
	ds_read_b128 v[206:209], v143 offset:22528
	ds_read_b128 v[210:213], v143 offset:23552
	global_load_lds_dwordx4 v[192:193], off
	s_add_i32 m0, s46, 0x2000
	s_add_u32 s46, s52, 0x80000
	v_lshl_add_u64 v[214:215], s[52:53], 0, v[134:135]
	s_addc_u32 s47, s53, 0
	s_add_i32 s45, s45, s37
	global_load_lds_dwordx4 v[214:215], off
	v_lshl_add_u64 v[216:217], s[46:47], 0, v[32:33]
	s_mov_b32 m0, s45
	v_lshl_add_u64 v[218:219], s[56:57], 0, v[132:133]
	global_load_lds_dwordx4 v[216:217], off
	s_add_i32 m0, s45, 0x2000
	v_lshl_add_u64 v[216:217], s[46:47], 0, v[134:135]
	global_load_lds_dwordx4 v[216:217], off
	s_mov_b32 m0, s13
	v_lshl_add_u64 v[216:217], s[56:57], 0, v[130:131]
	global_load_lds_dwordx4 v[216:217], off
	s_mov_b32 m0, s24
	s_nop 0
	global_load_lds_dwordx4 v[218:219], off
	s_waitcnt vmcnt(24)
	s_waitcnt lgkmcnt(0)
	s_barrier
; #define PG8_STAGE(bufoff, gbase, voff) do { _Pragma("unroll") for (int _i = 0; _i < 2; ++_i) \
;         __builtin_amdgcn_global_load_lds((const unsigned*)((const char*)(gbase) + (voff)[_i]), (PG8_LAS unsigned*)(lds + (bufoff) + ldsw + _i * 8192), 16, 0, 0); } while (0)
; #define PG8_LDA(dst, b, h) do { _Pragma("unroll") for (int m = 0; m < 4; ++m) _Pragma("unroll") for (int k = 0; k < 2; ++k) dst[m][k] = *(const PG8_LAS bf16x8*)(lds + PG8_SA(b, h) + aoff + m * 2048 + k * 1024); } while (0)
; #define PG8_LDB(dst, b, h) do { _Pragma("unroll") for (int n = 0; n < 2; ++n) _Pragma("unroll") for (int k = 0; k < 2; ++k) dst[n][k] = *(const PG8_LAS bf16x8*)(lds + PG8_SB(b, h) + boff + n * 2048 + k * 1024); } while (0)
; #define PG8_MMA(ai, bj, At, Bt) do { __builtin_amdgcn_s_setprio(1); _Pragma("unroll") for (int m = 0; m < 4; ++m) _Pragma("unroll") for (int n = 0; n < 2; ++n) _Pragma("unroll") for (int k = 0; k < 2; ++k) \
;         acc[ai][bj][m][n] = __builtin_amdgcn_mfma_f32_16x16x32_bf16(Bt[n][k], At[m][k], acc[ai][bj][m][n], 0, 0, 0); __builtin_amdgcn_s_setprio(0); } while (0)
; template <class Epi, class Sched, bool ALIGN_EPI = false, bool SP2 = false, bool KHOOK = false>
; __device__ __forceinline__ void gemm_phase(PG8_LAS unsigned char* lds, const Gemm g, const Sched& S, const Epi& E, const int tid_in) {
;     ...
;             PG8_LDB(B0, 0, 0); PG8_LDB(B1, 0, 1); PG8_SCHED; PG8_LDA(At, 0, 0); PG8_STAGE(PG8_SA(1, 1), a1 + hstep, voffA);
;             PG8_WAIT_V(8); PG8_WAIT_L(0); PG8_BAR; PG8_MMA(0, 0, At, B0); PG8_MMA(0, 1, At, B1); PG8_BAR; PG8_SCHED;
;             PG8_LDA(At, 0, 1); PG8_STAGE(PG8_SB(0, 0), b2, voffB); PG8_STAGE(PG8_SB(0, 1), b2 + hstep, voffB); PG8_STAGE(PG8_SA(0, 0), a2, voffA);
;             PG8_WAIT_V(8); PG8_WAIT_L(0); PG8_BAR; PG8_MMA(1, 0, At, B0); PG8_MMA(1, 1, At, B1); PG8_BAR; PG8_SCHED;
;             PG8_LDB(B0, 1, 0); PG8_LDB(B1, 1, 1); PG8_SCHED; PG8_LDA(At, 1, 0); PG8_STAGE(PG8_SA(0, 1), a2 + hstep, voffA);
;             PG8_WAIT_V(8); PG8_WAIT_L(0); PG8_BAR; PG8_MMA(0, 0, At, B0); PG8_MMA(0, 1, At, B1); PG8_BAR; PG8_SCHED;
;             PG8_LDA(At, 1, 1); PG8_STAGE(PG8_SB(1, 0), b3, voffB); PG8_STAGE(PG8_SB(1, 1), b3 + hstep, voffB); PG8_STAGE(PG8_SA(1, 0), a3, voffA);
;             PG8_WAIT_V(8); PG8_WAIT_L(0); PG8_BAR; PG8_MMA(1, 0, At, B0); PG8_MMA(1, 1, At, B1); PG8_BAR; PG8_SCHED;
	s_setprio 1
	v_mfma_f32_16x16x32_bf16 v[62:65], v[144:147], v[176:179], 0
	v_mfma_f32_16x16x32_bf16 v[58:61], v[152:155], v[176:179], 0
	v_mfma_f32_16x16x32_bf16 v[54:57], v[144:147], v[184:187], 0
	v_mfma_f32_16x16x32_bf16 v[50:53], v[152:155], v[184:187], 0
	v_mfma_f32_16x16x32_bf16 v[38:41], v[144:147], v[198:201], 0
	v_mfma_f32_16x16x32_bf16 v[34:37], v[152:155], v[198:201], 0
	v_mfma_f32_16x16x32_bf16 v[20:23], v[144:147], v[206:209], 0
	v_mfma_f32_16x16x32_bf16 v[16:19], v[152:155], v[206:209], 0
	v_mfma_f32_16x16x32_bf16 v[62:65], v[148:151], v[180:183], v[62:65]
	v_mfma_f32_16x16x32_bf16 v[58:61], v[156:159], v[180:183], v[58:61]
	v_mfma_f32_16x16x32_bf16 v[54:57], v[148:151], v[188:191], v[54:57]
	v_mfma_f32_16x16x32_bf16 v[50:53], v[156:159], v[188:191], v[50:53]
	v_mfma_f32_16x16x32_bf16 v[38:41], v[148:151], v[202:205], v[38:41]
	v_mfma_f32_16x16x32_bf16 v[34:37], v[156:159], v[202:205], v[34:37]
	v_mfma_f32_16x16x32_bf16 v[20:23], v[148:151], v[210:213], v[20:23]
	v_mfma_f32_16x16x32_bf16 v[16:19], v[156:159], v[210:213], v[16:19]
	s_setprio 0
	s_setprio 1
	v_mfma_f32_16x16x32_bf16 v[46:49], v[160:163], v[176:179], 0
	v_mfma_f32_16x16x32_bf16 v[42:45], v[168:171], v[176:179], 0
	v_mfma_f32_16x16x32_bf16 v[28:31], v[160:163], v[184:187], 0
	v_mfma_f32_16x16x32_bf16 v[24:27], v[168:171], v[184:187], 0
	v_mfma_f32_16x16x32_bf16 v[12:15], v[160:163], v[198:201], 0
	v_mfma_f32_16x16x32_bf16 v[8:11], v[168:171], v[198:201], 0
	v_mfma_f32_16x16x32_bf16 v[4:7], v[160:163], v[206:209], 0
	v_mfma_f32_16x16x32_bf16 v[0:3], v[168:171], v[206:209], 0
	v_mfma_f32_16x16x32_bf16 v[46:49], v[164:167], v[180:183], v[46:49]
	v_mfma_f32_16x16x32_bf16 v[42:45], v[172:175], v[180:183], v[42:45]
	v_mfma_f32_16x16x32_bf16 v[28:31], v[164:167], v[188:191], v[28:31]
	v_mfma_f32_16x16x32_bf16 v[24:27], v[172:175], v[188:191], v[24:27]
	v_mfma_f32_16x16x32_bf16 v[12:15], v[164:167], v[202:205], v[12:15]
	v_mfma_f32_16x16x32_bf16 v[8:11], v[172:175], v[202:205], v[8:11]
	v_mfma_f32_16x16x32_bf16 v[4:7], v[164:167], v[210:213], v[4:7]
	v_mfma_f32_16x16x32_bf16 v[0:3], v[172:175], v[210:213], v[0:3]
	s_setprio 0
	s_barrier
	s_add_i32 s45, 0, 0x18000
	s_add_i32 s50, 0, 0x1c000
	v_add_u32_e32 v156, s45, v141
	v_add_u32_e32 v172, s50, v141
	ds_read_b128 v[144:147], v156
	ds_read_b128 v[148:151], v156 offset:1024
	ds_read_b128 v[152:155], v156 offset:2048
	ds_read_b128 v[156:159], v156 offset:3072
	ds_read_b128 v[160:163], v172
	ds_read_b128 v[164:167], v172 offset:1024
	ds_read_b128 v[168:171], v172 offset:2048
	ds_read_b128 v[172:175], v172 offset:3072
	s_add_u32 s46, s56, 0x80000
	s_addc_u32 s47, s57, 0
	s_mov_b32 m0, s25
	v_lshl_add_u64 v[220:221], s[46:47], 0, v[130:131]
	ds_read_b128 v[176:179], v143 offset:32768
	ds_read_b128 v[180:183], v143 offset:33792
	ds_read_b128 v[184:187], v143 offset:34816
	ds_read_b128 v[188:191], v143 offset:35840
	ds_read_b128 v[198:201], v143 offset:36864
	ds_read_b128 v[202:205], v143 offset:37888
	ds_read_b128 v[206:209], v143 offset:38912
	ds_read_b128 v[210:213], v143 offset:39936
	global_load_lds_dwordx4 v[220:221], off
	s_mov_b32 m0, s38
	v_lshl_add_u64 v[220:221], s[46:47], 0, v[132:133]
	global_load_lds_dwordx4 v[220:221], off
	s_waitcnt vmcnt(8)
	s_waitcnt lgkmcnt(0)
	s_barrier
	s_setprio 1
	v_mfma_f32_16x16x32_bf16 v[126:129], v[144:147], v[176:179], v[126:129]
	v_mfma_f32_16x16x32_bf16 v[122:125], v[152:155], v[176:179], v[122:125]
	v_mfma_f32_16x16x32_bf16 v[118:121], v[144:147], v[184:187], v[118:121]
	v_mfma_f32_16x16x32_bf16 v[114:117], v[152:155], v[184:187], v[114:117]
	v_mfma_f32_16x16x32_bf16 v[102:105], v[144:147], v[198:201], v[102:105]
	v_mfma_f32_16x16x32_bf16 v[98:101], v[152:155], v[198:201], v[98:101]
	v_mfma_f32_16x16x32_bf16 v[86:89], v[144:147], v[206:209], v[86:89]
	v_mfma_f32_16x16x32_bf16 v[82:85], v[152:155], v[206:209], v[82:85]
	v_mfma_f32_16x16x32_bf16 v[126:129], v[148:151], v[180:183], v[126:129]
	v_mfma_f32_16x16x32_bf16 v[122:125], v[156:159], v[180:183], v[122:125]
	v_mfma_f32_16x16x32_bf16 v[118:121], v[148:151], v[188:191], v[118:121]
	v_mfma_f32_16x16x32_bf16 v[114:117], v[156:159], v[188:191], v[114:117]
	v_mfma_f32_16x16x32_bf16 v[102:105], v[148:151], v[202:205], v[102:105]
	v_mfma_f32_16x16x32_bf16 v[98:101], v[156:159], v[202:205], v[98:101]
	v_mfma_f32_16x16x32_bf16 v[86:89], v[148:151], v[210:213], v[86:89]
	v_mfma_f32_16x16x32_bf16 v[82:85], v[156:159], v[210:213], v[82:85]
	s_setprio 0
	s_setprio 1
	v_mfma_f32_16x16x32_bf16 v[110:113], v[160:163], v[176:179], v[110:113]
	v_mfma_f32_16x16x32_bf16 v[106:109], v[168:171], v[176:179], v[106:109]
	v_mfma_f32_16x16x32_bf16 v[94:97], v[160:163], v[184:187], v[94:97]
	v_mfma_f32_16x16x32_bf16 v[90:93], v[168:171], v[184:187], v[90:93]
	v_mfma_f32_16x16x32_bf16 v[78:81], v[160:163], v[198:201], v[78:81]
	v_mfma_f32_16x16x32_bf16 v[74:77], v[168:171], v[198:201], v[74:77]
	v_mfma_f32_16x16x32_bf16 v[70:73], v[160:163], v[206:209], v[70:73]
	v_mfma_f32_16x16x32_bf16 v[66:69], v[168:171], v[206:209], v[66:69]
	v_mfma_f32_16x16x32_bf16 v[110:113], v[164:167], v[180:183], v[110:113]
	v_mfma_f32_16x16x32_bf16 v[106:109], v[172:175], v[180:183], v[106:109]
	v_mfma_f32_16x16x32_bf16 v[94:97], v[164:167], v[188:191], v[94:97]
	v_mfma_f32_16x16x32_bf16 v[90:93], v[172:175], v[188:191], v[90:93]
	v_mfma_f32_16x16x32_bf16 v[78:81], v[164:167], v[202:205], v[78:81]
	v_mfma_f32_16x16x32_bf16 v[74:77], v[172:175], v[202:205], v[74:77]
	v_mfma_f32_16x16x32_bf16 v[70:73], v[164:167], v[210:213], v[70:73]
	v_mfma_f32_16x16x32_bf16 v[66:69], v[172:175], v[210:213], v[66:69]
	s_setprio 0
	s_barrier
; __device__ __forceinline__ unsigned cvt_pk_bf16(float lo, float hi) { const f32x2_t v = {lo, hi}; const bf16x2_t c = __builtin_convertvector(v, bf16x2_t); return __builtin_bit_cast(unsigned, c); }
; #define PG8_WAIT_V(n) asm volatile("s_waitcnt vmcnt(" #n ")" ::: "memory")
; #define PG8_WAIT_L(n) asm volatile("s_waitcnt lgkmcnt(" #n ")" ::: "memory")
;     __device__ __forceinline__ void operator()(const f32x4 (&acc)[2][2][4][2], const Unit& u, int wr, int wc, int fr, int fq) const {
;         const int row0 = u.pm * BM + wr * 64 + fr, col0 = u.pn * BM + wc * 32 + 8 * fq;
; #pragma unroll
;         for (int ai = 0; ai < 2; ++ai)
; #pragma unroll
;             for (int m = 0; m < 4; ++m) { bf16_t* rowp = O + (size_t)(row0 + ai * HALF + m * 16) * ldc + col0;
; #pragma unroll
;                 for (int bj = 0; bj < 2; ++bj) { const f32x4 v0 = acc[ai][bj][m][0], v1 = acc[ai][bj][m][1];
;                     u32x4 w; w.x = cvt_pk_bf16(v0[0], v0[1]); w.y = cvt_pk_bf16(v0[2], v0[3]); w.z = cvt_pk_bf16(v1[0], v1[1]); w.w = cvt_pk_bf16(v1[2], v1[3]);
;                     *(u32x4*)(rowp + bj * HALF) = w; } }
; template <class Epi, class Sched, bool ALIGN_EPI = false, bool SP2 = false, bool KHOOK = false>
; __device__ __forceinline__ void gemm_phase(PG8_LAS unsigned char* lds, const Gemm g, const Sched& S, const Epi& E, const int tid_in) {
;     ...
;             PG8_LDB(B0, 0, 0); PG8_LDB(B1, 0, 1); PG8_SCHED; PG8_LDA(At, 0, 0); PG8_STAGE(PG8_SA(1, 1), a1 + hstep, voffA);
;             PG8_WAIT_V(8); PG8_WAIT_L(0); PG8_BAR; PG8_MMA(0, 0, At, B0); PG8_MMA(0, 1, At, B1); PG8_BAR; PG8_SCHED;
;             PG8_LDA(At, 0, 1); PG8_STAGE(PG8_SB(0, 0), b2, voffB); PG8_STAGE(PG8_SB(0, 1), b2 + hstep, voffB); PG8_STAGE(PG8_SA(0, 0), a2, voffA);
;             PG8_WAIT_V(8); PG8_WAIT_L(0); PG8_BAR; PG8_MMA(1, 0, At, B0); PG8_MMA(1, 1, At, B1); PG8_BAR; PG8_SCHED;
;             PG8_LDB(B0, 1, 0); PG8_LDB(B1, 1, 1); PG8_SCHED; PG8_LDA(At, 1, 0); PG8_STAGE(PG8_SA(0, 1), a2 + hstep, voffA);
;             PG8_WAIT_V(8); PG8_WAIT_L(0); PG8_BAR; PG8_MMA(0, 0, At, B0); PG8_MMA(0, 1, At, B1); PG8_BAR; PG8_SCHED;
;             PG8_LDA(At, 1, 1); PG8_STAGE(PG8_SB(1, 0), b3, voffB); PG8_STAGE(PG8_SB(1, 1), b3 + hstep, voffB); PG8_STAGE(PG8_SA(1, 0), a3, voffA);
;             PG8_WAIT_V(8); PG8_WAIT_L(0); PG8_BAR; PG8_MMA(1, 0, At, B0); PG8_MMA(1, 1, At, B1); PG8_BAR; PG8_SCHED;
	s_add_i32 s45, s45, s37
	v_lshl_add_u64 v[192:193], v[192:193], 0, s[90:91]
	s_mov_b32 m0, s45
	ds_read_b128 v[176:179], v143 offset:49152
	ds_read_b128 v[180:183], v143 offset:50176
	ds_read_b128 v[184:187], v143 offset:51200
	ds_read_b128 v[188:191], v143 offset:52224
	ds_read_b128 v[198:201], v143 offset:53248
	ds_read_b128 v[202:205], v143 offset:54272
	ds_read_b128 v[206:209], v143 offset:55296
	ds_read_b128 v[210:213], v143 offset:56320
	global_load_lds_dwordx4 v[192:193], off
	s_add_i32 m0, s45, 0x2000
	s_add_u32 s46, s52, 0x80080
	v_lshl_add_u64 v[192:193], v[214:215], 0, s[90:91]
	s_addc_u32 s47, s53, 0
	s_add_i32 s45, s50, s37
	global_load_lds_dwordx4 v[192:193], off
	s_mov_b32 m0, s45
	v_lshl_add_u64 v[192:193], s[46:47], 0, v[32:33]
	global_load_lds_dwordx4 v[192:193], off
	s_add_i32 m0, s45, 0x2000
	v_lshl_add_u64 v[192:193], s[46:47], 0, v[134:135]
	global_load_lds_dwordx4 v[192:193], off
	s_mov_b32 m0, s39
	v_lshl_add_u64 v[192:193], v[216:217], 0, s[90:91]
	global_load_lds_dwordx4 v[192:193], off
	s_mov_b32 m0, s40
	v_lshl_add_u64 v[192:193], v[218:219], 0, s[90:91]
	global_load_lds_dwordx4 v[192:193], off
	s_waitcnt vmcnt(8)
	s_waitcnt lgkmcnt(0)
	s_barrier
	s_setprio 1
	v_mfma_f32_16x16x32_bf16 v[62:65], v[144:147], v[176:179], v[62:65]
	v_mfma_f32_16x16x32_bf16 v[58:61], v[152:155], v[176:179], v[58:61]
	v_mfma_f32_16x16x32_bf16 v[54:57], v[144:147], v[184:187], v[54:57]
	v_mfma_f32_16x16x32_bf16 v[50:53], v[152:155], v[184:187], v[50:53]
	v_mfma_f32_16x16x32_bf16 v[38:41], v[144:147], v[198:201], v[38:41]
	v_mfma_f32_16x16x32_bf16 v[34:37], v[152:155], v[198:201], v[34:37]
	v_mfma_f32_16x16x32_bf16 v[20:23], v[144:147], v[206:209], v[20:23]
	v_mfma_f32_16x16x32_bf16 v[16:19], v[152:155], v[206:209], v[16:19]
	v_mfma_f32_16x16x32_bf16 v[62:65], v[148:151], v[180:183], v[62:65]
	v_mfma_f32_16x16x32_bf16 v[58:61], v[156:159], v[180:183], v[58:61]
	v_mfma_f32_16x16x32_bf16 v[54:57], v[148:151], v[188:191], v[54:57]
	v_mfma_f32_16x16x32_bf16 v[50:53], v[156:159], v[188:191], v[50:53]
	v_mfma_f32_16x16x32_bf16 v[38:41], v[148:151], v[202:205], v[38:41]
	v_mfma_f32_16x16x32_bf16 v[34:37], v[156:159], v[202:205], v[34:37]
	v_mfma_f32_16x16x32_bf16 v[20:23], v[148:151], v[210:213], v[20:23]
	v_mfma_f32_16x16x32_bf16 v[16:19], v[156:159], v[210:213], v[16:19]
	s_setprio 0
	s_setprio 1
	v_mfma_f32_16x16x32_bf16 v[46:49], v[160:163], v[176:179], v[46:49]
	v_mfma_f32_16x16x32_bf16 v[42:45], v[168:171], v[176:179], v[42:45]
	v_mfma_f32_16x16x32_bf16 v[28:31], v[160:163], v[184:187], v[28:31]
	v_mfma_f32_16x16x32_bf16 v[24:27], v[168:171], v[184:187], v[24:27]
	v_mfma_f32_16x16x32_bf16 v[12:15], v[160:163], v[198:201], v[12:15]
	v_mfma_f32_16x16x32_bf16 v[8:11], v[168:171], v[198:201], v[8:11]
	v_mfma_f32_16x16x32_bf16 v[4:7], v[160:163], v[206:209], v[4:7]
	v_mfma_f32_16x16x32_bf16 v[0:3], v[168:171], v[206:209], v[0:3]
	v_mfma_f32_16x16x32_bf16 v[46:49], v[164:167], v[180:183], v[46:49]
	v_mfma_f32_16x16x32_bf16 v[42:45], v[172:175], v[180:183], v[42:45]
	v_mfma_f32_16x16x32_bf16 v[28:31], v[164:167], v[188:191], v[28:31]
	v_mfma_f32_16x16x32_bf16 v[24:27], v[172:175], v[188:191], v[24:27]
	v_mfma_f32_16x16x32_bf16 v[12:15], v[164:167], v[202:205], v[12:15]
	v_mfma_f32_16x16x32_bf16 v[8:11], v[172:175], v[202:205], v[8:11]
	v_mfma_f32_16x16x32_bf16 v[4:7], v[164:167], v[210:213], v[4:7]
	v_mfma_f32_16x16x32_bf16 v[0:3], v[172:175], v[210:213], v[0:3]
	s_setprio 0
	s_barrier
	s_add_i32 s44, s44, 2
	s_add_u32 s48, s48, 0x100
	s_addc_u32 s49, s49, 0
	s_add_u32 s19, s19, 0x100
	s_addc_u32 s42, s42, 0
	s_cmp_gt_u32 s44, 29
	s_branch .LBB0_263
.Lg1_peel_e1:
	s_add_u32 s45, s48, 0xfff80080
	s_addc_u32 s46, s49, -1
	s_add_i32 s47, 0, 0x10000
	s_cmp_eq_u32 s44, 28
	s_cselect_b32 s57, s11, s46
	s_cselect_b32 s56, s17, s45
	s_cselect_b32 s53, s15, s42
	s_cselect_b32 s52, s18, s19
	s_add_i32 s45, 0, 0x14000
	v_add_u32_e32 v156, s47, v141
	v_add_u32_e32 v172, s45, v141
	ds_read_b128 v[144:147], v156
	ds_read_b128 v[148:151], v156 offset:1024
	ds_read_b128 v[152:155], v156 offset:2048
	ds_read_b128 v[156:159], v156 offset:3072
	ds_read_b128 v[160:163], v172
	ds_read_b128 v[164:167], v172 offset:1024
	ds_read_b128 v[168:171], v172 offset:2048
	ds_read_b128 v[172:175], v172 offset:3072
	v_lshl_add_u64 v[192:193], s[48:49], 0, v[136:137]
	s_add_i32 m0, s13, 0xc000
	ds_read_b128 v[176:179], v143
	ds_read_b128 v[180:183], v143 offset:1024
	ds_read_b128 v[184:187], v143 offset:2048
	ds_read_b128 v[188:191], v143 offset:3072
	ds_read_b128 v[198:201], v143 offset:4096
	ds_read_b128 v[202:205], v143 offset:5120
	ds_read_b128 v[206:209], v143 offset:6144
	ds_read_b128 v[210:213], v143 offset:7168
	global_load_lds_dwordx4 v[192:193], off
	s_add_i32 m0, s13, 0xe000
	v_lshl_add_u64 v[192:193], s[48:49], 0, v[138:139]
	global_load_lds_dwordx4 v[192:193], off
	v_lshl_add_u32 v246, s68, 8, v140
	v_add_u32_e32 v246, 0x80, v246
	v_lshl_or_b32 v222, s69, 8, v142
	v_lshlrev_b32_e32 v222, 1, v222
	v_mov_b32_e32 v223, 0
	v_mad_u64_u32 v[248:249], s[70:71], v246, s67, v[222:223]
	s_mov_b32 s72, 0xa2000
	s_mov_b32 s73, 0
	v_lshl_add_u64 v[248:249], v[248:249], 0, s[76:77]
	v_cvt_pk_bf16_f32 v62, v62, v63
	v_cvt_pk_bf16_f32 v63, v64, v65
	v_cvt_pk_bf16_f32 v64, v58, v59
	v_cvt_pk_bf16_f32 v65, v60, v61
	global_store_dwordx4 v[248:249], v[62:65], off
	v_cvt_pk_bf16_f32 v46, v46, v47
	v_cvt_pk_bf16_f32 v47, v48, v49
	v_cvt_pk_bf16_f32 v48, v42, v43
	v_cvt_pk_bf16_f32 v49, v44, v45
	global_store_dwordx4 v[248:249], v[46:49], off offset:256
	v_lshl_add_u64 v[248:249], v[248:249], 0, s[72:73]
	v_cvt_pk_bf16_f32 v54, v54, v55
	v_cvt_pk_bf16_f32 v55, v56, v57
	v_cvt_pk_bf16_f32 v56, v50, v51
	v_cvt_pk_bf16_f32 v57, v52, v53
	global_store_dwordx4 v[248:249], v[54:57], off
	v_cvt_pk_bf16_f32 v28, v28, v29
	v_cvt_pk_bf16_f32 v29, v30, v31
	v_cvt_pk_bf16_f32 v30, v24, v25
	v_cvt_pk_bf16_f32 v31, v26, v27
	global_store_dwordx4 v[248:249], v[28:31], off offset:256
	v_lshl_add_u64 v[248:249], v[248:249], 0, s[72:73]
	v_cvt_pk_bf16_f32 v38, v38, v39
	v_cvt_pk_bf16_f32 v39, v40, v41
	v_cvt_pk_bf16_f32 v40, v34, v35
	v_cvt_pk_bf16_f32 v41, v36, v37
	global_store_dwordx4 v[248:249], v[38:41], off
	v_cvt_pk_bf16_f32 v12, v12, v13
	v_cvt_pk_bf16_f32 v13, v14, v15
	v_cvt_pk_bf16_f32 v14, v8, v9
	v_cvt_pk_bf16_f32 v15, v10, v11
	global_store_dwordx4 v[248:249], v[12:15], off offset:256
	v_lshl_add_u64 v[248:249], v[248:249], 0, s[72:73]
	v_cvt_pk_bf16_f32 v20, v20, v21
	v_cvt_pk_bf16_f32 v21, v22, v23
	v_cvt_pk_bf16_f32 v22, v16, v17
	v_cvt_pk_bf16_f32 v23, v18, v19
	global_store_dwordx4 v[248:249], v[20:23], off
	v_cvt_pk_bf16_f32 v4, v4, v5
	v_cvt_pk_bf16_f32 v5, v6, v7
	v_cvt_pk_bf16_f32 v6, v0, v1
	v_cvt_pk_bf16_f32 v7, v2, v3
	global_store_dwordx4 v[248:249], v[4:7], off offset:256
	s_waitcnt vmcnt(24)
	s_waitcnt lgkmcnt(0)
	s_barrier
; #define PG8_STAGE(bufoff, gbase, voff) do { _Pragma("unroll") for (int _i = 0; _i < 2; ++_i) \
;         __builtin_amdgcn_global_load_lds((const unsigned*)((const char*)(gbase) + (voff)[_i]), (PG8_LAS unsigned*)(lds + (bufoff) + ldsw + _i * 8192), 16, 0, 0); } while (0)
; #define PG8_LDA(dst, b, h) do { _Pragma("unroll") for (int m = 0; m < 4; ++m) _Pragma("unroll") for (int k = 0; k < 2; ++k) dst[m][k] = *(const PG8_LAS bf16x8*)(lds + PG8_SA(b, h) + aoff + m * 2048 + k * 1024); } while (0)
; #define PG8_LDB(dst, b, h) do { _Pragma("unroll") for (int n = 0; n < 2; ++n) _Pragma("unroll") for (int k = 0; k < 2; ++k) dst[n][k] = *(const PG8_LAS bf16x8*)(lds + PG8_SB(b, h) + boff + n * 2048 + k * 1024); } while (0)
; #define PG8_MMA(ai, bj, At, Bt) do { __builtin_amdgcn_s_setprio(1); _Pragma("unroll") for (int m = 0; m < 4; ++m) _Pragma("unroll") for (int n = 0; n < 2; ++n) _Pragma("unroll") for (int k = 0; k < 2; ++k) \
;         acc[ai][bj][m][n] = __builtin_amdgcn_mfma_f32_16x16x32_bf16(Bt[n][k], At[m][k], acc[ai][bj][m][n], 0, 0, 0); __builtin_amdgcn_s_setprio(0); } while (0)
; template <class Epi, class Sched, bool ALIGN_EPI = false, bool SP2 = false, bool KHOOK = false>
; __device__ __forceinline__ void gemm_phase(PG8_LAS unsigned char* lds, const Gemm g, const Sched& S, const Epi& E, const int tid_in) {
;     ...
;             PG8_LDB(B0, 0, 0); PG8_LDB(B1, 0, 1); PG8_SCHED; PG8_LDA(At, 0, 0); PG8_STAGE(PG8_SA(1, 1), a1 + hstep, voffA);
;             PG8_WAIT_V(8); PG8_WAIT_L(0); PG8_BAR; PG8_MMA(0, 0, At, B0); PG8_MMA(0, 1, At, B1); PG8_BAR; PG8_SCHED;
;             PG8_LDA(At, 0, 1); PG8_STAGE(PG8_SB(0, 0), b2, voffB); PG8_STAGE(PG8_SB(0, 1), b2 + hstep, voffB); PG8_STAGE(PG8_SA(0, 0), a2, voffA);
;             PG8_WAIT_V(8); PG8_WAIT_L(0); PG8_BAR; PG8_MMA(1, 0, At, B0); PG8_MMA(1, 1, At, B1); PG8_BAR; PG8_SCHED;
;             PG8_LDB(B0, 1, 0); PG8_LDB(B1, 1, 1); PG8_SCHED; PG8_LDA(At, 1, 0); PG8_STAGE(PG8_SA(0, 1), a2 + hstep, voffA);
;             PG8_WAIT_V(8); PG8_WAIT_L(0); PG8_BAR; PG8_MMA(0, 0, At, B0); PG8_MMA(0, 1, At, B1); PG8_BAR; PG8_SCHED;
;             PG8_LDA(At, 1, 1); PG8_STAGE(PG8_SB(1, 0), b3, voffB); PG8_STAGE(PG8_SB(1, 1), b3 + hstep, voffB); PG8_STAGE(PG8_SA(1, 0), a3, voffA);
;             PG8_WAIT_V(8); PG8_WAIT_L(0); PG8_BAR; PG8_MMA(1, 0, At, B0); PG8_MMA(1, 1, At, B1); PG8_BAR; PG8_SCHED;
	s_setprio 1
	v_mfma_f32_16x16x32_bf16 v[126:129], v[144:147], v[176:179], 0
	v_mfma_f32_16x16x32_bf16 v[122:125], v[152:155], v[176:179], 0
	v_mfma_f32_16x16x32_bf16 v[118:121], v[144:147], v[184:187], 0
	v_mfma_f32_16x16x32_bf16 v[114:117], v[152:155], v[184:187], 0
	v_mfma_f32_16x16x32_bf16 v[102:105], v[144:147], v[198:201], 0
	v_mfma_f32_16x16x32_bf16 v[98:101], v[152:155], v[198:201], 0
	v_mfma_f32_16x16x32_bf16 v[86:89], v[144:147], v[206:209], 0
	v_mfma_f32_16x16x32_bf16 v[82:85], v[152:155], v[206:209], 0
	v_mfma_f32_16x16x32_bf16 v[126:129], v[148:151], v[180:183], v[126:129]
	v_mfma_f32_16x16x32_bf16 v[122:125], v[156:159], v[180:183], v[122:125]
	v_mfma_f32_16x16x32_bf16 v[118:121], v[148:151], v[188:191], v[118:121]
	v_mfma_f32_16x16x32_bf16 v[114:117], v[156:159], v[188:191], v[114:117]
	v_mfma_f32_16x16x32_bf16 v[102:105], v[148:151], v[202:205], v[102:105]
	v_mfma_f32_16x16x32_bf16 v[98:101], v[156:159], v[202:205], v[98:101]
	v_mfma_f32_16x16x32_bf16 v[86:89], v[148:151], v[210:213], v[86:89]
	v_mfma_f32_16x16x32_bf16 v[82:85], v[156:159], v[210:213], v[82:85]
	s_setprio 0
	s_setprio 1
	v_mfma_f32_16x16x32_bf16 v[110:113], v[160:163], v[176:179], 0
	v_mfma_f32_16x16x32_bf16 v[106:109], v[168:171], v[176:179], 0
	v_mfma_f32_16x16x32_bf16 v[94:97], v[160:163], v[184:187], 0
	v_mfma_f32_16x16x32_bf16 v[90:93], v[168:171], v[184:187], 0
	v_mfma_f32_16x16x32_bf16 v[78:81], v[160:163], v[198:201], 0
	v_mfma_f32_16x16x32_bf16 v[74:77], v[168:171], v[198:201], 0
	v_mfma_f32_16x16x32_bf16 v[70:73], v[160:163], v[206:209], 0
	v_mfma_f32_16x16x32_bf16 v[66:69], v[168:171], v[206:209], 0
	v_mfma_f32_16x16x32_bf16 v[110:113], v[164:167], v[180:183], v[110:113]
	v_mfma_f32_16x16x32_bf16 v[106:109], v[172:175], v[180:183], v[106:109]
	v_mfma_f32_16x16x32_bf16 v[94:97], v[164:167], v[188:191], v[94:97]
	v_mfma_f32_16x16x32_bf16 v[90:93], v[172:175], v[188:191], v[90:93]
	v_mfma_f32_16x16x32_bf16 v[78:81], v[164:167], v[202:205], v[78:81]
	v_mfma_f32_16x16x32_bf16 v[74:77], v[172:175], v[202:205], v[74:77]
	v_mfma_f32_16x16x32_bf16 v[70:73], v[164:167], v[210:213], v[70:73]
	v_mfma_f32_16x16x32_bf16 v[66:69], v[172:175], v[210:213], v[66:69]
	s_setprio 0
	s_barrier
	s_add_i32 s46, s47, s37
	v_lshl_add_u64 v[192:193], s[52:53], 0, v[32:33]
	s_mov_b32 m0, s46
	ds_read_b128 v[176:179], v143 offset:16384
	ds_read_b128 v[180:183], v143 offset:17408
	ds_read_b128 v[184:187], v143 offset:18432
	ds_read_b128 v[188:191], v143 offset:19456
	ds_read_b128 v[198:201], v143 offset:20480
	ds_read_b128 v[202:205], v143 offset:21504
	ds_read_b128 v[206:209], v143 offset:22528
	ds_read_b128 v[210:213], v143 offset:23552
	global_load_lds_dwordx4 v[192:193], off
	s_add_i32 m0, s46, 0x2000
	s_add_u32 s46, s52, 0x80000
	v_lshl_add_u64 v[214:215], s[52:53], 0, v[134:135]
	s_addc_u32 s47, s53, 0
	s_add_i32 s45, s45, s37
	global_load_lds_dwordx4 v[214:215], off
	v_lshl_add_u64 v[216:217], s[46:47], 0, v[32:33]
	s_mov_b32 m0, s45
	v_lshl_add_u64 v[218:219], s[56:57], 0, v[132:133]
	global_load_lds_dwordx4 v[216:217], off
	s_add_i32 m0, s45, 0x2000
	v_lshl_add_u64 v[216:217], s[46:47], 0, v[134:135]
	global_load_lds_dwordx4 v[216:217], off
	s_mov_b32 m0, s13
	v_lshl_add_u64 v[216:217], s[56:57], 0, v[130:131]
	global_load_lds_dwordx4 v[216:217], off
	s_mov_b32 m0, s24
	s_nop 0
	global_load_lds_dwordx4 v[218:219], off
	s_waitcnt vmcnt(24)
	s_waitcnt lgkmcnt(0)
	s_barrier
	s_setprio 1
	v_mfma_f32_16x16x32_bf16 v[62:65], v[144:147], v[176:179], 0
	v_mfma_f32_16x16x32_bf16 v[58:61], v[152:155], v[176:179], 0
	v_mfma_f32_16x16x32_bf16 v[54:57], v[144:147], v[184:187], 0
	v_mfma_f32_16x16x32_bf16 v[50:53], v[152:155], v[184:187], 0
	v_mfma_f32_16x16x32_bf16 v[38:41], v[144:147], v[198:201], 0
	v_mfma_f32_16x16x32_bf16 v[34:37], v[152:155], v[198:201], 0
	v_mfma_f32_16x16x32_bf16 v[20:23], v[144:147], v[206:209], 0
	v_mfma_f32_16x16x32_bf16 v[16:19], v[152:155], v[206:209], 0
	v_mfma_f32_16x16x32_bf16 v[62:65], v[148:151], v[180:183], v[62:65]
	v_mfma_f32_16x16x32_bf16 v[58:61], v[156:159], v[180:183], v[58:61]
	v_mfma_f32_16x16x32_bf16 v[54:57], v[148:151], v[188:191], v[54:57]
	v_mfma_f32_16x16x32_bf16 v[50:53], v[156:159], v[188:191], v[50:53]
	v_mfma_f32_16x16x32_bf16 v[38:41], v[148:151], v[202:205], v[38:41]
	v_mfma_f32_16x16x32_bf16 v[34:37], v[156:159], v[202:205], v[34:37]
	v_mfma_f32_16x16x32_bf16 v[20:23], v[148:151], v[210:213], v[20:23]
	v_mfma_f32_16x16x32_bf16 v[16:19], v[156:159], v[210:213], v[16:19]
	s_setprio 0
	s_setprio 1
	v_mfma_f32_16x16x32_bf16 v[46:49], v[160:163], v[176:179], 0
	v_mfma_f32_16x16x32_bf16 v[42:45], v[168:171], v[176:179], 0
	v_mfma_f32_16x16x32_bf16 v[28:31], v[160:163], v[184:187], 0
	v_mfma_f32_16x16x32_bf16 v[24:27], v[168:171], v[184:187], 0
	v_mfma_f32_16x16x32_bf16 v[12:15], v[160:163], v[198:201], 0
	v_mfma_f32_16x16x32_bf16 v[8:11], v[168:171], v[198:201], 0
	v_mfma_f32_16x16x32_bf16 v[4:7], v[160:163], v[206:209], 0
	v_mfma_f32_16x16x32_bf16 v[0:3], v[168:171], v[206:209], 0
	v_mfma_f32_16x16x32_bf16 v[46:49], v[164:167], v[180:183], v[46:49]
	v_mfma_f32_16x16x32_bf16 v[42:45], v[172:175], v[180:183], v[42:45]
	v_mfma_f32_16x16x32_bf16 v[28:31], v[164:167], v[188:191], v[28:31]
	v_mfma_f32_16x16x32_bf16 v[24:27], v[172:175], v[188:191], v[24:27]
	v_mfma_f32_16x16x32_bf16 v[12:15], v[164:167], v[202:205], v[12:15]
	v_mfma_f32_16x16x32_bf16 v[8:11], v[172:175], v[202:205], v[8:11]
	v_mfma_f32_16x16x32_bf16 v[4:7], v[164:167], v[210:213], v[4:7]
	v_mfma_f32_16x16x32_bf16 v[0:3], v[172:175], v[210:213], v[0:3]
	s_setprio 0
	s_barrier
; #define PG8_STAGE(bufoff, gbase, voff) do { _Pragma("unroll") for (int _i = 0; _i < 2; ++_i) \
;         __builtin_amdgcn_global_load_lds((const unsigned*)((const char*)(gbase) + (voff)[_i]), (PG8_LAS unsigned*)(lds + (bufoff) + ldsw + _i * 8192), 16, 0, 0); } while (0)
; #define PG8_LDA(dst, b, h) do { _Pragma("unroll") for (int m = 0; m < 4; ++m) _Pragma("unroll") for (int k = 0; k < 2; ++k) dst[m][k] = *(const PG8_LAS bf16x8*)(lds + PG8_SA(b, h) + aoff + m * 2048 + k * 1024); } while (0)
; #define PG8_LDB(dst, b, h) do { _Pragma("unroll") for (int n = 0; n < 2; ++n) _Pragma("unroll") for (int k = 0; k < 2; ++k) dst[n][k] = *(const PG8_LAS bf16x8*)(lds + PG8_SB(b, h) + boff + n * 2048 + k * 1024); } while (0)
; #define PG8_MMA(ai, bj, At, Bt) do { __builtin_amdgcn_s_setprio(1); _Pragma("unroll") for (int m = 0; m < 4; ++m) _Pragma("unroll") for (int n = 0; n < 2; ++n) _Pragma("unroll") for (int k = 0; k < 2; ++k) \
;         acc[ai][bj][m][n] = __builtin_amdgcn_mfma_f32_16x16x32_bf16(Bt[n][k], At[m][k], acc[ai][bj][m][n], 0, 0, 0); __builtin_amdgcn_s_setprio(0); } while (0)
; template <class Epi, class Sched, bool ALIGN_EPI = false, bool SP2 = false, bool KHOOK = false>
; __device__ __forceinline__ void gemm_phase(PG8_LAS unsigned char* lds, const Gemm g, const Sched& S, const Epi& E, const int tid_in) {
;     ...
;             PG8_LDB(B0, 0, 0); PG8_LDB(B1, 0, 1); PG8_SCHED; PG8_LDA(At, 0, 0); PG8_STAGE(PG8_SA(1, 1), a1 + hstep, voffA);
;             PG8_WAIT_V(8); PG8_WAIT_L(0); PG8_BAR; PG8_MMA(0, 0, At, B0); PG8_MMA(0, 1, At, B1); PG8_BAR; PG8_SCHED;
;             PG8_LDA(At, 0, 1); PG8_STAGE(PG8_SB(0, 0), b2, voffB); PG8_STAGE(PG8_SB(0, 1), b2 + hstep, voffB); PG8_STAGE(PG8_SA(0, 0), a2, voffA);
;             PG8_WAIT_V(8); PG8_WAIT_L(0); PG8_BAR; PG8_MMA(1, 0, At, B0); PG8_MMA(1, 1, At, B1); PG8_BAR; PG8_SCHED;
;             PG8_LDB(B0, 1, 0); PG8_LDB(B1, 1, 1); PG8_SCHED; PG8_LDA(At, 1, 0); PG8_STAGE(PG8_SA(0, 1), a2 + hstep, voffA);
;             PG8_WAIT_V(8); PG8_WAIT_L(0); PG8_BAR; PG8_MMA(0, 0, At, B0); PG8_MMA(0, 1, At, B1); PG8_BAR; PG8_SCHED;
;             PG8_LDA(At, 1, 1); PG8_STAGE(PG8_SB(1, 0), b3, voffB); PG8_STAGE(PG8_SB(1, 1), b3 + hstep, voffB); PG8_STAGE(PG8_SA(1, 0), a3, voffA);
;             PG8_WAIT_V(8); PG8_WAIT_L(0); PG8_BAR; PG8_MMA(1, 0, At, B0); PG8_MMA(1, 1, At, B1); PG8_BAR; PG8_SCHED;
	s_add_i32 s45, 0, 0x18000
	s_add_i32 s50, 0, 0x1c000
	v_add_u32_e32 v156, s45, v141
	v_add_u32_e32 v172, s50, v141
	ds_read_b128 v[144:147], v156
	ds_read_b128 v[148:151], v156 offset:1024
	ds_read_b128 v[152:155], v156 offset:2048
	ds_read_b128 v[156:159], v156 offset:3072
	ds_read_b128 v[160:163], v172
	ds_read_b128 v[164:167], v172 offset:1024
	ds_read_b128 v[168:171], v172 offset:2048
	ds_read_b128 v[172:175], v172 offset:3072
	s_add_u32 s46, s56, 0x80000
	s_addc_u32 s47, s57, 0
	s_mov_b32 m0, s25
	v_lshl_add_u64 v[220:221], s[46:47], 0, v[130:131]
	ds_read_b128 v[176:179], v143 offset:32768
	ds_read_b128 v[180:183], v143 offset:33792
	ds_read_b128 v[184:187], v143 offset:34816
	ds_read_b128 v[188:191], v143 offset:35840
	ds_read_b128 v[198:201], v143 offset:36864
	ds_read_b128 v[202:205], v143 offset:37888
	ds_read_b128 v[206:209], v143 offset:38912
	ds_read_b128 v[210:213], v143 offset:39936
	global_load_lds_dwordx4 v[220:221], off
	s_mov_b32 m0, s38
	v_lshl_add_u64 v[220:221], s[46:47], 0, v[132:133]
	global_load_lds_dwordx4 v[220:221], off
	s_waitcnt vmcnt(16)
	s_waitcnt lgkmcnt(0)
	s_barrier
	s_setprio 1
	v_mfma_f32_16x16x32_bf16 v[126:129], v[144:147], v[176:179], v[126:129]
	v_mfma_f32_16x16x32_bf16 v[122:125], v[152:155], v[176:179], v[122:125]
	v_mfma_f32_16x16x32_bf16 v[118:121], v[144:147], v[184:187], v[118:121]
	v_mfma_f32_16x16x32_bf16 v[114:117], v[152:155], v[184:187], v[114:117]
	v_mfma_f32_16x16x32_bf16 v[102:105], v[144:147], v[198:201], v[102:105]
	v_mfma_f32_16x16x32_bf16 v[98:101], v[152:155], v[198:201], v[98:101]
	v_mfma_f32_16x16x32_bf16 v[86:89], v[144:147], v[206:209], v[86:89]
	v_mfma_f32_16x16x32_bf16 v[82:85], v[152:155], v[206:209], v[82:85]
	v_mfma_f32_16x16x32_bf16 v[126:129], v[148:151], v[180:183], v[126:129]
	v_mfma_f32_16x16x32_bf16 v[122:125], v[156:159], v[180:183], v[122:125]
	v_mfma_f32_16x16x32_bf16 v[118:121], v[148:151], v[188:191], v[118:121]
	v_mfma_f32_16x16x32_bf16 v[114:117], v[156:159], v[188:191], v[114:117]
	v_mfma_f32_16x16x32_bf16 v[102:105], v[148:151], v[202:205], v[102:105]
	v_mfma_f32_16x16x32_bf16 v[98:101], v[156:159], v[202:205], v[98:101]
	v_mfma_f32_16x16x32_bf16 v[86:89], v[148:151], v[210:213], v[86:89]
	v_mfma_f32_16x16x32_bf16 v[82:85], v[156:159], v[210:213], v[82:85]
	s_setprio 0
	s_setprio 1
	v_mfma_f32_16x16x32_bf16 v[110:113], v[160:163], v[176:179], v[110:113]
	v_mfma_f32_16x16x32_bf16 v[106:109], v[168:171], v[176:179], v[106:109]
	v_mfma_f32_16x16x32_bf16 v[94:97], v[160:163], v[184:187], v[94:97]
	v_mfma_f32_16x16x32_bf16 v[90:93], v[168:171], v[184:187], v[90:93]
	v_mfma_f32_16x16x32_bf16 v[78:81], v[160:163], v[198:201], v[78:81]
	v_mfma_f32_16x16x32_bf16 v[74:77], v[168:171], v[198:201], v[74:77]
	v_mfma_f32_16x16x32_bf16 v[70:73], v[160:163], v[206:209], v[70:73]
	v_mfma_f32_16x16x32_bf16 v[66:69], v[168:171], v[206:209], v[66:69]
	v_mfma_f32_16x16x32_bf16 v[110:113], v[164:167], v[180:183], v[110:113]
	v_mfma_f32_16x16x32_bf16 v[106:109], v[172:175], v[180:183], v[106:109]
	v_mfma_f32_16x16x32_bf16 v[94:97], v[164:167], v[188:191], v[94:97]
	v_mfma_f32_16x16x32_bf16 v[90:93], v[172:175], v[188:191], v[90:93]
	v_mfma_f32_16x16x32_bf16 v[78:81], v[164:167], v[202:205], v[78:81]
	v_mfma_f32_16x16x32_bf16 v[74:77], v[172:175], v[202:205], v[74:77]
	v_mfma_f32_16x16x32_bf16 v[70:73], v[164:167], v[210:213], v[70:73]
	v_mfma_f32_16x16x32_bf16 v[66:69], v[172:175], v[210:213], v[66:69]
	s_setprio 0
	s_barrier
	s_add_i32 s45, s45, s37
	v_lshl_add_u64 v[192:193], v[192:193], 0, s[90:91]
	s_mov_b32 m0, s45
	ds_read_b128 v[176:179], v143 offset:49152
	ds_read_b128 v[180:183], v143 offset:50176
	ds_read_b128 v[184:187], v143 offset:51200
	ds_read_b128 v[188:191], v143 offset:52224
	ds_read_b128 v[198:201], v143 offset:53248
	ds_read_b128 v[202:205], v143 offset:54272
	ds_read_b128 v[206:209], v143 offset:55296
	ds_read_b128 v[210:213], v143 offset:56320
	global_load_lds_dwordx4 v[192:193], off
	s_add_i32 m0, s45, 0x2000
	s_add_u32 s46, s52, 0x80080
	v_lshl_add_u64 v[192:193], v[214:215], 0, s[90:91]
	s_addc_u32 s47, s53, 0
	s_add_i32 s45, s50, s37
	global_load_lds_dwordx4 v[192:193], off
	s_mov_b32 m0, s45
	v_lshl_add_u64 v[192:193], s[46:47], 0, v[32:33]
	global_load_lds_dwordx4 v[192:193], off
	s_add_i32 m0, s45, 0x2000
	v_lshl_add_u64 v[192:193], s[46:47], 0, v[134:135]
	global_load_lds_dwordx4 v[192:193], off
	s_mov_b32 m0, s39
	v_lshl_add_u64 v[192:193], v[216:217], 0, s[90:91]
	global_load_lds_dwordx4 v[192:193], off
	s_mov_b32 m0, s40
	v_lshl_add_u64 v[192:193], v[218:219], 0, s[90:91]
	global_load_lds_dwordx4 v[192:193], off
	s_waitcnt vmcnt(8)
	s_waitcnt lgkmcnt(0)
	s_barrier
	s_setprio 1
	v_mfma_f32_16x16x32_bf16 v[62:65], v[144:147], v[176:179], v[62:65]
	v_mfma_f32_16x16x32_bf16 v[58:61], v[152:155], v[176:179], v[58:61]
	v_mfma_f32_16x16x32_bf16 v[54:57], v[144:147], v[184:187], v[54:57]
	v_mfma_f32_16x16x32_bf16 v[50:53], v[152:155], v[184:187], v[50:53]
	v_mfma_f32_16x16x32_bf16 v[38:41], v[144:147], v[198:201], v[38:41]
	v_mfma_f32_16x16x32_bf16 v[34:37], v[152:155], v[198:201], v[34:37]
	v_mfma_f32_16x16x32_bf16 v[20:23], v[144:147], v[206:209], v[20:23]
	v_mfma_f32_16x16x32_bf16 v[16:19], v[152:155], v[206:209], v[16:19]
	v_mfma_f32_16x16x32_bf16 v[62:65], v[148:151], v[180:183], v[62:65]
	v_mfma_f32_16x16x32_bf16 v[58:61], v[156:159], v[180:183], v[58:61]
	v_mfma_f32_16x16x32_bf16 v[54:57], v[148:151], v[188:191], v[54:57]
	v_mfma_f32_16x16x32_bf16 v[50:53], v[156:159], v[188:191], v[50:53]
	v_mfma_f32_16x16x32_bf16 v[38:41], v[148:151], v[202:205], v[38:41]
	v_mfma_f32_16x16x32_bf16 v[34:37], v[156:159], v[202:205], v[34:37]
	v_mfma_f32_16x16x32_bf16 v[20:23], v[148:151], v[210:213], v[20:23]
	v_mfma_f32_16x16x32_bf16 v[16:19], v[156:159], v[210:213], v[16:19]
	s_setprio 0
	s_setprio 1
	v_mfma_f32_16x16x32_bf16 v[46:49], v[160:163], v[176:179], v[46:49]
	v_mfma_f32_16x16x32_bf16 v[42:45], v[168:171], v[176:179], v[42:45]
	v_mfma_f32_16x16x32_bf16 v[28:31], v[160:163], v[184:187], v[28:31]
	v_mfma_f32_16x16x32_bf16 v[24:27], v[168:171], v[184:187], v[24:27]
	v_mfma_f32_16x16x32_bf16 v[12:15], v[160:163], v[198:201], v[12:15]
	v_mfma_f32_16x16x32_bf16 v[8:11], v[168:171], v[198:201], v[8:11]
	v_mfma_f32_16x16x32_bf16 v[4:7], v[160:163], v[206:209], v[4:7]
	v_mfma_f32_16x16x32_bf16 v[0:3], v[168:171], v[206:209], v[0:3]
	v_mfma_f32_16x16x32_bf16 v[46:49], v[164:167], v[180:183], v[46:49]
	v_mfma_f32_16x16x32_bf16 v[42:45], v[172:175], v[180:183], v[42:45]
	v_mfma_f32_16x16x32_bf16 v[28:31], v[164:167], v[188:191], v[28:31]
	v_mfma_f32_16x16x32_bf16 v[24:27], v[172:175], v[188:191], v[24:27]
	v_mfma_f32_16x16x32_bf16 v[12:15], v[164:167], v[202:205], v[12:15]
	v_mfma_f32_16x16x32_bf16 v[8:11], v[172:175], v[202:205], v[8:11]
	v_mfma_f32_16x16x32_bf16 v[4:7], v[164:167], v[210:213], v[4:7]
	v_mfma_f32_16x16x32_bf16 v[0:3], v[172:175], v[210:213], v[0:3]
	s_setprio 0
	s_barrier
	s_add_i32 s44, s44, 2
	s_add_u32 s48, s48, 0x100
	s_addc_u32 s49, s49, 0
	s_add_u32 s19, s19, 0x100
	s_addc_u32 s42, s42, 0
	s_cmp_gt_u32 s44, 29
; #define PG8_STAGE(bufoff, gbase, voff) do { _Pragma("unroll") for (int _i = 0; _i < 2; ++_i) \
;         __builtin_amdgcn_global_load_lds((const unsigned*)((const char*)(gbase) + (voff)[_i]), (PG8_LAS unsigned*)(lds + (bufoff) + ldsw + _i * 8192), 16, 0, 0); } while (0)
; #define PG8_LDA(dst, b, h) do { _Pragma("unroll") for (int m = 0; m < 4; ++m) _Pragma("unroll") for (int k = 0; k < 2; ++k) dst[m][k] = *(const PG8_LAS bf16x8*)(lds + PG8_SA(b, h) + aoff + m * 2048 + k * 1024); } while (0)
; #define PG8_WAIT_V(n) asm volatile("s_waitcnt vmcnt(" #n ")" ::: "memory")
; #define PG8_WAIT_L(n) asm volatile("s_waitcnt lgkmcnt(" #n ")" ::: "memory")
; template <class Epi, class Sched, bool ALIGN_EPI = false, bool SP2 = false, bool KHOOK = false>
; __device__ __forceinline__ void gemm_phase(PG8_LAS unsigned char* lds, const Gemm g, const Sched& S, const Epi& E, const int tid_in) {
;     ...
;         for (int t = 0; t < nt; t += 2) {
;             const bool last = (t == nt - 2);
;             const char* a1 = cA + (size_t)(t + 1) * kstep;
;             const char* a2 = last ? nA : cA + (size_t)(t + 2) * kstep; const char* b2 = last ? nB : cB + (size_t)(t + 2) * kstep;
;             const char* a3 = a2 + kstep; const char* b3 = b2 + kstep;
;             if (last && has_next) S.a_ready(nxt);
;             if constexpr (SP2) {
;             PG8_LDB(B0, 0, 0); PG8_LDB(B1, 0, 1); PG8_SCHED; PG8_LDA(At, 0, 0); PG8_STAGE(PG8_SA(1, 1), a1 + hstep, voffA);
;             PG8_WAIT_V(8); PG8_WAIT_L(0); PG8_BAR; PG8_MMA(0, 0, At, B0); PG8_MMA(0, 1, At, B1); PG8_BAR; PG8_SCHED;
;             PG8_LDA(At, 0, 1); PG8_STAGE(PG8_SB(0, 0), b2, voffB); PG8_STAGE(PG8_SB(0, 1), b2 + hstep, voffB); PG8_STAGE(PG8_SA(0, 0), a2, voffA);
;             PG8_WAIT_V(8); PG8_WAIT_L(0); PG8_BAR; PG8_MMA(1, 0, At, B0); PG8_MMA(1, 1, At, B1); PG8_BAR; PG8_SCHED;
;             PG8_LDB(B0, 1, 0); PG8_LDB(B1, 1, 1); PG8_SCHED; PG8_LDA(At, 1, 0); PG8_STAGE(PG8_SA(0, 1), a2 + hstep, voffA);
;             PG8_WAIT_V(8); PG8_WAIT_L(0); PG8_BAR; PG8_MMA(0, 0, At, B0); PG8_MMA(0, 1, At, B1); PG8_BAR; PG8_SCHED;
;             PG8_LDA(At, 1, 1); PG8_STAGE(PG8_SB(1, 0), b3, voffB); PG8_STAGE(PG8_SB(1, 1), b3 + hstep, voffB); PG8_STAGE(PG8_SA(1, 0), a3, voffA);
;             PG8_WAIT_V(8); PG8_WAIT_L(0); PG8_BAR; PG8_MMA(1, 0, At, B0); PG8_MMA(1, 1, At, B1); PG8_BAR; PG8_SCHED;
.LBB0_263:
	s_add_u32 s45, s48, 0xfff80080
	s_addc_u32 s46, s49, -1
	s_add_i32 s47, 0, 0x10000
	s_cmp_eq_u32 s44, 28
	s_cselect_b32 s57, s11, s46
	s_cselect_b32 s56, s17, s45
	s_cselect_b32 s53, s15, s42
	s_cselect_b32 s52, s18, s19
	s_add_i32 s45, 0, 0x14000
	v_add_u32_e32 v156, s47, v141
	v_add_u32_e32 v172, s45, v141
	ds_read_b128 v[144:147], v156
	ds_read_b128 v[148:151], v156 offset:1024
	ds_read_b128 v[152:155], v156 offset:2048
	ds_read_b128 v[156:159], v156 offset:3072
	ds_read_b128 v[160:163], v172
	ds_read_b128 v[164:167], v172 offset:1024
	ds_read_b128 v[168:171], v172 offset:2048
	ds_read_b128 v[172:175], v172 offset:3072
	v_lshl_add_u64 v[192:193], s[48:49], 0, v[136:137]
	s_add_i32 m0, s13, 0xc000
	ds_read_b128 v[176:179], v143
	ds_read_b128 v[180:183], v143 offset:1024
	ds_read_b128 v[184:187], v143 offset:2048
	ds_read_b128 v[188:191], v143 offset:3072
	ds_read_b128 v[198:201], v143 offset:4096
	ds_read_b128 v[202:205], v143 offset:5120
	ds_read_b128 v[206:209], v143 offset:6144
	ds_read_b128 v[210:213], v143 offset:7168
	global_load_lds_dwordx4 v[192:193], off
	s_add_i32 m0, s13, 0xe000
	v_lshl_add_u64 v[192:193], s[48:49], 0, v[138:139]
	global_load_lds_dwordx4 v[192:193], off
	s_waitcnt vmcnt(8)
	s_waitcnt lgkmcnt(0)
	s_barrier
	s_setprio 1
	v_mfma_f32_16x16x32_bf16 v[126:129], v[144:147], v[176:179], v[126:129]
	v_mfma_f32_16x16x32_bf16 v[122:125], v[152:155], v[176:179], v[122:125]
	v_mfma_f32_16x16x32_bf16 v[118:121], v[144:147], v[184:187], v[118:121]
	v_mfma_f32_16x16x32_bf16 v[114:117], v[152:155], v[184:187], v[114:117]
	v_mfma_f32_16x16x32_bf16 v[102:105], v[144:147], v[198:201], v[102:105]
	v_mfma_f32_16x16x32_bf16 v[98:101], v[152:155], v[198:201], v[98:101]
	v_mfma_f32_16x16x32_bf16 v[86:89], v[144:147], v[206:209], v[86:89]
	v_mfma_f32_16x16x32_bf16 v[82:85], v[152:155], v[206:209], v[82:85]
	v_mfma_f32_16x16x32_bf16 v[126:129], v[148:151], v[180:183], v[126:129]
	v_mfma_f32_16x16x32_bf16 v[122:125], v[156:159], v[180:183], v[122:125]
	v_mfma_f32_16x16x32_bf16 v[118:121], v[148:151], v[188:191], v[118:121]
	v_mfma_f32_16x16x32_bf16 v[114:117], v[156:159], v[188:191], v[114:117]
	v_mfma_f32_16x16x32_bf16 v[102:105], v[148:151], v[202:205], v[102:105]
	v_mfma_f32_16x16x32_bf16 v[98:101], v[156:159], v[202:205], v[98:101]
	v_mfma_f32_16x16x32_bf16 v[86:89], v[148:151], v[210:213], v[86:89]
	v_mfma_f32_16x16x32_bf16 v[82:85], v[156:159], v[210:213], v[82:85]
	s_setprio 0
	s_setprio 1
	v_mfma_f32_16x16x32_bf16 v[110:113], v[160:163], v[176:179], v[110:113]
	v_mfma_f32_16x16x32_bf16 v[106:109], v[168:171], v[176:179], v[106:109]
	v_mfma_f32_16x16x32_bf16 v[94:97], v[160:163], v[184:187], v[94:97]
	v_mfma_f32_16x16x32_bf16 v[90:93], v[168:171], v[184:187], v[90:93]
	v_mfma_f32_16x16x32_bf16 v[78:81], v[160:163], v[198:201], v[78:81]
	v_mfma_f32_16x16x32_bf16 v[74:77], v[168:171], v[198:201], v[74:77]
	v_mfma_f32_16x16x32_bf16 v[70:73], v[160:163], v[206:209], v[70:73]
	v_mfma_f32_16x16x32_bf16 v[66:69], v[168:171], v[206:209], v[66:69]
	v_mfma_f32_16x16x32_bf16 v[110:113], v[164:167], v[180:183], v[110:113]
	v_mfma_f32_16x16x32_bf16 v[106:109], v[172:175], v[180:183], v[106:109]
	v_mfma_f32_16x16x32_bf16 v[94:97], v[164:167], v[188:191], v[94:97]
	v_mfma_f32_16x16x32_bf16 v[90:93], v[172:175], v[188:191], v[90:93]
	v_mfma_f32_16x16x32_bf16 v[78:81], v[164:167], v[202:205], v[78:81]
	v_mfma_f32_16x16x32_bf16 v[74:77], v[172:175], v[202:205], v[74:77]
	v_mfma_f32_16x16x32_bf16 v[70:73], v[164:167], v[210:213], v[70:73]
	v_mfma_f32_16x16x32_bf16 v[66:69], v[172:175], v[210:213], v[66:69]
	s_setprio 0
	s_barrier
	s_add_i32 s46, s47, s37
	v_lshl_add_u64 v[192:193], s[52:53], 0, v[32:33]
	s_mov_b32 m0, s46
	ds_read_b128 v[176:179], v143 offset:16384
	ds_read_b128 v[180:183], v143 offset:17408
	ds_read_b128 v[184:187], v143 offset:18432
	ds_read_b128 v[188:191], v143 offset:19456
	ds_read_b128 v[198:201], v143 offset:20480
	ds_read_b128 v[202:205], v143 offset:21504
	ds_read_b128 v[206:209], v143 offset:22528
	ds_read_b128 v[210:213], v143 offset:23552
	global_load_lds_dwordx4 v[192:193], off
	s_add_i32 m0, s46, 0x2000
	s_add_u32 s46, s52, 0x80000
	v_lshl_add_u64 v[214:215], s[52:53], 0, v[134:135]
	s_addc_u32 s47, s53, 0
	s_add_i32 s45, s45, s37
	global_load_lds_dwordx4 v[214:215], off
	v_lshl_add_u64 v[216:217], s[46:47], 0, v[32:33]
	s_mov_b32 m0, s45
	v_lshl_add_u64 v[218:219], s[56:57], 0, v[132:133]
	global_load_lds_dwordx4 v[216:217], off
	s_add_i32 m0, s45, 0x2000
	v_lshl_add_u64 v[216:217], s[46:47], 0, v[134:135]
	global_load_lds_dwordx4 v[216:217], off
	s_mov_b32 m0, s13
	v_lshl_add_u64 v[216:217], s[56:57], 0, v[130:131]
	global_load_lds_dwordx4 v[216:217], off
	s_mov_b32 m0, s24
	s_nop 0
	global_load_lds_dwordx4 v[218:219], off
	s_waitcnt vmcnt(8)
	s_waitcnt lgkmcnt(0)
	s_barrier
; #define PG8_STAGE(bufoff, gbase, voff) do { _Pragma("unroll") for (int _i = 0; _i < 2; ++_i) \
;         __builtin_amdgcn_global_load_lds((const unsigned*)((const char*)(gbase) + (voff)[_i]), (PG8_LAS unsigned*)(lds + (bufoff) + ldsw + _i * 8192), 16, 0, 0); } while (0)
; #define PG8_LDA(dst, b, h) do { _Pragma("unroll") for (int m = 0; m < 4; ++m) _Pragma("unroll") for (int k = 0; k < 2; ++k) dst[m][k] = *(const PG8_LAS bf16x8*)(lds + PG8_SA(b, h) + aoff + m * 2048 + k * 1024); } while (0)
; #define PG8_LDB(dst, b, h) do { _Pragma("unroll") for (int n = 0; n < 2; ++n) _Pragma("unroll") for (int k = 0; k < 2; ++k) dst[n][k] = *(const PG8_LAS bf16x8*)(lds + PG8_SB(b, h) + boff + n * 2048 + k * 1024); } while (0)
; #define PG8_MMA(ai, bj, At, Bt) do { __builtin_amdgcn_s_setprio(1); _Pragma("unroll") for (int m = 0; m < 4; ++m) _Pragma("unroll") for (int n = 0; n < 2; ++n) _Pragma("unroll") for (int k = 0; k < 2; ++k) \
;         acc[ai][bj][m][n] = __builtin_amdgcn_mfma_f32_16x16x32_bf16(Bt[n][k], At[m][k], acc[ai][bj][m][n], 0, 0, 0); __builtin_amdgcn_s_setprio(0); } while (0)
; template <class Epi, class Sched, bool ALIGN_EPI = false, bool SP2 = false, bool KHOOK = false>
; __device__ __forceinline__ void gemm_phase(PG8_LAS unsigned char* lds, const Gemm g, const Sched& S, const Epi& E, const int tid_in) {
;     ...
;             PG8_LDB(B0, 0, 0); PG8_LDB(B1, 0, 1); PG8_SCHED; PG8_LDA(At, 0, 0); PG8_STAGE(PG8_SA(1, 1), a1 + hstep, voffA);
;             PG8_WAIT_V(8); PG8_WAIT_L(0); PG8_BAR; PG8_MMA(0, 0, At, B0); PG8_MMA(0, 1, At, B1); PG8_BAR; PG8_SCHED;
;             PG8_LDA(At, 0, 1); PG8_STAGE(PG8_SB(0, 0), b2, voffB); PG8_STAGE(PG8_SB(0, 1), b2 + hstep, voffB); PG8_STAGE(PG8_SA(0, 0), a2, voffA);
;             PG8_WAIT_V(8); PG8_WAIT_L(0); PG8_BAR; PG8_MMA(1, 0, At, B0); PG8_MMA(1, 1, At, B1); PG8_BAR; PG8_SCHED;
;             PG8_LDB(B0, 1, 0); PG8_LDB(B1, 1, 1); PG8_SCHED; PG8_LDA(At, 1, 0); PG8_STAGE(PG8_SA(0, 1), a2 + hstep, voffA);
;             PG8_WAIT_V(8); PG8_WAIT_L(0); PG8_BAR; PG8_MMA(0, 0, At, B0); PG8_MMA(0, 1, At, B1); PG8_BAR; PG8_SCHED;
;             PG8_LDA(At, 1, 1); PG8_STAGE(PG8_SB(1, 0), b3, voffB); PG8_STAGE(PG8_SB(1, 1), b3 + hstep, voffB); PG8_STAGE(PG8_SA(1, 0), a3, voffA);
;             PG8_WAIT_V(8); PG8_WAIT_L(0); PG8_BAR; PG8_MMA(1, 0, At, B0); PG8_MMA(1, 1, At, B1); PG8_BAR; PG8_SCHED;
	s_setprio 1
	v_mfma_f32_16x16x32_bf16 v[62:65], v[144:147], v[176:179], v[62:65]
	v_mfma_f32_16x16x32_bf16 v[58:61], v[152:155], v[176:179], v[58:61]
	v_mfma_f32_16x16x32_bf16 v[54:57], v[144:147], v[184:187], v[54:57]
	v_mfma_f32_16x16x32_bf16 v[50:53], v[152:155], v[184:187], v[50:53]
	v_mfma_f32_16x16x32_bf16 v[38:41], v[144:147], v[198:201], v[38:41]
	v_mfma_f32_16x16x32_bf16 v[34:37], v[152:155], v[198:201], v[34:37]
	v_mfma_f32_16x16x32_bf16 v[20:23], v[144:147], v[206:209], v[20:23]
	v_mfma_f32_16x16x32_bf16 v[16:19], v[152:155], v[206:209], v[16:19]
	v_mfma_f32_16x16x32_bf16 v[62:65], v[148:151], v[180:183], v[62:65]
	v_mfma_f32_16x16x32_bf16 v[58:61], v[156:159], v[180:183], v[58:61]
	v_mfma_f32_16x16x32_bf16 v[54:57], v[148:151], v[188:191], v[54:57]
	v_mfma_f32_16x16x32_bf16 v[50:53], v[156:159], v[188:191], v[50:53]
	v_mfma_f32_16x16x32_bf16 v[38:41], v[148:151], v[202:205], v[38:41]
	v_mfma_f32_16x16x32_bf16 v[34:37], v[156:159], v[202:205], v[34:37]
	v_mfma_f32_16x16x32_bf16 v[20:23], v[148:151], v[210:213], v[20:23]
	v_mfma_f32_16x16x32_bf16 v[16:19], v[156:159], v[210:213], v[16:19]
	s_setprio 0
	s_setprio 1
	v_mfma_f32_16x16x32_bf16 v[46:49], v[160:163], v[176:179], v[46:49]
	v_mfma_f32_16x16x32_bf16 v[42:45], v[168:171], v[176:179], v[42:45]
	v_mfma_f32_16x16x32_bf16 v[28:31], v[160:163], v[184:187], v[28:31]
	v_mfma_f32_16x16x32_bf16 v[24:27], v[168:171], v[184:187], v[24:27]
	v_mfma_f32_16x16x32_bf16 v[12:15], v[160:163], v[198:201], v[12:15]
	v_mfma_f32_16x16x32_bf16 v[8:11], v[168:171], v[198:201], v[8:11]
	v_mfma_f32_16x16x32_bf16 v[4:7], v[160:163], v[206:209], v[4:7]
	v_mfma_f32_16x16x32_bf16 v[0:3], v[168:171], v[206:209], v[0:3]
	v_mfma_f32_16x16x32_bf16 v[46:49], v[164:167], v[180:183], v[46:49]
	v_mfma_f32_16x16x32_bf16 v[42:45], v[172:175], v[180:183], v[42:45]
	v_mfma_f32_16x16x32_bf16 v[28:31], v[164:167], v[188:191], v[28:31]
	v_mfma_f32_16x16x32_bf16 v[24:27], v[172:175], v[188:191], v[24:27]
	v_mfma_f32_16x16x32_bf16 v[12:15], v[164:167], v[202:205], v[12:15]
	v_mfma_f32_16x16x32_bf16 v[8:11], v[172:175], v[202:205], v[8:11]
	v_mfma_f32_16x16x32_bf16 v[4:7], v[164:167], v[210:213], v[4:7]
	v_mfma_f32_16x16x32_bf16 v[0:3], v[172:175], v[210:213], v[0:3]
	s_setprio 0
	s_barrier
	s_add_i32 s45, 0, 0x18000
	s_add_i32 s50, 0, 0x1c000
	v_add_u32_e32 v156, s45, v141
	v_add_u32_e32 v172, s50, v141
	ds_read_b128 v[144:147], v156
	ds_read_b128 v[148:151], v156 offset:1024
	ds_read_b128 v[152:155], v156 offset:2048
	ds_read_b128 v[156:159], v156 offset:3072
	ds_read_b128 v[160:163], v172
	ds_read_b128 v[164:167], v172 offset:1024
	ds_read_b128 v[168:171], v172 offset:2048
	ds_read_b128 v[172:175], v172 offset:3072
	s_add_u32 s46, s56, 0x80000
	s_addc_u32 s47, s57, 0
	s_mov_b32 m0, s25
	v_lshl_add_u64 v[220:221], s[46:47], 0, v[130:131]
	ds_read_b128 v[176:179], v143 offset:32768
	ds_read_b128 v[180:183], v143 offset:33792
	ds_read_b128 v[184:187], v143 offset:34816
	ds_read_b128 v[188:191], v143 offset:35840
	ds_read_b128 v[198:201], v143 offset:36864
	ds_read_b128 v[202:205], v143 offset:37888
	ds_read_b128 v[206:209], v143 offset:38912
	ds_read_b128 v[210:213], v143 offset:39936
	global_load_lds_dwordx4 v[220:221], off
	s_mov_b32 m0, s38
	v_lshl_add_u64 v[220:221], s[46:47], 0, v[132:133]
	global_load_lds_dwordx4 v[220:221], off
	s_waitcnt vmcnt(8)
	s_waitcnt lgkmcnt(0)
	s_barrier
	s_setprio 1
	v_mfma_f32_16x16x32_bf16 v[126:129], v[144:147], v[176:179], v[126:129]
	v_mfma_f32_16x16x32_bf16 v[122:125], v[152:155], v[176:179], v[122:125]
	v_mfma_f32_16x16x32_bf16 v[118:121], v[144:147], v[184:187], v[118:121]
	v_mfma_f32_16x16x32_bf16 v[114:117], v[152:155], v[184:187], v[114:117]
	v_mfma_f32_16x16x32_bf16 v[102:105], v[144:147], v[198:201], v[102:105]
	v_mfma_f32_16x16x32_bf16 v[98:101], v[152:155], v[198:201], v[98:101]
	v_mfma_f32_16x16x32_bf16 v[86:89], v[144:147], v[206:209], v[86:89]
	v_mfma_f32_16x16x32_bf16 v[82:85], v[152:155], v[206:209], v[82:85]
	v_mfma_f32_16x16x32_bf16 v[126:129], v[148:151], v[180:183], v[126:129]
	v_mfma_f32_16x16x32_bf16 v[122:125], v[156:159], v[180:183], v[122:125]
	v_mfma_f32_16x16x32_bf16 v[118:121], v[148:151], v[188:191], v[118:121]
	v_mfma_f32_16x16x32_bf16 v[114:117], v[156:159], v[188:191], v[114:117]
	v_mfma_f32_16x16x32_bf16 v[102:105], v[148:151], v[202:205], v[102:105]
	v_mfma_f32_16x16x32_bf16 v[98:101], v[156:159], v[202:205], v[98:101]
	v_mfma_f32_16x16x32_bf16 v[86:89], v[148:151], v[210:213], v[86:89]
	v_mfma_f32_16x16x32_bf16 v[82:85], v[156:159], v[210:213], v[82:85]
	s_setprio 0
	s_setprio 1
	v_mfma_f32_16x16x32_bf16 v[110:113], v[160:163], v[176:179], v[110:113]
	v_mfma_f32_16x16x32_bf16 v[106:109], v[168:171], v[176:179], v[106:109]
	v_mfma_f32_16x16x32_bf16 v[94:97], v[160:163], v[184:187], v[94:97]
	v_mfma_f32_16x16x32_bf16 v[90:93], v[168:171], v[184:187], v[90:93]
	v_mfma_f32_16x16x32_bf16 v[78:81], v[160:163], v[198:201], v[78:81]
	v_mfma_f32_16x16x32_bf16 v[74:77], v[168:171], v[198:201], v[74:77]
	v_mfma_f32_16x16x32_bf16 v[70:73], v[160:163], v[206:209], v[70:73]
	v_mfma_f32_16x16x32_bf16 v[66:69], v[168:171], v[206:209], v[66:69]
	v_mfma_f32_16x16x32_bf16 v[110:113], v[164:167], v[180:183], v[110:113]
	v_mfma_f32_16x16x32_bf16 v[106:109], v[172:175], v[180:183], v[106:109]
	v_mfma_f32_16x16x32_bf16 v[94:97], v[164:167], v[188:191], v[94:97]
	v_mfma_f32_16x16x32_bf16 v[90:93], v[172:175], v[188:191], v[90:93]
	v_mfma_f32_16x16x32_bf16 v[78:81], v[164:167], v[202:205], v[78:81]
	v_mfma_f32_16x16x32_bf16 v[74:77], v[172:175], v[202:205], v[74:77]
	v_mfma_f32_16x16x32_bf16 v[70:73], v[164:167], v[210:213], v[70:73]
	v_mfma_f32_16x16x32_bf16 v[66:69], v[172:175], v[210:213], v[66:69]
	s_setprio 0
	s_barrier
; #define PG8_STAGE(bufoff, gbase, voff) do { _Pragma("unroll") for (int _i = 0; _i < 2; ++_i) \
;         __builtin_amdgcn_global_load_lds((const unsigned*)((const char*)(gbase) + (voff)[_i]), (PG8_LAS unsigned*)(lds + (bufoff) + ldsw + _i * 8192), 16, 0, 0); } while (0)
; #define PG8_LDA(dst, b, h) do { _Pragma("unroll") for (int m = 0; m < 4; ++m) _Pragma("unroll") for (int k = 0; k < 2; ++k) dst[m][k] = *(const PG8_LAS bf16x8*)(lds + PG8_SA(b, h) + aoff + m * 2048 + k * 1024); } while (0)
; #define PG8_LDB(dst, b, h) do { _Pragma("unroll") for (int n = 0; n < 2; ++n) _Pragma("unroll") for (int k = 0; k < 2; ++k) dst[n][k] = *(const PG8_LAS bf16x8*)(lds + PG8_SB(b, h) + boff + n * 2048 + k * 1024); } while (0)
; #define PG8_MMA(ai, bj, At, Bt) do { __builtin_amdgcn_s_setprio(1); _Pragma("unroll") for (int m = 0; m < 4; ++m) _Pragma("unroll") for (int n = 0; n < 2; ++n) _Pragma("unroll") for (int k = 0; k < 2; ++k) \
;         acc[ai][bj][m][n] = __builtin_amdgcn_mfma_f32_16x16x32_bf16(Bt[n][k], At[m][k], acc[ai][bj][m][n], 0, 0, 0); __builtin_amdgcn_s_setprio(0); } while (0)
; template <class Epi, class Sched, bool ALIGN_EPI = false, bool SP2 = false, bool KHOOK = false>
; __device__ __forceinline__ void gemm_phase(PG8_LAS unsigned char* lds, const Gemm g, const Sched& S, const Epi& E, const int tid_in) {
;     ...
;             PG8_LDB(B0, 0, 0); PG8_LDB(B1, 0, 1); PG8_SCHED; PG8_LDA(At, 0, 0); PG8_STAGE(PG8_SA(1, 1), a1 + hstep, voffA);
;             PG8_WAIT_V(8); PG8_WAIT_L(0); PG8_BAR; PG8_MMA(0, 0, At, B0); PG8_MMA(0, 1, At, B1); PG8_BAR; PG8_SCHED;
;             PG8_LDA(At, 0, 1); PG8_STAGE(PG8_SB(0, 0), b2, voffB); PG8_STAGE(PG8_SB(0, 1), b2 + hstep, voffB); PG8_STAGE(PG8_SA(0, 0), a2, voffA);
;             PG8_WAIT_V(8); PG8_WAIT_L(0); PG8_BAR; PG8_MMA(1, 0, At, B0); PG8_MMA(1, 1, At, B1); PG8_BAR; PG8_SCHED;
;             PG8_LDB(B0, 1, 0); PG8_LDB(B1, 1, 1); PG8_SCHED; PG8_LDA(At, 1, 0); PG8_STAGE(PG8_SA(0, 1), a2 + hstep, voffA);
;             PG8_WAIT_V(8); PG8_WAIT_L(0); PG8_BAR; PG8_MMA(0, 0, At, B0); PG8_MMA(0, 1, At, B1); PG8_BAR; PG8_SCHED;
;             PG8_LDA(At, 1, 1); PG8_STAGE(PG8_SB(1, 0), b3, voffB); PG8_STAGE(PG8_SB(1, 1), b3 + hstep, voffB); PG8_STAGE(PG8_SA(1, 0), a3, voffA);
;             PG8_WAIT_V(8); PG8_WAIT_L(0); PG8_BAR; PG8_MMA(1, 0, At, B0); PG8_MMA(1, 1, At, B1); PG8_BAR; PG8_SCHED;
	s_add_i32 s45, s45, s37
	v_lshl_add_u64 v[192:193], v[192:193], 0, s[90:91]
	s_mov_b32 m0, s45
	ds_read_b128 v[176:179], v143 offset:49152
	ds_read_b128 v[180:183], v143 offset:50176
	ds_read_b128 v[184:187], v143 offset:51200
	ds_read_b128 v[188:191], v143 offset:52224
	ds_read_b128 v[198:201], v143 offset:53248
	ds_read_b128 v[202:205], v143 offset:54272
	ds_read_b128 v[206:209], v143 offset:55296
	ds_read_b128 v[210:213], v143 offset:56320
	global_load_lds_dwordx4 v[192:193], off
	s_add_i32 m0, s45, 0x2000
	s_add_u32 s46, s52, 0x80080
	v_lshl_add_u64 v[192:193], v[214:215], 0, s[90:91]
	s_addc_u32 s47, s53, 0
	s_add_i32 s45, s50, s37
	global_load_lds_dwordx4 v[192:193], off
	s_mov_b32 m0, s45
	v_lshl_add_u64 v[192:193], s[46:47], 0, v[32:33]
	global_load_lds_dwordx4 v[192:193], off
	s_add_i32 m0, s45, 0x2000
	v_lshl_add_u64 v[192:193], s[46:47], 0, v[134:135]
	global_load_lds_dwordx4 v[192:193], off
	s_mov_b32 m0, s39
	v_lshl_add_u64 v[192:193], v[216:217], 0, s[90:91]
	global_load_lds_dwordx4 v[192:193], off
	s_mov_b32 m0, s40
	v_lshl_add_u64 v[192:193], v[218:219], 0, s[90:91]
	global_load_lds_dwordx4 v[192:193], off
	s_waitcnt vmcnt(8)
	s_waitcnt lgkmcnt(0)
	s_barrier
	s_setprio 1
	v_mfma_f32_16x16x32_bf16 v[62:65], v[144:147], v[176:179], v[62:65]
	v_mfma_f32_16x16x32_bf16 v[58:61], v[152:155], v[176:179], v[58:61]
	v_mfma_f32_16x16x32_bf16 v[54:57], v[144:147], v[184:187], v[54:57]
	v_mfma_f32_16x16x32_bf16 v[50:53], v[152:155], v[184:187], v[50:53]
	v_mfma_f32_16x16x32_bf16 v[38:41], v[144:147], v[198:201], v[38:41]
	v_mfma_f32_16x16x32_bf16 v[34:37], v[152:155], v[198:201], v[34:37]
	v_mfma_f32_16x16x32_bf16 v[20:23], v[144:147], v[206:209], v[20:23]
	v_mfma_f32_16x16x32_bf16 v[16:19], v[152:155], v[206:209], v[16:19]
	v_mfma_f32_16x16x32_bf16 v[62:65], v[148:151], v[180:183], v[62:65]
	v_mfma_f32_16x16x32_bf16 v[58:61], v[156:159], v[180:183], v[58:61]
	v_mfma_f32_16x16x32_bf16 v[54:57], v[148:151], v[188:191], v[54:57]
	v_mfma_f32_16x16x32_bf16 v[50:53], v[156:159], v[188:191], v[50:53]
	v_mfma_f32_16x16x32_bf16 v[38:41], v[148:151], v[202:205], v[38:41]
	v_mfma_f32_16x16x32_bf16 v[34:37], v[156:159], v[202:205], v[34:37]
	v_mfma_f32_16x16x32_bf16 v[20:23], v[148:151], v[210:213], v[20:23]
	v_mfma_f32_16x16x32_bf16 v[16:19], v[156:159], v[210:213], v[16:19]
	s_setprio 0
	s_setprio 1
	v_mfma_f32_16x16x32_bf16 v[46:49], v[160:163], v[176:179], v[46:49]
	v_mfma_f32_16x16x32_bf16 v[42:45], v[168:171], v[176:179], v[42:45]
	v_mfma_f32_16x16x32_bf16 v[28:31], v[160:163], v[184:187], v[28:31]
	v_mfma_f32_16x16x32_bf16 v[24:27], v[168:171], v[184:187], v[24:27]
	v_mfma_f32_16x16x32_bf16 v[12:15], v[160:163], v[198:201], v[12:15]
	v_mfma_f32_16x16x32_bf16 v[8:11], v[168:171], v[198:201], v[8:11]
	v_mfma_f32_16x16x32_bf16 v[4:7], v[160:163], v[206:209], v[4:7]
	v_mfma_f32_16x16x32_bf16 v[0:3], v[168:171], v[206:209], v[0:3]
	v_mfma_f32_16x16x32_bf16 v[46:49], v[164:167], v[180:183], v[46:49]
	v_mfma_f32_16x16x32_bf16 v[42:45], v[172:175], v[180:183], v[42:45]
	v_mfma_f32_16x16x32_bf16 v[28:31], v[164:167], v[188:191], v[28:31]
	v_mfma_f32_16x16x32_bf16 v[24:27], v[172:175], v[188:191], v[24:27]
	v_mfma_f32_16x16x32_bf16 v[12:15], v[164:167], v[202:205], v[12:15]
	v_mfma_f32_16x16x32_bf16 v[8:11], v[172:175], v[202:205], v[8:11]
	v_mfma_f32_16x16x32_bf16 v[4:7], v[164:167], v[210:213], v[4:7]
	v_mfma_f32_16x16x32_bf16 v[0:3], v[172:175], v[210:213], v[0:3]
	s_setprio 0
	s_barrier
	s_add_i32 s44, s44, 2
	s_add_u32 s48, s48, 0x100
	s_addc_u32 s49, s49, 0
	s_add_u32 s19, s19, 0x100
	s_addc_u32 s42, s42, 0
	s_cmp_lg_u32 s44, 28
	s_cbranch_scc1 .Lg1_cont
	s_cmp_lg_u64 s[22:23], 0
	s_cbranch_scc1 .Lg1_last

; #define PG8_STAGE(bufoff, gbase, voff) do { _Pragma("unroll") for (int _i = 0; _i < 2; ++_i) \
;         __builtin_amdgcn_global_load_lds((const unsigned*)((const char*)(gbase) + (voff)[_i]), (PG8_LAS unsigned*)(lds + (bufoff) + ldsw + _i * 8192), 16, 0, 0); } while (0)
; #define PG8_LDA(dst, b, h) do { _Pragma("unroll") for (int m = 0; m < 4; ++m) _Pragma("unroll") for (int k = 0; k < 2; ++k) dst[m][k] = *(const PG8_LAS bf16x8*)(lds + PG8_SA(b, h) + aoff + m * 2048 + k * 1024); } while (0)
; #define PG8_LDB(dst, b, h) do { _Pragma("unroll") for (int n = 0; n < 2; ++n) _Pragma("unroll") for (int k = 0; k < 2; ++k) dst[n][k] = *(const PG8_LAS bf16x8*)(lds + PG8_SB(b, h) + boff + n * 2048 + k * 1024); } while (0)
; #define PG8_WAIT_V(n) asm volatile("s_waitcnt vmcnt(" #n ")" ::: "memory")
; #define PG8_BAR __builtin_amdgcn_s_barrier()
; template <class Epi, class Sched, bool ALIGN_EPI = false, bool SP2 = false, bool KHOOK = false>
; __device__ __forceinline__ void gemm_phase(PG8_LAS unsigned char* lds, const Gemm g, const Sched& S, const Epi& E, const int tid_in) {
;     ...
;             const char* a2 = last ? nA : cA + (size_t)(t + 2) * kstep; const char* b2 = last ? nB : cB + (size_t)(t + 2) * kstep;
;             const char* a3 = a2 + kstep; const char* b3 = b2 + kstep;
;             if (last && has_next) S.a_ready(nxt);
;             if constexpr (SP2) {
;             PG8_LDB(B0, 0, 0); PG8_LDB(B1, 0, 1); PG8_SCHED; PG8_LDA(At, 0, 0); PG8_STAGE(PG8_SA(1, 1), a1 + hstep, voffA);
;             PG8_WAIT_V(8); PG8_WAIT_L(0); PG8_BAR; PG8_MMA(0, 0, At, B0); PG8_MMA(0, 1, At, B1); PG8_BAR; PG8_SCHED;
;             PG8_LDA(At, 0, 1); PG8_STAGE(PG8_SB(0, 0), b2, voffB); PG8_STAGE(PG8_SB(0, 1), b2 + hstep, voffB); PG8_STAGE(PG8_SA(0, 0), a2, voffA);
;             PG8_WAIT_V(8); PG8_WAIT_L(0); PG8_BAR; PG8_MMA(1, 0, At, B0); PG8_MMA(1, 1, At, B1); PG8_BAR; PG8_SCHED;
;             PG8_LDB(B0, 1, 0); PG8_LDB(B1, 1, 1); PG8_SCHED; PG8_LDA(At, 1, 0); PG8_STAGE(PG8_SA(0, 1), a2 + hstep, voffA);
;             PG8_WAIT_V(8); PG8_WAIT_L(0); PG8_BAR; PG8_MMA(0, 0, At, B0); PG8_MMA(0, 1, At, B1); PG8_BAR; PG8_SCHED;
;             PG8_LDA(At, 1, 1); PG8_STAGE(PG8_SB(1, 0), b3, voffB); PG8_STAGE(PG8_SB(1, 1), b3 + hstep, voffB); PG8_STAGE(PG8_SA(1, 0), a3, voffA);
;             PG8_WAIT_V(8); PG8_WAIT_L(0); PG8_BAR; PG8_MMA(1, 0, At, B0); PG8_MMA(1, 1, At, B1); PG8_BAR; PG8_SCHED;
.Lg1_last:
	s_add_u32 s45, s48, 0xfff80080
	s_addc_u32 s46, s49, -1
	s_add_i32 s47, 0, 0x10000
	s_cmp_eq_u32 s44, 28
	s_cselect_b32 s57, s11, s46
	s_cselect_b32 s56, s17, s45
	s_cselect_b32 s53, s15, s42
	s_cselect_b32 s52, s18, s19
	s_add_i32 s45, 0, 0x14000
	v_add_u32_e32 v156, s47, v141
	v_add_u32_e32 v172, s45, v141
	ds_read_b128 v[144:147], v156
	ds_read_b128 v[148:151], v156 offset:1024
	ds_read_b128 v[152:155], v156 offset:2048
	ds_read_b128 v[156:159], v156 offset:3072
	ds_read_b128 v[160:163], v172
	ds_read_b128 v[164:167], v172 offset:1024
	ds_read_b128 v[168:171], v172 offset:2048
	ds_read_b128 v[172:175], v172 offset:3072
	v_lshl_add_u64 v[192:193], s[48:49], 0, v[136:137]
	s_add_i32 m0, s13, 0xc000
	ds_read_b128 v[176:179], v143
	ds_read_b128 v[180:183], v143 offset:1024
	ds_read_b128 v[184:187], v143 offset:2048
	ds_read_b128 v[188:191], v143 offset:3072
	ds_read_b128 v[198:201], v143 offset:4096
	ds_read_b128 v[202:205], v143 offset:5120
	ds_read_b128 v[206:209], v143 offset:6144
	ds_read_b128 v[210:213], v143 offset:7168
	global_load_lds_dwordx4 v[192:193], off
	s_add_i32 m0, s13, 0xe000
	v_lshl_add_u64 v[192:193], s[48:49], 0, v[138:139]
	global_load_lds_dwordx4 v[192:193], off
	s_waitcnt vmcnt(8)
	s_waitcnt lgkmcnt(0)
	s_barrier
	s_setprio 1
	v_mfma_f32_16x16x32_bf16 v[126:129], v[144:147], v[176:179], v[126:129]
	v_mfma_f32_16x16x32_bf16 v[122:125], v[152:155], v[176:179], v[122:125]
	v_mfma_f32_16x16x32_bf16 v[118:121], v[144:147], v[184:187], v[118:121]
	v_mfma_f32_16x16x32_bf16 v[114:117], v[152:155], v[184:187], v[114:117]
	v_mfma_f32_16x16x32_bf16 v[102:105], v[144:147], v[198:201], v[102:105]
	v_mfma_f32_16x16x32_bf16 v[98:101], v[152:155], v[198:201], v[98:101]
	v_mfma_f32_16x16x32_bf16 v[86:89], v[144:147], v[206:209], v[86:89]
	v_mfma_f32_16x16x32_bf16 v[82:85], v[152:155], v[206:209], v[82:85]
	v_mfma_f32_16x16x32_bf16 v[126:129], v[148:151], v[180:183], v[126:129]
	v_mfma_f32_16x16x32_bf16 v[122:125], v[156:159], v[180:183], v[122:125]
	v_mfma_f32_16x16x32_bf16 v[118:121], v[148:151], v[188:191], v[118:121]
	v_mfma_f32_16x16x32_bf16 v[114:117], v[156:159], v[188:191], v[114:117]
	v_mfma_f32_16x16x32_bf16 v[102:105], v[148:151], v[202:205], v[102:105]
	v_mfma_f32_16x16x32_bf16 v[98:101], v[156:159], v[202:205], v[98:101]
	v_mfma_f32_16x16x32_bf16 v[86:89], v[148:151], v[210:213], v[86:89]
	v_mfma_f32_16x16x32_bf16 v[82:85], v[156:159], v[210:213], v[82:85]
	s_setprio 0
	s_setprio 1
	v_mfma_f32_16x16x32_bf16 v[110:113], v[160:163], v[176:179], v[110:113]
	v_mfma_f32_16x16x32_bf16 v[106:109], v[168:171], v[176:179], v[106:109]
	v_mfma_f32_16x16x32_bf16 v[94:97], v[160:163], v[184:187], v[94:97]
	v_mfma_f32_16x16x32_bf16 v[90:93], v[168:171], v[184:187], v[90:93]
	v_mfma_f32_16x16x32_bf16 v[78:81], v[160:163], v[198:201], v[78:81]
	v_mfma_f32_16x16x32_bf16 v[74:77], v[168:171], v[198:201], v[74:77]
	v_mfma_f32_16x16x32_bf16 v[70:73], v[160:163], v[206:209], v[70:73]
	v_mfma_f32_16x16x32_bf16 v[66:69], v[168:171], v[206:209], v[66:69]
	v_mfma_f32_16x16x32_bf16 v[110:113], v[164:167], v[180:183], v[110:113]
	v_mfma_f32_16x16x32_bf16 v[106:109], v[172:175], v[180:183], v[106:109]
	v_mfma_f32_16x16x32_bf16 v[94:97], v[164:167], v[188:191], v[94:97]
	v_mfma_f32_16x16x32_bf16 v[90:93], v[172:175], v[188:191], v[90:93]
	v_mfma_f32_16x16x32_bf16 v[78:81], v[164:167], v[202:205], v[78:81]
	v_mfma_f32_16x16x32_bf16 v[74:77], v[172:175], v[202:205], v[74:77]
	v_mfma_f32_16x16x32_bf16 v[70:73], v[164:167], v[210:213], v[70:73]
	v_mfma_f32_16x16x32_bf16 v[66:69], v[172:175], v[210:213], v[66:69]
	s_setprio 0
	s_barrier
	s_add_i32 s46, s47, s37
	v_lshl_add_u64 v[192:193], s[52:53], 0, v[32:33]
	s_mov_b32 m0, s46
	ds_read_b128 v[176:179], v143 offset:16384
	ds_read_b128 v[180:183], v143 offset:17408
	ds_read_b128 v[184:187], v143 offset:18432
	ds_read_b128 v[188:191], v143 offset:19456
	ds_read_b128 v[198:201], v143 offset:20480
	ds_read_b128 v[202:205], v143 offset:21504
	ds_read_b128 v[206:209], v143 offset:22528
	ds_read_b128 v[210:213], v143 offset:23552
	global_load_lds_dwordx4 v[192:193], off
	s_add_i32 m0, s46, 0x2000
	s_add_u32 s46, s52, 0x80000
	v_lshl_add_u64 v[214:215], s[52:53], 0, v[134:135]
	s_addc_u32 s47, s53, 0
	s_add_i32 s45, s45, s37
	global_load_lds_dwordx4 v[214:215], off
	v_lshl_add_u64 v[216:217], s[46:47], 0, v[32:33]
	s_mov_b32 m0, s45
	v_lshl_add_u64 v[218:219], s[56:57], 0, v[132:133]
	global_load_lds_dwordx4 v[216:217], off
	s_add_i32 m0, s45, 0x2000
	v_lshl_add_u64 v[216:217], s[46:47], 0, v[134:135]
	global_load_lds_dwordx4 v[216:217], off
	s_mov_b32 m0, s13
	v_lshl_add_u64 v[216:217], s[56:57], 0, v[130:131]
	global_load_lds_dwordx4 v[216:217], off
	s_mov_b32 m0, s24
	s_nop 0
	global_load_lds_dwordx4 v[218:219], off
	s_waitcnt vmcnt(8)
	s_waitcnt lgkmcnt(0)
	s_barrier
; #define PG8_STAGE(bufoff, gbase, voff) do { _Pragma("unroll") for (int _i = 0; _i < 2; ++_i) \
;         __builtin_amdgcn_global_load_lds((const unsigned*)((const char*)(gbase) + (voff)[_i]), (PG8_LAS unsigned*)(lds + (bufoff) + ldsw + _i * 8192), 16, 0, 0); } while (0)
; #define PG8_LDA(dst, b, h) do { _Pragma("unroll") for (int m = 0; m < 4; ++m) _Pragma("unroll") for (int k = 0; k < 2; ++k) dst[m][k] = *(const PG8_LAS bf16x8*)(lds + PG8_SA(b, h) + aoff + m * 2048 + k * 1024); } while (0)
; #define PG8_LDB(dst, b, h) do { _Pragma("unroll") for (int n = 0; n < 2; ++n) _Pragma("unroll") for (int k = 0; k < 2; ++k) dst[n][k] = *(const PG8_LAS bf16x8*)(lds + PG8_SB(b, h) + boff + n * 2048 + k * 1024); } while (0)
; #define PG8_MMA(ai, bj, At, Bt) do { __builtin_amdgcn_s_setprio(1); _Pragma("unroll") for (int m = 0; m < 4; ++m) _Pragma("unroll") for (int n = 0; n < 2; ++n) _Pragma("unroll") for (int k = 0; k < 2; ++k) \
;         acc[ai][bj][m][n] = __builtin_amdgcn_mfma_f32_16x16x32_bf16(Bt[n][k], At[m][k], acc[ai][bj][m][n], 0, 0, 0); __builtin_amdgcn_s_setprio(0); } while (0)
; template <class Epi, class Sched, bool ALIGN_EPI = false, bool SP2 = false, bool KHOOK = false>
; __device__ __forceinline__ void gemm_phase(PG8_LAS unsigned char* lds, const Gemm g, const Sched& S, const Epi& E, const int tid_in) {
;     ...
;             PG8_LDB(B0, 0, 0); PG8_LDB(B1, 0, 1); PG8_SCHED; PG8_LDA(At, 0, 0); PG8_STAGE(PG8_SA(1, 1), a1 + hstep, voffA);
;             PG8_WAIT_V(8); PG8_WAIT_L(0); PG8_BAR; PG8_MMA(0, 0, At, B0); PG8_MMA(0, 1, At, B1); PG8_BAR; PG8_SCHED;
;             PG8_LDA(At, 0, 1); PG8_STAGE(PG8_SB(0, 0), b2, voffB); PG8_STAGE(PG8_SB(0, 1), b2 + hstep, voffB); PG8_STAGE(PG8_SA(0, 0), a2, voffA);
;             PG8_WAIT_V(8); PG8_WAIT_L(0); PG8_BAR; PG8_MMA(1, 0, At, B0); PG8_MMA(1, 1, At, B1); PG8_BAR; PG8_SCHED;
;             PG8_LDB(B0, 1, 0); PG8_LDB(B1, 1, 1); PG8_SCHED; PG8_LDA(At, 1, 0); PG8_STAGE(PG8_SA(0, 1), a2 + hstep, voffA);
;             PG8_WAIT_V(8); PG8_WAIT_L(0); PG8_BAR; PG8_MMA(0, 0, At, B0); PG8_MMA(0, 1, At, B1); PG8_BAR; PG8_SCHED;
;             PG8_LDA(At, 1, 1); PG8_STAGE(PG8_SB(1, 0), b3, voffB); PG8_STAGE(PG8_SB(1, 1), b3 + hstep, voffB); PG8_STAGE(PG8_SA(1, 0), a3, voffA);
;             PG8_WAIT_V(8); PG8_WAIT_L(0); PG8_BAR; PG8_MMA(1, 0, At, B0); PG8_MMA(1, 1, At, B1); PG8_BAR; PG8_SCHED;
	s_setprio 1
	v_mfma_f32_16x16x32_bf16 v[62:65], v[144:147], v[176:179], v[62:65]
	v_mfma_f32_16x16x32_bf16 v[58:61], v[152:155], v[176:179], v[58:61]
	v_mfma_f32_16x16x32_bf16 v[54:57], v[144:147], v[184:187], v[54:57]
	v_mfma_f32_16x16x32_bf16 v[50:53], v[152:155], v[184:187], v[50:53]
	v_mfma_f32_16x16x32_bf16 v[38:41], v[144:147], v[198:201], v[38:41]
	v_mfma_f32_16x16x32_bf16 v[34:37], v[152:155], v[198:201], v[34:37]
	v_mfma_f32_16x16x32_bf16 v[20:23], v[144:147], v[206:209], v[20:23]
	v_mfma_f32_16x16x32_bf16 v[16:19], v[152:155], v[206:209], v[16:19]
	v_mfma_f32_16x16x32_bf16 v[62:65], v[148:151], v[180:183], v[62:65]
	v_mfma_f32_16x16x32_bf16 v[58:61], v[156:159], v[180:183], v[58:61]
	v_mfma_f32_16x16x32_bf16 v[54:57], v[148:151], v[188:191], v[54:57]
	v_mfma_f32_16x16x32_bf16 v[50:53], v[156:159], v[188:191], v[50:53]
	v_mfma_f32_16x16x32_bf16 v[38:41], v[148:151], v[202:205], v[38:41]
	v_mfma_f32_16x16x32_bf16 v[34:37], v[156:159], v[202:205], v[34:37]
	v_mfma_f32_16x16x32_bf16 v[20:23], v[148:151], v[210:213], v[20:23]
	v_mfma_f32_16x16x32_bf16 v[16:19], v[156:159], v[210:213], v[16:19]
	s_setprio 0
	s_setprio 1
	v_mfma_f32_16x16x32_bf16 v[46:49], v[160:163], v[176:179], v[46:49]
	v_mfma_f32_16x16x32_bf16 v[42:45], v[168:171], v[176:179], v[42:45]
	v_mfma_f32_16x16x32_bf16 v[28:31], v[160:163], v[184:187], v[28:31]
	v_mfma_f32_16x16x32_bf16 v[24:27], v[168:171], v[184:187], v[24:27]
	v_mfma_f32_16x16x32_bf16 v[12:15], v[160:163], v[198:201], v[12:15]
	v_mfma_f32_16x16x32_bf16 v[8:11], v[168:171], v[198:201], v[8:11]
	v_mfma_f32_16x16x32_bf16 v[4:7], v[160:163], v[206:209], v[4:7]
	v_mfma_f32_16x16x32_bf16 v[0:3], v[168:171], v[206:209], v[0:3]
	v_mfma_f32_16x16x32_bf16 v[46:49], v[164:167], v[180:183], v[46:49]
	v_mfma_f32_16x16x32_bf16 v[42:45], v[172:175], v[180:183], v[42:45]
	v_mfma_f32_16x16x32_bf16 v[28:31], v[164:167], v[188:191], v[28:31]
	v_mfma_f32_16x16x32_bf16 v[24:27], v[172:175], v[188:191], v[24:27]
	v_mfma_f32_16x16x32_bf16 v[12:15], v[164:167], v[202:205], v[12:15]
	v_mfma_f32_16x16x32_bf16 v[8:11], v[172:175], v[202:205], v[8:11]
	v_mfma_f32_16x16x32_bf16 v[4:7], v[164:167], v[210:213], v[4:7]
	v_mfma_f32_16x16x32_bf16 v[0:3], v[172:175], v[210:213], v[0:3]
	s_setprio 0
	s_barrier
	s_add_i32 s45, 0, 0x18000
	s_add_i32 s50, 0, 0x1c000
	v_add_u32_e32 v156, s45, v141
	v_add_u32_e32 v172, s50, v141
	ds_read_b128 v[144:147], v156
	ds_read_b128 v[148:151], v156 offset:1024
	ds_read_b128 v[152:155], v156 offset:2048
	ds_read_b128 v[156:159], v156 offset:3072
	ds_read_b128 v[160:163], v172
	ds_read_b128 v[164:167], v172 offset:1024
	ds_read_b128 v[168:171], v172 offset:2048
	ds_read_b128 v[172:175], v172 offset:3072
	s_add_u32 s46, s56, 0x80000
	s_addc_u32 s47, s57, 0
	s_mov_b32 m0, s25
	v_lshl_add_u64 v[220:221], s[46:47], 0, v[130:131]
	ds_read_b128 v[176:179], v143 offset:32768
	ds_read_b128 v[180:183], v143 offset:33792
	ds_read_b128 v[184:187], v143 offset:34816
	ds_read_b128 v[188:191], v143 offset:35840
	ds_read_b128 v[198:201], v143 offset:36864
	ds_read_b128 v[202:205], v143 offset:37888
	ds_read_b128 v[206:209], v143 offset:38912
	ds_read_b128 v[210:213], v143 offset:39936
	global_load_lds_dwordx4 v[220:221], off
	s_mov_b32 m0, s38
	v_lshl_add_u64 v[220:221], s[46:47], 0, v[132:133]
	global_load_lds_dwordx4 v[220:221], off
	s_waitcnt vmcnt(8)
	s_waitcnt lgkmcnt(0)
	s_barrier
	s_setprio 1
	v_mfma_f32_16x16x32_bf16 v[126:129], v[144:147], v[176:179], v[126:129]
	v_mfma_f32_16x16x32_bf16 v[122:125], v[152:155], v[176:179], v[122:125]
	v_mfma_f32_16x16x32_bf16 v[118:121], v[144:147], v[184:187], v[118:121]
	v_mfma_f32_16x16x32_bf16 v[114:117], v[152:155], v[184:187], v[114:117]
	v_mfma_f32_16x16x32_bf16 v[102:105], v[144:147], v[198:201], v[102:105]
	v_mfma_f32_16x16x32_bf16 v[98:101], v[152:155], v[198:201], v[98:101]
	v_mfma_f32_16x16x32_bf16 v[86:89], v[144:147], v[206:209], v[86:89]
	v_mfma_f32_16x16x32_bf16 v[82:85], v[152:155], v[206:209], v[82:85]
	v_mfma_f32_16x16x32_bf16 v[126:129], v[148:151], v[180:183], v[126:129]
	v_mfma_f32_16x16x32_bf16 v[122:125], v[156:159], v[180:183], v[122:125]
	v_mfma_f32_16x16x32_bf16 v[118:121], v[148:151], v[188:191], v[118:121]
	v_mfma_f32_16x16x32_bf16 v[114:117], v[156:159], v[188:191], v[114:117]
	v_mfma_f32_16x16x32_bf16 v[102:105], v[148:151], v[202:205], v[102:105]
	v_mfma_f32_16x16x32_bf16 v[98:101], v[156:159], v[202:205], v[98:101]
	v_mfma_f32_16x16x32_bf16 v[86:89], v[148:151], v[210:213], v[86:89]
	v_mfma_f32_16x16x32_bf16 v[82:85], v[156:159], v[210:213], v[82:85]
	s_setprio 0
	s_setprio 1
	v_mfma_f32_16x16x32_bf16 v[110:113], v[160:163], v[176:179], v[110:113]
	v_mfma_f32_16x16x32_bf16 v[106:109], v[168:171], v[176:179], v[106:109]
	v_mfma_f32_16x16x32_bf16 v[94:97], v[160:163], v[184:187], v[94:97]
	v_mfma_f32_16x16x32_bf16 v[90:93], v[168:171], v[184:187], v[90:93]
	v_mfma_f32_16x16x32_bf16 v[78:81], v[160:163], v[198:201], v[78:81]
	v_mfma_f32_16x16x32_bf16 v[74:77], v[168:171], v[198:201], v[74:77]
	v_mfma_f32_16x16x32_bf16 v[70:73], v[160:163], v[206:209], v[70:73]
	v_mfma_f32_16x16x32_bf16 v[66:69], v[168:171], v[206:209], v[66:69]
	v_mfma_f32_16x16x32_bf16 v[110:113], v[164:167], v[180:183], v[110:113]
	v_mfma_f32_16x16x32_bf16 v[106:109], v[172:175], v[180:183], v[106:109]
	v_mfma_f32_16x16x32_bf16 v[94:97], v[164:167], v[188:191], v[94:97]
	v_mfma_f32_16x16x32_bf16 v[90:93], v[172:175], v[188:191], v[90:93]
	v_mfma_f32_16x16x32_bf16 v[78:81], v[164:167], v[202:205], v[78:81]
	v_mfma_f32_16x16x32_bf16 v[74:77], v[172:175], v[202:205], v[74:77]
	v_mfma_f32_16x16x32_bf16 v[70:73], v[164:167], v[210:213], v[70:73]
	v_mfma_f32_16x16x32_bf16 v[66:69], v[172:175], v[210:213], v[66:69]
	s_setprio 0
	s_barrier
; __device__ __forceinline__ unsigned cvt_pk_bf16(float lo, float hi) { const f32x2_t v = {lo, hi}; const bf16x2_t c = __builtin_convertvector(v, bf16x2_t); return __builtin_bit_cast(unsigned, c); }
; #define PG8_WAIT_V(n) asm volatile("s_waitcnt vmcnt(" #n ")" ::: "memory")
; #define PG8_WAIT_L(n) asm volatile("s_waitcnt lgkmcnt(" #n ")" ::: "memory")
;     __device__ __forceinline__ void operator()(const f32x4 (&acc)[2][2][4][2], const Unit& u, int wr, int wc, int fr, int fq) const {
;         const int row0 = u.pm * BM + wr * 64 + fr, col0 = u.pn * BM + wc * 32 + 8 * fq;
; #pragma unroll
;         for (int ai = 0; ai < 2; ++ai)
; #pragma unroll
;             for (int m = 0; m < 4; ++m) { bf16_t* rowp = O + (size_t)(row0 + ai * HALF + m * 16) * ldc + col0;
; #pragma unroll
;                 for (int bj = 0; bj < 2; ++bj) { const f32x4 v0 = acc[ai][bj][m][0], v1 = acc[ai][bj][m][1];
;                     u32x4 w; w.x = cvt_pk_bf16(v0[0], v0[1]); w.y = cvt_pk_bf16(v0[2], v0[3]); w.z = cvt_pk_bf16(v1[0], v1[1]); w.w = cvt_pk_bf16(v1[2], v1[3]);
;                     *(u32x4*)(rowp + bj * HALF) = w; } }
; template <class Epi, class Sched, bool ALIGN_EPI = false, bool SP2 = false, bool KHOOK = false>
; __device__ __forceinline__ void gemm_phase(PG8_LAS unsigned char* lds, const Gemm g, const Sched& S, const Epi& E, const int tid_in) {
;     ...
;             PG8_LDB(B0, 0, 0); PG8_LDB(B1, 0, 1); PG8_SCHED; PG8_LDA(At, 0, 0); PG8_STAGE(PG8_SA(1, 1), a1 + hstep, voffA);
;             PG8_WAIT_V(8); PG8_WAIT_L(0); PG8_BAR; PG8_MMA(0, 0, At, B0); PG8_MMA(0, 1, At, B1); PG8_BAR; PG8_SCHED;
;             PG8_LDA(At, 0, 1); PG8_STAGE(PG8_SB(0, 0), b2, voffB); PG8_STAGE(PG8_SB(0, 1), b2 + hstep, voffB); PG8_STAGE(PG8_SA(0, 0), a2, voffA);
;             PG8_WAIT_V(8); PG8_WAIT_L(0); PG8_BAR; PG8_MMA(1, 0, At, B0); PG8_MMA(1, 1, At, B1); PG8_BAR; PG8_SCHED;
;             PG8_LDB(B0, 1, 0); PG8_LDB(B1, 1, 1); PG8_SCHED; PG8_LDA(At, 1, 0); PG8_STAGE(PG8_SA(0, 1), a2 + hstep, voffA);
;             PG8_WAIT_V(8); PG8_WAIT_L(0); PG8_BAR; PG8_MMA(0, 0, At, B0); PG8_MMA(0, 1, At, B1); PG8_BAR; PG8_SCHED;
;             PG8_LDA(At, 1, 1); PG8_STAGE(PG8_SB(1, 0), b3, voffB); PG8_STAGE(PG8_SB(1, 1), b3 + hstep, voffB); PG8_STAGE(PG8_SA(1, 0), a3, voffA);
;             PG8_WAIT_V(8); PG8_WAIT_L(0); PG8_BAR; PG8_MMA(1, 0, At, B0); PG8_MMA(1, 1, At, B1); PG8_BAR; PG8_SCHED;
	s_add_i32 s45, s45, s37
	v_lshl_add_u64 v[192:193], v[192:193], 0, s[90:91]
	s_mov_b32 m0, s45
	ds_read_b128 v[176:179], v143 offset:49152
	ds_read_b128 v[180:183], v143 offset:50176
	ds_read_b128 v[184:187], v143 offset:51200
	ds_read_b128 v[188:191], v143 offset:52224
	ds_read_b128 v[198:201], v143 offset:53248
	ds_read_b128 v[202:205], v143 offset:54272
	ds_read_b128 v[206:209], v143 offset:55296
	ds_read_b128 v[210:213], v143 offset:56320
	global_load_lds_dwordx4 v[192:193], off
	s_add_i32 m0, s45, 0x2000
	s_add_u32 s46, s52, 0x80080
	v_lshl_add_u64 v[192:193], v[214:215], 0, s[90:91]
	s_addc_u32 s47, s53, 0
	s_add_i32 s45, s50, s37
	global_load_lds_dwordx4 v[192:193], off
	s_mov_b32 m0, s45
	v_lshl_add_u64 v[192:193], s[46:47], 0, v[32:33]
	global_load_lds_dwordx4 v[192:193], off
	s_add_i32 m0, s45, 0x2000
	v_lshl_add_u64 v[192:193], s[46:47], 0, v[134:135]
	global_load_lds_dwordx4 v[192:193], off
	s_mov_b32 m0, s39
	v_lshl_add_u64 v[192:193], v[216:217], 0, s[90:91]
	global_load_lds_dwordx4 v[192:193], off
	s_mov_b32 m0, s40
	v_lshl_add_u64 v[192:193], v[218:219], 0, s[90:91]
	global_load_lds_dwordx4 v[192:193], off
	v_lshl_add_u32 v246, s12, 8, v140
	v_lshl_or_b32 v222, s10, 8, v142
	v_lshlrev_b32_e32 v222, 1, v222
	v_mov_b32_e32 v223, 0
	v_mad_u64_u32 v[248:249], s[70:71], v246, s67, v[222:223]
	s_mov_b32 s72, 0xa2000
	s_mov_b32 s73, 0
	v_lshl_add_u64 v[248:249], v[248:249], 0, s[76:77]
	v_cvt_pk_bf16_f32 v126, v126, v127
	v_cvt_pk_bf16_f32 v127, v128, v129
	v_cvt_pk_bf16_f32 v128, v122, v123
	v_cvt_pk_bf16_f32 v129, v124, v125
	global_store_dwordx4 v[248:249], v[126:129], off
	v_cvt_pk_bf16_f32 v110, v110, v111
	v_cvt_pk_bf16_f32 v111, v112, v113
	v_cvt_pk_bf16_f32 v112, v106, v107
	v_cvt_pk_bf16_f32 v113, v108, v109
	global_store_dwordx4 v[248:249], v[110:113], off offset:256
	v_lshl_add_u64 v[248:249], v[248:249], 0, s[72:73]
	v_cvt_pk_bf16_f32 v118, v118, v119
	v_cvt_pk_bf16_f32 v119, v120, v121
	v_cvt_pk_bf16_f32 v120, v114, v115
	v_cvt_pk_bf16_f32 v121, v116, v117
	global_store_dwordx4 v[248:249], v[118:121], off
	v_cvt_pk_bf16_f32 v94, v94, v95
	v_cvt_pk_bf16_f32 v95, v96, v97
	v_cvt_pk_bf16_f32 v96, v90, v91
	v_cvt_pk_bf16_f32 v97, v92, v93
	global_store_dwordx4 v[248:249], v[94:97], off offset:256
	v_lshl_add_u64 v[248:249], v[248:249], 0, s[72:73]
	v_cvt_pk_bf16_f32 v102, v102, v103
	v_cvt_pk_bf16_f32 v103, v104, v105
	v_cvt_pk_bf16_f32 v104, v98, v99
	v_cvt_pk_bf16_f32 v105, v100, v101
	global_store_dwordx4 v[248:249], v[102:105], off
	v_cvt_pk_bf16_f32 v78, v78, v79
	v_cvt_pk_bf16_f32 v79, v80, v81
	v_cvt_pk_bf16_f32 v80, v74, v75
	v_cvt_pk_bf16_f32 v81, v76, v77
	global_store_dwordx4 v[248:249], v[78:81], off offset:256
	v_lshl_add_u64 v[248:249], v[248:249], 0, s[72:73]
	v_cvt_pk_bf16_f32 v86, v86, v87
	v_cvt_pk_bf16_f32 v87, v88, v89
	v_cvt_pk_bf16_f32 v88, v82, v83
	v_cvt_pk_bf16_f32 v89, v84, v85
	global_store_dwordx4 v[248:249], v[86:89], off
	v_cvt_pk_bf16_f32 v70, v70, v71
	v_cvt_pk_bf16_f32 v71, v72, v73
	v_cvt_pk_bf16_f32 v72, v66, v67
	v_cvt_pk_bf16_f32 v73, v68, v69
	global_store_dwordx4 v[248:249], v[70:73], off offset:256
	s_waitcnt vmcnt(16)
	s_waitcnt lgkmcnt(0)
	s_barrier
	s_setprio 1
	v_mfma_f32_16x16x32_bf16 v[62:65], v[144:147], v[176:179], v[62:65]
	v_mfma_f32_16x16x32_bf16 v[58:61], v[152:155], v[176:179], v[58:61]
	v_mfma_f32_16x16x32_bf16 v[54:57], v[144:147], v[184:187], v[54:57]
	v_mfma_f32_16x16x32_bf16 v[50:53], v[152:155], v[184:187], v[50:53]
	v_mfma_f32_16x16x32_bf16 v[38:41], v[144:147], v[198:201], v[38:41]
	v_mfma_f32_16x16x32_bf16 v[34:37], v[152:155], v[198:201], v[34:37]
	v_mfma_f32_16x16x32_bf16 v[20:23], v[144:147], v[206:209], v[20:23]
	v_mfma_f32_16x16x32_bf16 v[16:19], v[152:155], v[206:209], v[16:19]
	v_mfma_f32_16x16x32_bf16 v[62:65], v[148:151], v[180:183], v[62:65]
	v_mfma_f32_16x16x32_bf16 v[58:61], v[156:159], v[180:183], v[58:61]
	v_mfma_f32_16x16x32_bf16 v[54:57], v[148:151], v[188:191], v[54:57]
	v_mfma_f32_16x16x32_bf16 v[50:53], v[156:159], v[188:191], v[50:53]
	v_mfma_f32_16x16x32_bf16 v[38:41], v[148:151], v[202:205], v[38:41]
	v_mfma_f32_16x16x32_bf16 v[34:37], v[156:159], v[202:205], v[34:37]
	v_mfma_f32_16x16x32_bf16 v[20:23], v[148:151], v[210:213], v[20:23]
	v_mfma_f32_16x16x32_bf16 v[16:19], v[156:159], v[210:213], v[16:19]
	s_setprio 0
	s_setprio 1
	v_mfma_f32_16x16x32_bf16 v[46:49], v[160:163], v[176:179], v[46:49]
	v_mfma_f32_16x16x32_bf16 v[42:45], v[168:171], v[176:179], v[42:45]
	v_mfma_f32_16x16x32_bf16 v[28:31], v[160:163], v[184:187], v[28:31]
	v_mfma_f32_16x16x32_bf16 v[24:27], v[168:171], v[184:187], v[24:27]
	v_mfma_f32_16x16x32_bf16 v[12:15], v[160:163], v[198:201], v[12:15]
	v_mfma_f32_16x16x32_bf16 v[8:11], v[168:171], v[198:201], v[8:11]
	v_mfma_f32_16x16x32_bf16 v[4:7], v[160:163], v[206:209], v[4:7]
	v_mfma_f32_16x16x32_bf16 v[0:3], v[168:171], v[206:209], v[0:3]
	v_mfma_f32_16x16x32_bf16 v[46:49], v[164:167], v[180:183], v[46:49]
	v_mfma_f32_16x16x32_bf16 v[42:45], v[172:175], v[180:183], v[42:45]
	v_mfma_f32_16x16x32_bf16 v[28:31], v[164:167], v[188:191], v[28:31]
	v_mfma_f32_16x16x32_bf16 v[24:27], v[172:175], v[188:191], v[24:27]
	v_mfma_f32_16x16x32_bf16 v[12:15], v[164:167], v[202:205], v[12:15]
	v_mfma_f32_16x16x32_bf16 v[8:11], v[172:175], v[202:205], v[8:11]
	v_mfma_f32_16x16x32_bf16 v[4:7], v[164:167], v[210:213], v[4:7]
	v_mfma_f32_16x16x32_bf16 v[0:3], v[172:175], v[210:213], v[0:3]
	s_setprio 0
	s_barrier
	s_add_i32 s44, s44, 2
	s_add_u32 s48, s48, 0x100
	s_addc_u32 s49, s49, 0
	s_add_u32 s19, s19, 0x100
	s_addc_u32 s42, s42, 0
	s_mov_b32 s68, s12
	s_mov_b32 s69, s10
	s_mov_b32 s60, 1
	s_branch .LBB0_257

; #define GPROBE_BEGIN(id) do { if (((PROBE_GEMM_SEL >> (id)) & 1) && blockIdx.x == 0 && tid_in < 64 && g.N == 20480) { volatile PG8_LAS unsigned long long* PW_ = (volatile PG8_LAS unsigned long long*)(lds + 163840 - 512 + 64); PW_[0] = __builtin_amdgcn_s_memrealtime(); } } while (0)
; #define PG8_WAIT_V(n) asm volatile("s_waitcnt vmcnt(" #n ")" ::: "memory")
; template <class Epi, class Sched, bool ALIGN_EPI = false, bool SP2 = false, bool KHOOK = false>
; __device__ __forceinline__ void gemm_phase(PG8_LAS unsigned char* lds, const Gemm g, const Sched& S, const Epi& E, const int tid_in) {
;     ...
;         const char* nA = has_next ? (const char*)g.A + (size_t)nxt.pm * tstep + (size_t)nxt.pn * ksl : cA; const char* nB = has_next ? (const char*)g.Bt + (size_t)nxt.pn * bts + (size_t)nxt.pn * ksl + (gdv ? (size_t)(nxt.pm / gdv) * gst : 0) : cB;
;         GPROBE_END(2); GPROBE_BEGIN(1);
;         for (int t = 0; t < nt; t += 2) {
;             const bool last = (t == nt - 2);
;             const char* a1 = cA + (size_t)(t + 1) * kstep;
;             const char* a2 = last ? nA : cA + (size_t)(t + 2) * kstep; const char* b2 = last ? nB : cB + (size_t)(t + 2) * kstep;
;             const char* a3 = a2 + kstep; const char* b3 = b2 + kstep;
;             if (last && has_next) S.a_ready(nxt);
;             if constexpr (SP2) {
;             PG8_LDB(B0, 0, 0); PG8_LDB(B1, 0, 1); PG8_SCHED; PG8_LDA(At, 0, 0); PG8_STAGE(PG8_SA(1, 1), a1 + hstep, voffA);
;             PG8_WAIT_V(8); PG8_WAIT_L(0); PG8_BAR; PG8_MMA(0, 0, At, B0); PG8_MMA(0, 1, At, B1); PG8_BAR; PG8_SCHED;
;             PG8_LDA(At, 0, 1); PG8_STAGE(PG8_SB(0, 0), b2, voffB); PG8_STAGE(PG8_SB(0, 1), b2 + hstep, voffB); PG8_STAGE(PG8_SA(0, 0), a2, voffA);
;             PG8_WAIT_V(8); PG8_WAIT_L(0); PG8_BAR; PG8_MMA(1, 0, At, B0); PG8_MMA(1, 1, At, B1); PG8_BAR; PG8_SCHED;
;             PG8_LDB(B0, 1, 0); PG8_LDB(B1, 1, 1); PG8_SCHED; PG8_LDA(At, 1, 0); PG8_STAGE(PG8_SA(0, 1), a2 + hstep, voffA);
;             PG8_WAIT_V(8); PG8_WAIT_L(0); PG8_BAR; PG8_MMA(0, 0, At, B0); PG8_MMA(0, 1, At, B1); PG8_BAR; PG8_SCHED;
;             PG8_LDA(At, 1, 1); PG8_STAGE(PG8_SB(1, 0), b3, voffB); PG8_STAGE(PG8_SB(1, 1), b3 + hstep, voffB); PG8_STAGE(PG8_SA(1, 0), a3, voffA);
;             PG8_WAIT_V(8); PG8_WAIT_L(0); PG8_BAR; PG8_MMA(1, 0, At, B0); PG8_MMA(1, 1, At, B1); PG8_BAR; PG8_SCHED;
.LBB0_416:
	s_ashr_i32 s13, s12, 31
	s_lshl_b64 s[22:23], s[12:13], 20
	s_add_u32 s13, s78, s22
	s_addc_u32 s23, s79, s23
	s_ashr_i32 s11, s10, 31
	s_lshl_b64 s[26:27], s[10:11], 9
	s_add_u32 s22, s13, s26
	s_addc_u32 s23, s23, s27
	s_and_b64 s[44:45], s[16:17], exec
	s_cselect_b32 s57, s23, s53
	s_cselect_b32 s56, s22, s52
	s_add_u32 s26, s2, s26
	s_addc_u32 s27, s18, s27
	s_and_b64 s[44:45], s[16:17], exec
	s_cselect_b32 s49, s27, s31
	s_cselect_b32 s48, s26, s30
	s_add_i32 s44, 0, 0x10000
	v_add_u32_e32 v132, s44, v71
	ds_read_b128 v[0:3], v132
	ds_read_b128 v[4:7], v132 offset:1024
	ds_read_b128 v[8:11], v132 offset:2048
	ds_read_b128 v[12:15], v132 offset:3072
	s_add_u32 s46, s52, 0x80080
	s_addc_u32 s47, s53, 0
	s_add_i32 s45, s20, 0xc000
	v_lshl_add_u64 v[50:51], s[46:47], 0, v[32:33]
	s_mov_b32 m0, s45
	s_add_i32 s11, s20, 0xe000
	ds_read_b128 v[16:19], v72
	ds_read_b128 v[20:23], v72 offset:1024
	ds_read_b128 v[24:27], v72 offset:2048
	ds_read_b128 v[28:31], v72 offset:3072
	ds_read_b128 v[34:37], v72 offset:4096
	ds_read_b128 v[38:41], v72 offset:5120
	ds_read_b128 v[42:45], v72 offset:6144
	ds_read_b128 v[46:49], v72 offset:7168
	global_load_lds_dwordx4 v[50:51], off
	s_mov_b32 m0, s11
	v_lshl_add_u64 v[50:51], s[46:47], 0, v[66:67]
	global_load_lds_dwordx4 v[50:51], off
	s_waitcnt vmcnt(8)
	s_waitcnt lgkmcnt(0)
	s_barrier
	s_setprio 1
	v_mfma_f32_16x16x32_bf16 v[50:53], v[0:3], v[16:19], 0
	v_mfma_f32_16x16x32_bf16 v[16:19], v[8:11], v[16:19], 0
	v_mfma_f32_16x16x32_bf16 v[50:53], v[4:7], v[20:23], v[50:53]
	v_mfma_f32_16x16x32_bf16 v[16:19], v[12:15], v[20:23], v[16:19]
	v_mfma_f32_16x16x32_bf16 v[20:23], v[0:3], v[24:27], 0
	v_mfma_f32_16x16x32_bf16 v[24:27], v[8:11], v[24:27], 0
	v_mfma_f32_16x16x32_bf16 v[20:23], v[4:7], v[28:31], v[20:23]
	v_mfma_f32_16x16x32_bf16 v[24:27], v[12:15], v[28:31], v[24:27]
	v_mfma_f32_16x16x32_bf16 v[28:31], v[0:3], v[34:37], 0
	v_mfma_f32_16x16x32_bf16 v[34:37], v[8:11], v[34:37], 0
	v_mfma_f32_16x16x32_bf16 v[28:31], v[4:7], v[38:41], v[28:31]
	v_mfma_f32_16x16x32_bf16 v[34:37], v[12:15], v[38:41], v[34:37]
	v_mfma_f32_16x16x32_bf16 v[38:41], v[0:3], v[42:45], 0
	v_mfma_f32_16x16x32_bf16 v[42:45], v[8:11], v[42:45], 0
	v_mfma_f32_16x16x32_bf16 v[38:41], v[4:7], v[46:49], v[38:41]
	v_mfma_f32_16x16x32_bf16 v[42:45], v[12:15], v[46:49], v[42:45]
	s_setprio 0
	s_setprio 1
	s_setprio 0
	s_barrier
	s_add_i32 s44, s44, s19
	v_lshl_add_u64 v[122:123], s[30:31], 0, v[32:33]
	s_mov_b64 s[50:51], 0x100
	s_add_i32 s13, s44, 0x2000
	v_lshl_add_u64 v[90:91], v[122:123], 0, s[50:51]
	s_mov_b32 m0, s44
	v_lshl_add_u64 v[124:125], s[30:31], 0, v[66:67]
	s_add_u32 s46, s30, 0x80100
	ds_read_b128 v[46:49], v72 offset:16384
	ds_read_b128 v[54:57], v72 offset:17408
	ds_read_b128 v[58:61], v72 offset:18432
	ds_read_b128 v[62:65], v72 offset:19456
	ds_read_b128 v[74:77], v72 offset:20480
	ds_read_b128 v[78:81], v72 offset:21504
	ds_read_b128 v[82:85], v72 offset:22528
	ds_read_b128 v[86:89], v72 offset:23552
	global_load_lds_dwordx4 v[90:91], off
	v_lshl_add_u64 v[90:91], v[124:125], 0, s[50:51]
	s_mov_b32 m0, s13
	s_addc_u32 s47, s31, 0
	global_load_lds_dwordx4 v[90:91], off
	v_lshl_add_u64 v[90:91], s[46:47], 0, v[32:33]
	s_mov_b32 m0, s24
	v_lshl_add_u64 v[126:127], s[52:53], 0, v[32:33]
	global_load_lds_dwordx4 v[90:91], off
	v_lshl_add_u64 v[90:91], s[46:47], 0, v[66:67]
	s_mov_b32 m0, s25
	v_lshl_add_u64 v[128:129], s[52:53], 0, v[66:67]
	global_load_lds_dwordx4 v[90:91], off
	s_mov_b32 m0, s20
	v_lshl_add_u64 v[90:91], v[126:127], 0, s[50:51]
	global_load_lds_dwordx4 v[90:91], off
	s_mov_b32 m0, s33
	v_lshl_add_u64 v[90:91], v[128:129], 0, s[50:51]
	global_load_lds_dwordx4 v[90:91], off
	s_waitcnt vmcnt(8)
	s_waitcnt lgkmcnt(0)
	s_barrier
	s_setprio 1
	v_mfma_f32_16x16x32_bf16 v[90:93], v[0:3], v[46:49], 0
	v_mfma_f32_16x16x32_bf16 v[46:49], v[8:11], v[46:49], 0
	v_mfma_f32_16x16x32_bf16 v[90:93], v[4:7], v[54:57], v[90:93]
	v_mfma_f32_16x16x32_bf16 v[46:49], v[12:15], v[54:57], v[46:49]
	v_mfma_f32_16x16x32_bf16 v[54:57], v[0:3], v[58:61], 0
	v_mfma_f32_16x16x32_bf16 v[58:61], v[8:11], v[58:61], 0
	v_mfma_f32_16x16x32_bf16 v[54:57], v[4:7], v[62:65], v[54:57]
	v_mfma_f32_16x16x32_bf16 v[58:61], v[12:15], v[62:65], v[58:61]
	v_mfma_f32_16x16x32_bf16 v[62:65], v[0:3], v[74:77], 0
	v_mfma_f32_16x16x32_bf16 v[0:3], v[0:3], v[82:85], 0
	v_mfma_f32_16x16x32_bf16 v[62:65], v[4:7], v[78:81], v[62:65]
	v_mfma_f32_16x16x32_bf16 v[0:3], v[4:7], v[86:89], v[0:3]
	v_mfma_f32_16x16x32_bf16 v[4:7], v[8:11], v[82:85], 0
	v_mfma_f32_16x16x32_bf16 v[74:77], v[8:11], v[74:77], 0
	v_mfma_f32_16x16x32_bf16 v[4:7], v[12:15], v[86:89], v[4:7]
	v_mfma_f32_16x16x32_bf16 v[74:77], v[12:15], v[78:81], v[74:77]
	s_setprio 0
	s_setprio 1
	s_setprio 0
	s_barrier
	s_add_i32 s42, 0, 0x18000
	v_add_u32_e32 v133, s42, v71
	ds_read_b128 v[8:11], v133
	ds_read_b128 v[12:15], v133 offset:1024
	ds_read_b128 v[78:81], v133 offset:2048
	ds_read_b128 v[82:85], v133 offset:3072
	s_add_u32 s46, s52, 0x80100
	s_addc_u32 s47, s53, 0
	s_mov_b32 m0, s36
	v_lshl_add_u64 v[130:131], s[46:47], 0, v[32:33]
	ds_read_b128 v[86:89], v72 offset:32768
	ds_read_b128 v[94:97], v72 offset:33792
	ds_read_b128 v[98:101], v72 offset:34816
	ds_read_b128 v[102:105], v72 offset:35840
	ds_read_b128 v[106:109], v72 offset:36864
	ds_read_b128 v[110:113], v72 offset:37888
	ds_read_b128 v[114:117], v72 offset:38912
	ds_read_b128 v[118:121], v72 offset:39936
	global_load_lds_dwordx4 v[130:131], off
	s_mov_b32 m0, s37
	v_lshl_add_u64 v[130:131], s[46:47], 0, v[66:67]
	global_load_lds_dwordx4 v[130:131], off
	s_waitcnt vmcnt(8)
	s_waitcnt lgkmcnt(0)
	s_barrier
; #define PG8_STAGE(bufoff, gbase, voff) do { _Pragma("unroll") for (int _i = 0; _i < 2; ++_i) \
;         __builtin_amdgcn_global_load_lds((const unsigned*)((const char*)(gbase) + (voff)[_i]), (PG8_LAS unsigned*)(lds + (bufoff) + ldsw + _i * 8192), 16, 0, 0); } while (0)
; #define PG8_LDA(dst, b, h) do { _Pragma("unroll") for (int m = 0; m < 4; ++m) _Pragma("unroll") for (int k = 0; k < 2; ++k) dst[m][k] = *(const PG8_LAS bf16x8*)(lds + PG8_SA(b, h) + aoff + m * 2048 + k * 1024); } while (0)
; #define PG8_LDB(dst, b, h) do { _Pragma("unroll") for (int n = 0; n < 2; ++n) _Pragma("unroll") for (int k = 0; k < 2; ++k) dst[n][k] = *(const PG8_LAS bf16x8*)(lds + PG8_SB(b, h) + boff + n * 2048 + k * 1024); } while (0)
; #define PG8_MMA(ai, bj, At, Bt) do { __builtin_amdgcn_s_setprio(1); _Pragma("unroll") for (int m = 0; m < 4; ++m) _Pragma("unroll") for (int n = 0; n < 2; ++n) _Pragma("unroll") for (int k = 0; k < 2; ++k) \
;         acc[ai][bj][m][n] = __builtin_amdgcn_mfma_f32_16x16x32_bf16(Bt[n][k], At[m][k], acc[ai][bj][m][n], 0, 0, 0); __builtin_amdgcn_s_setprio(0); } while (0)
; template <class Epi, class Sched, bool ALIGN_EPI = false, bool SP2 = false, bool KHOOK = false>
; __device__ __forceinline__ void gemm_phase(PG8_LAS unsigned char* lds, const Gemm g, const Sched& S, const Epi& E, const int tid_in) {
;     ...
;             PG8_LDB(B0, 0, 0); PG8_LDB(B1, 0, 1); PG8_SCHED; PG8_LDA(At, 0, 0); PG8_STAGE(PG8_SA(1, 1), a1 + hstep, voffA);
;             PG8_WAIT_V(8); PG8_WAIT_L(0); PG8_BAR; PG8_MMA(0, 0, At, B0); PG8_MMA(0, 1, At, B1); PG8_BAR; PG8_SCHED;
;             PG8_LDA(At, 0, 1); PG8_STAGE(PG8_SB(0, 0), b2, voffB); PG8_STAGE(PG8_SB(0, 1), b2 + hstep, voffB); PG8_STAGE(PG8_SA(0, 0), a2, voffA);
;             PG8_WAIT_V(8); PG8_WAIT_L(0); PG8_BAR; PG8_MMA(1, 0, At, B0); PG8_MMA(1, 1, At, B1); PG8_BAR; PG8_SCHED;
;             PG8_LDB(B0, 1, 0); PG8_LDB(B1, 1, 1); PG8_SCHED; PG8_LDA(At, 1, 0); PG8_STAGE(PG8_SA(0, 1), a2 + hstep, voffA);
;             PG8_WAIT_V(8); PG8_WAIT_L(0); PG8_BAR; PG8_MMA(0, 0, At, B0); PG8_MMA(0, 1, At, B1); PG8_BAR; PG8_SCHED;
;             PG8_LDA(At, 1, 1); PG8_STAGE(PG8_SB(1, 0), b3, voffB); PG8_STAGE(PG8_SB(1, 1), b3 + hstep, voffB); PG8_STAGE(PG8_SA(1, 0), a3, voffA);
;             PG8_WAIT_V(8); PG8_WAIT_L(0); PG8_BAR; PG8_MMA(1, 0, At, B0); PG8_MMA(1, 1, At, B1); PG8_BAR; PG8_SCHED;
	s_setprio 1
	v_mfma_f32_16x16x32_bf16 v[50:53], v[8:11], v[86:89], v[50:53]
	v_mfma_f32_16x16x32_bf16 v[16:19], v[78:81], v[86:89], v[16:19]
	v_mfma_f32_16x16x32_bf16 v[20:23], v[8:11], v[98:101], v[20:23]
	v_mfma_f32_16x16x32_bf16 v[24:27], v[78:81], v[98:101], v[24:27]
	v_mfma_f32_16x16x32_bf16 v[28:31], v[8:11], v[106:109], v[28:31]
	v_mfma_f32_16x16x32_bf16 v[34:37], v[78:81], v[106:109], v[34:37]
	v_mfma_f32_16x16x32_bf16 v[38:41], v[8:11], v[114:117], v[38:41]
	v_mfma_f32_16x16x32_bf16 v[42:45], v[78:81], v[114:117], v[42:45]
	v_mfma_f32_16x16x32_bf16 v[50:53], v[12:15], v[94:97], v[50:53]
	v_mfma_f32_16x16x32_bf16 v[16:19], v[82:85], v[94:97], v[16:19]
	v_mfma_f32_16x16x32_bf16 v[20:23], v[12:15], v[102:105], v[20:23]
	v_mfma_f32_16x16x32_bf16 v[24:27], v[82:85], v[102:105], v[24:27]
	v_mfma_f32_16x16x32_bf16 v[28:31], v[12:15], v[110:113], v[28:31]
	v_mfma_f32_16x16x32_bf16 v[34:37], v[82:85], v[110:113], v[34:37]
	v_mfma_f32_16x16x32_bf16 v[38:41], v[12:15], v[118:121], v[38:41]
	v_mfma_f32_16x16x32_bf16 v[42:45], v[82:85], v[118:121], v[42:45]
	s_setprio 0
	s_setprio 1
	s_setprio 0
	s_barrier
	s_add_i32 s46, s42, s19
	s_mov_b64 s[50:51], 0x180
	s_add_i32 s42, s46, 0x2000
	v_lshl_add_u64 v[122:123], v[122:123], 0, s[50:51]
	s_mov_b32 m0, s46
	s_add_u32 s30, s30, 0x80180
	ds_read_b128 v[86:89], v72 offset:49152
	ds_read_b128 v[94:97], v72 offset:50176
	ds_read_b128 v[98:101], v72 offset:51200
	ds_read_b128 v[102:105], v72 offset:52224
	ds_read_b128 v[106:109], v72 offset:53248
	ds_read_b128 v[110:113], v72 offset:54272
	ds_read_b128 v[114:117], v72 offset:55296
	ds_read_b128 v[118:121], v72 offset:56320
	global_load_lds_dwordx4 v[122:123], off
	v_lshl_add_u64 v[122:123], v[124:125], 0, s[50:51]
	s_mov_b32 m0, s42
	s_addc_u32 s31, s31, 0
	global_load_lds_dwordx4 v[122:123], off
	s_mov_b32 m0, s40
	v_lshl_add_u64 v[122:123], s[30:31], 0, v[32:33]
	global_load_lds_dwordx4 v[122:123], off
	s_mov_b32 m0, s41
	v_lshl_add_u64 v[122:123], s[30:31], 0, v[66:67]
	global_load_lds_dwordx4 v[122:123], off
	s_mov_b32 m0, s38
	v_lshl_add_u64 v[122:123], v[126:127], 0, s[50:51]
	global_load_lds_dwordx4 v[122:123], off
	s_mov_b32 m0, s39
	v_lshl_add_u64 v[122:123], v[128:129], 0, s[50:51]
	global_load_lds_dwordx4 v[122:123], off
	s_waitcnt vmcnt(8)
	s_waitcnt lgkmcnt(0)
	s_barrier
	s_setprio 1
	v_mfma_f32_16x16x32_bf16 v[46:49], v[78:81], v[86:89], v[46:49]
	v_mfma_f32_16x16x32_bf16 v[54:57], v[8:11], v[98:101], v[54:57]
	v_mfma_f32_16x16x32_bf16 v[58:61], v[78:81], v[98:101], v[58:61]
	v_mfma_f32_16x16x32_bf16 v[62:65], v[8:11], v[106:109], v[62:65]
	v_mfma_f32_16x16x32_bf16 v[0:3], v[8:11], v[114:117], v[0:3]
	v_mfma_f32_16x16x32_bf16 v[4:7], v[78:81], v[114:117], v[4:7]
	v_mfma_f32_16x16x32_bf16 v[90:93], v[8:11], v[86:89], v[90:93]
	v_mfma_f32_16x16x32_bf16 v[46:49], v[82:85], v[94:97], v[46:49]
	v_mfma_f32_16x16x32_bf16 v[54:57], v[12:15], v[102:105], v[54:57]
	v_mfma_f32_16x16x32_bf16 v[58:61], v[82:85], v[102:105], v[58:61]
	v_mfma_f32_16x16x32_bf16 v[62:65], v[12:15], v[110:113], v[62:65]
	v_mfma_f32_16x16x32_bf16 v[74:77], v[78:81], v[106:109], v[74:77]
	v_mfma_f32_16x16x32_bf16 v[0:3], v[12:15], v[118:121], v[0:3]
	v_mfma_f32_16x16x32_bf16 v[4:7], v[82:85], v[118:121], v[4:7]
	v_mfma_f32_16x16x32_bf16 v[90:93], v[12:15], v[94:97], v[90:93]
	v_mfma_f32_16x16x32_bf16 v[74:77], v[82:85], v[110:113], v[74:77]
	s_setprio 0
	s_setprio 1
	s_setprio 0
	s_barrier
	ds_read_b128 v[8:11], v132
	ds_read_b128 v[12:15], v132 offset:1024
	ds_read_b128 v[78:81], v132 offset:2048
	ds_read_b128 v[82:85], v132 offset:3072
	s_add_u32 s30, s52, 0x80180
	s_addc_u32 s31, s53, 0
	s_mov_b32 m0, s45
	v_lshl_add_u64 v[122:123], s[30:31], 0, v[32:33]
	ds_read_b128 v[86:89], v72
	ds_read_b128 v[94:97], v72 offset:1024
	ds_read_b128 v[98:101], v72 offset:2048
	ds_read_b128 v[102:105], v72 offset:3072
	ds_read_b128 v[106:109], v72 offset:4096
	ds_read_b128 v[110:113], v72 offset:5120
	ds_read_b128 v[114:117], v72 offset:6144
	ds_read_b128 v[118:121], v72 offset:7168
	global_load_lds_dwordx4 v[122:123], off
	s_mov_b32 m0, s11
	v_lshl_add_u64 v[122:123], s[30:31], 0, v[66:67]
	global_load_lds_dwordx4 v[122:123], off
	s_waitcnt vmcnt(8)
	s_waitcnt lgkmcnt(0)
	s_barrier
	s_setprio 1
	v_mfma_f32_16x16x32_bf16 v[24:27], v[78:81], v[98:101], v[24:27]
	v_mfma_f32_16x16x32_bf16 v[50:53], v[8:11], v[86:89], v[50:53]
	v_mfma_f32_16x16x32_bf16 v[16:19], v[78:81], v[86:89], v[16:19]
	v_mfma_f32_16x16x32_bf16 v[86:89], v[82:85], v[102:105], v[24:27]
	v_mfma_f32_16x16x32_bf16 v[24:27], v[8:11], v[106:109], v[28:31]
	v_mfma_f32_16x16x32_bf16 v[50:53], v[12:15], v[94:97], v[50:53]
	v_mfma_f32_16x16x32_bf16 v[16:19], v[82:85], v[94:97], v[16:19]
	v_mfma_f32_16x16x32_bf16 v[94:97], v[12:15], v[110:113], v[24:27]
	v_mfma_f32_16x16x32_bf16 v[24:27], v[78:81], v[106:109], v[34:37]
	v_mfma_f32_16x16x32_bf16 v[34:37], v[82:85], v[110:113], v[24:27]
	v_mfma_f32_16x16x32_bf16 v[24:27], v[8:11], v[114:117], v[38:41]
	v_mfma_f32_16x16x32_bf16 v[20:23], v[8:11], v[98:101], v[20:23]
	v_mfma_f32_16x16x32_bf16 v[38:41], v[12:15], v[118:121], v[24:27]
	v_mfma_f32_16x16x32_bf16 v[24:27], v[78:81], v[114:117], v[42:45]
	v_mfma_f32_16x16x32_bf16 v[20:23], v[12:15], v[102:105], v[20:23]
	v_mfma_f32_16x16x32_bf16 v[42:45], v[82:85], v[118:121], v[24:27]
	s_setprio 0
	s_setprio 1
	s_setprio 0
	s_barrier
; #define PG8_STAGE(bufoff, gbase, voff) do { _Pragma("unroll") for (int _i = 0; _i < 2; ++_i) \
;         __builtin_amdgcn_global_load_lds((const unsigned*)((const char*)(gbase) + (voff)[_i]), (PG8_LAS unsigned*)(lds + (bufoff) + ldsw + _i * 8192), 16, 0, 0); } while (0)
; #define PG8_LDA(dst, b, h) do { _Pragma("unroll") for (int m = 0; m < 4; ++m) _Pragma("unroll") for (int k = 0; k < 2; ++k) dst[m][k] = *(const PG8_LAS bf16x8*)(lds + PG8_SA(b, h) + aoff + m * 2048 + k * 1024); } while (0)
; #define PG8_LDB(dst, b, h) do { _Pragma("unroll") for (int n = 0; n < 2; ++n) _Pragma("unroll") for (int k = 0; k < 2; ++k) dst[n][k] = *(const PG8_LAS bf16x8*)(lds + PG8_SB(b, h) + boff + n * 2048 + k * 1024); } while (0)
; #define PG8_WAIT_V(n) asm volatile("s_waitcnt vmcnt(" #n ")" ::: "memory")
; #define PG8_WAIT_L(n) asm volatile("s_waitcnt lgkmcnt(" #n ")" ::: "memory")
; #define PG8_BAR __builtin_amdgcn_s_barrier()
; template <class Epi, class Sched, bool ALIGN_EPI = false, bool SP2 = false, bool KHOOK = false>
; __device__ __forceinline__ void gemm_phase(PG8_LAS unsigned char* lds, const Gemm g, const Sched& S, const Epi& E, const int tid_in) {
;     ...
;             PG8_LDB(B0, 0, 0); PG8_LDB(B1, 0, 1); PG8_SCHED; PG8_LDA(At, 0, 0); PG8_STAGE(PG8_SA(1, 1), a1 + hstep, voffA);
;             PG8_WAIT_V(8); PG8_WAIT_L(0); PG8_BAR; PG8_MMA(0, 0, At, B0); PG8_MMA(0, 1, At, B1); PG8_BAR; PG8_SCHED;
;             PG8_LDA(At, 0, 1); PG8_STAGE(PG8_SB(0, 0), b2, voffB); PG8_STAGE(PG8_SB(0, 1), b2 + hstep, voffB); PG8_STAGE(PG8_SA(0, 0), a2, voffA);
;             PG8_WAIT_V(8); PG8_WAIT_L(0); PG8_BAR; PG8_MMA(1, 0, At, B0); PG8_MMA(1, 1, At, B1); PG8_BAR; PG8_SCHED;
;             PG8_LDB(B0, 1, 0); PG8_LDB(B1, 1, 1); PG8_SCHED; PG8_LDA(At, 1, 0); PG8_STAGE(PG8_SA(0, 1), a2 + hstep, voffA);
;             PG8_WAIT_V(8); PG8_WAIT_L(0); PG8_BAR; PG8_MMA(0, 0, At, B0); PG8_MMA(0, 1, At, B1); PG8_BAR; PG8_SCHED;
;             PG8_LDA(At, 1, 1); PG8_STAGE(PG8_SB(1, 0), b3, voffB); PG8_STAGE(PG8_SB(1, 1), b3 + hstep, voffB); PG8_STAGE(PG8_SA(1, 0), a3, voffA);
;             PG8_WAIT_V(8); PG8_WAIT_L(0); PG8_BAR; PG8_MMA(1, 0, At, B0); PG8_MMA(1, 1, At, B1); PG8_BAR; PG8_SCHED;
;     ...
;         if constexpr (ALIGN_EPI) { if (wr == 0) PG8_BAR; }
;         if constexpr (!Epi::AFTER_DRAIN) { E(acc, cur, wr, wc, fr, fq); S.done(cur); }
;         if (!has_next) break;
	s_mov_b32 m0, s44
	v_lshl_add_u64 v[134:135], s[48:49], 0, v[32:33]
	s_add_u32 s30, s48, 0x80000
	ds_read_b128 v[24:27], v72 offset:16384
	ds_read_b128 v[28:31], v72 offset:17408
	ds_read_b128 v[98:101], v72 offset:18432
	ds_read_b128 v[102:105], v72 offset:19456
	ds_read_b128 v[106:109], v72 offset:20480
	ds_read_b128 v[110:113], v72 offset:21504
	ds_read_b128 v[114:117], v72 offset:22528
	ds_read_b128 v[118:121], v72 offset:23552
	global_load_lds_dwordx4 v[134:135], off
	v_lshl_add_u64 v[136:137], s[48:49], 0, v[66:67]
	s_mov_b32 m0, s13
	s_addc_u32 s31, s49, 0
	global_load_lds_dwordx4 v[136:137], off
	v_lshl_add_u64 v[122:123], s[30:31], 0, v[32:33]
	s_mov_b32 m0, s24
	v_lshl_add_u64 v[138:139], s[56:57], 0, v[32:33]
	global_load_lds_dwordx4 v[122:123], off
	v_lshl_add_u64 v[122:123], s[30:31], 0, v[66:67]
	s_mov_b32 m0, s25
	v_lshl_add_u64 v[140:141], s[56:57], 0, v[66:67]
	global_load_lds_dwordx4 v[122:123], off
	s_mov_b32 m0, s20
	s_nop 0
	global_load_lds_dwordx4 v[138:139], off
	s_mov_b32 m0, s33
	s_nop 0
	global_load_lds_dwordx4 v[140:141], off
	s_waitcnt vmcnt(8)
	s_waitcnt lgkmcnt(0)
	s_barrier
	s_setprio 1
	v_mfma_f32_16x16x32_bf16 v[90:93], v[8:11], v[24:27], v[90:93]
	v_mfma_f32_16x16x32_bf16 v[24:27], v[78:81], v[24:27], v[46:49]
	v_mfma_f32_16x16x32_bf16 v[46:49], v[82:85], v[28:31], v[24:27]
	v_mfma_f32_16x16x32_bf16 v[24:27], v[8:11], v[98:101], v[54:57]
	v_mfma_f32_16x16x32_bf16 v[54:57], v[12:15], v[102:105], v[24:27]
	v_mfma_f32_16x16x32_bf16 v[24:27], v[78:81], v[98:101], v[58:61]
	v_mfma_f32_16x16x32_bf16 v[98:101], v[82:85], v[102:105], v[24:27]
	v_mfma_f32_16x16x32_bf16 v[24:27], v[8:11], v[106:109], v[62:65]
	v_mfma_f32_16x16x32_bf16 v[0:3], v[8:11], v[114:117], v[0:3]
	v_mfma_f32_16x16x32_bf16 v[102:105], v[12:15], v[110:113], v[24:27]
	v_mfma_f32_16x16x32_bf16 v[24:27], v[78:81], v[106:109], v[74:77]
	v_mfma_f32_16x16x32_bf16 v[106:109], v[12:15], v[118:121], v[0:3]
	v_mfma_f32_16x16x32_bf16 v[0:3], v[78:81], v[114:117], v[4:7]
	v_mfma_f32_16x16x32_bf16 v[90:93], v[12:15], v[28:31], v[90:93]
	v_mfma_f32_16x16x32_bf16 v[74:77], v[82:85], v[110:113], v[24:27]
	v_mfma_f32_16x16x32_bf16 v[78:81], v[82:85], v[118:121], v[0:3]
	s_setprio 0
	s_setprio 1
	s_setprio 0
	s_barrier
	ds_read_b128 v[82:85], v133
	ds_read_b128 v[110:113], v133 offset:1024
	ds_read_b128 v[114:117], v133 offset:2048
	ds_read_b128 v[118:121], v133 offset:3072
	s_add_u32 s30, s56, 0x80000
	s_addc_u32 s31, s57, 0
	s_mov_b32 m0, s36
	v_lshl_add_u64 v[24:25], s[30:31], 0, v[32:33]
	ds_read_b128 v[0:3], v72 offset:32768
	ds_read_b128 v[4:7], v72 offset:33792
	ds_read_b128 v[8:11], v72 offset:34816
	ds_read_b128 v[12:15], v72 offset:35840
	ds_read_b128 v[58:61], v72 offset:36864
	ds_read_b128 v[62:65], v72 offset:37888
	ds_read_b128 v[122:125], v72 offset:38912
	ds_read_b128 v[126:129], v72 offset:39936
	global_load_lds_dwordx4 v[24:25], off
	s_mov_b32 m0, s37
	v_lshl_add_u64 v[24:25], s[30:31], 0, v[66:67]
	global_load_lds_dwordx4 v[24:25], off
	s_waitcnt vmcnt(8)
	s_waitcnt lgkmcnt(0)
	s_barrier
	s_setprio 1
	v_mfma_f32_16x16x32_bf16 v[24:27], v[82:85], v[0:3], v[50:53]
	v_mfma_f32_16x16x32_bf16 v[0:3], v[114:117], v[0:3], v[16:19]
	v_mfma_f32_16x16x32_bf16 v[28:31], v[118:121], v[4:7], v[0:3]
	v_mfma_f32_16x16x32_bf16 v[0:3], v[82:85], v[8:11], v[20:23]
	v_mfma_f32_16x16x32_bf16 v[16:19], v[110:113], v[12:15], v[0:3]
	v_mfma_f32_16x16x32_bf16 v[0:3], v[114:117], v[8:11], v[86:89]
	v_mfma_f32_16x16x32_bf16 v[20:23], v[118:121], v[12:15], v[0:3]
	v_mfma_f32_16x16x32_bf16 v[0:3], v[82:85], v[58:61], v[94:97]
	v_mfma_f32_16x16x32_bf16 v[8:11], v[110:113], v[62:65], v[0:3]
	v_mfma_f32_16x16x32_bf16 v[0:3], v[114:117], v[58:61], v[34:37]
	v_mfma_f32_16x16x32_bf16 v[24:27], v[110:113], v[4:7], v[24:27]
	v_mfma_f32_16x16x32_bf16 v[12:15], v[118:121], v[62:65], v[0:3]
	v_mfma_f32_16x16x32_bf16 v[0:3], v[82:85], v[122:125], v[38:41]
	v_mfma_f32_16x16x32_bf16 v[4:7], v[114:117], v[122:125], v[42:45]
	v_mfma_f32_16x16x32_bf16 v[0:3], v[110:113], v[126:129], v[0:3]
	v_mfma_f32_16x16x32_bf16 v[4:7], v[118:121], v[126:129], v[4:7]
	s_setprio 0
	s_setprio 1
	s_setprio 0
	s_barrier
	s_mov_b32 m0, s46
	v_lshl_add_u64 v[50:51], v[134:135], 0, s[90:91]
	s_add_u32 s30, s48, 0x80080
	ds_read_b128 v[34:37], v72 offset:49152
	ds_read_b128 v[38:41], v72 offset:50176
	ds_read_b128 v[42:45], v72 offset:51200
	ds_read_b128 v[86:89], v72 offset:52224
	ds_read_b128 v[94:97], v72 offset:53248
	ds_read_b128 v[122:125], v72 offset:54272
	ds_read_b128 v[126:129], v72 offset:55296
	ds_read_b128 v[130:133], v72 offset:56320
	global_load_lds_dwordx4 v[50:51], off
	v_lshl_add_u64 v[50:51], v[136:137], 0, s[90:91]
	s_mov_b32 m0, s42
	s_addc_u32 s31, s49, 0
	global_load_lds_dwordx4 v[50:51], off
	s_mov_b32 m0, s40
	v_lshl_add_u64 v[50:51], s[30:31], 0, v[32:33]
	global_load_lds_dwordx4 v[50:51], off
	s_mov_b32 m0, s41
	v_lshl_add_u64 v[50:51], s[30:31], 0, v[66:67]
	global_load_lds_dwordx4 v[50:51], off
	s_mov_b32 m0, s38
	v_lshl_add_u64 v[50:51], v[138:139], 0, s[90:91]
	global_load_lds_dwordx4 v[50:51], off
	s_mov_b32 m0, s39
	v_lshl_add_u64 v[50:51], v[140:141], 0, s[90:91]
	global_load_lds_dwordx4 v[50:51], off
	s_waitcnt vmcnt(8)
	s_waitcnt lgkmcnt(0)
	s_barrier
	s_setprio 1
	v_mfma_f32_16x16x32_bf16 v[50:53], v[82:85], v[34:37], v[90:93]
	v_mfma_f32_16x16x32_bf16 v[34:37], v[114:117], v[34:37], v[46:49]
	v_mfma_f32_16x16x32_bf16 v[62:65], v[118:121], v[38:41], v[34:37]
	v_mfma_f32_16x16x32_bf16 v[34:37], v[82:85], v[42:45], v[54:57]
	v_mfma_f32_16x16x32_bf16 v[58:61], v[110:113], v[38:41], v[50:53]
	v_mfma_f32_16x16x32_bf16 v[50:53], v[110:113], v[86:89], v[34:37]
	v_mfma_f32_16x16x32_bf16 v[34:37], v[114:117], v[42:45], v[98:101]
	v_mfma_f32_16x16x32_bf16 v[54:57], v[118:121], v[86:89], v[34:37]
	v_mfma_f32_16x16x32_bf16 v[34:37], v[82:85], v[94:97], v[102:105]
	v_mfma_f32_16x16x32_bf16 v[42:45], v[110:113], v[122:125], v[34:37]
	v_mfma_f32_16x16x32_bf16 v[34:37], v[114:117], v[94:97], v[74:77]
	v_mfma_f32_16x16x32_bf16 v[46:49], v[118:121], v[122:125], v[34:37]
	v_mfma_f32_16x16x32_bf16 v[34:37], v[82:85], v[126:129], v[106:109]
	v_mfma_f32_16x16x32_bf16 v[38:41], v[114:117], v[126:129], v[78:81]
	v_mfma_f32_16x16x32_bf16 v[34:37], v[110:113], v[130:133], v[34:37]
	v_mfma_f32_16x16x32_bf16 v[38:41], v[118:121], v[130:133], v[38:41]
	s_setprio 0
	s_setprio 1
	s_setprio 0
	s_barrier
	s_andn2_b64 vcc, exec, s[4:5]
	s_cbranch_vccnz .LBB0_421
	s_barrier
	s_andn2_b64 vcc, exec, s[6:7]
	s_cbranch_vccz .LBB0_422

; #define PG8_STAGE(bufoff, gbase, voff) do { _Pragma("unroll") for (int _i = 0; _i < 2; ++_i) \
;         __builtin_amdgcn_global_load_lds((const unsigned*)((const char*)(gbase) + (voff)[_i]), (PG8_LAS unsigned*)(lds + (bufoff) + ldsw + _i * 8192), 16, 0, 0); } while (0)
; #define PG8_LDA(dst, b, h) do { _Pragma("unroll") for (int m = 0; m < 4; ++m) _Pragma("unroll") for (int k = 0; k < 2; ++k) dst[m][k] = *(const PG8_LAS bf16x8*)(lds + PG8_SA(b, h) + aoff + m * 2048 + k * 1024); } while (0)
; #define PG8_LDB(dst, b, h) do { _Pragma("unroll") for (int n = 0; n < 2; ++n) _Pragma("unroll") for (int k = 0; k < 2; ++k) dst[n][k] = *(const PG8_LAS bf16x8*)(lds + PG8_SB(b, h) + boff + n * 2048 + k * 1024); } while (0)
; #define PG8_MMA(ai, bj, At, Bt) do { __builtin_amdgcn_s_setprio(1); _Pragma("unroll") for (int m = 0; m < 4; ++m) _Pragma("unroll") for (int n = 0; n < 2; ++n) _Pragma("unroll") for (int k = 0; k < 2; ++k) \
;         acc[ai][bj][m][n] = __builtin_amdgcn_mfma_f32_16x16x32_bf16(Bt[n][k], At[m][k], acc[ai][bj][m][n], 0, 0, 0); __builtin_amdgcn_s_setprio(0); } while (0)
; template <class Epi, class Sched, bool ALIGN_EPI = false, bool SP2 = false, bool KHOOK = false>
; __device__ __forceinline__ void gemm_phase(PG8_LAS unsigned char* lds, const Gemm g, const Sched& S, const Epi& E, const int tid_in) {
;     ...
;             PG8_LDB(B0, 0, 0); PG8_LDB(B1, 0, 1); PG8_SCHED; PG8_LDA(At, 0, 0); PG8_STAGE(PG8_SA(1, 1), a1 + hstep, voffA);
;             PG8_WAIT_V(8); PG8_WAIT_L(0); PG8_BAR; PG8_MMA(0, 0, At, B0); PG8_MMA(0, 1, At, B1); PG8_BAR; PG8_SCHED;
;             PG8_LDA(At, 0, 1); PG8_STAGE(PG8_SB(0, 0), b2, voffB); PG8_STAGE(PG8_SB(0, 1), b2 + hstep, voffB); PG8_STAGE(PG8_SA(0, 0), a2, voffA);
;             PG8_WAIT_V(8); PG8_WAIT_L(0); PG8_BAR; PG8_MMA(1, 0, At, B0); PG8_MMA(1, 1, At, B1); PG8_BAR; PG8_SCHED;
;             PG8_LDB(B0, 1, 0); PG8_LDB(B1, 1, 1); PG8_SCHED; PG8_LDA(At, 1, 0); PG8_STAGE(PG8_SA(0, 1), a2 + hstep, voffA);
;             PG8_WAIT_V(8); PG8_WAIT_L(0); PG8_BAR; PG8_MMA(0, 0, At, B0); PG8_MMA(0, 1, At, B1); PG8_BAR; PG8_SCHED;
;             PG8_LDA(At, 1, 1); PG8_STAGE(PG8_SB(1, 0), b3, voffB); PG8_STAGE(PG8_SB(1, 1), b3 + hstep, voffB); PG8_STAGE(PG8_SA(1, 0), a3, voffA);
;             PG8_WAIT_V(8); PG8_WAIT_L(0); PG8_BAR; PG8_MMA(1, 0, At, B0); PG8_MMA(1, 1, At, B1); PG8_BAR; PG8_SCHED;
.LBB0_845:
	s_add_i32 s47, s47, 2
	s_add_u32 s26, s16, s22
	s_addc_u32 s27, s17, s23
	s_add_u32 s26, s26, 0x100
	s_addc_u32 s27, s27, 0
	s_add_u32 s48, s44, s22
	s_addc_u32 s49, s45, s23
	s_add_i32 s50, 0, 0x10000
	s_cmpk_eq_i32 s22, 0x1f00
	s_cselect_b32 s31, s9, s27
	s_cselect_b32 s30, s41, s26
	v_add_u32_e32 v32, s50, v187
	s_cselect_b32 s27, s7, s49
	s_cselect_b32 s26, s42, s48
	s_add_i32 s51, 0, 0x14000
	ds_read_b128 v[112:115], v32
	ds_read_b128 v[124:127], v32 offset:1024
	ds_read_b128 v[136:139], v32 offset:2048
	ds_read_b128 v[140:143], v32 offset:3072
	v_add_u32_e32 v32, s51, v187
	ds_read_b128 v[144:147], v32
	ds_read_b128 v[152:155], v32 offset:1024
	ds_read_b128 v[174:177], v32 offset:2048
	ds_read_b128 v[178:181], v32 offset:3072
	v_lshl_add_u64 v[34:35], v[100:101], 0, s[22:23]
	s_add_i32 m0, s20, 0xc000
	ds_read_b128 v[202:205], v190
	ds_read_b128 v[206:209], v190 offset:1024
	ds_read_b128 v[210:213], v190 offset:2048
	ds_read_b128 v[214:217], v190 offset:3072
	ds_read_b128 v[218:221], v190 offset:4096
	ds_read_b128 v[222:225], v190 offset:5120
	ds_read_b128 v[246:249], v190 offset:6144
	ds_read_b128 v[198:201], v190 offset:7168
	global_load_lds_dwordx4 v[34:35], off
	s_add_i32 m0, s20, 0xe000
	v_lshl_add_u64 v[34:35], v[102:103], 0, s[22:23]
	global_load_lds_dwordx4 v[34:35], off
	s_waitcnt vmcnt(8)
	s_waitcnt lgkmcnt(0)
	s_barrier
	s_setprio 1
	v_mfma_f32_16x16x32_bf16 v[156:159], v[112:115], v[202:205], v[156:159]
	v_mfma_f32_16x16x32_bf16 v[148:151], v[136:139], v[202:205], v[148:151]
	v_mfma_f32_16x16x32_bf16 v[120:123], v[112:115], v[210:213], v[120:123]
	v_mfma_f32_16x16x32_bf16 v[116:119], v[136:139], v[210:213], v[116:119]
	v_mfma_f32_16x16x32_bf16 v[96:99], v[112:115], v[218:221], v[96:99]
	v_mfma_f32_16x16x32_bf16 v[92:95], v[136:139], v[218:221], v[92:95]
	v_mfma_f32_16x16x32_bf16 v[80:83], v[112:115], v[246:249], v[80:83]
	v_mfma_f32_16x16x32_bf16 v[76:79], v[136:139], v[246:249], v[76:79]
	v_mfma_f32_16x16x32_bf16 v[156:159], v[124:127], v[206:209], v[156:159]
	v_mfma_f32_16x16x32_bf16 v[148:151], v[140:143], v[206:209], v[148:151]
	v_mfma_f32_16x16x32_bf16 v[120:123], v[124:127], v[214:217], v[120:123]
	v_mfma_f32_16x16x32_bf16 v[116:119], v[140:143], v[214:217], v[116:119]
	v_mfma_f32_16x16x32_bf16 v[96:99], v[124:127], v[222:225], v[96:99]
	v_mfma_f32_16x16x32_bf16 v[92:95], v[140:143], v[222:225], v[92:95]
	v_mfma_f32_16x16x32_bf16 v[80:83], v[124:127], v[198:201], v[80:83]
	v_mfma_f32_16x16x32_bf16 v[76:79], v[140:143], v[198:201], v[76:79]
	s_setprio 0
	s_setprio 1
	v_mfma_f32_16x16x32_bf16 v[132:135], v[144:147], v[202:205], v[132:135]
	v_mfma_f32_16x16x32_bf16 v[128:131], v[174:177], v[202:205], v[128:131]
	v_mfma_f32_16x16x32_bf16 v[108:111], v[144:147], v[210:213], v[108:111]
	v_mfma_f32_16x16x32_bf16 v[104:107], v[174:177], v[210:213], v[104:107]
	v_mfma_f32_16x16x32_bf16 v[88:91], v[144:147], v[218:221], v[88:91]
	v_mfma_f32_16x16x32_bf16 v[84:87], v[174:177], v[218:221], v[84:87]
	v_mfma_f32_16x16x32_bf16 v[72:75], v[144:147], v[246:249], v[72:75]
	v_mfma_f32_16x16x32_bf16 v[68:71], v[174:177], v[246:249], v[68:71]
	v_mfma_f32_16x16x32_bf16 v[132:135], v[152:155], v[206:209], v[132:135]
	v_mfma_f32_16x16x32_bf16 v[128:131], v[178:181], v[206:209], v[128:131]
	v_mfma_f32_16x16x32_bf16 v[108:111], v[152:155], v[214:217], v[108:111]
	v_mfma_f32_16x16x32_bf16 v[104:107], v[178:181], v[214:217], v[104:107]
	v_mfma_f32_16x16x32_bf16 v[88:91], v[152:155], v[222:225], v[88:91]
	v_mfma_f32_16x16x32_bf16 v[84:87], v[178:181], v[222:225], v[84:87]
	v_mfma_f32_16x16x32_bf16 v[72:75], v[152:155], v[198:201], v[72:75]
	v_mfma_f32_16x16x32_bf16 v[68:71], v[178:181], v[198:201], v[68:71]
	s_setprio 0
	s_barrier
	s_add_i32 s48, s50, s19
	v_lshl_add_u64 v[182:183], s[26:27], 0, v[164:165]
	s_mov_b32 m0, s48
	ds_read_b128 v[198:201], v190 offset:16384
	ds_read_b128 v[202:205], v190 offset:17408
	ds_read_b128 v[206:209], v190 offset:18432
	ds_read_b128 v[210:213], v190 offset:19456
	ds_read_b128 v[214:217], v190 offset:20480
	ds_read_b128 v[218:221], v190 offset:21504
	ds_read_b128 v[222:225], v190 offset:22528
	ds_read_b128 v[246:249], v190 offset:23552
	global_load_lds_dwordx4 v[182:183], off
	s_add_i32 m0, s48, 0x2000
	s_add_u32 s48, s26, 0x100000
	v_lshl_add_u64 v[192:193], s[26:27], 0, v[160:161]
	s_addc_u32 s49, s27, 0
	s_add_i32 s50, s51, s19
	global_load_lds_dwordx4 v[192:193], off
	v_lshl_add_u64 v[34:35], s[48:49], 0, v[164:165]
	s_mov_b32 m0, s50
	v_lshl_add_u64 v[226:227], s[30:31], 0, v[166:167]
	global_load_lds_dwordx4 v[34:35], off
	v_lshl_add_u64 v[34:35], s[48:49], 0, v[160:161]
	s_add_i32 m0, s50, 0x2000
	v_lshl_add_u64 v[230:231], s[30:31], 0, v[162:163]
	global_load_lds_dwordx4 v[34:35], off
	s_mov_b32 m0, s20
	s_nop 0
	global_load_lds_dwordx4 v[226:227], off
	s_mov_b32 m0, s33
	s_nop 0
	global_load_lds_dwordx4 v[230:231], off
	s_waitcnt vmcnt(8)
	s_waitcnt lgkmcnt(0)
	s_barrier
; #define PG8_STAGE(bufoff, gbase, voff) do { _Pragma("unroll") for (int _i = 0; _i < 2; ++_i) \
;         __builtin_amdgcn_global_load_lds((const unsigned*)((const char*)(gbase) + (voff)[_i]), (PG8_LAS unsigned*)(lds + (bufoff) + ldsw + _i * 8192), 16, 0, 0); } while (0)
; #define PG8_LDA(dst, b, h) do { _Pragma("unroll") for (int m = 0; m < 4; ++m) _Pragma("unroll") for (int k = 0; k < 2; ++k) dst[m][k] = *(const PG8_LAS bf16x8*)(lds + PG8_SA(b, h) + aoff + m * 2048 + k * 1024); } while (0)
; #define PG8_LDB(dst, b, h) do { _Pragma("unroll") for (int n = 0; n < 2; ++n) _Pragma("unroll") for (int k = 0; k < 2; ++k) dst[n][k] = *(const PG8_LAS bf16x8*)(lds + PG8_SB(b, h) + boff + n * 2048 + k * 1024); } while (0)
; #define PG8_MMA(ai, bj, At, Bt) do { __builtin_amdgcn_s_setprio(1); _Pragma("unroll") for (int m = 0; m < 4; ++m) _Pragma("unroll") for (int n = 0; n < 2; ++n) _Pragma("unroll") for (int k = 0; k < 2; ++k) \
;         acc[ai][bj][m][n] = __builtin_amdgcn_mfma_f32_16x16x32_bf16(Bt[n][k], At[m][k], acc[ai][bj][m][n], 0, 0, 0); __builtin_amdgcn_s_setprio(0); } while (0)
; #define PG8_WAIT_V(n) asm volatile("s_waitcnt vmcnt(" #n ")" ::: "memory")
; #define PG8_WAIT_L(n) asm volatile("s_waitcnt lgkmcnt(" #n ")" ::: "memory")
; #define PG8_BAR __builtin_amdgcn_s_barrier()
; #define PG8_SCHED __builtin_amdgcn_sched_barrier(0)
; template <class Epi, class Sched, bool ALIGN_EPI = false, bool SP2 = false, bool KHOOK = false>
; __device__ __forceinline__ void gemm_phase(PG8_LAS unsigned char* lds, const Gemm g, const Sched& S, const Epi& E, const int tid_in) {
;     ...
;             PG8_WAIT_V(8); PG8_WAIT_L(0); PG8_BAR; PG8_MMA(0, 0, At, B0); PG8_MMA(0, 1, At, B1); PG8_BAR; PG8_SCHED;
;             PG8_LDA(At, 0, 1); PG8_STAGE(PG8_SB(0, 0), b2, voffB); PG8_STAGE(PG8_SB(0, 1), b2 + hstep, voffB); PG8_STAGE(PG8_SA(0, 0), a2, voffA);
;             PG8_WAIT_V(8); PG8_WAIT_L(0); PG8_BAR; PG8_MMA(1, 0, At, B0); PG8_MMA(1, 1, At, B1); PG8_BAR; PG8_SCHED;
;             PG8_LDB(B0, 1, 0); PG8_LDB(B1, 1, 1); PG8_SCHED; PG8_LDA(At, 1, 0); PG8_STAGE(PG8_SA(0, 1), a2 + hstep, voffA);
;             PG8_WAIT_V(8); PG8_WAIT_L(0); PG8_BAR; PG8_MMA(0, 0, At, B0); PG8_MMA(0, 1, At, B1); PG8_BAR; PG8_SCHED;
	s_setprio 1
	v_mfma_f32_16x16x32_bf16 v[64:67], v[112:115], v[198:201], v[64:67]
	v_mfma_f32_16x16x32_bf16 v[60:63], v[136:139], v[198:201], v[60:63]
	v_mfma_f32_16x16x32_bf16 v[48:51], v[112:115], v[206:209], v[48:51]
	v_mfma_f32_16x16x32_bf16 v[44:47], v[136:139], v[206:209], v[44:47]
	v_mfma_f32_16x16x32_bf16 v[28:31], v[112:115], v[214:217], v[28:31]
	v_mfma_f32_16x16x32_bf16 v[24:27], v[136:139], v[214:217], v[24:27]
	v_mfma_f32_16x16x32_bf16 v[12:15], v[112:115], v[222:225], v[12:15]
	v_mfma_f32_16x16x32_bf16 v[8:11], v[136:139], v[222:225], v[8:11]
	v_mfma_f32_16x16x32_bf16 v[64:67], v[124:127], v[202:205], v[64:67]
	v_mfma_f32_16x16x32_bf16 v[60:63], v[140:143], v[202:205], v[60:63]
	v_mfma_f32_16x16x32_bf16 v[48:51], v[124:127], v[210:213], v[48:51]
	v_mfma_f32_16x16x32_bf16 v[44:47], v[140:143], v[210:213], v[44:47]
	v_mfma_f32_16x16x32_bf16 v[28:31], v[124:127], v[218:221], v[28:31]
	v_mfma_f32_16x16x32_bf16 v[24:27], v[140:143], v[218:221], v[24:27]
	v_mfma_f32_16x16x32_bf16 v[12:15], v[124:127], v[246:249], v[12:15]
	v_mfma_f32_16x16x32_bf16 v[8:11], v[140:143], v[246:249], v[8:11]
	s_setprio 0
	s_setprio 1
	v_mfma_f32_16x16x32_bf16 v[56:59], v[144:147], v[198:201], v[56:59]
	v_mfma_f32_16x16x32_bf16 v[52:55], v[174:177], v[198:201], v[52:55]
	v_mfma_f32_16x16x32_bf16 v[40:43], v[144:147], v[206:209], v[40:43]
	v_mfma_f32_16x16x32_bf16 v[34:37], v[174:177], v[206:209], v[36:39]
	v_mfma_f32_16x16x32_bf16 v[20:23], v[144:147], v[214:217], v[20:23]
	v_mfma_f32_16x16x32_bf16 v[16:19], v[174:177], v[214:217], v[16:19]
	v_mfma_f32_16x16x32_bf16 v[4:7], v[144:147], v[222:225], v[4:7]
	v_mfma_f32_16x16x32_bf16 v[0:3], v[174:177], v[222:225], v[0:3]
	v_mfma_f32_16x16x32_bf16 v[56:59], v[152:155], v[202:205], v[56:59]
	v_mfma_f32_16x16x32_bf16 v[52:55], v[178:181], v[202:205], v[52:55]
	v_mfma_f32_16x16x32_bf16 v[40:43], v[152:155], v[210:213], v[40:43]
	v_mfma_f32_16x16x32_bf16 v[34:37], v[178:181], v[210:213], v[34:37]
	v_mfma_f32_16x16x32_bf16 v[20:23], v[152:155], v[218:221], v[20:23]
	v_mfma_f32_16x16x32_bf16 v[16:19], v[178:181], v[218:221], v[16:19]
	v_mfma_f32_16x16x32_bf16 v[4:7], v[152:155], v[246:249], v[4:7]
	v_mfma_f32_16x16x32_bf16 v[0:3], v[178:181], v[246:249], v[0:3]
	s_setprio 0
	s_barrier
	s_add_i32 s48, 0, 0x18000
	v_add_u32_e32 v32, s48, v187
	s_add_i32 s49, 0, 0x1c000
	ds_read_b128 v[112:115], v32
	ds_read_b128 v[124:127], v32 offset:1024
	ds_read_b128 v[136:139], v32 offset:2048
	ds_read_b128 v[140:143], v32 offset:3072
	v_add_u32_e32 v32, s49, v187
	ds_read_b128 v[144:147], v32
	ds_read_b128 v[152:155], v32 offset:1024
	ds_read_b128 v[174:177], v32 offset:2048
	ds_read_b128 v[178:181], v32 offset:3072
	s_add_u32 s30, s30, 0x100000
	s_addc_u32 s31, s31, 0
	s_mov_b32 m0, s36
	v_lshl_add_u64 v[38:39], s[30:31], 0, v[166:167]
	ds_read_b128 v[198:201], v190 offset:32768
	ds_read_b128 v[202:205], v190 offset:33792
	ds_read_b128 v[206:209], v190 offset:34816
	ds_read_b128 v[210:213], v190 offset:35840
	ds_read_b128 v[214:217], v190 offset:36864
	ds_read_b128 v[218:221], v190 offset:37888
	ds_read_b128 v[222:225], v190 offset:38912
	ds_read_b128 v[246:249], v190 offset:39936
	global_load_lds_dwordx4 v[38:39], off
	s_mov_b32 m0, s37
	v_lshl_add_u64 v[38:39], s[30:31], 0, v[162:163]
	global_load_lds_dwordx4 v[38:39], off
	s_waitcnt vmcnt(8)
	s_waitcnt lgkmcnt(0)
	s_barrier
	s_setprio 1
	v_mfma_f32_16x16x32_bf16 v[156:159], v[112:115], v[198:201], v[156:159]
	v_mfma_f32_16x16x32_bf16 v[148:151], v[136:139], v[198:201], v[148:151]
	v_mfma_f32_16x16x32_bf16 v[120:123], v[112:115], v[206:209], v[120:123]
	v_mfma_f32_16x16x32_bf16 v[116:119], v[136:139], v[206:209], v[116:119]
	v_mfma_f32_16x16x32_bf16 v[96:99], v[112:115], v[214:217], v[96:99]
	v_mfma_f32_16x16x32_bf16 v[92:95], v[136:139], v[214:217], v[92:95]
	v_mfma_f32_16x16x32_bf16 v[80:83], v[112:115], v[222:225], v[80:83]
	v_mfma_f32_16x16x32_bf16 v[76:79], v[136:139], v[222:225], v[76:79]
	v_mfma_f32_16x16x32_bf16 v[156:159], v[124:127], v[202:205], v[156:159]
	v_mfma_f32_16x16x32_bf16 v[148:151], v[140:143], v[202:205], v[148:151]
	v_mfma_f32_16x16x32_bf16 v[120:123], v[124:127], v[210:213], v[120:123]
	v_mfma_f32_16x16x32_bf16 v[116:119], v[140:143], v[210:213], v[116:119]
	v_mfma_f32_16x16x32_bf16 v[96:99], v[124:127], v[218:221], v[96:99]
	v_mfma_f32_16x16x32_bf16 v[92:95], v[140:143], v[218:221], v[92:95]
	v_mfma_f32_16x16x32_bf16 v[80:83], v[124:127], v[246:249], v[80:83]
	v_mfma_f32_16x16x32_bf16 v[76:79], v[140:143], v[246:249], v[76:79]
	s_setprio 0
	s_setprio 1
	v_mfma_f32_16x16x32_bf16 v[132:135], v[144:147], v[198:201], v[132:135]
	v_mfma_f32_16x16x32_bf16 v[128:131], v[174:177], v[198:201], v[128:131]
	v_mfma_f32_16x16x32_bf16 v[108:111], v[144:147], v[206:209], v[108:111]
	v_mfma_f32_16x16x32_bf16 v[104:107], v[174:177], v[206:209], v[104:107]
	v_mfma_f32_16x16x32_bf16 v[88:91], v[144:147], v[214:217], v[88:91]
	v_mfma_f32_16x16x32_bf16 v[84:87], v[174:177], v[214:217], v[84:87]
	v_mfma_f32_16x16x32_bf16 v[72:75], v[144:147], v[222:225], v[72:75]
	v_mfma_f32_16x16x32_bf16 v[68:71], v[174:177], v[222:225], v[68:71]
	v_mfma_f32_16x16x32_bf16 v[132:135], v[152:155], v[202:205], v[132:135]
	v_mfma_f32_16x16x32_bf16 v[128:131], v[178:181], v[202:205], v[128:131]
	v_mfma_f32_16x16x32_bf16 v[108:111], v[152:155], v[210:213], v[108:111]
	v_mfma_f32_16x16x32_bf16 v[104:107], v[178:181], v[210:213], v[104:107]
	v_mfma_f32_16x16x32_bf16 v[88:91], v[152:155], v[218:221], v[88:91]
	v_mfma_f32_16x16x32_bf16 v[84:87], v[178:181], v[218:221], v[84:87]
	v_mfma_f32_16x16x32_bf16 v[72:75], v[152:155], v[246:249], v[72:75]
	v_mfma_f32_16x16x32_bf16 v[68:71], v[178:181], v[246:249], v[68:71]
	s_setprio 0
	s_barrier
; #define PG8_STAGE(bufoff, gbase, voff) do { _Pragma("unroll") for (int _i = 0; _i < 2; ++_i) \
;         __builtin_amdgcn_global_load_lds((const unsigned*)((const char*)(gbase) + (voff)[_i]), (PG8_LAS unsigned*)(lds + (bufoff) + ldsw + _i * 8192), 16, 0, 0); } while (0)
; #define PG8_LDA(dst, b, h) do { _Pragma("unroll") for (int m = 0; m < 4; ++m) _Pragma("unroll") for (int k = 0; k < 2; ++k) dst[m][k] = *(const PG8_LAS bf16x8*)(lds + PG8_SA(b, h) + aoff + m * 2048 + k * 1024); } while (0)
; #define PG8_MMA(ai, bj, At, Bt) do { __builtin_amdgcn_s_setprio(1); _Pragma("unroll") for (int m = 0; m < 4; ++m) _Pragma("unroll") for (int n = 0; n < 2; ++n) _Pragma("unroll") for (int k = 0; k < 2; ++k) \
;         acc[ai][bj][m][n] = __builtin_amdgcn_mfma_f32_16x16x32_bf16(Bt[n][k], At[m][k], acc[ai][bj][m][n], 0, 0, 0); __builtin_amdgcn_s_setprio(0); } while (0)
; #define PG8_WAIT_V(n) asm volatile("s_waitcnt vmcnt(" #n ")" ::: "memory")
; #define PG8_WAIT_L(n) asm volatile("s_waitcnt lgkmcnt(" #n ")" ::: "memory")
; #define PG8_BAR __builtin_amdgcn_s_barrier()
; #define PG8_SCHED __builtin_amdgcn_sched_barrier(0)
; template <class Epi, class Sched, bool ALIGN_EPI = false, bool SP2 = false, bool KHOOK = false>
; __device__ __forceinline__ void gemm_phase(PG8_LAS unsigned char* lds, const Gemm g, const Sched& S, const Epi& E, const int tid_in) {
;     ...
;             PG8_LDA(At, 1, 1); PG8_STAGE(PG8_SB(1, 0), b3, voffB); PG8_STAGE(PG8_SB(1, 1), b3 + hstep, voffB); PG8_STAGE(PG8_SA(1, 0), a3, voffA);
;             PG8_WAIT_V(8); PG8_WAIT_L(0); PG8_BAR; PG8_MMA(1, 0, At, B0); PG8_MMA(1, 1, At, B1); PG8_BAR; PG8_SCHED;
;             if constexpr (KHOOK) { if ((t & 7) == 6) {
	s_add_i32 s30, s48, s19
	v_lshl_add_u64 v[38:39], v[182:183], 0, s[90:91]
	s_mov_b32 m0, s30
	ds_read_b128 v[198:201], v190 offset:49152
	ds_read_b128 v[202:205], v190 offset:50176
	ds_read_b128 v[206:209], v190 offset:51200
	ds_read_b128 v[210:213], v190 offset:52224
	ds_read_b128 v[214:217], v190 offset:53248
	ds_read_b128 v[218:221], v190 offset:54272
	ds_read_b128 v[222:225], v190 offset:55296
	ds_read_b128 v[246:249], v190 offset:56320
	global_load_lds_dwordx4 v[38:39], off
	s_add_i32 m0, s30, 0x2000
	s_add_u32 s26, s26, 0x100080
	v_lshl_add_u64 v[38:39], v[192:193], 0, s[90:91]
	s_addc_u32 s27, s27, 0
	s_add_i32 s30, s49, s19
	global_load_lds_dwordx4 v[38:39], off
	s_mov_b32 m0, s30
	v_lshl_add_u64 v[38:39], s[26:27], 0, v[164:165]
	global_load_lds_dwordx4 v[38:39], off
	s_add_i32 m0, s30, 0x2000
	v_lshl_add_u64 v[38:39], s[26:27], 0, v[160:161]
	global_load_lds_dwordx4 v[38:39], off
	s_mov_b32 m0, s38
	v_lshl_add_u64 v[38:39], v[226:227], 0, s[90:91]
	global_load_lds_dwordx4 v[38:39], off
	s_mov_b32 m0, s39
	v_lshl_add_u64 v[38:39], v[230:231], 0, s[90:91]
	global_load_lds_dwordx4 v[38:39], off
	s_waitcnt vmcnt(8)
	s_waitcnt lgkmcnt(0)
	s_barrier
	s_setprio 1
	v_mfma_f32_16x16x32_bf16 v[64:67], v[112:115], v[198:201], v[64:67]
	v_mfma_f32_16x16x32_bf16 v[60:63], v[136:139], v[198:201], v[60:63]
	v_mfma_f32_16x16x32_bf16 v[48:51], v[112:115], v[206:209], v[48:51]
	v_mfma_f32_16x16x32_bf16 v[44:47], v[136:139], v[206:209], v[44:47]
	v_mfma_f32_16x16x32_bf16 v[28:31], v[112:115], v[214:217], v[28:31]
	v_mfma_f32_16x16x32_bf16 v[24:27], v[136:139], v[214:217], v[24:27]
	v_mfma_f32_16x16x32_bf16 v[12:15], v[112:115], v[222:225], v[12:15]
	v_mfma_f32_16x16x32_bf16 v[8:11], v[136:139], v[222:225], v[8:11]
	v_mfma_f32_16x16x32_bf16 v[64:67], v[124:127], v[202:205], v[64:67]
	v_mfma_f32_16x16x32_bf16 v[60:63], v[140:143], v[202:205], v[60:63]
	v_mfma_f32_16x16x32_bf16 v[48:51], v[124:127], v[210:213], v[48:51]
	v_mfma_f32_16x16x32_bf16 v[44:47], v[140:143], v[210:213], v[44:47]
	v_mfma_f32_16x16x32_bf16 v[28:31], v[124:127], v[218:221], v[28:31]
	v_mfma_f32_16x16x32_bf16 v[24:27], v[140:143], v[218:221], v[24:27]
	v_mfma_f32_16x16x32_bf16 v[12:15], v[124:127], v[246:249], v[12:15]
	v_mfma_f32_16x16x32_bf16 v[8:11], v[140:143], v[246:249], v[8:11]
	s_setprio 0
	s_setprio 1
	v_mfma_f32_16x16x32_bf16 v[56:59], v[144:147], v[198:201], v[56:59]
	v_mfma_f32_16x16x32_bf16 v[52:55], v[174:177], v[198:201], v[52:55]
	v_mfma_f32_16x16x32_bf16 v[38:41], v[144:147], v[206:209], v[40:43]
	v_mfma_f32_16x16x32_bf16 v[34:37], v[174:177], v[206:209], v[34:37]
	v_mfma_f32_16x16x32_bf16 v[20:23], v[144:147], v[214:217], v[20:23]
	v_mfma_f32_16x16x32_bf16 v[16:19], v[174:177], v[214:217], v[16:19]
	v_mfma_f32_16x16x32_bf16 v[4:7], v[144:147], v[222:225], v[4:7]
	v_mfma_f32_16x16x32_bf16 v[0:3], v[174:177], v[222:225], v[0:3]
	v_mfma_f32_16x16x32_bf16 v[56:59], v[152:155], v[202:205], v[56:59]
	v_mfma_f32_16x16x32_bf16 v[52:55], v[178:181], v[202:205], v[52:55]
	v_mfma_f32_16x16x32_bf16 v[40:43], v[152:155], v[210:213], v[38:41]
	v_mfma_f32_16x16x32_bf16 v[36:39], v[178:181], v[210:213], v[34:37]
	v_mfma_f32_16x16x32_bf16 v[20:23], v[152:155], v[218:221], v[20:23]
	v_mfma_f32_16x16x32_bf16 v[16:19], v[178:181], v[218:221], v[16:19]
	v_mfma_f32_16x16x32_bf16 v[4:7], v[152:155], v[246:249], v[4:7]
	v_mfma_f32_16x16x32_bf16 v[0:3], v[178:181], v[246:249], v[0:3]
	s_setprio 0
	s_barrier
	s_and_b32 s26, s47, 6
	s_cmp_lg_u32 s26, 6
	s_cbranch_scc1 .LBB0_844
; #define PG8_LAS __attribute__((address_space(3)))
; template <class Epi, class Sched, bool ALIGN_EPI = false, bool SP2 = false, bool KHOOK = false>
; __device__ __forceinline__ void gemm_phase(PG8_LAS unsigned char* lds, const Gemm g, const Sched& S, const Epi& E, const int tid_in) {
;     ...
;             if constexpr (KHOOK) { if ((t & 7) == 6) {
;                 const PG8_LAS float* RT = (const PG8_LAS float*)(lds + 8 * 16384) + (t >> 3) * 256 + wr * 64 + fr; float f[2][4];
; #pragma unroll
;                 for (int a = 0; a < 2; ++a)
; #pragma unroll
;                     for (int m = 0; m < 4; ++m) f[a][m] = RT[a * HALF + m * 16];
; #pragma unroll
;                 for (int a = 0; a < 2; ++a)
; #pragma unroll
;                     for (int b = 0; b < 2; ++b)
; #pragma unroll
;                         for (int m = 0; m < 4; ++m)
; #pragma unroll
;                             for (int n = 0; n < 2; ++n) acc[a][b][m][n] *= f[a][m]; } }
	s_and_b32 s26, s46, 0x700
	v_lshl_add_u32 v32, s26, 2, v188
	ds_read2_b32 v[112:113], v32 offset1:16
	ds_read2_b32 v[114:115], v32 offset0:32 offset1:48
	ds_read2_b32 v[124:125], v32 offset0:128 offset1:144
	ds_read2_b32 v[34:35], v32 offset0:160 offset1:176
	s_waitcnt lgkmcnt(0)
	v_mov_b32_e32 v32, v113
	v_pk_mul_f32 v[158:159], v[158:159], v[112:113] op_sel_hi:[1,0]
	v_pk_mul_f32 v[156:157], v[156:157], v[112:113] op_sel_hi:[1,0]
	v_pk_mul_f32 v[150:151], v[150:151], v[112:113] op_sel_hi:[1,0]
	v_pk_mul_f32 v[148:149], v[148:149], v[112:113] op_sel_hi:[1,0]
	v_pk_mul_f32 v[122:123], v[122:123], v[32:33] op_sel_hi:[1,0]
	v_pk_mul_f32 v[120:121], v[120:121], v[32:33] op_sel_hi:[1,0]
	v_pk_mul_f32 v[118:119], v[118:119], v[32:33] op_sel_hi:[1,0]
	v_pk_mul_f32 v[116:117], v[116:117], v[32:33] op_sel_hi:[1,0]
	v_mov_b32_e32 v126, v115
	v_pk_mul_f32 v[134:135], v[134:135], v[112:113] op_sel_hi:[1,0]
	v_pk_mul_f32 v[132:133], v[132:133], v[112:113] op_sel_hi:[1,0]
	v_pk_mul_f32 v[130:131], v[130:131], v[112:113] op_sel_hi:[1,0]
	v_pk_mul_f32 v[128:129], v[128:129], v[112:113] op_sel_hi:[1,0]
	v_pk_mul_f32 v[110:111], v[110:111], v[32:33] op_sel_hi:[1,0]
	v_pk_mul_f32 v[108:109], v[108:109], v[32:33] op_sel_hi:[1,0]
	v_pk_mul_f32 v[106:107], v[106:107], v[32:33] op_sel_hi:[1,0]
	v_pk_mul_f32 v[104:105], v[104:105], v[32:33] op_sel_hi:[1,0]
	v_mov_b32_e32 v32, v125
	v_mov_b32_e32 v112, v35
	v_pk_mul_f32 v[98:99], v[98:99], v[114:115] op_sel_hi:[1,0]
	v_pk_mul_f32 v[96:97], v[96:97], v[114:115] op_sel_hi:[1,0]
	v_pk_mul_f32 v[94:95], v[94:95], v[114:115] op_sel_hi:[1,0]
	v_pk_mul_f32 v[92:93], v[92:93], v[114:115] op_sel_hi:[1,0]
	v_pk_mul_f32 v[82:83], v[82:83], v[126:127] op_sel_hi:[1,0]
	v_pk_mul_f32 v[80:81], v[80:81], v[126:127] op_sel_hi:[1,0]
	v_pk_mul_f32 v[78:79], v[78:79], v[126:127] op_sel_hi:[1,0]
	v_pk_mul_f32 v[76:77], v[76:77], v[126:127] op_sel_hi:[1,0]
	v_pk_mul_f32 v[90:91], v[90:91], v[114:115] op_sel_hi:[1,0]
	v_pk_mul_f32 v[88:89], v[88:89], v[114:115] op_sel_hi:[1,0]
	v_pk_mul_f32 v[86:87], v[86:87], v[114:115] op_sel_hi:[1,0]
	v_pk_mul_f32 v[84:85], v[84:85], v[114:115] op_sel_hi:[1,0]
	v_pk_mul_f32 v[74:75], v[74:75], v[126:127] op_sel_hi:[1,0]
	v_pk_mul_f32 v[72:73], v[72:73], v[126:127] op_sel_hi:[1,0]
	v_pk_mul_f32 v[70:71], v[70:71], v[126:127] op_sel_hi:[1,0]
	v_pk_mul_f32 v[68:69], v[68:69], v[126:127] op_sel_hi:[1,0]
	v_pk_mul_f32 v[66:67], v[66:67], v[124:125] op_sel_hi:[1,0]
	v_pk_mul_f32 v[64:65], v[64:65], v[124:125] op_sel_hi:[1,0]
	v_pk_mul_f32 v[62:63], v[62:63], v[124:125] op_sel_hi:[1,0]
	v_pk_mul_f32 v[60:61], v[60:61], v[124:125] op_sel_hi:[1,0]
	v_pk_mul_f32 v[50:51], v[50:51], v[32:33] op_sel_hi:[1,0]
	v_pk_mul_f32 v[48:49], v[48:49], v[32:33] op_sel_hi:[1,0]
	v_pk_mul_f32 v[46:47], v[46:47], v[32:33] op_sel_hi:[1,0]
	v_pk_mul_f32 v[44:45], v[44:45], v[32:33] op_sel_hi:[1,0]
	v_pk_mul_f32 v[30:31], v[30:31], v[34:35] op_sel_hi:[1,0]
	v_pk_mul_f32 v[28:29], v[28:29], v[34:35] op_sel_hi:[1,0]
	v_pk_mul_f32 v[26:27], v[26:27], v[34:35] op_sel_hi:[1,0]
	v_pk_mul_f32 v[24:25], v[24:25], v[34:35] op_sel_hi:[1,0]
	v_pk_mul_f32 v[14:15], v[14:15], v[112:113] op_sel_hi:[1,0]
	v_pk_mul_f32 v[12:13], v[12:13], v[112:113] op_sel_hi:[1,0]
	v_pk_mul_f32 v[10:11], v[10:11], v[112:113] op_sel_hi:[1,0]
	v_pk_mul_f32 v[8:9], v[8:9], v[112:113] op_sel_hi:[1,0]
	v_pk_mul_f32 v[58:59], v[58:59], v[124:125] op_sel_hi:[1,0]
	v_pk_mul_f32 v[56:57], v[56:57], v[124:125] op_sel_hi:[1,0]
	v_pk_mul_f32 v[54:55], v[54:55], v[124:125] op_sel_hi:[1,0]
	v_pk_mul_f32 v[52:53], v[52:53], v[124:125] op_sel_hi:[1,0]
	v_pk_mul_f32 v[42:43], v[42:43], v[32:33] op_sel_hi:[1,0]
	v_pk_mul_f32 v[40:41], v[40:41], v[32:33] op_sel_hi:[1,0]
	v_pk_mul_f32 v[38:39], v[38:39], v[32:33] op_sel_hi:[1,0]
	v_pk_mul_f32 v[36:37], v[36:37], v[32:33] op_sel_hi:[1,0]
	v_pk_mul_f32 v[22:23], v[22:23], v[34:35] op_sel_hi:[1,0]
	v_pk_mul_f32 v[20:21], v[20:21], v[34:35] op_sel_hi:[1,0]
	v_pk_mul_f32 v[18:19], v[18:19], v[34:35] op_sel_hi:[1,0]
	v_pk_mul_f32 v[16:17], v[16:17], v[34:35] op_sel_hi:[1,0]
	v_pk_mul_f32 v[6:7], v[6:7], v[112:113] op_sel_hi:[1,0]
	v_pk_mul_f32 v[4:5], v[4:5], v[112:113] op_sel_hi:[1,0]
	v_pk_mul_f32 v[2:3], v[2:3], v[112:113] op_sel_hi:[1,0]
	v_pk_mul_f32 v[0:1], v[0:1], v[112:113] op_sel_hi:[1,0]
	s_branch .LBB0_844

; #define PG8_STAGE(bufoff, gbase, voff) do { _Pragma("unroll") for (int _i = 0; _i < 2; ++_i) \
;         __builtin_amdgcn_global_load_lds((const unsigned*)((const char*)(gbase) + (voff)[_i]), (PG8_LAS unsigned*)(lds + (bufoff) + ldsw + _i * 8192), 16, 0, 0); } while (0)
; #define PG8_LDA(dst, b, h) do { _Pragma("unroll") for (int m = 0; m < 4; ++m) _Pragma("unroll") for (int k = 0; k < 2; ++k) dst[m][k] = *(const PG8_LAS bf16x8*)(lds + PG8_SA(b, h) + aoff + m * 2048 + k * 1024); } while (0)
; #define PG8_LDB(dst, b, h) do { _Pragma("unroll") for (int n = 0; n < 2; ++n) _Pragma("unroll") for (int k = 0; k < 2; ++k) dst[n][k] = *(const PG8_LAS bf16x8*)(lds + PG8_SB(b, h) + boff + n * 2048 + k * 1024); } while (0)
; #define PG8_MMA(ai, bj, At, Bt) do { __builtin_amdgcn_s_setprio(1); _Pragma("unroll") for (int m = 0; m < 4; ++m) _Pragma("unroll") for (int n = 0; n < 2; ++n) _Pragma("unroll") for (int k = 0; k < 2; ++k) \
;         acc[ai][bj][m][n] = __builtin_amdgcn_mfma_f32_16x16x32_bf16(Bt[n][k], At[m][k], acc[ai][bj][m][n], 0, 0, 0); __builtin_amdgcn_s_setprio(0); } while (0)
; #define PG8_WAIT_V(n) asm volatile("s_waitcnt vmcnt(" #n ")" ::: "memory")
; #define PG8_WAIT_L(n) asm volatile("s_waitcnt lgkmcnt(" #n ")" ::: "memory")
; #define PG8_BAR __builtin_amdgcn_s_barrier()
; #define PG8_SCHED __builtin_amdgcn_sched_barrier(0)
; template <class Epi, class Sched, bool ALIGN_EPI = false, bool SP2 = false, bool KHOOK = false>
; __device__ __forceinline__ void gemm_phase(PG8_LAS unsigned char* lds, const Gemm g, const Sched& S, const Epi& E, const int tid_in) {
;     ...
;             PG8_LDB(B0, 0, 0); PG8_LDB(B1, 0, 1); PG8_SCHED; PG8_LDA(At, 0, 0); PG8_STAGE(PG8_SA(1, 1), a1 + hstep, voffA);
;             PG8_WAIT_V(8); PG8_WAIT_L(0); PG8_BAR; PG8_MMA(0, 0, At, B0); PG8_MMA(0, 1, At, B1); PG8_BAR; PG8_SCHED;
;             PG8_LDA(At, 0, 1); PG8_STAGE(PG8_SB(0, 0), b2, voffB); PG8_STAGE(PG8_SB(0, 1), b2 + hstep, voffB); PG8_STAGE(PG8_SA(0, 0), a2, voffA);
;             PG8_WAIT_V(8); PG8_WAIT_L(0); PG8_BAR; PG8_MMA(1, 0, At, B0); PG8_MMA(1, 1, At, B1); PG8_BAR; PG8_SCHED;
;             PG8_LDB(B0, 1, 0); PG8_LDB(B1, 1, 1); PG8_SCHED; PG8_LDA(At, 1, 0); PG8_STAGE(PG8_SA(0, 1), a2 + hstep, voffA);
;             PG8_WAIT_V(8); PG8_WAIT_L(0); PG8_BAR; PG8_MMA(0, 0, At, B0); PG8_MMA(0, 1, At, B1); PG8_BAR; PG8_SCHED;
.LBB0_866:
	s_ashr_i32 s9, s8, 31
	s_lshl_b64 s[12:13], s[8:9], 20
	s_add_u32 s12, s55, s12
	v_readlane_b32 s7, v253, 61
	s_addc_u32 s13, s7, s13
	s_and_b64 s[14:15], s[10:11], exec
	s_cselect_b32 s9, s13, s17
	s_cselect_b32 s39, s12, s16
	s_ashr_i32 s7, s6, 31
	s_lshl_b64 s[14:15], s[6:7], 20
	s_add_u32 s14, s2, s14
	s_addc_u32 s15, s18, s15
	s_and_b64 s[26:27], s[10:11], exec
	s_cselect_b32 s7, s15, s23
	s_cselect_b32 s40, s14, s22
	s_add_u32 s16, s16, 0x80080
	s_addc_u32 s17, s17, 0
	s_add_u32 s41, s22, 0x100
	s_addc_u32 s42, s23, 0
	s_mov_b32 s44, -2
	s_add_u32 s22, s16, 0xfff80080
	s_addc_u32 s23, s17, -1
	s_add_i32 s45, 0, 0x10000
	s_cmp_eq_u32 s44, 28
	s_cselect_b32 s27, s9, s23
	s_cselect_b32 s26, s39, s22
	s_cselect_b32 s23, s7, s42
	s_cselect_b32 s22, s40, s41
	s_add_i32 s48, 0, 0x14000
	v_add_u32_e32 v130, s45, v247
	v_add_u32_e32 v154, s48, v247
	ds_read_b128 v[106:109], v130
	ds_read_b128 v[110:113], v130 offset:1024
	ds_read_b128 v[122:125], v130 offset:2048
	ds_read_b128 v[130:133], v130 offset:3072
	ds_read_b128 v[134:137], v154
	ds_read_b128 v[138:141], v154 offset:1024
	ds_read_b128 v[150:153], v154 offset:2048
	ds_read_b128 v[154:157], v154 offset:3072
	v_lshl_add_u64 v[198:199], s[16:17], 0, v[208:209]
	s_add_i32 m0, s20, 0xc000
	ds_read_b128 v[158:161], v249
	ds_read_b128 v[162:165], v249 offset:1024
	ds_read_b128 v[170:173], v249 offset:2048
	ds_read_b128 v[174:177], v249 offset:3072
	ds_read_b128 v[178:181], v249 offset:4096
	ds_read_b128 v[182:185], v249 offset:5120
	ds_read_b128 v[186:189], v249 offset:6144
	ds_read_b128 v[190:193], v249 offset:7168
	global_load_lds_dwordx4 v[198:199], off
	s_add_i32 m0, s20, 0xe000
	v_lshl_add_u64 v[198:199], s[16:17], 0, v[210:211]
	global_load_lds_dwordx4 v[198:199], off
	s_waitcnt vmcnt(8)
	s_waitcnt lgkmcnt(0)
	s_barrier
	s_setprio 1
	v_mfma_f32_16x16x32_bf16 v[166:169], v[106:109], v[158:161], 0
	v_mfma_f32_16x16x32_bf16 v[146:149], v[122:125], v[158:161], 0
	v_mfma_f32_16x16x32_bf16 v[118:121], v[106:109], v[170:173], 0
	v_mfma_f32_16x16x32_bf16 v[114:117], v[122:125], v[170:173], 0
	v_mfma_f32_16x16x32_bf16 v[94:97], v[106:109], v[178:181], 0
	v_mfma_f32_16x16x32_bf16 v[90:93], v[122:125], v[178:181], 0
	v_mfma_f32_16x16x32_bf16 v[78:81], v[106:109], v[186:189], 0
	v_mfma_f32_16x16x32_bf16 v[74:77], v[122:125], v[186:189], 0
	v_mfma_f32_16x16x32_bf16 v[166:169], v[110:113], v[162:165], v[166:169]
	v_mfma_f32_16x16x32_bf16 v[146:149], v[130:133], v[162:165], v[146:149]
	v_mfma_f32_16x16x32_bf16 v[118:121], v[110:113], v[174:177], v[118:121]
	v_mfma_f32_16x16x32_bf16 v[114:117], v[130:133], v[174:177], v[114:117]
	v_mfma_f32_16x16x32_bf16 v[94:97], v[110:113], v[182:185], v[94:97]
	v_mfma_f32_16x16x32_bf16 v[90:93], v[130:133], v[182:185], v[90:93]
	v_mfma_f32_16x16x32_bf16 v[78:81], v[110:113], v[190:193], v[78:81]
	v_mfma_f32_16x16x32_bf16 v[74:77], v[130:133], v[190:193], v[74:77]
	s_setprio 0
	s_setprio 1
	v_mfma_f32_16x16x32_bf16 v[142:145], v[134:137], v[158:161], 0
	v_mfma_f32_16x16x32_bf16 v[126:129], v[150:153], v[158:161], 0
	v_mfma_f32_16x16x32_bf16 v[102:105], v[134:137], v[170:173], 0
	v_mfma_f32_16x16x32_bf16 v[98:101], v[150:153], v[170:173], 0
	v_mfma_f32_16x16x32_bf16 v[86:89], v[134:137], v[178:181], 0
	v_mfma_f32_16x16x32_bf16 v[82:85], v[150:153], v[178:181], 0
	v_mfma_f32_16x16x32_bf16 v[70:73], v[134:137], v[186:189], 0
	v_mfma_f32_16x16x32_bf16 v[66:69], v[150:153], v[186:189], 0
	v_mfma_f32_16x16x32_bf16 v[142:145], v[138:141], v[162:165], v[142:145]
	v_mfma_f32_16x16x32_bf16 v[126:129], v[154:157], v[162:165], v[126:129]
	v_mfma_f32_16x16x32_bf16 v[102:105], v[138:141], v[174:177], v[102:105]
	v_mfma_f32_16x16x32_bf16 v[98:101], v[154:157], v[174:177], v[98:101]
	v_mfma_f32_16x16x32_bf16 v[86:89], v[138:141], v[182:185], v[86:89]
	v_mfma_f32_16x16x32_bf16 v[82:85], v[154:157], v[182:185], v[82:85]
	v_mfma_f32_16x16x32_bf16 v[70:73], v[138:141], v[190:193], v[70:73]
	v_mfma_f32_16x16x32_bf16 v[66:69], v[154:157], v[190:193], v[66:69]
	s_setprio 0
	s_barrier
	s_add_i32 s45, s45, s19
	v_lshl_add_u64 v[198:199], s[22:23], 0, v[32:33]
	s_mov_b32 m0, s45
	ds_read_b128 v[158:161], v249 offset:16384
	ds_read_b128 v[162:165], v249 offset:17408
	ds_read_b128 v[170:173], v249 offset:18432
	ds_read_b128 v[174:177], v249 offset:19456
	ds_read_b128 v[178:181], v249 offset:20480
	ds_read_b128 v[182:185], v249 offset:21504
	ds_read_b128 v[186:189], v249 offset:22528
	ds_read_b128 v[190:193], v249 offset:23552
	global_load_lds_dwordx4 v[198:199], off
	s_add_i32 m0, s45, 0x2000
	s_add_u32 s46, s22, 0x80000
	v_lshl_add_u64 v[200:201], s[22:23], 0, v[202:203]
	s_addc_u32 s47, s23, 0
	s_add_i32 s45, s48, s19
	global_load_lds_dwordx4 v[200:201], off
	v_lshl_add_u64 v[212:213], s[46:47], 0, v[32:33]
	s_mov_b32 m0, s45
	v_lshl_add_u64 v[214:215], s[26:27], 0, v[204:205]
	global_load_lds_dwordx4 v[212:213], off
	s_add_i32 m0, s45, 0x2000
	v_lshl_add_u64 v[212:213], s[46:47], 0, v[202:203]
	global_load_lds_dwordx4 v[212:213], off
	s_mov_b32 m0, s20
	v_lshl_add_u64 v[212:213], s[26:27], 0, v[206:207]
	global_load_lds_dwordx4 v[212:213], off
	s_mov_b32 m0, s30
	s_nop 0
	global_load_lds_dwordx4 v[214:215], off
	s_waitcnt vmcnt(8)
	s_waitcnt lgkmcnt(0)
	s_barrier
; #define PG8_STAGE(bufoff, gbase, voff) do { _Pragma("unroll") for (int _i = 0; _i < 2; ++_i) \
;         __builtin_amdgcn_global_load_lds((const unsigned*)((const char*)(gbase) + (voff)[_i]), (PG8_LAS unsigned*)(lds + (bufoff) + ldsw + _i * 8192), 16, 0, 0); } while (0)
; #define PG8_LDA(dst, b, h) do { _Pragma("unroll") for (int m = 0; m < 4; ++m) _Pragma("unroll") for (int k = 0; k < 2; ++k) dst[m][k] = *(const PG8_LAS bf16x8*)(lds + PG8_SA(b, h) + aoff + m * 2048 + k * 1024); } while (0)
; #define PG8_LDB(dst, b, h) do { _Pragma("unroll") for (int n = 0; n < 2; ++n) _Pragma("unroll") for (int k = 0; k < 2; ++k) dst[n][k] = *(const PG8_LAS bf16x8*)(lds + PG8_SB(b, h) + boff + n * 2048 + k * 1024); } while (0)
; #define PG8_MMA(ai, bj, At, Bt) do { __builtin_amdgcn_s_setprio(1); _Pragma("unroll") for (int m = 0; m < 4; ++m) _Pragma("unroll") for (int n = 0; n < 2; ++n) _Pragma("unroll") for (int k = 0; k < 2; ++k) \
;         acc[ai][bj][m][n] = __builtin_amdgcn_mfma_f32_16x16x32_bf16(Bt[n][k], At[m][k], acc[ai][bj][m][n], 0, 0, 0); __builtin_amdgcn_s_setprio(0); } while (0)
; #define PG8_WAIT_V(n) asm volatile("s_waitcnt vmcnt(" #n ")" ::: "memory")
; #define PG8_WAIT_L(n) asm volatile("s_waitcnt lgkmcnt(" #n ")" ::: "memory")
; #define PG8_BAR __builtin_amdgcn_s_barrier()
; #define PG8_SCHED __builtin_amdgcn_sched_barrier(0)
; template <class Epi, class Sched, bool ALIGN_EPI = false, bool SP2 = false, bool KHOOK = false>
; __device__ __forceinline__ void gemm_phase(PG8_LAS unsigned char* lds, const Gemm g, const Sched& S, const Epi& E, const int tid_in) {
;     ...
;             PG8_WAIT_V(8); PG8_WAIT_L(0); PG8_BAR; PG8_MMA(1, 0, At, B0); PG8_MMA(1, 1, At, B1); PG8_BAR; PG8_SCHED;
;             PG8_LDB(B0, 1, 0); PG8_LDB(B1, 1, 1); PG8_SCHED; PG8_LDA(At, 1, 0); PG8_STAGE(PG8_SA(0, 1), a2 + hstep, voffA);
;             PG8_WAIT_V(8); PG8_WAIT_L(0); PG8_BAR; PG8_MMA(0, 0, At, B0); PG8_MMA(0, 1, At, B1); PG8_BAR; PG8_SCHED;
	s_setprio 1
	v_mfma_f32_16x16x32_bf16 v[62:65], v[106:109], v[158:161], 0
	v_mfma_f32_16x16x32_bf16 v[58:61], v[122:125], v[158:161], 0
	v_mfma_f32_16x16x32_bf16 v[46:49], v[106:109], v[170:173], 0
	v_mfma_f32_16x16x32_bf16 v[42:45], v[122:125], v[170:173], 0
	v_mfma_f32_16x16x32_bf16 v[28:31], v[106:109], v[178:181], 0
	v_mfma_f32_16x16x32_bf16 v[24:27], v[122:125], v[178:181], 0
	v_mfma_f32_16x16x32_bf16 v[12:15], v[106:109], v[186:189], 0
	v_mfma_f32_16x16x32_bf16 v[8:11], v[122:125], v[186:189], 0
	v_mfma_f32_16x16x32_bf16 v[62:65], v[110:113], v[162:165], v[62:65]
	v_mfma_f32_16x16x32_bf16 v[58:61], v[130:133], v[162:165], v[58:61]
	v_mfma_f32_16x16x32_bf16 v[46:49], v[110:113], v[174:177], v[46:49]
	v_mfma_f32_16x16x32_bf16 v[42:45], v[130:133], v[174:177], v[42:45]
	v_mfma_f32_16x16x32_bf16 v[28:31], v[110:113], v[182:185], v[28:31]
	v_mfma_f32_16x16x32_bf16 v[24:27], v[130:133], v[182:185], v[24:27]
	v_mfma_f32_16x16x32_bf16 v[12:15], v[110:113], v[190:193], v[12:15]
	v_mfma_f32_16x16x32_bf16 v[8:11], v[130:133], v[190:193], v[8:11]
	s_setprio 0
	s_setprio 1
	v_mfma_f32_16x16x32_bf16 v[54:57], v[134:137], v[158:161], 0
	v_mfma_f32_16x16x32_bf16 v[50:53], v[150:153], v[158:161], 0
	v_mfma_f32_16x16x32_bf16 v[38:41], v[134:137], v[170:173], 0
	v_mfma_f32_16x16x32_bf16 v[34:37], v[150:153], v[170:173], 0
	v_mfma_f32_16x16x32_bf16 v[20:23], v[134:137], v[178:181], 0
	v_mfma_f32_16x16x32_bf16 v[16:19], v[150:153], v[178:181], 0
	v_mfma_f32_16x16x32_bf16 v[4:7], v[134:137], v[186:189], 0
	v_mfma_f32_16x16x32_bf16 v[0:3], v[150:153], v[186:189], 0
	v_mfma_f32_16x16x32_bf16 v[54:57], v[138:141], v[162:165], v[54:57]
	v_mfma_f32_16x16x32_bf16 v[50:53], v[154:157], v[162:165], v[50:53]
	v_mfma_f32_16x16x32_bf16 v[38:41], v[138:141], v[174:177], v[38:41]
	v_mfma_f32_16x16x32_bf16 v[34:37], v[154:157], v[174:177], v[34:37]
	v_mfma_f32_16x16x32_bf16 v[20:23], v[138:141], v[182:185], v[20:23]
	v_mfma_f32_16x16x32_bf16 v[16:19], v[154:157], v[182:185], v[16:19]
	v_mfma_f32_16x16x32_bf16 v[4:7], v[138:141], v[190:193], v[4:7]
	v_mfma_f32_16x16x32_bf16 v[0:3], v[154:157], v[190:193], v[0:3]
	s_setprio 0
	s_barrier
	s_add_i32 s45, 0, 0x18000
	s_add_i32 s46, 0, 0x1c000
	v_add_u32_e32 v130, s45, v247
	v_add_u32_e32 v154, s46, v247
	ds_read_b128 v[106:109], v130
	ds_read_b128 v[110:113], v130 offset:1024
	ds_read_b128 v[122:125], v130 offset:2048
	ds_read_b128 v[130:133], v130 offset:3072
	ds_read_b128 v[134:137], v154
	ds_read_b128 v[138:141], v154 offset:1024
	ds_read_b128 v[150:153], v154 offset:2048
	ds_read_b128 v[154:157], v154 offset:3072
	s_add_u32 s26, s26, 0x80000
	s_addc_u32 s27, s27, 0
	s_mov_b32 m0, s31
	v_lshl_add_u64 v[216:217], s[26:27], 0, v[206:207]
	ds_read_b128 v[158:161], v249 offset:32768
	ds_read_b128 v[162:165], v249 offset:33792
	ds_read_b128 v[170:173], v249 offset:34816
	ds_read_b128 v[174:177], v249 offset:35840
	ds_read_b128 v[178:181], v249 offset:36864
	ds_read_b128 v[182:185], v249 offset:37888
	ds_read_b128 v[186:189], v249 offset:38912
	ds_read_b128 v[190:193], v249 offset:39936
	global_load_lds_dwordx4 v[216:217], off
	s_mov_b32 m0, s33
	v_lshl_add_u64 v[216:217], s[26:27], 0, v[204:205]
	global_load_lds_dwordx4 v[216:217], off
	s_waitcnt vmcnt(8)
	s_waitcnt lgkmcnt(0)
	s_barrier
	s_setprio 1
	v_mfma_f32_16x16x32_bf16 v[166:169], v[106:109], v[158:161], v[166:169]
	v_mfma_f32_16x16x32_bf16 v[146:149], v[122:125], v[158:161], v[146:149]
	v_mfma_f32_16x16x32_bf16 v[118:121], v[106:109], v[170:173], v[118:121]
	v_mfma_f32_16x16x32_bf16 v[114:117], v[122:125], v[170:173], v[114:117]
	v_mfma_f32_16x16x32_bf16 v[94:97], v[106:109], v[178:181], v[94:97]
	v_mfma_f32_16x16x32_bf16 v[90:93], v[122:125], v[178:181], v[90:93]
	v_mfma_f32_16x16x32_bf16 v[78:81], v[106:109], v[186:189], v[78:81]
	v_mfma_f32_16x16x32_bf16 v[74:77], v[122:125], v[186:189], v[74:77]
	v_mfma_f32_16x16x32_bf16 v[166:169], v[110:113], v[162:165], v[166:169]
	v_mfma_f32_16x16x32_bf16 v[146:149], v[130:133], v[162:165], v[146:149]
	v_mfma_f32_16x16x32_bf16 v[118:121], v[110:113], v[174:177], v[118:121]
	v_mfma_f32_16x16x32_bf16 v[114:117], v[130:133], v[174:177], v[114:117]
	v_mfma_f32_16x16x32_bf16 v[94:97], v[110:113], v[182:185], v[94:97]
	v_mfma_f32_16x16x32_bf16 v[90:93], v[130:133], v[182:185], v[90:93]
	v_mfma_f32_16x16x32_bf16 v[78:81], v[110:113], v[190:193], v[78:81]
	v_mfma_f32_16x16x32_bf16 v[74:77], v[130:133], v[190:193], v[74:77]
	s_setprio 0
	s_setprio 1
	v_mfma_f32_16x16x32_bf16 v[142:145], v[134:137], v[158:161], v[142:145]
	v_mfma_f32_16x16x32_bf16 v[126:129], v[150:153], v[158:161], v[126:129]
	v_mfma_f32_16x16x32_bf16 v[102:105], v[134:137], v[170:173], v[102:105]
	v_mfma_f32_16x16x32_bf16 v[98:101], v[150:153], v[170:173], v[98:101]
	v_mfma_f32_16x16x32_bf16 v[86:89], v[134:137], v[178:181], v[86:89]
	v_mfma_f32_16x16x32_bf16 v[82:85], v[150:153], v[178:181], v[82:85]
	v_mfma_f32_16x16x32_bf16 v[70:73], v[134:137], v[186:189], v[70:73]
	v_mfma_f32_16x16x32_bf16 v[66:69], v[150:153], v[186:189], v[66:69]
	v_mfma_f32_16x16x32_bf16 v[142:145], v[138:141], v[162:165], v[142:145]
	v_mfma_f32_16x16x32_bf16 v[126:129], v[154:157], v[162:165], v[126:129]
	v_mfma_f32_16x16x32_bf16 v[102:105], v[138:141], v[174:177], v[102:105]
	v_mfma_f32_16x16x32_bf16 v[98:101], v[154:157], v[174:177], v[98:101]
	v_mfma_f32_16x16x32_bf16 v[86:89], v[138:141], v[182:185], v[86:89]
	v_mfma_f32_16x16x32_bf16 v[82:85], v[154:157], v[182:185], v[82:85]
	v_mfma_f32_16x16x32_bf16 v[70:73], v[138:141], v[190:193], v[70:73]
	v_mfma_f32_16x16x32_bf16 v[66:69], v[154:157], v[190:193], v[66:69]
	s_setprio 0
	s_barrier
; #define PG8_STAGE(bufoff, gbase, voff) do { _Pragma("unroll") for (int _i = 0; _i < 2; ++_i) \
;         __builtin_amdgcn_global_load_lds((const unsigned*)((const char*)(gbase) + (voff)[_i]), (PG8_LAS unsigned*)(lds + (bufoff) + ldsw + _i * 8192), 16, 0, 0); } while (0)
; #define PG8_LDA(dst, b, h) do { _Pragma("unroll") for (int m = 0; m < 4; ++m) _Pragma("unroll") for (int k = 0; k < 2; ++k) dst[m][k] = *(const PG8_LAS bf16x8*)(lds + PG8_SA(b, h) + aoff + m * 2048 + k * 1024); } while (0)
; #define PG8_LDB(dst, b, h) do { _Pragma("unroll") for (int n = 0; n < 2; ++n) _Pragma("unroll") for (int k = 0; k < 2; ++k) dst[n][k] = *(const PG8_LAS bf16x8*)(lds + PG8_SB(b, h) + boff + n * 2048 + k * 1024); } while (0)
; #define PG8_MMA(ai, bj, At, Bt) do { __builtin_amdgcn_s_setprio(1); _Pragma("unroll") for (int m = 0; m < 4; ++m) _Pragma("unroll") for (int n = 0; n < 2; ++n) _Pragma("unroll") for (int k = 0; k < 2; ++k) \
;         acc[ai][bj][m][n] = __builtin_amdgcn_mfma_f32_16x16x32_bf16(Bt[n][k], At[m][k], acc[ai][bj][m][n], 0, 0, 0); __builtin_amdgcn_s_setprio(0); } while (0)
; #define PG8_WAIT_V(n) asm volatile("s_waitcnt vmcnt(" #n ")" ::: "memory")
; #define PG8_WAIT_L(n) asm volatile("s_waitcnt lgkmcnt(" #n ")" ::: "memory")
; #define PG8_BAR __builtin_amdgcn_s_barrier()
; #define PG8_SCHED __builtin_amdgcn_sched_barrier(0)
; template <class Epi, class Sched, bool ALIGN_EPI = false, bool SP2 = false, bool KHOOK = false>
; __device__ __forceinline__ void gemm_phase(PG8_LAS unsigned char* lds, const Gemm g, const Sched& S, const Epi& E, const int tid_in) {
;     ...
;             PG8_LDB(B0, 0, 0); PG8_LDB(B1, 0, 1); PG8_SCHED; PG8_LDA(At, 0, 0); PG8_STAGE(PG8_SA(1, 1), a1 + hstep, voffA);
;             PG8_WAIT_V(8); PG8_WAIT_L(0); PG8_BAR; PG8_MMA(0, 0, At, B0); PG8_MMA(0, 1, At, B1); PG8_BAR; PG8_SCHED;
;             PG8_LDA(At, 0, 1); PG8_STAGE(PG8_SB(0, 0), b2, voffB); PG8_STAGE(PG8_SB(0, 1), b2 + hstep, voffB); PG8_STAGE(PG8_SA(0, 0), a2, voffA);
;             PG8_WAIT_V(8); PG8_WAIT_L(0); PG8_BAR; PG8_MMA(1, 0, At, B0); PG8_MMA(1, 1, At, B1); PG8_BAR; PG8_SCHED;
;     ...
;             PG8_LDA(At, 1, 1); PG8_STAGE(PG8_SB(1, 0), b3, voffB); PG8_STAGE(PG8_SB(1, 1), b3 + hstep, voffB); PG8_STAGE(PG8_SA(1, 0), a3, voffA);
;             PG8_WAIT_V(8); PG8_WAIT_L(0); PG8_BAR; PG8_MMA(1, 0, At, B0); PG8_MMA(1, 1, At, B1); PG8_BAR; PG8_SCHED;
	s_add_i32 s26, s45, s19
	v_lshl_add_u64 v[198:199], v[198:199], 0, s[90:91]
	s_mov_b32 m0, s26
	ds_read_b128 v[158:161], v249 offset:49152
	ds_read_b128 v[162:165], v249 offset:50176
	ds_read_b128 v[170:173], v249 offset:51200
	ds_read_b128 v[174:177], v249 offset:52224
	ds_read_b128 v[178:181], v249 offset:53248
	ds_read_b128 v[182:185], v249 offset:54272
	ds_read_b128 v[186:189], v249 offset:55296
	ds_read_b128 v[190:193], v249 offset:56320
	global_load_lds_dwordx4 v[198:199], off
	s_add_i32 m0, s26, 0x2000
	s_add_u32 s22, s22, 0x80080
	v_lshl_add_u64 v[198:199], v[200:201], 0, s[90:91]
	s_addc_u32 s23, s23, 0
	s_add_i32 s26, s46, s19
	global_load_lds_dwordx4 v[198:199], off
	s_mov_b32 m0, s26
	v_lshl_add_u64 v[198:199], s[22:23], 0, v[32:33]
	global_load_lds_dwordx4 v[198:199], off
	s_add_i32 m0, s26, 0x2000
	v_lshl_add_u64 v[198:199], s[22:23], 0, v[202:203]
	global_load_lds_dwordx4 v[198:199], off
	s_mov_b32 m0, s36
	v_lshl_add_u64 v[198:199], v[212:213], 0, s[90:91]
	global_load_lds_dwordx4 v[198:199], off
	s_mov_b32 m0, s37
	v_lshl_add_u64 v[198:199], v[214:215], 0, s[90:91]
	global_load_lds_dwordx4 v[198:199], off
	s_waitcnt vmcnt(8)
	s_waitcnt lgkmcnt(0)
	s_barrier
	s_setprio 1
	v_mfma_f32_16x16x32_bf16 v[62:65], v[106:109], v[158:161], v[62:65]
	v_mfma_f32_16x16x32_bf16 v[58:61], v[122:125], v[158:161], v[58:61]
	v_mfma_f32_16x16x32_bf16 v[46:49], v[106:109], v[170:173], v[46:49]
	v_mfma_f32_16x16x32_bf16 v[42:45], v[122:125], v[170:173], v[42:45]
	v_mfma_f32_16x16x32_bf16 v[28:31], v[106:109], v[178:181], v[28:31]
	v_mfma_f32_16x16x32_bf16 v[24:27], v[122:125], v[178:181], v[24:27]
	v_mfma_f32_16x16x32_bf16 v[12:15], v[106:109], v[186:189], v[12:15]
	v_mfma_f32_16x16x32_bf16 v[8:11], v[122:125], v[186:189], v[8:11]
	v_mfma_f32_16x16x32_bf16 v[62:65], v[110:113], v[162:165], v[62:65]
	v_mfma_f32_16x16x32_bf16 v[58:61], v[130:133], v[162:165], v[58:61]
	v_mfma_f32_16x16x32_bf16 v[46:49], v[110:113], v[174:177], v[46:49]
	v_mfma_f32_16x16x32_bf16 v[42:45], v[130:133], v[174:177], v[42:45]
	v_mfma_f32_16x16x32_bf16 v[28:31], v[110:113], v[182:185], v[28:31]
	v_mfma_f32_16x16x32_bf16 v[24:27], v[130:133], v[182:185], v[24:27]
	v_mfma_f32_16x16x32_bf16 v[12:15], v[110:113], v[190:193], v[12:15]
	v_mfma_f32_16x16x32_bf16 v[8:11], v[130:133], v[190:193], v[8:11]
	s_setprio 0
	s_setprio 1
	v_mfma_f32_16x16x32_bf16 v[54:57], v[134:137], v[158:161], v[54:57]
	v_mfma_f32_16x16x32_bf16 v[50:53], v[150:153], v[158:161], v[50:53]
	v_mfma_f32_16x16x32_bf16 v[38:41], v[134:137], v[170:173], v[38:41]
	v_mfma_f32_16x16x32_bf16 v[34:37], v[150:153], v[170:173], v[34:37]
	v_mfma_f32_16x16x32_bf16 v[20:23], v[134:137], v[178:181], v[20:23]
	v_mfma_f32_16x16x32_bf16 v[16:19], v[150:153], v[178:181], v[16:19]
	v_mfma_f32_16x16x32_bf16 v[4:7], v[134:137], v[186:189], v[4:7]
	v_mfma_f32_16x16x32_bf16 v[0:3], v[150:153], v[186:189], v[0:3]
	v_mfma_f32_16x16x32_bf16 v[54:57], v[138:141], v[162:165], v[54:57]
	v_mfma_f32_16x16x32_bf16 v[50:53], v[154:157], v[162:165], v[50:53]
	v_mfma_f32_16x16x32_bf16 v[38:41], v[138:141], v[174:177], v[38:41]
	v_mfma_f32_16x16x32_bf16 v[34:37], v[154:157], v[174:177], v[34:37]
	v_mfma_f32_16x16x32_bf16 v[20:23], v[138:141], v[182:185], v[20:23]
	v_mfma_f32_16x16x32_bf16 v[16:19], v[154:157], v[182:185], v[16:19]
	v_mfma_f32_16x16x32_bf16 v[4:7], v[138:141], v[190:193], v[4:7]
	v_mfma_f32_16x16x32_bf16 v[0:3], v[154:157], v[190:193], v[0:3]
	s_setprio 0
	s_barrier
	s_add_i32 s44, s44, 2
	s_add_u32 s16, s16, 0x100
	s_addc_u32 s17, s17, 0
	s_add_u32 s41, s41, 0x100
	s_addc_u32 s42, s42, 0
	s_cmp_gt_u32 s44, 29
.LBB0_867:
	s_add_u32 s22, s16, 0xfff80080
	s_addc_u32 s23, s17, -1
	s_add_i32 s45, 0, 0x10000
	s_cmp_eq_u32 s44, 28
	s_cselect_b32 s27, s9, s23
	s_cselect_b32 s26, s39, s22
	s_cselect_b32 s23, s7, s42
	s_cselect_b32 s22, s40, s41
	s_add_i32 s48, 0, 0x14000
	v_add_u32_e32 v130, s45, v247
	v_add_u32_e32 v154, s48, v247
	ds_read_b128 v[106:109], v130
	ds_read_b128 v[110:113], v130 offset:1024
	ds_read_b128 v[122:125], v130 offset:2048
	ds_read_b128 v[130:133], v130 offset:3072
	ds_read_b128 v[134:137], v154
	ds_read_b128 v[138:141], v154 offset:1024
	ds_read_b128 v[150:153], v154 offset:2048
	ds_read_b128 v[154:157], v154 offset:3072
	v_lshl_add_u64 v[198:199], s[16:17], 0, v[208:209]
	s_add_i32 m0, s20, 0xc000
	ds_read_b128 v[158:161], v249
	ds_read_b128 v[162:165], v249 offset:1024
	ds_read_b128 v[170:173], v249 offset:2048
	ds_read_b128 v[174:177], v249 offset:3072
	ds_read_b128 v[178:181], v249 offset:4096
	ds_read_b128 v[182:185], v249 offset:5120
	ds_read_b128 v[186:189], v249 offset:6144
	ds_read_b128 v[190:193], v249 offset:7168
	global_load_lds_dwordx4 v[198:199], off
	s_add_i32 m0, s20, 0xe000
	v_lshl_add_u64 v[198:199], s[16:17], 0, v[210:211]
	global_load_lds_dwordx4 v[198:199], off
	s_waitcnt vmcnt(8)
	s_waitcnt lgkmcnt(0)
	s_barrier
; #define PG8_STAGE(bufoff, gbase, voff) do { _Pragma("unroll") for (int _i = 0; _i < 2; ++_i) \
;         __builtin_amdgcn_global_load_lds((const unsigned*)((const char*)(gbase) + (voff)[_i]), (PG8_LAS unsigned*)(lds + (bufoff) + ldsw + _i * 8192), 16, 0, 0); } while (0)
; #define PG8_LDA(dst, b, h) do { _Pragma("unroll") for (int m = 0; m < 4; ++m) _Pragma("unroll") for (int k = 0; k < 2; ++k) dst[m][k] = *(const PG8_LAS bf16x8*)(lds + PG8_SA(b, h) + aoff + m * 2048 + k * 1024); } while (0)
; #define PG8_MMA(ai, bj, At, Bt) do { __builtin_amdgcn_s_setprio(1); _Pragma("unroll") for (int m = 0; m < 4; ++m) _Pragma("unroll") for (int n = 0; n < 2; ++n) _Pragma("unroll") for (int k = 0; k < 2; ++k) \
;         acc[ai][bj][m][n] = __builtin_amdgcn_mfma_f32_16x16x32_bf16(Bt[n][k], At[m][k], acc[ai][bj][m][n], 0, 0, 0); __builtin_amdgcn_s_setprio(0); } while (0)
; #define PG8_WAIT_V(n) asm volatile("s_waitcnt vmcnt(" #n ")" ::: "memory")
; #define PG8_WAIT_L(n) asm volatile("s_waitcnt lgkmcnt(" #n ")" ::: "memory")
; #define PG8_BAR __builtin_amdgcn_s_barrier()
; #define PG8_SCHED __builtin_amdgcn_sched_barrier(0)
; template <class Epi, class Sched, bool ALIGN_EPI = false, bool SP2 = false, bool KHOOK = false>
; __device__ __forceinline__ void gemm_phase(PG8_LAS unsigned char* lds, const Gemm g, const Sched& S, const Epi& E, const int tid_in) {
;     ...
;             PG8_WAIT_V(8); PG8_WAIT_L(0); PG8_BAR; PG8_MMA(0, 0, At, B0); PG8_MMA(0, 1, At, B1); PG8_BAR; PG8_SCHED;
;             PG8_LDA(At, 0, 1); PG8_STAGE(PG8_SB(0, 0), b2, voffB); PG8_STAGE(PG8_SB(0, 1), b2 + hstep, voffB); PG8_STAGE(PG8_SA(0, 0), a2, voffA);
;             PG8_WAIT_V(8); PG8_WAIT_L(0); PG8_BAR; PG8_MMA(1, 0, At, B0); PG8_MMA(1, 1, At, B1); PG8_BAR; PG8_SCHED;
	s_setprio 1
	v_mfma_f32_16x16x32_bf16 v[166:169], v[106:109], v[158:161], v[166:169]
	v_mfma_f32_16x16x32_bf16 v[146:149], v[122:125], v[158:161], v[146:149]
	v_mfma_f32_16x16x32_bf16 v[118:121], v[106:109], v[170:173], v[118:121]
	v_mfma_f32_16x16x32_bf16 v[114:117], v[122:125], v[170:173], v[114:117]
	v_mfma_f32_16x16x32_bf16 v[94:97], v[106:109], v[178:181], v[94:97]
	v_mfma_f32_16x16x32_bf16 v[90:93], v[122:125], v[178:181], v[90:93]
	v_mfma_f32_16x16x32_bf16 v[78:81], v[106:109], v[186:189], v[78:81]
	v_mfma_f32_16x16x32_bf16 v[74:77], v[122:125], v[186:189], v[74:77]
	v_mfma_f32_16x16x32_bf16 v[166:169], v[110:113], v[162:165], v[166:169]
	v_mfma_f32_16x16x32_bf16 v[146:149], v[130:133], v[162:165], v[146:149]
	v_mfma_f32_16x16x32_bf16 v[118:121], v[110:113], v[174:177], v[118:121]
	v_mfma_f32_16x16x32_bf16 v[114:117], v[130:133], v[174:177], v[114:117]
	v_mfma_f32_16x16x32_bf16 v[94:97], v[110:113], v[182:185], v[94:97]
	v_mfma_f32_16x16x32_bf16 v[90:93], v[130:133], v[182:185], v[90:93]
	v_mfma_f32_16x16x32_bf16 v[78:81], v[110:113], v[190:193], v[78:81]
	v_mfma_f32_16x16x32_bf16 v[74:77], v[130:133], v[190:193], v[74:77]
	s_setprio 0
	s_setprio 1
	v_mfma_f32_16x16x32_bf16 v[142:145], v[134:137], v[158:161], v[142:145]
	v_mfma_f32_16x16x32_bf16 v[126:129], v[150:153], v[158:161], v[126:129]
	v_mfma_f32_16x16x32_bf16 v[102:105], v[134:137], v[170:173], v[102:105]
	v_mfma_f32_16x16x32_bf16 v[98:101], v[150:153], v[170:173], v[98:101]
	v_mfma_f32_16x16x32_bf16 v[86:89], v[134:137], v[178:181], v[86:89]
	v_mfma_f32_16x16x32_bf16 v[82:85], v[150:153], v[178:181], v[82:85]
	v_mfma_f32_16x16x32_bf16 v[70:73], v[134:137], v[186:189], v[70:73]
	v_mfma_f32_16x16x32_bf16 v[66:69], v[150:153], v[186:189], v[66:69]
	v_mfma_f32_16x16x32_bf16 v[142:145], v[138:141], v[162:165], v[142:145]
	v_mfma_f32_16x16x32_bf16 v[126:129], v[154:157], v[162:165], v[126:129]
	v_mfma_f32_16x16x32_bf16 v[102:105], v[138:141], v[174:177], v[102:105]
	v_mfma_f32_16x16x32_bf16 v[98:101], v[154:157], v[174:177], v[98:101]
	v_mfma_f32_16x16x32_bf16 v[86:89], v[138:141], v[182:185], v[86:89]
	v_mfma_f32_16x16x32_bf16 v[82:85], v[154:157], v[182:185], v[82:85]
	v_mfma_f32_16x16x32_bf16 v[70:73], v[138:141], v[190:193], v[70:73]
	v_mfma_f32_16x16x32_bf16 v[66:69], v[154:157], v[190:193], v[66:69]
	s_setprio 0
	s_barrier
	s_add_i32 s45, s45, s19
	v_lshl_add_u64 v[198:199], s[22:23], 0, v[32:33]
	s_mov_b32 m0, s45
	ds_read_b128 v[158:161], v249 offset:16384
	ds_read_b128 v[162:165], v249 offset:17408
	ds_read_b128 v[170:173], v249 offset:18432
	ds_read_b128 v[174:177], v249 offset:19456
	ds_read_b128 v[178:181], v249 offset:20480
	ds_read_b128 v[182:185], v249 offset:21504
	ds_read_b128 v[186:189], v249 offset:22528
	ds_read_b128 v[190:193], v249 offset:23552
	global_load_lds_dwordx4 v[198:199], off
	s_add_i32 m0, s45, 0x2000
	s_add_u32 s46, s22, 0x80000
	v_lshl_add_u64 v[200:201], s[22:23], 0, v[202:203]
	s_addc_u32 s47, s23, 0
	s_add_i32 s45, s48, s19
	global_load_lds_dwordx4 v[200:201], off
	v_lshl_add_u64 v[212:213], s[46:47], 0, v[32:33]
	s_mov_b32 m0, s45
	v_lshl_add_u64 v[214:215], s[26:27], 0, v[204:205]
	global_load_lds_dwordx4 v[212:213], off
	s_add_i32 m0, s45, 0x2000
	v_lshl_add_u64 v[212:213], s[46:47], 0, v[202:203]
	global_load_lds_dwordx4 v[212:213], off
	s_mov_b32 m0, s20
	v_lshl_add_u64 v[212:213], s[26:27], 0, v[206:207]
	global_load_lds_dwordx4 v[212:213], off
	s_mov_b32 m0, s30
	s_nop 0
	global_load_lds_dwordx4 v[214:215], off
	s_waitcnt vmcnt(8)
	s_waitcnt lgkmcnt(0)
	s_barrier
	s_setprio 1
	v_mfma_f32_16x16x32_bf16 v[62:65], v[106:109], v[158:161], v[62:65]
	v_mfma_f32_16x16x32_bf16 v[58:61], v[122:125], v[158:161], v[58:61]
	v_mfma_f32_16x16x32_bf16 v[46:49], v[106:109], v[170:173], v[46:49]
	v_mfma_f32_16x16x32_bf16 v[42:45], v[122:125], v[170:173], v[42:45]
	v_mfma_f32_16x16x32_bf16 v[28:31], v[106:109], v[178:181], v[28:31]
	v_mfma_f32_16x16x32_bf16 v[24:27], v[122:125], v[178:181], v[24:27]
	v_mfma_f32_16x16x32_bf16 v[12:15], v[106:109], v[186:189], v[12:15]
	v_mfma_f32_16x16x32_bf16 v[8:11], v[122:125], v[186:189], v[8:11]
	v_mfma_f32_16x16x32_bf16 v[62:65], v[110:113], v[162:165], v[62:65]
	v_mfma_f32_16x16x32_bf16 v[58:61], v[130:133], v[162:165], v[58:61]
	v_mfma_f32_16x16x32_bf16 v[46:49], v[110:113], v[174:177], v[46:49]
	v_mfma_f32_16x16x32_bf16 v[42:45], v[130:133], v[174:177], v[42:45]
	v_mfma_f32_16x16x32_bf16 v[28:31], v[110:113], v[182:185], v[28:31]
	v_mfma_f32_16x16x32_bf16 v[24:27], v[130:133], v[182:185], v[24:27]
	v_mfma_f32_16x16x32_bf16 v[12:15], v[110:113], v[190:193], v[12:15]
	v_mfma_f32_16x16x32_bf16 v[8:11], v[130:133], v[190:193], v[8:11]
	s_setprio 0
	s_setprio 1
	v_mfma_f32_16x16x32_bf16 v[54:57], v[134:137], v[158:161], v[54:57]
	v_mfma_f32_16x16x32_bf16 v[50:53], v[150:153], v[158:161], v[50:53]
	v_mfma_f32_16x16x32_bf16 v[38:41], v[134:137], v[170:173], v[38:41]
	v_mfma_f32_16x16x32_bf16 v[34:37], v[150:153], v[170:173], v[34:37]
	v_mfma_f32_16x16x32_bf16 v[20:23], v[134:137], v[178:181], v[20:23]
	v_mfma_f32_16x16x32_bf16 v[16:19], v[150:153], v[178:181], v[16:19]
	v_mfma_f32_16x16x32_bf16 v[4:7], v[134:137], v[186:189], v[4:7]
	v_mfma_f32_16x16x32_bf16 v[0:3], v[150:153], v[186:189], v[0:3]
	v_mfma_f32_16x16x32_bf16 v[54:57], v[138:141], v[162:165], v[54:57]
	v_mfma_f32_16x16x32_bf16 v[50:53], v[154:157], v[162:165], v[50:53]
	v_mfma_f32_16x16x32_bf16 v[38:41], v[138:141], v[174:177], v[38:41]
	v_mfma_f32_16x16x32_bf16 v[34:37], v[154:157], v[174:177], v[34:37]
	v_mfma_f32_16x16x32_bf16 v[20:23], v[138:141], v[182:185], v[20:23]
	v_mfma_f32_16x16x32_bf16 v[16:19], v[154:157], v[182:185], v[16:19]
	v_mfma_f32_16x16x32_bf16 v[4:7], v[138:141], v[190:193], v[4:7]
	v_mfma_f32_16x16x32_bf16 v[0:3], v[154:157], v[190:193], v[0:3]
	s_setprio 0
	s_barrier
; #define PG8_STAGE(bufoff, gbase, voff) do { _Pragma("unroll") for (int _i = 0; _i < 2; ++_i) \
;         __builtin_amdgcn_global_load_lds((const unsigned*)((const char*)(gbase) + (voff)[_i]), (PG8_LAS unsigned*)(lds + (bufoff) + ldsw + _i * 8192), 16, 0, 0); } while (0)
; #define PG8_LDA(dst, b, h) do { _Pragma("unroll") for (int m = 0; m < 4; ++m) _Pragma("unroll") for (int k = 0; k < 2; ++k) dst[m][k] = *(const PG8_LAS bf16x8*)(lds + PG8_SA(b, h) + aoff + m * 2048 + k * 1024); } while (0)
; #define PG8_LDB(dst, b, h) do { _Pragma("unroll") for (int n = 0; n < 2; ++n) _Pragma("unroll") for (int k = 0; k < 2; ++k) dst[n][k] = *(const PG8_LAS bf16x8*)(lds + PG8_SB(b, h) + boff + n * 2048 + k * 1024); } while (0)
; #define PG8_MMA(ai, bj, At, Bt) do { __builtin_amdgcn_s_setprio(1); _Pragma("unroll") for (int m = 0; m < 4; ++m) _Pragma("unroll") for (int n = 0; n < 2; ++n) _Pragma("unroll") for (int k = 0; k < 2; ++k) \
;         acc[ai][bj][m][n] = __builtin_amdgcn_mfma_f32_16x16x32_bf16(Bt[n][k], At[m][k], acc[ai][bj][m][n], 0, 0, 0); __builtin_amdgcn_s_setprio(0); } while (0)
; #define PG8_WAIT_V(n) asm volatile("s_waitcnt vmcnt(" #n ")" ::: "memory")
; #define PG8_WAIT_L(n) asm volatile("s_waitcnt lgkmcnt(" #n ")" ::: "memory")
; #define PG8_BAR __builtin_amdgcn_s_barrier()
; #define PG8_SCHED __builtin_amdgcn_sched_barrier(0)
; template <class Epi, class Sched, bool ALIGN_EPI = false, bool SP2 = false, bool KHOOK = false>
; __device__ __forceinline__ void gemm_phase(PG8_LAS unsigned char* lds, const Gemm g, const Sched& S, const Epi& E, const int tid_in) {
;     ...
;             PG8_LDB(B0, 1, 0); PG8_LDB(B1, 1, 1); PG8_SCHED; PG8_LDA(At, 1, 0); PG8_STAGE(PG8_SA(0, 1), a2 + hstep, voffA);
;             PG8_WAIT_V(8); PG8_WAIT_L(0); PG8_BAR; PG8_MMA(0, 0, At, B0); PG8_MMA(0, 1, At, B1); PG8_BAR; PG8_SCHED;
	s_add_i32 s45, 0, 0x18000
	s_add_i32 s46, 0, 0x1c000
	v_add_u32_e32 v130, s45, v247
	v_add_u32_e32 v154, s46, v247
	ds_read_b128 v[106:109], v130
	ds_read_b128 v[110:113], v130 offset:1024
	ds_read_b128 v[122:125], v130 offset:2048
	ds_read_b128 v[130:133], v130 offset:3072
	ds_read_b128 v[134:137], v154
	ds_read_b128 v[138:141], v154 offset:1024
	ds_read_b128 v[150:153], v154 offset:2048
	ds_read_b128 v[154:157], v154 offset:3072
	s_add_u32 s26, s26, 0x80000
	s_addc_u32 s27, s27, 0
	s_mov_b32 m0, s31
	v_lshl_add_u64 v[216:217], s[26:27], 0, v[206:207]
	ds_read_b128 v[158:161], v249 offset:32768
	ds_read_b128 v[162:165], v249 offset:33792
	ds_read_b128 v[170:173], v249 offset:34816
	ds_read_b128 v[174:177], v249 offset:35840
	ds_read_b128 v[178:181], v249 offset:36864
	ds_read_b128 v[182:185], v249 offset:37888
	ds_read_b128 v[186:189], v249 offset:38912
	ds_read_b128 v[190:193], v249 offset:39936
	global_load_lds_dwordx4 v[216:217], off
	s_mov_b32 m0, s33
	v_lshl_add_u64 v[216:217], s[26:27], 0, v[204:205]
	global_load_lds_dwordx4 v[216:217], off
	s_waitcnt vmcnt(8)
	s_waitcnt lgkmcnt(0)
	s_barrier
	s_setprio 1
	v_mfma_f32_16x16x32_bf16 v[166:169], v[106:109], v[158:161], v[166:169]
	v_mfma_f32_16x16x32_bf16 v[146:149], v[122:125], v[158:161], v[146:149]
	v_mfma_f32_16x16x32_bf16 v[118:121], v[106:109], v[170:173], v[118:121]
	v_mfma_f32_16x16x32_bf16 v[114:117], v[122:125], v[170:173], v[114:117]
	v_mfma_f32_16x16x32_bf16 v[94:97], v[106:109], v[178:181], v[94:97]
	v_mfma_f32_16x16x32_bf16 v[90:93], v[122:125], v[178:181], v[90:93]
	v_mfma_f32_16x16x32_bf16 v[78:81], v[106:109], v[186:189], v[78:81]
	v_mfma_f32_16x16x32_bf16 v[74:77], v[122:125], v[186:189], v[74:77]
	v_mfma_f32_16x16x32_bf16 v[166:169], v[110:113], v[162:165], v[166:169]
	v_mfma_f32_16x16x32_bf16 v[146:149], v[130:133], v[162:165], v[146:149]
	v_mfma_f32_16x16x32_bf16 v[118:121], v[110:113], v[174:177], v[118:121]
	v_mfma_f32_16x16x32_bf16 v[114:117], v[130:133], v[174:177], v[114:117]
	v_mfma_f32_16x16x32_bf16 v[94:97], v[110:113], v[182:185], v[94:97]
	v_mfma_f32_16x16x32_bf16 v[90:93], v[130:133], v[182:185], v[90:93]
	v_mfma_f32_16x16x32_bf16 v[78:81], v[110:113], v[190:193], v[78:81]
	v_mfma_f32_16x16x32_bf16 v[74:77], v[130:133], v[190:193], v[74:77]
	s_setprio 0
	s_setprio 1
	v_mfma_f32_16x16x32_bf16 v[142:145], v[134:137], v[158:161], v[142:145]
	v_mfma_f32_16x16x32_bf16 v[126:129], v[150:153], v[158:161], v[126:129]
	v_mfma_f32_16x16x32_bf16 v[102:105], v[134:137], v[170:173], v[102:105]
	v_mfma_f32_16x16x32_bf16 v[98:101], v[150:153], v[170:173], v[98:101]
	v_mfma_f32_16x16x32_bf16 v[86:89], v[134:137], v[178:181], v[86:89]
	v_mfma_f32_16x16x32_bf16 v[82:85], v[150:153], v[178:181], v[82:85]
	v_mfma_f32_16x16x32_bf16 v[70:73], v[134:137], v[186:189], v[70:73]
	v_mfma_f32_16x16x32_bf16 v[66:69], v[150:153], v[186:189], v[66:69]
	v_mfma_f32_16x16x32_bf16 v[142:145], v[138:141], v[162:165], v[142:145]
	v_mfma_f32_16x16x32_bf16 v[126:129], v[154:157], v[162:165], v[126:129]
	v_mfma_f32_16x16x32_bf16 v[102:105], v[138:141], v[174:177], v[102:105]
	v_mfma_f32_16x16x32_bf16 v[98:101], v[154:157], v[174:177], v[98:101]
	v_mfma_f32_16x16x32_bf16 v[86:89], v[138:141], v[182:185], v[86:89]
	v_mfma_f32_16x16x32_bf16 v[82:85], v[154:157], v[182:185], v[82:85]
	v_mfma_f32_16x16x32_bf16 v[70:73], v[138:141], v[190:193], v[70:73]
	v_mfma_f32_16x16x32_bf16 v[66:69], v[154:157], v[190:193], v[66:69]
	s_setprio 0
	s_barrier
; #define PG8_STAGE(bufoff, gbase, voff) do { _Pragma("unroll") for (int _i = 0; _i < 2; ++_i) \
;         __builtin_amdgcn_global_load_lds((const unsigned*)((const char*)(gbase) + (voff)[_i]), (PG8_LAS unsigned*)(lds + (bufoff) + ldsw + _i * 8192), 16, 0, 0); } while (0)
; #define PG8_LDA(dst, b, h) do { _Pragma("unroll") for (int m = 0; m < 4; ++m) _Pragma("unroll") for (int k = 0; k < 2; ++k) dst[m][k] = *(const PG8_LAS bf16x8*)(lds + PG8_SA(b, h) + aoff + m * 2048 + k * 1024); } while (0)
; #define PG8_MMA(ai, bj, At, Bt) do { __builtin_amdgcn_s_setprio(1); _Pragma("unroll") for (int m = 0; m < 4; ++m) _Pragma("unroll") for (int n = 0; n < 2; ++n) _Pragma("unroll") for (int k = 0; k < 2; ++k) \
;         acc[ai][bj][m][n] = __builtin_amdgcn_mfma_f32_16x16x32_bf16(Bt[n][k], At[m][k], acc[ai][bj][m][n], 0, 0, 0); __builtin_amdgcn_s_setprio(0); } while (0)
; #define PG8_WAIT_V(n) asm volatile("s_waitcnt vmcnt(" #n ")" ::: "memory")
; #define PG8_WAIT_L(n) asm volatile("s_waitcnt lgkmcnt(" #n ")" ::: "memory")
; #define PG8_BAR __builtin_amdgcn_s_barrier()
; #define PG8_SCHED __builtin_amdgcn_sched_barrier(0)
; template <class Epi, class Sched, bool ALIGN_EPI = false, bool SP2 = false, bool KHOOK = false>
; __device__ __forceinline__ void gemm_phase(PG8_LAS unsigned char* lds, const Gemm g, const Sched& S, const Epi& E, const int tid_in) {
;     ...
;             PG8_LDA(At, 1, 1); PG8_STAGE(PG8_SB(1, 0), b3, voffB); PG8_STAGE(PG8_SB(1, 1), b3 + hstep, voffB); PG8_STAGE(PG8_SA(1, 0), a3, voffA);
;             PG8_WAIT_V(8); PG8_WAIT_L(0); PG8_BAR; PG8_MMA(1, 0, At, B0); PG8_MMA(1, 1, At, B1); PG8_BAR; PG8_SCHED;
	s_add_i32 s26, s45, s19
	v_lshl_add_u64 v[198:199], v[198:199], 0, s[90:91]
	s_mov_b32 m0, s26
	ds_read_b128 v[158:161], v249 offset:49152
	ds_read_b128 v[162:165], v249 offset:50176
	ds_read_b128 v[170:173], v249 offset:51200
	ds_read_b128 v[174:177], v249 offset:52224
	ds_read_b128 v[178:181], v249 offset:53248
	ds_read_b128 v[182:185], v249 offset:54272
	ds_read_b128 v[186:189], v249 offset:55296
	ds_read_b128 v[190:193], v249 offset:56320
	global_load_lds_dwordx4 v[198:199], off
	s_add_i32 m0, s26, 0x2000
	s_add_u32 s22, s22, 0x80080
	v_lshl_add_u64 v[198:199], v[200:201], 0, s[90:91]
	s_addc_u32 s23, s23, 0
	s_add_i32 s26, s46, s19
	global_load_lds_dwordx4 v[198:199], off
	s_mov_b32 m0, s26
	v_lshl_add_u64 v[198:199], s[22:23], 0, v[32:33]
	global_load_lds_dwordx4 v[198:199], off
	s_add_i32 m0, s26, 0x2000
	v_lshl_add_u64 v[198:199], s[22:23], 0, v[202:203]
	global_load_lds_dwordx4 v[198:199], off
	s_mov_b32 m0, s36
	v_lshl_add_u64 v[198:199], v[212:213], 0, s[90:91]
	global_load_lds_dwordx4 v[198:199], off
	s_mov_b32 m0, s37
	v_lshl_add_u64 v[198:199], v[214:215], 0, s[90:91]
	global_load_lds_dwordx4 v[198:199], off
	s_waitcnt vmcnt(8)
	s_waitcnt lgkmcnt(0)
	s_barrier
	s_setprio 1
	v_mfma_f32_16x16x32_bf16 v[62:65], v[106:109], v[158:161], v[62:65]
	v_mfma_f32_16x16x32_bf16 v[58:61], v[122:125], v[158:161], v[58:61]
	v_mfma_f32_16x16x32_bf16 v[46:49], v[106:109], v[170:173], v[46:49]
	v_mfma_f32_16x16x32_bf16 v[42:45], v[122:125], v[170:173], v[42:45]
	v_mfma_f32_16x16x32_bf16 v[28:31], v[106:109], v[178:181], v[28:31]
	v_mfma_f32_16x16x32_bf16 v[24:27], v[122:125], v[178:181], v[24:27]
	v_mfma_f32_16x16x32_bf16 v[12:15], v[106:109], v[186:189], v[12:15]
	v_mfma_f32_16x16x32_bf16 v[8:11], v[122:125], v[186:189], v[8:11]
	v_mfma_f32_16x16x32_bf16 v[62:65], v[110:113], v[162:165], v[62:65]
	v_mfma_f32_16x16x32_bf16 v[58:61], v[130:133], v[162:165], v[58:61]
	v_mfma_f32_16x16x32_bf16 v[46:49], v[110:113], v[174:177], v[46:49]
	v_mfma_f32_16x16x32_bf16 v[42:45], v[130:133], v[174:177], v[42:45]
	v_mfma_f32_16x16x32_bf16 v[28:31], v[110:113], v[182:185], v[28:31]
	v_mfma_f32_16x16x32_bf16 v[24:27], v[130:133], v[182:185], v[24:27]
	v_mfma_f32_16x16x32_bf16 v[12:15], v[110:113], v[190:193], v[12:15]
	v_mfma_f32_16x16x32_bf16 v[8:11], v[130:133], v[190:193], v[8:11]
	s_setprio 0
	s_setprio 1
	v_mfma_f32_16x16x32_bf16 v[54:57], v[134:137], v[158:161], v[54:57]
	v_mfma_f32_16x16x32_bf16 v[50:53], v[150:153], v[158:161], v[50:53]
	v_mfma_f32_16x16x32_bf16 v[38:41], v[134:137], v[170:173], v[38:41]
	v_mfma_f32_16x16x32_bf16 v[34:37], v[150:153], v[170:173], v[34:37]
	v_mfma_f32_16x16x32_bf16 v[20:23], v[134:137], v[178:181], v[20:23]
	v_mfma_f32_16x16x32_bf16 v[16:19], v[150:153], v[178:181], v[16:19]
	v_mfma_f32_16x16x32_bf16 v[4:7], v[134:137], v[186:189], v[4:7]
	v_mfma_f32_16x16x32_bf16 v[0:3], v[150:153], v[186:189], v[0:3]
	v_mfma_f32_16x16x32_bf16 v[54:57], v[138:141], v[162:165], v[54:57]
	v_mfma_f32_16x16x32_bf16 v[50:53], v[154:157], v[162:165], v[50:53]
	v_mfma_f32_16x16x32_bf16 v[38:41], v[138:141], v[174:177], v[38:41]
	v_mfma_f32_16x16x32_bf16 v[34:37], v[154:157], v[174:177], v[34:37]
	v_mfma_f32_16x16x32_bf16 v[20:23], v[138:141], v[182:185], v[20:23]
	v_mfma_f32_16x16x32_bf16 v[16:19], v[154:157], v[182:185], v[16:19]
	v_mfma_f32_16x16x32_bf16 v[4:7], v[138:141], v[190:193], v[4:7]
	v_mfma_f32_16x16x32_bf16 v[0:3], v[154:157], v[190:193], v[0:3]
	s_setprio 0
	s_barrier
	s_add_i32 s44, s44, 2
	s_add_u32 s16, s16, 0x100
	s_addc_u32 s17, s17, 0
	s_add_u32 s41, s41, 0x100
	s_addc_u32 s42, s42, 0
	s_cmp_gt_u32 s44, 29
	s_cbranch_scc0 .LBB0_867
	s_and_b64 vcc, exec, s[4:5]
	s_cbranch_vccz .LBB0_870
	s_barrier

; #define PG8_STAGE(bufoff, gbase, voff) do { _Pragma("unroll") for (int _i = 0; _i < 2; ++_i) \
;         __builtin_amdgcn_global_load_lds((const unsigned*)((const char*)(gbase) + (voff)[_i]), (PG8_LAS unsigned*)(lds + (bufoff) + ldsw + _i * 8192), 16, 0, 0); } while (0)
; #define PG8_LDA(dst, b, h) do { _Pragma("unroll") for (int m = 0; m < 4; ++m) _Pragma("unroll") for (int k = 0; k < 2; ++k) dst[m][k] = *(const PG8_LAS bf16x8*)(lds + PG8_SA(b, h) + aoff + m * 2048 + k * 1024); } while (0)
; #define PG8_LDB(dst, b, h) do { _Pragma("unroll") for (int n = 0; n < 2; ++n) _Pragma("unroll") for (int k = 0; k < 2; ++k) dst[n][k] = *(const PG8_LAS bf16x8*)(lds + PG8_SB(b, h) + boff + n * 2048 + k * 1024); } while (0)
; #define PG8_MMA(ai, bj, At, Bt) do { __builtin_amdgcn_s_setprio(1); _Pragma("unroll") for (int m = 0; m < 4; ++m) _Pragma("unroll") for (int n = 0; n < 2; ++n) _Pragma("unroll") for (int k = 0; k < 2; ++k) \
;         acc[ai][bj][m][n] = __builtin_amdgcn_mfma_f32_16x16x32_bf16(Bt[n][k], At[m][k], acc[ai][bj][m][n], 0, 0, 0); __builtin_amdgcn_s_setprio(0); } while (0)
; #define PG8_WAIT_V(n) asm volatile("s_waitcnt vmcnt(" #n ")" ::: "memory")
; #define PG8_WAIT_L(n) asm volatile("s_waitcnt lgkmcnt(" #n ")" ::: "memory")
; #define PG8_BAR __builtin_amdgcn_s_barrier()
; #define PG8_SCHED __builtin_amdgcn_sched_barrier(0)
; template <class Epi, class Sched, bool ALIGN_EPI = false, bool SP2 = false, bool KHOOK = false>
; __device__ __forceinline__ void gemm_phase(PG8_LAS unsigned char* lds, const Gemm g, const Sched& S, const Epi& E, const int tid_in) {
;     ...
;             PG8_LDB(B0, 0, 0); PG8_LDB(B1, 0, 1); PG8_SCHED; PG8_LDA(At, 0, 0); PG8_STAGE(PG8_SA(1, 1), a1 + hstep, voffA);
;             PG8_WAIT_V(8); PG8_WAIT_L(0); PG8_BAR; PG8_MMA(0, 0, At, B0); PG8_MMA(0, 1, At, B1); PG8_BAR; PG8_SCHED;
;             PG8_LDA(At, 0, 1); PG8_STAGE(PG8_SB(0, 0), b2, voffB); PG8_STAGE(PG8_SB(0, 1), b2 + hstep, voffB); PG8_STAGE(PG8_SA(0, 0), a2, voffA);
;             PG8_WAIT_V(8); PG8_WAIT_L(0); PG8_BAR; PG8_MMA(1, 0, At, B0); PG8_MMA(1, 1, At, B1); PG8_BAR; PG8_SCHED;
;             PG8_LDB(B0, 1, 0); PG8_LDB(B1, 1, 1); PG8_SCHED; PG8_LDA(At, 1, 0); PG8_STAGE(PG8_SA(0, 1), a2 + hstep, voffA);
;             PG8_WAIT_V(8); PG8_WAIT_L(0); PG8_BAR; PG8_MMA(0, 0, At, B0); PG8_MMA(0, 1, At, B1); PG8_BAR; PG8_SCHED;
.LBB0_948:
	s_add_u32 s48, s4, s22
	s_addc_u32 s49, s5, s23
	s_add_u32 s48, s48, 0x100
	s_addc_u32 s49, s49, 0
	s_add_u32 s57, s18, s22
	s_addc_u32 s58, s19, s23
	s_add_i32 s59, 0, 0x10000
	s_cmpk_eq_i32 s22, 0xf00
	s_cselect_b32 s53, s13, s49
	s_cselect_b32 s52, s25, s48
	s_cselect_b32 s49, s11, s58
	s_cselect_b32 s48, s51, s57
	s_add_i32 s57, 0, 0x14000
	v_add_u32_e32 v158, s59, v144
	v_add_u32_e32 v170, s57, v144
	ds_read_b128 v[146:149], v158
	ds_read_b128 v[150:153], v158 offset:1024
	ds_read_b128 v[154:157], v158 offset:2048
	ds_read_b128 v[158:161], v158 offset:3072
	ds_read_b128 v[162:165], v170
	ds_read_b128 v[166:169], v170 offset:1024
	ds_read_b128 v[176:179], v170 offset:2048
	ds_read_b128 v[180:183], v170 offset:3072
	v_lshl_add_u64 v[170:171], v[140:141], 0, s[22:23]
	s_add_i32 m0, s40, 0xc000
	ds_read_b128 v[184:187], v145
	ds_read_b128 v[188:191], v145 offset:1024
	ds_read_b128 v[198:201], v145 offset:2048
	ds_read_b128 v[202:205], v145 offset:3072
	ds_read_b128 v[206:209], v145 offset:4096
	ds_read_b128 v[210:213], v145 offset:5120
	ds_read_b128 v[214:217], v145 offset:6144
	ds_read_b128 v[218:221], v145 offset:7168
	global_load_lds_dwordx4 v[170:171], off
	s_add_i32 m0, s40, 0xe000
	v_lshl_add_u64 v[170:171], v[142:143], 0, s[22:23]
	global_load_lds_dwordx4 v[170:171], off
	s_waitcnt vmcnt(8)
	s_waitcnt lgkmcnt(0)
	s_barrier
	s_setprio 1
	v_mfma_f32_16x16x32_bf16 v[118:121], v[146:149], v[184:187], v[118:121]
	v_mfma_f32_16x16x32_bf16 v[114:117], v[154:157], v[184:187], v[114:117]
	v_mfma_f32_16x16x32_bf16 v[134:137], v[146:149], v[198:201], v[134:137]
	v_mfma_f32_16x16x32_bf16 v[130:133], v[154:157], v[198:201], v[130:133]
	v_mfma_f32_16x16x32_bf16 v[94:97], v[146:149], v[206:209], v[94:97]
	v_mfma_f32_16x16x32_bf16 v[90:93], v[154:157], v[206:209], v[90:93]
	v_mfma_f32_16x16x32_bf16 v[78:81], v[146:149], v[214:217], v[78:81]
	v_mfma_f32_16x16x32_bf16 v[74:77], v[154:157], v[214:217], v[74:77]
	v_mfma_f32_16x16x32_bf16 v[118:121], v[150:153], v[188:191], v[118:121]
	v_mfma_f32_16x16x32_bf16 v[114:117], v[158:161], v[188:191], v[114:117]
	v_mfma_f32_16x16x32_bf16 v[134:137], v[150:153], v[202:205], v[134:137]
	v_mfma_f32_16x16x32_bf16 v[130:133], v[158:161], v[202:205], v[130:133]
	v_mfma_f32_16x16x32_bf16 v[94:97], v[150:153], v[210:213], v[94:97]
	v_mfma_f32_16x16x32_bf16 v[90:93], v[158:161], v[210:213], v[90:93]
	v_mfma_f32_16x16x32_bf16 v[78:81], v[150:153], v[218:221], v[78:81]
	v_mfma_f32_16x16x32_bf16 v[74:77], v[158:161], v[218:221], v[74:77]
	s_setprio 0
	s_setprio 1
	v_mfma_f32_16x16x32_bf16 v[106:109], v[162:165], v[184:187], v[106:109]
	v_mfma_f32_16x16x32_bf16 v[102:105], v[176:179], v[184:187], v[102:105]
	v_mfma_f32_16x16x32_bf16 v[110:113], v[162:165], v[198:201], v[110:113]
	v_mfma_f32_16x16x32_bf16 v[98:101], v[176:179], v[198:201], v[98:101]
	v_mfma_f32_16x16x32_bf16 v[86:89], v[162:165], v[206:209], v[86:89]
	v_mfma_f32_16x16x32_bf16 v[82:85], v[176:179], v[206:209], v[82:85]
	v_mfma_f32_16x16x32_bf16 v[70:73], v[162:165], v[214:217], v[70:73]
	v_mfma_f32_16x16x32_bf16 v[66:69], v[176:179], v[214:217], v[66:69]
	v_mfma_f32_16x16x32_bf16 v[106:109], v[166:169], v[188:191], v[106:109]
	v_mfma_f32_16x16x32_bf16 v[102:105], v[180:183], v[188:191], v[102:105]
	v_mfma_f32_16x16x32_bf16 v[110:113], v[166:169], v[202:205], v[110:113]
	v_mfma_f32_16x16x32_bf16 v[98:101], v[180:183], v[202:205], v[98:101]
	v_mfma_f32_16x16x32_bf16 v[86:89], v[166:169], v[210:213], v[86:89]
	v_mfma_f32_16x16x32_bf16 v[82:85], v[180:183], v[210:213], v[82:85]
	v_mfma_f32_16x16x32_bf16 v[70:73], v[166:169], v[218:221], v[70:73]
	v_mfma_f32_16x16x32_bf16 v[66:69], v[180:183], v[218:221], v[66:69]
	s_setprio 0
	s_barrier
	s_add_i32 s58, s59, s39
	v_lshl_add_u64 v[170:171], s[48:49], 0, v[32:33]
	s_mov_b32 m0, s58
	ds_read_b128 v[184:187], v145 offset:16384
	ds_read_b128 v[188:191], v145 offset:17408
	ds_read_b128 v[198:201], v145 offset:18432
	ds_read_b128 v[202:205], v145 offset:19456
	ds_read_b128 v[206:209], v145 offset:20480
	ds_read_b128 v[210:213], v145 offset:21504
	ds_read_b128 v[214:217], v145 offset:22528
	ds_read_b128 v[218:221], v145 offset:23552
	global_load_lds_dwordx4 v[170:171], off
	s_add_i32 m0, s58, 0x2000
	s_add_u32 s58, s48, 0x80000
	v_lshl_add_u64 v[192:193], s[48:49], 0, v[122:123]
	s_addc_u32 s59, s49, 0
	s_add_i32 s57, s57, s39
	global_load_lds_dwordx4 v[192:193], off
	v_lshl_add_u64 v[222:223], s[58:59], 0, v[32:33]
	s_mov_b32 m0, s57
	v_lshl_add_u64 v[224:225], s[52:53], 0, v[124:125]
	global_load_lds_dwordx4 v[222:223], off
	s_add_i32 m0, s57, 0x2000
	v_lshl_add_u64 v[222:223], s[58:59], 0, v[122:123]
	global_load_lds_dwordx4 v[222:223], off
	s_mov_b32 m0, s40
	v_lshl_add_u64 v[222:223], s[52:53], 0, v[126:127]
	global_load_lds_dwordx4 v[222:223], off
	s_mov_b32 m0, s41
	s_nop 0
	global_load_lds_dwordx4 v[224:225], off
	s_waitcnt vmcnt(8)
	s_waitcnt lgkmcnt(0)
	s_barrier
; #define PG8_STAGE(bufoff, gbase, voff) do { _Pragma("unroll") for (int _i = 0; _i < 2; ++_i) \
;         __builtin_amdgcn_global_load_lds((const unsigned*)((const char*)(gbase) + (voff)[_i]), (PG8_LAS unsigned*)(lds + (bufoff) + ldsw + _i * 8192), 16, 0, 0); } while (0)
; #define PG8_LDA(dst, b, h) do { _Pragma("unroll") for (int m = 0; m < 4; ++m) _Pragma("unroll") for (int k = 0; k < 2; ++k) dst[m][k] = *(const PG8_LAS bf16x8*)(lds + PG8_SA(b, h) + aoff + m * 2048 + k * 1024); } while (0)
; #define PG8_LDB(dst, b, h) do { _Pragma("unroll") for (int n = 0; n < 2; ++n) _Pragma("unroll") for (int k = 0; k < 2; ++k) dst[n][k] = *(const PG8_LAS bf16x8*)(lds + PG8_SB(b, h) + boff + n * 2048 + k * 1024); } while (0)
; #define PG8_MMA(ai, bj, At, Bt) do { __builtin_amdgcn_s_setprio(1); _Pragma("unroll") for (int m = 0; m < 4; ++m) _Pragma("unroll") for (int n = 0; n < 2; ++n) _Pragma("unroll") for (int k = 0; k < 2; ++k) \
;         acc[ai][bj][m][n] = __builtin_amdgcn_mfma_f32_16x16x32_bf16(Bt[n][k], At[m][k], acc[ai][bj][m][n], 0, 0, 0); __builtin_amdgcn_s_setprio(0); } while (0)
; #define PG8_WAIT_V(n) asm volatile("s_waitcnt vmcnt(" #n ")" ::: "memory")
; #define PG8_WAIT_L(n) asm volatile("s_waitcnt lgkmcnt(" #n ")" ::: "memory")
; #define PG8_BAR __builtin_amdgcn_s_barrier()
; #define PG8_SCHED __builtin_amdgcn_sched_barrier(0)
; template <class Epi, class Sched, bool ALIGN_EPI = false, bool SP2 = false, bool KHOOK = false>
; __device__ __forceinline__ void gemm_phase(PG8_LAS unsigned char* lds, const Gemm g, const Sched& S, const Epi& E, const int tid_in) {
;     ...
;             PG8_WAIT_V(8); PG8_WAIT_L(0); PG8_BAR; PG8_MMA(1, 0, At, B0); PG8_MMA(1, 1, At, B1); PG8_BAR; PG8_SCHED;
;             PG8_LDB(B0, 1, 0); PG8_LDB(B1, 1, 1); PG8_SCHED; PG8_LDA(At, 1, 0); PG8_STAGE(PG8_SA(0, 1), a2 + hstep, voffA);
;             PG8_WAIT_V(8); PG8_WAIT_L(0); PG8_BAR; PG8_MMA(0, 0, At, B0); PG8_MMA(0, 1, At, B1); PG8_BAR; PG8_SCHED;
	s_setprio 1
	v_mfma_f32_16x16x32_bf16 v[62:65], v[146:149], v[184:187], v[62:65]
	v_mfma_f32_16x16x32_bf16 v[58:61], v[154:157], v[184:187], v[58:61]
	v_mfma_f32_16x16x32_bf16 v[46:49], v[146:149], v[198:201], v[46:49]
	v_mfma_f32_16x16x32_bf16 v[42:45], v[154:157], v[198:201], v[42:45]
	v_mfma_f32_16x16x32_bf16 v[28:31], v[146:149], v[206:209], v[28:31]
	v_mfma_f32_16x16x32_bf16 v[24:27], v[154:157], v[206:209], v[24:27]
	v_mfma_f32_16x16x32_bf16 v[12:15], v[146:149], v[214:217], v[12:15]
	v_mfma_f32_16x16x32_bf16 v[8:11], v[154:157], v[214:217], v[8:11]
	v_mfma_f32_16x16x32_bf16 v[62:65], v[150:153], v[188:191], v[62:65]
	v_mfma_f32_16x16x32_bf16 v[58:61], v[158:161], v[188:191], v[58:61]
	v_mfma_f32_16x16x32_bf16 v[46:49], v[150:153], v[202:205], v[46:49]
	v_mfma_f32_16x16x32_bf16 v[42:45], v[158:161], v[202:205], v[42:45]
	v_mfma_f32_16x16x32_bf16 v[28:31], v[150:153], v[210:213], v[28:31]
	v_mfma_f32_16x16x32_bf16 v[24:27], v[158:161], v[210:213], v[24:27]
	v_mfma_f32_16x16x32_bf16 v[12:15], v[150:153], v[218:221], v[12:15]
	v_mfma_f32_16x16x32_bf16 v[8:11], v[158:161], v[218:221], v[8:11]
	s_setprio 0
	s_setprio 1
	v_mfma_f32_16x16x32_bf16 v[54:57], v[162:165], v[184:187], v[54:57]
	v_mfma_f32_16x16x32_bf16 v[50:53], v[176:179], v[184:187], v[50:53]
	v_mfma_f32_16x16x32_bf16 v[38:41], v[162:165], v[198:201], v[38:41]
	v_mfma_f32_16x16x32_bf16 v[34:37], v[176:179], v[198:201], v[34:37]
	v_mfma_f32_16x16x32_bf16 v[20:23], v[162:165], v[206:209], v[20:23]
	v_mfma_f32_16x16x32_bf16 v[16:19], v[176:179], v[206:209], v[16:19]
	v_mfma_f32_16x16x32_bf16 v[4:7], v[162:165], v[214:217], v[4:7]
	v_mfma_f32_16x16x32_bf16 v[0:3], v[176:179], v[214:217], v[0:3]
	v_mfma_f32_16x16x32_bf16 v[54:57], v[166:169], v[188:191], v[54:57]
	v_mfma_f32_16x16x32_bf16 v[50:53], v[180:183], v[188:191], v[50:53]
	v_mfma_f32_16x16x32_bf16 v[38:41], v[166:169], v[202:205], v[38:41]
	v_mfma_f32_16x16x32_bf16 v[34:37], v[180:183], v[202:205], v[34:37]
	v_mfma_f32_16x16x32_bf16 v[20:23], v[166:169], v[210:213], v[20:23]
	v_mfma_f32_16x16x32_bf16 v[16:19], v[180:183], v[210:213], v[16:19]
	v_mfma_f32_16x16x32_bf16 v[4:7], v[166:169], v[218:221], v[4:7]
	v_mfma_f32_16x16x32_bf16 v[0:3], v[180:183], v[218:221], v[0:3]
	s_setprio 0
	s_barrier
	s_add_i32 s57, 0, 0x18000
	s_add_i32 s58, 0, 0x1c000
	v_add_u32_e32 v158, s57, v144
	v_add_u32_e32 v175, s58, v144
	ds_read_b128 v[146:149], v158
	ds_read_b128 v[150:153], v158 offset:1024
	ds_read_b128 v[154:157], v158 offset:2048
	ds_read_b128 v[158:161], v158 offset:3072
	ds_read_b128 v[162:165], v175
	ds_read_b128 v[166:169], v175 offset:1024
	ds_read_b128 v[176:179], v175 offset:2048
	ds_read_b128 v[180:183], v175 offset:3072
	s_add_u32 s52, s52, 0x80000
	s_addc_u32 s53, s53, 0
	s_mov_b32 m0, s42
	v_lshl_add_u64 v[226:227], s[52:53], 0, v[126:127]
	ds_read_b128 v[184:187], v145 offset:32768
	ds_read_b128 v[188:191], v145 offset:33792
	ds_read_b128 v[198:201], v145 offset:34816
	ds_read_b128 v[202:205], v145 offset:35840
	ds_read_b128 v[206:209], v145 offset:36864
	ds_read_b128 v[210:213], v145 offset:37888
	ds_read_b128 v[214:217], v145 offset:38912
	ds_read_b128 v[218:221], v145 offset:39936
	global_load_lds_dwordx4 v[226:227], off
	s_mov_b32 m0, s44
	v_lshl_add_u64 v[226:227], s[52:53], 0, v[124:125]
	global_load_lds_dwordx4 v[226:227], off
	s_waitcnt vmcnt(8)
	s_waitcnt lgkmcnt(0)
	s_barrier
	s_setprio 1
	v_mfma_f32_16x16x32_bf16 v[118:121], v[146:149], v[184:187], v[118:121]
	v_mfma_f32_16x16x32_bf16 v[114:117], v[154:157], v[184:187], v[114:117]
	v_mfma_f32_16x16x32_bf16 v[134:137], v[146:149], v[198:201], v[134:137]
	v_mfma_f32_16x16x32_bf16 v[130:133], v[154:157], v[198:201], v[130:133]
	v_mfma_f32_16x16x32_bf16 v[94:97], v[146:149], v[206:209], v[94:97]
	v_mfma_f32_16x16x32_bf16 v[90:93], v[154:157], v[206:209], v[90:93]
	v_mfma_f32_16x16x32_bf16 v[78:81], v[146:149], v[214:217], v[78:81]
	v_mfma_f32_16x16x32_bf16 v[74:77], v[154:157], v[214:217], v[74:77]
	v_mfma_f32_16x16x32_bf16 v[118:121], v[150:153], v[188:191], v[118:121]
	v_mfma_f32_16x16x32_bf16 v[114:117], v[158:161], v[188:191], v[114:117]
	v_mfma_f32_16x16x32_bf16 v[134:137], v[150:153], v[202:205], v[134:137]
	v_mfma_f32_16x16x32_bf16 v[130:133], v[158:161], v[202:205], v[130:133]
	v_mfma_f32_16x16x32_bf16 v[94:97], v[150:153], v[210:213], v[94:97]
	v_mfma_f32_16x16x32_bf16 v[90:93], v[158:161], v[210:213], v[90:93]
	v_mfma_f32_16x16x32_bf16 v[78:81], v[150:153], v[218:221], v[78:81]
	v_mfma_f32_16x16x32_bf16 v[74:77], v[158:161], v[218:221], v[74:77]
	s_setprio 0
	s_setprio 1
	v_mfma_f32_16x16x32_bf16 v[106:109], v[162:165], v[184:187], v[106:109]
	v_mfma_f32_16x16x32_bf16 v[102:105], v[176:179], v[184:187], v[102:105]
	v_mfma_f32_16x16x32_bf16 v[110:113], v[162:165], v[198:201], v[110:113]
	v_mfma_f32_16x16x32_bf16 v[98:101], v[176:179], v[198:201], v[98:101]
	v_mfma_f32_16x16x32_bf16 v[86:89], v[162:165], v[206:209], v[86:89]
	v_mfma_f32_16x16x32_bf16 v[82:85], v[176:179], v[206:209], v[82:85]
	v_mfma_f32_16x16x32_bf16 v[70:73], v[162:165], v[214:217], v[70:73]
	v_mfma_f32_16x16x32_bf16 v[66:69], v[176:179], v[214:217], v[66:69]
	v_mfma_f32_16x16x32_bf16 v[106:109], v[166:169], v[188:191], v[106:109]
	v_mfma_f32_16x16x32_bf16 v[102:105], v[180:183], v[188:191], v[102:105]
	v_mfma_f32_16x16x32_bf16 v[110:113], v[166:169], v[202:205], v[110:113]
	v_mfma_f32_16x16x32_bf16 v[98:101], v[180:183], v[202:205], v[98:101]
	v_mfma_f32_16x16x32_bf16 v[86:89], v[166:169], v[210:213], v[86:89]
	v_mfma_f32_16x16x32_bf16 v[82:85], v[180:183], v[210:213], v[82:85]
	v_mfma_f32_16x16x32_bf16 v[70:73], v[166:169], v[218:221], v[70:73]
	v_mfma_f32_16x16x32_bf16 v[66:69], v[180:183], v[218:221], v[66:69]
	s_setprio 0
	s_barrier
; #define PG8_STAGE(bufoff, gbase, voff) do { _Pragma("unroll") for (int _i = 0; _i < 2; ++_i) \
;         __builtin_amdgcn_global_load_lds((const unsigned*)((const char*)(gbase) + (voff)[_i]), (PG8_LAS unsigned*)(lds + (bufoff) + ldsw + _i * 8192), 16, 0, 0); } while (0)
; #define PG8_LDA(dst, b, h) do { _Pragma("unroll") for (int m = 0; m < 4; ++m) _Pragma("unroll") for (int k = 0; k < 2; ++k) dst[m][k] = *(const PG8_LAS bf16x8*)(lds + PG8_SA(b, h) + aoff + m * 2048 + k * 1024); } while (0)
; #define PG8_MMA(ai, bj, At, Bt) do { __builtin_amdgcn_s_setprio(1); _Pragma("unroll") for (int m = 0; m < 4; ++m) _Pragma("unroll") for (int n = 0; n < 2; ++n) _Pragma("unroll") for (int k = 0; k < 2; ++k) \
;         acc[ai][bj][m][n] = __builtin_amdgcn_mfma_f32_16x16x32_bf16(Bt[n][k], At[m][k], acc[ai][bj][m][n], 0, 0, 0); __builtin_amdgcn_s_setprio(0); } while (0)
; #define PG8_WAIT_V(n) asm volatile("s_waitcnt vmcnt(" #n ")" ::: "memory")
; #define PG8_WAIT_L(n) asm volatile("s_waitcnt lgkmcnt(" #n ")" ::: "memory")
; #define PG8_BAR __builtin_amdgcn_s_barrier()
; #define PG8_SCHED __builtin_amdgcn_sched_barrier(0)
; template <class Epi, class Sched, bool ALIGN_EPI = false, bool SP2 = false, bool KHOOK = false>
; __device__ __forceinline__ void gemm_phase(PG8_LAS unsigned char* lds, const Gemm g, const Sched& S, const Epi& E, const int tid_in) {
;     ...
;             PG8_LDA(At, 1, 1); PG8_STAGE(PG8_SB(1, 0), b3, voffB); PG8_STAGE(PG8_SB(1, 1), b3 + hstep, voffB); PG8_STAGE(PG8_SA(1, 0), a3, voffA);
;             PG8_WAIT_V(8); PG8_WAIT_L(0); PG8_BAR; PG8_MMA(1, 0, At, B0); PG8_MMA(1, 1, At, B1); PG8_BAR; PG8_SCHED;
;     ...
; #pragma unroll
;         for (int a = 0; a < 2; ++a)
; #pragma unroll
;             for (int b = 0; b < 2; ++b)
; #pragma unroll
;                 for (int m = 0; m < 4; ++m)
; #pragma unroll
;                     for (int n = 0; n < 2; ++n) acc[a][b][m][n] = (f32x4){0.f, 0.f, 0.f, 0.f};
;         cur = nxt; cA = nA; cB = nB; ++ui; load_rr(cur);
	s_add_i32 s52, s57, s39
	v_lshl_add_u64 v[170:171], v[170:171], 0, s[90:91]
	s_mov_b32 m0, s52
	ds_read_b128 v[184:187], v145 offset:49152
	ds_read_b128 v[188:191], v145 offset:50176
	ds_read_b128 v[198:201], v145 offset:51200
	ds_read_b128 v[202:205], v145 offset:52224
	ds_read_b128 v[206:209], v145 offset:53248
	ds_read_b128 v[210:213], v145 offset:54272
	ds_read_b128 v[214:217], v145 offset:55296
	ds_read_b128 v[218:221], v145 offset:56320
	global_load_lds_dwordx4 v[170:171], off
	s_add_i32 m0, s52, 0x2000
	s_add_u32 s48, s48, 0x80080
	v_lshl_add_u64 v[170:171], v[192:193], 0, s[90:91]
	s_addc_u32 s49, s49, 0
	s_add_i32 s52, s58, s39
	global_load_lds_dwordx4 v[170:171], off
	s_mov_b32 m0, s52
	v_lshl_add_u64 v[170:171], s[48:49], 0, v[32:33]
	global_load_lds_dwordx4 v[170:171], off
	s_add_i32 m0, s52, 0x2000
	v_lshl_add_u64 v[170:171], s[48:49], 0, v[122:123]
	global_load_lds_dwordx4 v[170:171], off
	s_mov_b32 m0, s46
	v_lshl_add_u64 v[170:171], v[222:223], 0, s[90:91]
	global_load_lds_dwordx4 v[170:171], off
	s_mov_b32 m0, s47
	v_lshl_add_u64 v[170:171], v[224:225], 0, s[90:91]
	global_load_lds_dwordx4 v[170:171], off
	s_waitcnt vmcnt(8)
	s_waitcnt lgkmcnt(0)
	s_barrier
	s_setprio 1
	v_mfma_f32_16x16x32_bf16 v[62:65], v[146:149], v[184:187], v[62:65]
	v_mfma_f32_16x16x32_bf16 v[58:61], v[154:157], v[184:187], v[58:61]
	v_mfma_f32_16x16x32_bf16 v[46:49], v[146:149], v[198:201], v[46:49]
	v_mfma_f32_16x16x32_bf16 v[42:45], v[154:157], v[198:201], v[42:45]
	v_mfma_f32_16x16x32_bf16 v[28:31], v[146:149], v[206:209], v[28:31]
	v_mfma_f32_16x16x32_bf16 v[24:27], v[154:157], v[206:209], v[24:27]
	v_mfma_f32_16x16x32_bf16 v[12:15], v[146:149], v[214:217], v[12:15]
	v_mfma_f32_16x16x32_bf16 v[8:11], v[154:157], v[214:217], v[8:11]
	v_mfma_f32_16x16x32_bf16 v[62:65], v[150:153], v[188:191], v[62:65]
	v_mfma_f32_16x16x32_bf16 v[58:61], v[158:161], v[188:191], v[58:61]
	v_mfma_f32_16x16x32_bf16 v[46:49], v[150:153], v[202:205], v[46:49]
	v_mfma_f32_16x16x32_bf16 v[42:45], v[158:161], v[202:205], v[42:45]
	v_mfma_f32_16x16x32_bf16 v[28:31], v[150:153], v[210:213], v[28:31]
	v_mfma_f32_16x16x32_bf16 v[24:27], v[158:161], v[210:213], v[24:27]
	v_mfma_f32_16x16x32_bf16 v[12:15], v[150:153], v[218:221], v[12:15]
	v_mfma_f32_16x16x32_bf16 v[8:11], v[158:161], v[218:221], v[8:11]
	s_setprio 0
	s_setprio 1
	v_mfma_f32_16x16x32_bf16 v[54:57], v[162:165], v[184:187], v[54:57]
	v_mfma_f32_16x16x32_bf16 v[50:53], v[176:179], v[184:187], v[50:53]
	v_mfma_f32_16x16x32_bf16 v[38:41], v[162:165], v[198:201], v[38:41]
	v_mfma_f32_16x16x32_bf16 v[34:37], v[176:179], v[198:201], v[34:37]
	v_mfma_f32_16x16x32_bf16 v[20:23], v[162:165], v[206:209], v[20:23]
	v_mfma_f32_16x16x32_bf16 v[16:19], v[176:179], v[206:209], v[16:19]
	v_mfma_f32_16x16x32_bf16 v[4:7], v[162:165], v[214:217], v[4:7]
	v_mfma_f32_16x16x32_bf16 v[0:3], v[176:179], v[214:217], v[0:3]
	v_mfma_f32_16x16x32_bf16 v[54:57], v[166:169], v[188:191], v[54:57]
	v_mfma_f32_16x16x32_bf16 v[50:53], v[180:183], v[188:191], v[50:53]
	v_mfma_f32_16x16x32_bf16 v[38:41], v[166:169], v[202:205], v[38:41]
	v_mfma_f32_16x16x32_bf16 v[34:37], v[180:183], v[202:205], v[34:37]
	v_mfma_f32_16x16x32_bf16 v[20:23], v[166:169], v[210:213], v[20:23]
	v_mfma_f32_16x16x32_bf16 v[16:19], v[180:183], v[210:213], v[16:19]
	v_mfma_f32_16x16x32_bf16 v[4:7], v[166:169], v[218:221], v[4:7]
	v_mfma_f32_16x16x32_bf16 v[0:3], v[180:183], v[218:221], v[0:3]
	s_setprio 0
	s_barrier
	s_add_i32 s56, s56, 2
	s_add_u32 s22, s22, 0x100
	s_addc_u32 s23, s23, 0
	s_cmp_gt_u32 s56, 29
	s_cbranch_scc0 .LBB0_948
	s_add_u32 s18, s18, 0xffffff00
	s_addc_u32 s19, s19, -1
	s_andn2_b64 vcc, exec, s[26:27]
	s_cbranch_vccnz .LBB0_951
	v_mov_b32_e32 v0, 0
	s_mov_b32 s33, s12
	s_mov_b32 s0, s10
	s_mov_b64 s[4:5], s[30:31]
	s_mov_b32 s50, s24
	v_mov_b32_e32 v1, v0
	v_mov_b32_e32 v2, v0
	v_mov_b32_e32 v3, v0
	v_mov_b32_e32 v4, v0
	v_mov_b32_e32 v5, v0
	v_mov_b32_e32 v6, v0
	v_mov_b32_e32 v7, v0
	v_mov_b32_e32 v16, v0
	v_mov_b32_e32 v17, v0
	v_mov_b32_e32 v18, v0
	v_mov_b32_e32 v19, v0
	v_mov_b32_e32 v20, v0
	v_mov_b32_e32 v21, v0
	v_mov_b32_e32 v22, v0
	v_mov_b32_e32 v23, v0
	v_mov_b32_e32 v34, v0
	v_mov_b32_e32 v35, v0
	v_mov_b32_e32 v36, v0
	v_mov_b32_e32 v37, v0
	v_mov_b32_e32 v38, v0
	v_mov_b32_e32 v39, v0
	v_mov_b32_e32 v40, v0
	v_mov_b32_e32 v41, v0
	v_mov_b32_e32 v50, v0
	v_mov_b32_e32 v51, v0
	v_mov_b32_e32 v52, v0
	v_mov_b32_e32 v53, v0
	v_mov_b32_e32 v54, v0
	v_mov_b32_e32 v55, v0
	v_mov_b32_e32 v56, v0
	v_mov_b32_e32 v57, v0
	v_mov_b32_e32 v8, v0
	v_mov_b32_e32 v9, v0
	v_mov_b32_e32 v10, v0
	v_mov_b32_e32 v11, v0
	v_mov_b32_e32 v12, v0
	v_mov_b32_e32 v13, v0
	v_mov_b32_e32 v14, v0
	v_mov_b32_e32 v15, v0
	v_mov_b32_e32 v24, v0
	v_mov_b32_e32 v25, v0
	v_mov_b32_e32 v26, v0
	v_mov_b32_e32 v27, v0
	v_mov_b32_e32 v28, v0
	v_mov_b32_e32 v29, v0
	v_mov_b32_e32 v30, v0
	v_mov_b32_e32 v31, v0
	v_mov_b32_e32 v42, v0
	v_mov_b32_e32 v43, v0
	v_mov_b32_e32 v44, v0
	v_mov_b32_e32 v45, v0
	v_mov_b32_e32 v46, v0
	v_mov_b32_e32 v47, v0
	v_mov_b32_e32 v48, v0
	v_mov_b32_e32 v49, v0
	v_mov_b32_e32 v58, v0
	v_mov_b32_e32 v59, v0
	v_mov_b32_e32 v60, v0
	v_mov_b32_e32 v61, v0
	v_mov_b32_e32 v62, v0
	v_mov_b32_e32 v63, v0
	v_mov_b32_e32 v64, v0
	v_mov_b32_e32 v65, v0
	v_mov_b32_e32 v66, v0
	v_mov_b32_e32 v67, v0
	v_mov_b32_e32 v68, v0
	v_mov_b32_e32 v69, v0
	v_mov_b32_e32 v70, v0
	v_mov_b32_e32 v71, v0
	v_mov_b32_e32 v72, v0
	v_mov_b32_e32 v73, v0
	v_mov_b32_e32 v82, v0
	v_mov_b32_e32 v83, v0
	v_mov_b32_e32 v84, v0
	v_mov_b32_e32 v85, v0
	v_mov_b32_e32 v86, v0
	v_mov_b32_e32 v87, v0
	v_mov_b32_e32 v88, v0
	v_mov_b32_e32 v89, v0
	v_mov_b32_e32 v98, v0
	v_mov_b32_e32 v99, v0
	v_mov_b32_e32 v100, v0
	v_mov_b32_e32 v101, v0
	v_mov_b32_e32 v110, v0
	v_mov_b32_e32 v111, v0
	v_mov_b32_e32 v112, v0
	v_mov_b32_e32 v113, v0
	v_mov_b32_e32 v102, v0
	v_mov_b32_e32 v103, v0
	v_mov_b32_e32 v104, v0
	v_mov_b32_e32 v105, v0
	v_mov_b32_e32 v106, v0
	v_mov_b32_e32 v107, v0
	v_mov_b32_e32 v108, v0
	v_mov_b32_e32 v109, v0
	v_mov_b32_e32 v74, v0
	v_mov_b32_e32 v75, v0
	v_mov_b32_e32 v76, v0
	v_mov_b32_e32 v77, v0
	v_mov_b32_e32 v78, v0
	v_mov_b32_e32 v79, v0
	v_mov_b32_e32 v80, v0
	v_mov_b32_e32 v81, v0
	v_mov_b32_e32 v90, v0
	v_mov_b32_e32 v91, v0
	v_mov_b32_e32 v92, v0
	v_mov_b32_e32 v93, v0
	v_mov_b32_e32 v94, v0
	v_mov_b32_e32 v95, v0
	v_mov_b32_e32 v96, v0
	v_mov_b32_e32 v97, v0
	v_mov_b32_e32 v130, v0
	v_mov_b32_e32 v131, v0
	v_mov_b32_e32 v132, v0
	v_mov_b32_e32 v133, v0
	v_mov_b32_e32 v134, v0
	v_mov_b32_e32 v135, v0
	v_mov_b32_e32 v136, v0
	v_mov_b32_e32 v137, v0
	v_mov_b32_e32 v114, v0
	v_mov_b32_e32 v115, v0
	v_mov_b32_e32 v116, v0
	v_mov_b32_e32 v117, v0
	v_mov_b32_e32 v118, v0
	v_mov_b32_e32 v119, v0
	v_mov_b32_e32 v120, v0
	v_mov_b32_e32 v121, v0
	s_andn2_b64 vcc, exec, s[14:15]
	s_cbranch_vccnz .LBB0_952
	s_branch .LBB0_953

; #define PG8_STAGE(bufoff, gbase, voff) do { _Pragma("unroll") for (int _i = 0; _i < 2; ++_i) \
;         __builtin_amdgcn_global_load_lds((const unsigned*)((const char*)(gbase) + (voff)[_i]), (PG8_LAS unsigned*)(lds + (bufoff) + ldsw + _i * 8192), 16, 0, 0); } while (0)
; #define PG8_LDA(dst, b, h) do { _Pragma("unroll") for (int m = 0; m < 4; ++m) _Pragma("unroll") for (int k = 0; k < 2; ++k) dst[m][k] = *(const PG8_LAS bf16x8*)(lds + PG8_SA(b, h) + aoff + m * 2048 + k * 1024); } while (0)
; #define PG8_LDB(dst, b, h) do { _Pragma("unroll") for (int n = 0; n < 2; ++n) _Pragma("unroll") for (int k = 0; k < 2; ++k) dst[n][k] = *(const PG8_LAS bf16x8*)(lds + PG8_SB(b, h) + boff + n * 2048 + k * 1024); } while (0)
; #define PG8_MMA(ai, bj, At, Bt) do { __builtin_amdgcn_s_setprio(1); _Pragma("unroll") for (int m = 0; m < 4; ++m) _Pragma("unroll") for (int n = 0; n < 2; ++n) _Pragma("unroll") for (int k = 0; k < 2; ++k) \
;         acc[ai][bj][m][n] = __builtin_amdgcn_mfma_f32_16x16x32_bf16(Bt[n][k], At[m][k], acc[ai][bj][m][n], 0, 0, 0); __builtin_amdgcn_s_setprio(0); } while (0)
; #define PG8_WAIT_V(n) asm volatile("s_waitcnt vmcnt(" #n ")" ::: "memory")
; #define PG8_WAIT_L(n) asm volatile("s_waitcnt lgkmcnt(" #n ")" ::: "memory")
; #define PG8_BAR __builtin_amdgcn_s_barrier()
; #define PG8_SCHED __builtin_amdgcn_sched_barrier(0)
; template <class Epi, class Sched, bool ALIGN_EPI = false, bool SP2 = false, bool KHOOK = false>
; __device__ __forceinline__ void gemm_phase(PG8_LAS unsigned char* lds, const Gemm g, const Sched& S, const Epi& E, const int tid_in) {
;     ...
;             PG8_LDB(B0, 0, 0); PG8_LDB(B1, 0, 1); PG8_SCHED; PG8_LDA(At, 0, 0); PG8_STAGE(PG8_SA(1, 1), a1 + hstep, voffA);
;             PG8_WAIT_V(8); PG8_WAIT_L(0); PG8_BAR; PG8_MMA(0, 0, At, B0); PG8_MMA(0, 1, At, B1); PG8_BAR; PG8_SCHED;
;             PG8_LDA(At, 0, 1); PG8_STAGE(PG8_SB(0, 0), b2, voffB); PG8_STAGE(PG8_SB(0, 1), b2 + hstep, voffB); PG8_STAGE(PG8_SA(0, 0), a2, voffA);
;             PG8_WAIT_V(8); PG8_WAIT_L(0); PG8_BAR; PG8_MMA(1, 0, At, B0); PG8_MMA(1, 1, At, B1); PG8_BAR; PG8_SCHED;
;             PG8_LDB(B0, 1, 0); PG8_LDB(B1, 1, 1); PG8_SCHED; PG8_LDA(At, 1, 0); PG8_STAGE(PG8_SA(0, 1), a2 + hstep, voffA);
;             PG8_WAIT_V(8); PG8_WAIT_L(0); PG8_BAR; PG8_MMA(0, 0, At, B0); PG8_MMA(0, 1, At, B1); PG8_BAR; PG8_SCHED;
.LBB0_1062:
	s_ashr_i32 s13, s12, 31
	s_lshl_b64 s[16:17], s[12:13], 20
	v_readlane_b32 s22, v254, 34
	v_readlane_b32 s23, v254, 35
	s_add_u32 s16, s22, s16
	s_addc_u32 s17, s23, s17
	s_and_b64 s[22:23], s[14:15], exec
	s_cselect_b32 s13, s17, s27
	s_cselect_b32 s24, s16, s26
	s_ashr_i32 s11, s10, 31
	s_lshl_b64 s[22:23], s[10:11], 20
	s_add_u32 s22, s2, s22
	s_addc_u32 s23, s20, s23
	s_and_b64 s[44:45], s[14:15], exec
	s_cselect_b32 s11, s23, s31
	s_cselect_b32 s25, s22, s30
	s_add_u32 s26, s26, 0x80080
	s_addc_u32 s27, s27, 0
	s_add_u32 s44, s30, 0x100
	s_addc_u32 s45, s31, 0
	s_mov_b32 s46, -2
	s_add_u32 s30, s26, 0xfff80080
	s_addc_u32 s31, s27, -1
	s_add_i32 s47, 0, 0x10000
	s_cmp_eq_u32 s46, 28
	s_cselect_b32 s49, s13, s31
	s_cselect_b32 s48, s24, s30
	s_cselect_b32 s31, s11, s45
	s_cselect_b32 s30, s25, s44
	s_add_i32 s52, 0, 0x14000
	v_add_u32_e32 v152, s47, v137
	v_add_u32_e32 v168, s52, v137
	ds_read_b128 v[140:143], v152
	ds_read_b128 v[144:147], v152 offset:1024
	ds_read_b128 v[148:151], v152 offset:2048
	ds_read_b128 v[152:155], v152 offset:3072
	ds_read_b128 v[156:159], v168
	ds_read_b128 v[160:163], v168 offset:1024
	ds_read_b128 v[164:167], v168 offset:2048
	ds_read_b128 v[168:171], v168 offset:3072
	v_lshl_add_u64 v[192:193], s[26:27], 0, v[132:133]
	s_add_i32 m0, s36, 0xc000
	ds_read_b128 v[172:175], v139
	ds_read_b128 v[176:179], v139 offset:1024
	ds_read_b128 v[180:183], v139 offset:2048
	ds_read_b128 v[184:187], v139 offset:3072
	ds_read_b128 v[188:191], v139 offset:4096
	ds_read_b128 v[198:201], v139 offset:5120
	ds_read_b128 v[202:205], v139 offset:6144
	ds_read_b128 v[206:209], v139 offset:7168
	global_load_lds_dwordx4 v[192:193], off
	s_add_i32 m0, s36, 0xe000
	v_lshl_add_u64 v[192:193], s[26:27], 0, v[134:135]
	global_load_lds_dwordx4 v[192:193], off
	s_waitcnt vmcnt(10)
	s_waitcnt lgkmcnt(0)
	s_barrier
	s_setprio 1
	v_mfma_f32_16x16x32_bf16 v[126:129], v[140:143], v[172:175], 0
	v_mfma_f32_16x16x32_bf16 v[122:125], v[148:151], v[172:175], 0
	v_mfma_f32_16x16x32_bf16 v[110:113], v[140:143], v[180:183], 0
	v_mfma_f32_16x16x32_bf16 v[106:109], v[148:151], v[180:183], 0
	v_mfma_f32_16x16x32_bf16 v[94:97], v[140:143], v[188:191], 0
	v_mfma_f32_16x16x32_bf16 v[90:93], v[148:151], v[188:191], 0
	v_mfma_f32_16x16x32_bf16 v[78:81], v[140:143], v[202:205], 0
	v_mfma_f32_16x16x32_bf16 v[74:77], v[148:151], v[202:205], 0
	v_mfma_f32_16x16x32_bf16 v[126:129], v[144:147], v[176:179], v[126:129]
	v_mfma_f32_16x16x32_bf16 v[122:125], v[152:155], v[176:179], v[122:125]
	v_mfma_f32_16x16x32_bf16 v[110:113], v[144:147], v[184:187], v[110:113]
	v_mfma_f32_16x16x32_bf16 v[106:109], v[152:155], v[184:187], v[106:109]
	v_mfma_f32_16x16x32_bf16 v[94:97], v[144:147], v[198:201], v[94:97]
	v_mfma_f32_16x16x32_bf16 v[90:93], v[152:155], v[198:201], v[90:93]
	v_mfma_f32_16x16x32_bf16 v[78:81], v[144:147], v[206:209], v[78:81]
	v_mfma_f32_16x16x32_bf16 v[74:77], v[152:155], v[206:209], v[74:77]
	s_setprio 0
	s_setprio 1
	v_mfma_f32_16x16x32_bf16 v[118:121], v[156:159], v[172:175], 0
	v_mfma_f32_16x16x32_bf16 v[114:117], v[164:167], v[172:175], 0
	v_mfma_f32_16x16x32_bf16 v[102:105], v[156:159], v[180:183], 0
	v_mfma_f32_16x16x32_bf16 v[98:101], v[164:167], v[180:183], 0
	v_mfma_f32_16x16x32_bf16 v[86:89], v[156:159], v[188:191], 0
	v_mfma_f32_16x16x32_bf16 v[82:85], v[164:167], v[188:191], 0
	v_mfma_f32_16x16x32_bf16 v[70:73], v[156:159], v[202:205], 0
	v_mfma_f32_16x16x32_bf16 v[66:69], v[164:167], v[202:205], 0
	v_mfma_f32_16x16x32_bf16 v[118:121], v[160:163], v[176:179], v[118:121]
	v_mfma_f32_16x16x32_bf16 v[114:117], v[168:171], v[176:179], v[114:117]
	v_mfma_f32_16x16x32_bf16 v[102:105], v[160:163], v[184:187], v[102:105]
	v_mfma_f32_16x16x32_bf16 v[98:101], v[168:171], v[184:187], v[98:101]
	v_mfma_f32_16x16x32_bf16 v[86:89], v[160:163], v[198:201], v[86:89]
	v_mfma_f32_16x16x32_bf16 v[82:85], v[168:171], v[198:201], v[82:85]
	v_mfma_f32_16x16x32_bf16 v[70:73], v[160:163], v[206:209], v[70:73]
	v_mfma_f32_16x16x32_bf16 v[66:69], v[168:171], v[206:209], v[66:69]
	s_setprio 0
	s_barrier
	s_add_i32 s47, s47, s33
	v_lshl_add_u64 v[192:193], s[30:31], 0, v[32:33]
	s_mov_b32 m0, s47
	ds_read_b128 v[172:175], v139 offset:16384
	ds_read_b128 v[176:179], v139 offset:17408
	ds_read_b128 v[180:183], v139 offset:18432
	ds_read_b128 v[184:187], v139 offset:19456
	ds_read_b128 v[188:191], v139 offset:20480
	ds_read_b128 v[198:201], v139 offset:21504
	ds_read_b128 v[202:205], v139 offset:22528
	ds_read_b128 v[206:209], v139 offset:23552
	global_load_lds_dwordx4 v[192:193], off
	s_add_i32 m0, s47, 0x2000
	s_add_u32 s50, s30, 0x80000
	v_lshl_add_u64 v[210:211], s[30:31], 0, v[130:131]
	s_addc_u32 s51, s31, 0
	s_add_i32 s47, s52, s33
	global_load_lds_dwordx4 v[210:211], off
	v_lshl_add_u64 v[212:213], s[50:51], 0, v[32:33]
	s_mov_b32 m0, s47
	v_lshl_add_u64 v[214:215], s[48:49], 0, v[130:131]
	global_load_lds_dwordx4 v[212:213], off
	s_add_i32 m0, s47, 0x2000
	v_lshl_add_u64 v[212:213], s[50:51], 0, v[130:131]
	global_load_lds_dwordx4 v[212:213], off
	s_mov_b32 m0, s36
	v_lshl_add_u64 v[212:213], s[48:49], 0, v[32:33]
	global_load_lds_dwordx4 v[212:213], off
	s_mov_b32 m0, s37
	s_nop 0
	global_load_lds_dwordx4 v[214:215], off
	s_waitcnt vmcnt(16)
	s_waitcnt lgkmcnt(0)
	s_barrier
; #define PG8_STAGE(bufoff, gbase, voff) do { _Pragma("unroll") for (int _i = 0; _i < 2; ++_i) \
;         __builtin_amdgcn_global_load_lds((const unsigned*)((const char*)(gbase) + (voff)[_i]), (PG8_LAS unsigned*)(lds + (bufoff) + ldsw + _i * 8192), 16, 0, 0); } while (0)
; #define PG8_LDA(dst, b, h) do { _Pragma("unroll") for (int m = 0; m < 4; ++m) _Pragma("unroll") for (int k = 0; k < 2; ++k) dst[m][k] = *(const PG8_LAS bf16x8*)(lds + PG8_SA(b, h) + aoff + m * 2048 + k * 1024); } while (0)
; #define PG8_LDB(dst, b, h) do { _Pragma("unroll") for (int n = 0; n < 2; ++n) _Pragma("unroll") for (int k = 0; k < 2; ++k) dst[n][k] = *(const PG8_LAS bf16x8*)(lds + PG8_SB(b, h) + boff + n * 2048 + k * 1024); } while (0)
; #define PG8_MMA(ai, bj, At, Bt) do { __builtin_amdgcn_s_setprio(1); _Pragma("unroll") for (int m = 0; m < 4; ++m) _Pragma("unroll") for (int n = 0; n < 2; ++n) _Pragma("unroll") for (int k = 0; k < 2; ++k) \
;         acc[ai][bj][m][n] = __builtin_amdgcn_mfma_f32_16x16x32_bf16(Bt[n][k], At[m][k], acc[ai][bj][m][n], 0, 0, 0); __builtin_amdgcn_s_setprio(0); } while (0)
; #define PG8_WAIT_V(n) asm volatile("s_waitcnt vmcnt(" #n ")" ::: "memory")
; #define PG8_WAIT_L(n) asm volatile("s_waitcnt lgkmcnt(" #n ")" ::: "memory")
; #define PG8_BAR __builtin_amdgcn_s_barrier()
; #define PG8_SCHED __builtin_amdgcn_sched_barrier(0)
; template <class Epi, class Sched, bool ALIGN_EPI = false, bool SP2 = false, bool KHOOK = false>
; __device__ __forceinline__ void gemm_phase(PG8_LAS unsigned char* lds, const Gemm g, const Sched& S, const Epi& E, const int tid_in) {
;     ...
;             PG8_WAIT_V(8); PG8_WAIT_L(0); PG8_BAR; PG8_MMA(1, 0, At, B0); PG8_MMA(1, 1, At, B1); PG8_BAR; PG8_SCHED;
;             PG8_LDB(B0, 1, 0); PG8_LDB(B1, 1, 1); PG8_SCHED; PG8_LDA(At, 1, 0); PG8_STAGE(PG8_SA(0, 1), a2 + hstep, voffA);
;             PG8_WAIT_V(8); PG8_WAIT_L(0); PG8_BAR; PG8_MMA(0, 0, At, B0); PG8_MMA(0, 1, At, B1); PG8_BAR; PG8_SCHED;
	s_setprio 1
	v_mfma_f32_16x16x32_bf16 v[62:65], v[140:143], v[172:175], 0
	v_mfma_f32_16x16x32_bf16 v[58:61], v[148:151], v[172:175], 0
	v_mfma_f32_16x16x32_bf16 v[46:49], v[140:143], v[180:183], 0
	v_mfma_f32_16x16x32_bf16 v[42:45], v[148:151], v[180:183], 0
	v_mfma_f32_16x16x32_bf16 v[28:31], v[140:143], v[188:191], 0
	v_mfma_f32_16x16x32_bf16 v[24:27], v[148:151], v[188:191], 0
	v_mfma_f32_16x16x32_bf16 v[12:15], v[140:143], v[202:205], 0
	v_mfma_f32_16x16x32_bf16 v[8:11], v[148:151], v[202:205], 0
	v_mfma_f32_16x16x32_bf16 v[62:65], v[144:147], v[176:179], v[62:65]
	v_mfma_f32_16x16x32_bf16 v[58:61], v[152:155], v[176:179], v[58:61]
	v_mfma_f32_16x16x32_bf16 v[46:49], v[144:147], v[184:187], v[46:49]
	v_mfma_f32_16x16x32_bf16 v[42:45], v[152:155], v[184:187], v[42:45]
	v_mfma_f32_16x16x32_bf16 v[28:31], v[144:147], v[198:201], v[28:31]
	v_mfma_f32_16x16x32_bf16 v[24:27], v[152:155], v[198:201], v[24:27]
	v_mfma_f32_16x16x32_bf16 v[12:15], v[144:147], v[206:209], v[12:15]
	v_mfma_f32_16x16x32_bf16 v[8:11], v[152:155], v[206:209], v[8:11]
	s_setprio 0
	s_setprio 1
	v_mfma_f32_16x16x32_bf16 v[54:57], v[156:159], v[172:175], 0
	v_mfma_f32_16x16x32_bf16 v[50:53], v[164:167], v[172:175], 0
	v_mfma_f32_16x16x32_bf16 v[38:41], v[156:159], v[180:183], 0
	v_mfma_f32_16x16x32_bf16 v[34:37], v[164:167], v[180:183], 0
	v_mfma_f32_16x16x32_bf16 v[20:23], v[156:159], v[188:191], 0
	v_mfma_f32_16x16x32_bf16 v[16:19], v[164:167], v[188:191], 0
	v_mfma_f32_16x16x32_bf16 v[4:7], v[156:159], v[202:205], 0
	v_mfma_f32_16x16x32_bf16 v[0:3], v[164:167], v[202:205], 0
	v_mfma_f32_16x16x32_bf16 v[54:57], v[160:163], v[176:179], v[54:57]
	v_mfma_f32_16x16x32_bf16 v[50:53], v[168:171], v[176:179], v[50:53]
	v_mfma_f32_16x16x32_bf16 v[38:41], v[160:163], v[184:187], v[38:41]
	v_mfma_f32_16x16x32_bf16 v[34:37], v[168:171], v[184:187], v[34:37]
	v_mfma_f32_16x16x32_bf16 v[20:23], v[160:163], v[198:201], v[20:23]
	v_mfma_f32_16x16x32_bf16 v[16:19], v[168:171], v[198:201], v[16:19]
	v_mfma_f32_16x16x32_bf16 v[4:7], v[160:163], v[206:209], v[4:7]
	v_mfma_f32_16x16x32_bf16 v[0:3], v[168:171], v[206:209], v[0:3]
	s_setprio 0
	s_barrier
	s_add_i32 s47, 0, 0x18000
	s_add_i32 s50, 0, 0x1c000
	v_add_u32_e32 v152, s47, v137
	v_add_u32_e32 v168, s50, v137
	ds_read_b128 v[140:143], v152
	ds_read_b128 v[144:147], v152 offset:1024
	ds_read_b128 v[148:151], v152 offset:2048
	ds_read_b128 v[152:155], v152 offset:3072
	ds_read_b128 v[156:159], v168
	ds_read_b128 v[160:163], v168 offset:1024
	ds_read_b128 v[164:167], v168 offset:2048
	ds_read_b128 v[168:171], v168 offset:3072
	s_add_u32 s48, s48, 0x80000
	s_addc_u32 s49, s49, 0
	s_mov_b32 m0, s38
	v_lshl_add_u64 v[216:217], s[48:49], 0, v[32:33]
	ds_read_b128 v[172:175], v139 offset:32768
	ds_read_b128 v[176:179], v139 offset:33792
	ds_read_b128 v[180:183], v139 offset:34816
	ds_read_b128 v[184:187], v139 offset:35840
	ds_read_b128 v[188:191], v139 offset:36864
	ds_read_b128 v[198:201], v139 offset:37888
	ds_read_b128 v[202:205], v139 offset:38912
	ds_read_b128 v[206:209], v139 offset:39936
	global_load_lds_dwordx4 v[216:217], off
	s_mov_b32 m0, s39
	v_lshl_add_u64 v[216:217], s[48:49], 0, v[130:131]
	global_load_lds_dwordx4 v[216:217], off
	s_waitcnt vmcnt(8)
	s_waitcnt lgkmcnt(0)
	s_barrier
	s_setprio 1
	v_mfma_f32_16x16x32_bf16 v[126:129], v[140:143], v[172:175], v[126:129]
	v_mfma_f32_16x16x32_bf16 v[122:125], v[148:151], v[172:175], v[122:125]
	v_mfma_f32_16x16x32_bf16 v[110:113], v[140:143], v[180:183], v[110:113]
	v_mfma_f32_16x16x32_bf16 v[106:109], v[148:151], v[180:183], v[106:109]
	v_mfma_f32_16x16x32_bf16 v[94:97], v[140:143], v[188:191], v[94:97]
	v_mfma_f32_16x16x32_bf16 v[90:93], v[148:151], v[188:191], v[90:93]
	v_mfma_f32_16x16x32_bf16 v[78:81], v[140:143], v[202:205], v[78:81]
	v_mfma_f32_16x16x32_bf16 v[74:77], v[148:151], v[202:205], v[74:77]
	v_mfma_f32_16x16x32_bf16 v[126:129], v[144:147], v[176:179], v[126:129]
	v_mfma_f32_16x16x32_bf16 v[122:125], v[152:155], v[176:179], v[122:125]
	v_mfma_f32_16x16x32_bf16 v[110:113], v[144:147], v[184:187], v[110:113]
	v_mfma_f32_16x16x32_bf16 v[106:109], v[152:155], v[184:187], v[106:109]
	v_mfma_f32_16x16x32_bf16 v[94:97], v[144:147], v[198:201], v[94:97]
	v_mfma_f32_16x16x32_bf16 v[90:93], v[152:155], v[198:201], v[90:93]
	v_mfma_f32_16x16x32_bf16 v[78:81], v[144:147], v[206:209], v[78:81]
	v_mfma_f32_16x16x32_bf16 v[74:77], v[152:155], v[206:209], v[74:77]
	s_setprio 0
	s_setprio 1
	v_mfma_f32_16x16x32_bf16 v[118:121], v[156:159], v[172:175], v[118:121]
	v_mfma_f32_16x16x32_bf16 v[114:117], v[164:167], v[172:175], v[114:117]
	v_mfma_f32_16x16x32_bf16 v[102:105], v[156:159], v[180:183], v[102:105]
	v_mfma_f32_16x16x32_bf16 v[98:101], v[164:167], v[180:183], v[98:101]
	v_mfma_f32_16x16x32_bf16 v[86:89], v[156:159], v[188:191], v[86:89]
	v_mfma_f32_16x16x32_bf16 v[82:85], v[164:167], v[188:191], v[82:85]
	v_mfma_f32_16x16x32_bf16 v[70:73], v[156:159], v[202:205], v[70:73]
	v_mfma_f32_16x16x32_bf16 v[66:69], v[164:167], v[202:205], v[66:69]
	v_mfma_f32_16x16x32_bf16 v[118:121], v[160:163], v[176:179], v[118:121]
	v_mfma_f32_16x16x32_bf16 v[114:117], v[168:171], v[176:179], v[114:117]
	v_mfma_f32_16x16x32_bf16 v[102:105], v[160:163], v[184:187], v[102:105]
	v_mfma_f32_16x16x32_bf16 v[98:101], v[168:171], v[184:187], v[98:101]
	v_mfma_f32_16x16x32_bf16 v[86:89], v[160:163], v[198:201], v[86:89]
	v_mfma_f32_16x16x32_bf16 v[82:85], v[168:171], v[198:201], v[82:85]
	v_mfma_f32_16x16x32_bf16 v[70:73], v[160:163], v[206:209], v[70:73]
	v_mfma_f32_16x16x32_bf16 v[66:69], v[168:171], v[206:209], v[66:69]
	s_setprio 0
	s_barrier
; #define PG8_STAGE(bufoff, gbase, voff) do { _Pragma("unroll") for (int _i = 0; _i < 2; ++_i) \
;         __builtin_amdgcn_global_load_lds((const unsigned*)((const char*)(gbase) + (voff)[_i]), (PG8_LAS unsigned*)(lds + (bufoff) + ldsw + _i * 8192), 16, 0, 0); } while (0)
; #define PG8_LDA(dst, b, h) do { _Pragma("unroll") for (int m = 0; m < 4; ++m) _Pragma("unroll") for (int k = 0; k < 2; ++k) dst[m][k] = *(const PG8_LAS bf16x8*)(lds + PG8_SA(b, h) + aoff + m * 2048 + k * 1024); } while (0)
; #define PG8_LDB(dst, b, h) do { _Pragma("unroll") for (int n = 0; n < 2; ++n) _Pragma("unroll") for (int k = 0; k < 2; ++k) dst[n][k] = *(const PG8_LAS bf16x8*)(lds + PG8_SB(b, h) + boff + n * 2048 + k * 1024); } while (0)
; #define PG8_MMA(ai, bj, At, Bt) do { __builtin_amdgcn_s_setprio(1); _Pragma("unroll") for (int m = 0; m < 4; ++m) _Pragma("unroll") for (int n = 0; n < 2; ++n) _Pragma("unroll") for (int k = 0; k < 2; ++k) \
;         acc[ai][bj][m][n] = __builtin_amdgcn_mfma_f32_16x16x32_bf16(Bt[n][k], At[m][k], acc[ai][bj][m][n], 0, 0, 0); __builtin_amdgcn_s_setprio(0); } while (0)
; #define PG8_WAIT_V(n) asm volatile("s_waitcnt vmcnt(" #n ")" ::: "memory")
; #define PG8_WAIT_L(n) asm volatile("s_waitcnt lgkmcnt(" #n ")" ::: "memory")
; #define PG8_BAR __builtin_amdgcn_s_barrier()
; #define PG8_SCHED __builtin_amdgcn_sched_barrier(0)
; template <class Epi, class Sched, bool ALIGN_EPI = false, bool SP2 = false, bool KHOOK = false>
; __device__ __forceinline__ void gemm_phase(PG8_LAS unsigned char* lds, const Gemm g, const Sched& S, const Epi& E, const int tid_in) {
;     ...
;             PG8_LDB(B0, 0, 0); PG8_LDB(B1, 0, 1); PG8_SCHED; PG8_LDA(At, 0, 0); PG8_STAGE(PG8_SA(1, 1), a1 + hstep, voffA);
;             PG8_WAIT_V(8); PG8_WAIT_L(0); PG8_BAR; PG8_MMA(0, 0, At, B0); PG8_MMA(0, 1, At, B1); PG8_BAR; PG8_SCHED;
;             PG8_LDA(At, 0, 1); PG8_STAGE(PG8_SB(0, 0), b2, voffB); PG8_STAGE(PG8_SB(0, 1), b2 + hstep, voffB); PG8_STAGE(PG8_SA(0, 0), a2, voffA);
;             PG8_WAIT_V(8); PG8_WAIT_L(0); PG8_BAR; PG8_MMA(1, 0, At, B0); PG8_MMA(1, 1, At, B1); PG8_BAR; PG8_SCHED;
;     ...
;             PG8_LDA(At, 1, 1); PG8_STAGE(PG8_SB(1, 0), b3, voffB); PG8_STAGE(PG8_SB(1, 1), b3 + hstep, voffB); PG8_STAGE(PG8_SA(1, 0), a3, voffA);
;             PG8_WAIT_V(8); PG8_WAIT_L(0); PG8_BAR; PG8_MMA(1, 0, At, B0); PG8_MMA(1, 1, At, B1); PG8_BAR; PG8_SCHED;
	s_add_i32 s47, s47, s33
	v_lshl_add_u64 v[192:193], v[192:193], 0, s[90:91]
	s_mov_b32 m0, s47
	ds_read_b128 v[172:175], v139 offset:49152
	ds_read_b128 v[176:179], v139 offset:50176
	ds_read_b128 v[180:183], v139 offset:51200
	ds_read_b128 v[184:187], v139 offset:52224
	ds_read_b128 v[188:191], v139 offset:53248
	ds_read_b128 v[198:201], v139 offset:54272
	ds_read_b128 v[202:205], v139 offset:55296
	ds_read_b128 v[206:209], v139 offset:56320
	global_load_lds_dwordx4 v[192:193], off
	s_add_i32 m0, s47, 0x2000
	s_add_u32 s30, s30, 0x80080
	v_lshl_add_u64 v[192:193], v[210:211], 0, s[90:91]
	s_addc_u32 s31, s31, 0
	s_add_i32 s47, s50, s33
	global_load_lds_dwordx4 v[192:193], off
	s_mov_b32 m0, s47
	v_lshl_add_u64 v[192:193], s[30:31], 0, v[32:33]
	global_load_lds_dwordx4 v[192:193], off
	s_add_i32 m0, s47, 0x2000
	v_lshl_add_u64 v[192:193], s[30:31], 0, v[130:131]
	global_load_lds_dwordx4 v[192:193], off
	s_mov_b32 m0, s40
	v_lshl_add_u64 v[192:193], v[212:213], 0, s[90:91]
	global_load_lds_dwordx4 v[192:193], off
	s_mov_b32 m0, s41
	v_lshl_add_u64 v[192:193], v[214:215], 0, s[90:91]
	global_load_lds_dwordx4 v[192:193], off
	s_waitcnt vmcnt(8)
	s_waitcnt lgkmcnt(0)
	s_barrier
	s_setprio 1
	v_mfma_f32_16x16x32_bf16 v[62:65], v[140:143], v[172:175], v[62:65]
	v_mfma_f32_16x16x32_bf16 v[58:61], v[148:151], v[172:175], v[58:61]
	v_mfma_f32_16x16x32_bf16 v[46:49], v[140:143], v[180:183], v[46:49]
	v_mfma_f32_16x16x32_bf16 v[42:45], v[148:151], v[180:183], v[42:45]
	v_mfma_f32_16x16x32_bf16 v[28:31], v[140:143], v[188:191], v[28:31]
	v_mfma_f32_16x16x32_bf16 v[24:27], v[148:151], v[188:191], v[24:27]
	v_mfma_f32_16x16x32_bf16 v[12:15], v[140:143], v[202:205], v[12:15]
	v_mfma_f32_16x16x32_bf16 v[8:11], v[148:151], v[202:205], v[8:11]
	v_mfma_f32_16x16x32_bf16 v[62:65], v[144:147], v[176:179], v[62:65]
	v_mfma_f32_16x16x32_bf16 v[58:61], v[152:155], v[176:179], v[58:61]
	v_mfma_f32_16x16x32_bf16 v[46:49], v[144:147], v[184:187], v[46:49]
	v_mfma_f32_16x16x32_bf16 v[42:45], v[152:155], v[184:187], v[42:45]
	v_mfma_f32_16x16x32_bf16 v[28:31], v[144:147], v[198:201], v[28:31]
	v_mfma_f32_16x16x32_bf16 v[24:27], v[152:155], v[198:201], v[24:27]
	v_mfma_f32_16x16x32_bf16 v[12:15], v[144:147], v[206:209], v[12:15]
	v_mfma_f32_16x16x32_bf16 v[8:11], v[152:155], v[206:209], v[8:11]
	s_setprio 0
	s_setprio 1
	v_mfma_f32_16x16x32_bf16 v[54:57], v[156:159], v[172:175], v[54:57]
	v_mfma_f32_16x16x32_bf16 v[50:53], v[164:167], v[172:175], v[50:53]
	v_mfma_f32_16x16x32_bf16 v[38:41], v[156:159], v[180:183], v[38:41]
	v_mfma_f32_16x16x32_bf16 v[34:37], v[164:167], v[180:183], v[34:37]
	v_mfma_f32_16x16x32_bf16 v[20:23], v[156:159], v[188:191], v[20:23]
	v_mfma_f32_16x16x32_bf16 v[16:19], v[164:167], v[188:191], v[16:19]
	v_mfma_f32_16x16x32_bf16 v[4:7], v[156:159], v[202:205], v[4:7]
	v_mfma_f32_16x16x32_bf16 v[0:3], v[164:167], v[202:205], v[0:3]
	v_mfma_f32_16x16x32_bf16 v[54:57], v[160:163], v[176:179], v[54:57]
	v_mfma_f32_16x16x32_bf16 v[50:53], v[168:171], v[176:179], v[50:53]
	v_mfma_f32_16x16x32_bf16 v[38:41], v[160:163], v[184:187], v[38:41]
	v_mfma_f32_16x16x32_bf16 v[34:37], v[168:171], v[184:187], v[34:37]
	v_mfma_f32_16x16x32_bf16 v[20:23], v[160:163], v[198:201], v[20:23]
	v_mfma_f32_16x16x32_bf16 v[16:19], v[168:171], v[198:201], v[16:19]
	v_mfma_f32_16x16x32_bf16 v[4:7], v[160:163], v[206:209], v[4:7]
	v_mfma_f32_16x16x32_bf16 v[0:3], v[168:171], v[206:209], v[0:3]
	s_setprio 0
	s_barrier
	s_add_i32 s46, s46, 2
	s_add_u32 s26, s26, 0x100
	s_addc_u32 s27, s27, 0
	s_add_u32 s44, s44, 0x100
	s_addc_u32 s45, s45, 0
	s_cmp_gt_u32 s46, 29
.LBB0_1063:
	s_add_u32 s30, s26, 0xfff80080
	s_addc_u32 s31, s27, -1
	s_add_i32 s47, 0, 0x10000
	s_cmp_eq_u32 s46, 28
	s_cselect_b32 s49, s13, s31
	s_cselect_b32 s48, s24, s30
	s_cselect_b32 s31, s11, s45
	s_cselect_b32 s30, s25, s44
	s_add_i32 s52, 0, 0x14000
	v_add_u32_e32 v152, s47, v137
	v_add_u32_e32 v168, s52, v137
	ds_read_b128 v[140:143], v152
	ds_read_b128 v[144:147], v152 offset:1024
	ds_read_b128 v[148:151], v152 offset:2048
	ds_read_b128 v[152:155], v152 offset:3072
	ds_read_b128 v[156:159], v168
	ds_read_b128 v[160:163], v168 offset:1024
	ds_read_b128 v[164:167], v168 offset:2048
	ds_read_b128 v[168:171], v168 offset:3072
	v_lshl_add_u64 v[192:193], s[26:27], 0, v[132:133]
	s_add_i32 m0, s36, 0xc000
	ds_read_b128 v[172:175], v139
	ds_read_b128 v[176:179], v139 offset:1024
	ds_read_b128 v[180:183], v139 offset:2048
	ds_read_b128 v[184:187], v139 offset:3072
	ds_read_b128 v[188:191], v139 offset:4096
	ds_read_b128 v[198:201], v139 offset:5120
	ds_read_b128 v[202:205], v139 offset:6144
	ds_read_b128 v[206:209], v139 offset:7168
	global_load_lds_dwordx4 v[192:193], off
	s_add_i32 m0, s36, 0xe000
	v_lshl_add_u64 v[192:193], s[26:27], 0, v[134:135]
	global_load_lds_dwordx4 v[192:193], off
	s_waitcnt vmcnt(8)
	s_waitcnt lgkmcnt(0)
	s_barrier
; #define PG8_STAGE(bufoff, gbase, voff) do { _Pragma("unroll") for (int _i = 0; _i < 2; ++_i) \
;         __builtin_amdgcn_global_load_lds((const unsigned*)((const char*)(gbase) + (voff)[_i]), (PG8_LAS unsigned*)(lds + (bufoff) + ldsw + _i * 8192), 16, 0, 0); } while (0)
; #define PG8_LDA(dst, b, h) do { _Pragma("unroll") for (int m = 0; m < 4; ++m) _Pragma("unroll") for (int k = 0; k < 2; ++k) dst[m][k] = *(const PG8_LAS bf16x8*)(lds + PG8_SA(b, h) + aoff + m * 2048 + k * 1024); } while (0)
; #define PG8_MMA(ai, bj, At, Bt) do { __builtin_amdgcn_s_setprio(1); _Pragma("unroll") for (int m = 0; m < 4; ++m) _Pragma("unroll") for (int n = 0; n < 2; ++n) _Pragma("unroll") for (int k = 0; k < 2; ++k) \
;         acc[ai][bj][m][n] = __builtin_amdgcn_mfma_f32_16x16x32_bf16(Bt[n][k], At[m][k], acc[ai][bj][m][n], 0, 0, 0); __builtin_amdgcn_s_setprio(0); } while (0)
; #define PG8_WAIT_V(n) asm volatile("s_waitcnt vmcnt(" #n ")" ::: "memory")
; #define PG8_WAIT_L(n) asm volatile("s_waitcnt lgkmcnt(" #n ")" ::: "memory")
; #define PG8_BAR __builtin_amdgcn_s_barrier()
; #define PG8_SCHED __builtin_amdgcn_sched_barrier(0)
; template <class Epi, class Sched, bool ALIGN_EPI = false, bool SP2 = false, bool KHOOK = false>
; __device__ __forceinline__ void gemm_phase(PG8_LAS unsigned char* lds, const Gemm g, const Sched& S, const Epi& E, const int tid_in) {
;     ...
;             PG8_WAIT_V(8); PG8_WAIT_L(0); PG8_BAR; PG8_MMA(0, 0, At, B0); PG8_MMA(0, 1, At, B1); PG8_BAR; PG8_SCHED;
;             PG8_LDA(At, 0, 1); PG8_STAGE(PG8_SB(0, 0), b2, voffB); PG8_STAGE(PG8_SB(0, 1), b2 + hstep, voffB); PG8_STAGE(PG8_SA(0, 0), a2, voffA);
;             PG8_WAIT_V(8); PG8_WAIT_L(0); PG8_BAR; PG8_MMA(1, 0, At, B0); PG8_MMA(1, 1, At, B1); PG8_BAR; PG8_SCHED;
	s_setprio 1
	v_mfma_f32_16x16x32_bf16 v[126:129], v[140:143], v[172:175], v[126:129]
	v_mfma_f32_16x16x32_bf16 v[122:125], v[148:151], v[172:175], v[122:125]
	v_mfma_f32_16x16x32_bf16 v[110:113], v[140:143], v[180:183], v[110:113]
	v_mfma_f32_16x16x32_bf16 v[106:109], v[148:151], v[180:183], v[106:109]
	v_mfma_f32_16x16x32_bf16 v[94:97], v[140:143], v[188:191], v[94:97]
	v_mfma_f32_16x16x32_bf16 v[90:93], v[148:151], v[188:191], v[90:93]
	v_mfma_f32_16x16x32_bf16 v[78:81], v[140:143], v[202:205], v[78:81]
	v_mfma_f32_16x16x32_bf16 v[74:77], v[148:151], v[202:205], v[74:77]
	v_mfma_f32_16x16x32_bf16 v[126:129], v[144:147], v[176:179], v[126:129]
	v_mfma_f32_16x16x32_bf16 v[122:125], v[152:155], v[176:179], v[122:125]
	v_mfma_f32_16x16x32_bf16 v[110:113], v[144:147], v[184:187], v[110:113]
	v_mfma_f32_16x16x32_bf16 v[106:109], v[152:155], v[184:187], v[106:109]
	v_mfma_f32_16x16x32_bf16 v[94:97], v[144:147], v[198:201], v[94:97]
	v_mfma_f32_16x16x32_bf16 v[90:93], v[152:155], v[198:201], v[90:93]
	v_mfma_f32_16x16x32_bf16 v[78:81], v[144:147], v[206:209], v[78:81]
	v_mfma_f32_16x16x32_bf16 v[74:77], v[152:155], v[206:209], v[74:77]
	s_setprio 0
	s_setprio 1
	v_mfma_f32_16x16x32_bf16 v[118:121], v[156:159], v[172:175], v[118:121]
	v_mfma_f32_16x16x32_bf16 v[114:117], v[164:167], v[172:175], v[114:117]
	v_mfma_f32_16x16x32_bf16 v[102:105], v[156:159], v[180:183], v[102:105]
	v_mfma_f32_16x16x32_bf16 v[98:101], v[164:167], v[180:183], v[98:101]
	v_mfma_f32_16x16x32_bf16 v[86:89], v[156:159], v[188:191], v[86:89]
	v_mfma_f32_16x16x32_bf16 v[82:85], v[164:167], v[188:191], v[82:85]
	v_mfma_f32_16x16x32_bf16 v[70:73], v[156:159], v[202:205], v[70:73]
	v_mfma_f32_16x16x32_bf16 v[66:69], v[164:167], v[202:205], v[66:69]
	v_mfma_f32_16x16x32_bf16 v[118:121], v[160:163], v[176:179], v[118:121]
	v_mfma_f32_16x16x32_bf16 v[114:117], v[168:171], v[176:179], v[114:117]
	v_mfma_f32_16x16x32_bf16 v[102:105], v[160:163], v[184:187], v[102:105]
	v_mfma_f32_16x16x32_bf16 v[98:101], v[168:171], v[184:187], v[98:101]
	v_mfma_f32_16x16x32_bf16 v[86:89], v[160:163], v[198:201], v[86:89]
	v_mfma_f32_16x16x32_bf16 v[82:85], v[168:171], v[198:201], v[82:85]
	v_mfma_f32_16x16x32_bf16 v[70:73], v[160:163], v[206:209], v[70:73]
	v_mfma_f32_16x16x32_bf16 v[66:69], v[168:171], v[206:209], v[66:69]
	s_setprio 0
	s_barrier
	s_add_i32 s47, s47, s33
	v_lshl_add_u64 v[192:193], s[30:31], 0, v[32:33]
	s_mov_b32 m0, s47
	ds_read_b128 v[172:175], v139 offset:16384
	ds_read_b128 v[176:179], v139 offset:17408
	ds_read_b128 v[180:183], v139 offset:18432
	ds_read_b128 v[184:187], v139 offset:19456
	ds_read_b128 v[188:191], v139 offset:20480
	ds_read_b128 v[198:201], v139 offset:21504
	ds_read_b128 v[202:205], v139 offset:22528
	ds_read_b128 v[206:209], v139 offset:23552
	global_load_lds_dwordx4 v[192:193], off
	s_add_i32 m0, s47, 0x2000
	s_add_u32 s50, s30, 0x80000
	v_lshl_add_u64 v[210:211], s[30:31], 0, v[130:131]
	s_addc_u32 s51, s31, 0
	s_add_i32 s47, s52, s33
	global_load_lds_dwordx4 v[210:211], off
	v_lshl_add_u64 v[212:213], s[50:51], 0, v[32:33]
	s_mov_b32 m0, s47
	v_lshl_add_u64 v[214:215], s[48:49], 0, v[130:131]
	global_load_lds_dwordx4 v[212:213], off
	s_add_i32 m0, s47, 0x2000
	v_lshl_add_u64 v[212:213], s[50:51], 0, v[130:131]
	global_load_lds_dwordx4 v[212:213], off
	s_mov_b32 m0, s36
	v_lshl_add_u64 v[212:213], s[48:49], 0, v[32:33]
	global_load_lds_dwordx4 v[212:213], off
	s_mov_b32 m0, s37
	s_nop 0
	global_load_lds_dwordx4 v[214:215], off
	s_waitcnt vmcnt(8)
	s_waitcnt lgkmcnt(0)
	s_barrier
	s_setprio 1
	v_mfma_f32_16x16x32_bf16 v[62:65], v[140:143], v[172:175], v[62:65]
	v_mfma_f32_16x16x32_bf16 v[58:61], v[148:151], v[172:175], v[58:61]
	v_mfma_f32_16x16x32_bf16 v[46:49], v[140:143], v[180:183], v[46:49]
	v_mfma_f32_16x16x32_bf16 v[42:45], v[148:151], v[180:183], v[42:45]
	v_mfma_f32_16x16x32_bf16 v[28:31], v[140:143], v[188:191], v[28:31]
	v_mfma_f32_16x16x32_bf16 v[24:27], v[148:151], v[188:191], v[24:27]
	v_mfma_f32_16x16x32_bf16 v[12:15], v[140:143], v[202:205], v[12:15]
	v_mfma_f32_16x16x32_bf16 v[8:11], v[148:151], v[202:205], v[8:11]
	v_mfma_f32_16x16x32_bf16 v[62:65], v[144:147], v[176:179], v[62:65]
	v_mfma_f32_16x16x32_bf16 v[58:61], v[152:155], v[176:179], v[58:61]
	v_mfma_f32_16x16x32_bf16 v[46:49], v[144:147], v[184:187], v[46:49]
	v_mfma_f32_16x16x32_bf16 v[42:45], v[152:155], v[184:187], v[42:45]
	v_mfma_f32_16x16x32_bf16 v[28:31], v[144:147], v[198:201], v[28:31]
	v_mfma_f32_16x16x32_bf16 v[24:27], v[152:155], v[198:201], v[24:27]
	v_mfma_f32_16x16x32_bf16 v[12:15], v[144:147], v[206:209], v[12:15]
	v_mfma_f32_16x16x32_bf16 v[8:11], v[152:155], v[206:209], v[8:11]
	s_setprio 0
	s_setprio 1
	v_mfma_f32_16x16x32_bf16 v[54:57], v[156:159], v[172:175], v[54:57]
	v_mfma_f32_16x16x32_bf16 v[50:53], v[164:167], v[172:175], v[50:53]
	v_mfma_f32_16x16x32_bf16 v[38:41], v[156:159], v[180:183], v[38:41]
	v_mfma_f32_16x16x32_bf16 v[34:37], v[164:167], v[180:183], v[34:37]
	v_mfma_f32_16x16x32_bf16 v[20:23], v[156:159], v[188:191], v[20:23]
	v_mfma_f32_16x16x32_bf16 v[16:19], v[164:167], v[188:191], v[16:19]
	v_mfma_f32_16x16x32_bf16 v[4:7], v[156:159], v[202:205], v[4:7]
	v_mfma_f32_16x16x32_bf16 v[0:3], v[164:167], v[202:205], v[0:3]
	v_mfma_f32_16x16x32_bf16 v[54:57], v[160:163], v[176:179], v[54:57]
	v_mfma_f32_16x16x32_bf16 v[50:53], v[168:171], v[176:179], v[50:53]
	v_mfma_f32_16x16x32_bf16 v[38:41], v[160:163], v[184:187], v[38:41]
	v_mfma_f32_16x16x32_bf16 v[34:37], v[168:171], v[184:187], v[34:37]
	v_mfma_f32_16x16x32_bf16 v[20:23], v[160:163], v[198:201], v[20:23]
	v_mfma_f32_16x16x32_bf16 v[16:19], v[168:171], v[198:201], v[16:19]
	v_mfma_f32_16x16x32_bf16 v[4:7], v[160:163], v[206:209], v[4:7]
	v_mfma_f32_16x16x32_bf16 v[0:3], v[168:171], v[206:209], v[0:3]
	s_setprio 0
	s_barrier
; #define PG8_STAGE(bufoff, gbase, voff) do { _Pragma("unroll") for (int _i = 0; _i < 2; ++_i) \
;         __builtin_amdgcn_global_load_lds((const unsigned*)((const char*)(gbase) + (voff)[_i]), (PG8_LAS unsigned*)(lds + (bufoff) + ldsw + _i * 8192), 16, 0, 0); } while (0)
; #define PG8_LDA(dst, b, h) do { _Pragma("unroll") for (int m = 0; m < 4; ++m) _Pragma("unroll") for (int k = 0; k < 2; ++k) dst[m][k] = *(const PG8_LAS bf16x8*)(lds + PG8_SA(b, h) + aoff + m * 2048 + k * 1024); } while (0)
; #define PG8_LDB(dst, b, h) do { _Pragma("unroll") for (int n = 0; n < 2; ++n) _Pragma("unroll") for (int k = 0; k < 2; ++k) dst[n][k] = *(const PG8_LAS bf16x8*)(lds + PG8_SB(b, h) + boff + n * 2048 + k * 1024); } while (0)
; #define PG8_MMA(ai, bj, At, Bt) do { __builtin_amdgcn_s_setprio(1); _Pragma("unroll") for (int m = 0; m < 4; ++m) _Pragma("unroll") for (int n = 0; n < 2; ++n) _Pragma("unroll") for (int k = 0; k < 2; ++k) \
;         acc[ai][bj][m][n] = __builtin_amdgcn_mfma_f32_16x16x32_bf16(Bt[n][k], At[m][k], acc[ai][bj][m][n], 0, 0, 0); __builtin_amdgcn_s_setprio(0); } while (0)
; #define PG8_WAIT_V(n) asm volatile("s_waitcnt vmcnt(" #n ")" ::: "memory")
; #define PG8_WAIT_L(n) asm volatile("s_waitcnt lgkmcnt(" #n ")" ::: "memory")
; #define PG8_BAR __builtin_amdgcn_s_barrier()
; #define PG8_SCHED __builtin_amdgcn_sched_barrier(0)
; template <class Epi, class Sched, bool ALIGN_EPI = false, bool SP2 = false, bool KHOOK = false>
; __device__ __forceinline__ void gemm_phase(PG8_LAS unsigned char* lds, const Gemm g, const Sched& S, const Epi& E, const int tid_in) {
;     ...
;             PG8_LDB(B0, 1, 0); PG8_LDB(B1, 1, 1); PG8_SCHED; PG8_LDA(At, 1, 0); PG8_STAGE(PG8_SA(0, 1), a2 + hstep, voffA);
;             PG8_WAIT_V(8); PG8_WAIT_L(0); PG8_BAR; PG8_MMA(0, 0, At, B0); PG8_MMA(0, 1, At, B1); PG8_BAR; PG8_SCHED;
	s_add_i32 s47, 0, 0x18000
	s_add_i32 s50, 0, 0x1c000
	v_add_u32_e32 v152, s47, v137
	v_add_u32_e32 v168, s50, v137
	ds_read_b128 v[140:143], v152
	ds_read_b128 v[144:147], v152 offset:1024
	ds_read_b128 v[148:151], v152 offset:2048
	ds_read_b128 v[152:155], v152 offset:3072
	ds_read_b128 v[156:159], v168
	ds_read_b128 v[160:163], v168 offset:1024
	ds_read_b128 v[164:167], v168 offset:2048
	ds_read_b128 v[168:171], v168 offset:3072
	s_add_u32 s48, s48, 0x80000
	s_addc_u32 s49, s49, 0
	s_mov_b32 m0, s38
	v_lshl_add_u64 v[216:217], s[48:49], 0, v[32:33]
	ds_read_b128 v[172:175], v139 offset:32768
	ds_read_b128 v[176:179], v139 offset:33792
	ds_read_b128 v[180:183], v139 offset:34816
	ds_read_b128 v[184:187], v139 offset:35840
	ds_read_b128 v[188:191], v139 offset:36864
	ds_read_b128 v[198:201], v139 offset:37888
	ds_read_b128 v[202:205], v139 offset:38912
	ds_read_b128 v[206:209], v139 offset:39936
	global_load_lds_dwordx4 v[216:217], off
	s_mov_b32 m0, s39
	v_lshl_add_u64 v[216:217], s[48:49], 0, v[130:131]
	global_load_lds_dwordx4 v[216:217], off
	s_waitcnt vmcnt(8)
	s_waitcnt lgkmcnt(0)
	s_barrier
	s_setprio 1
	v_mfma_f32_16x16x32_bf16 v[126:129], v[140:143], v[172:175], v[126:129]
	v_mfma_f32_16x16x32_bf16 v[122:125], v[148:151], v[172:175], v[122:125]
	v_mfma_f32_16x16x32_bf16 v[110:113], v[140:143], v[180:183], v[110:113]
	v_mfma_f32_16x16x32_bf16 v[106:109], v[148:151], v[180:183], v[106:109]
	v_mfma_f32_16x16x32_bf16 v[94:97], v[140:143], v[188:191], v[94:97]
	v_mfma_f32_16x16x32_bf16 v[90:93], v[148:151], v[188:191], v[90:93]
	v_mfma_f32_16x16x32_bf16 v[78:81], v[140:143], v[202:205], v[78:81]
	v_mfma_f32_16x16x32_bf16 v[74:77], v[148:151], v[202:205], v[74:77]
	v_mfma_f32_16x16x32_bf16 v[126:129], v[144:147], v[176:179], v[126:129]
	v_mfma_f32_16x16x32_bf16 v[122:125], v[152:155], v[176:179], v[122:125]
	v_mfma_f32_16x16x32_bf16 v[110:113], v[144:147], v[184:187], v[110:113]
	v_mfma_f32_16x16x32_bf16 v[106:109], v[152:155], v[184:187], v[106:109]
	v_mfma_f32_16x16x32_bf16 v[94:97], v[144:147], v[198:201], v[94:97]
	v_mfma_f32_16x16x32_bf16 v[90:93], v[152:155], v[198:201], v[90:93]
	v_mfma_f32_16x16x32_bf16 v[78:81], v[144:147], v[206:209], v[78:81]
	v_mfma_f32_16x16x32_bf16 v[74:77], v[152:155], v[206:209], v[74:77]
	s_setprio 0
	s_setprio 1
	v_mfma_f32_16x16x32_bf16 v[118:121], v[156:159], v[172:175], v[118:121]
	v_mfma_f32_16x16x32_bf16 v[114:117], v[164:167], v[172:175], v[114:117]
	v_mfma_f32_16x16x32_bf16 v[102:105], v[156:159], v[180:183], v[102:105]
	v_mfma_f32_16x16x32_bf16 v[98:101], v[164:167], v[180:183], v[98:101]
	v_mfma_f32_16x16x32_bf16 v[86:89], v[156:159], v[188:191], v[86:89]
	v_mfma_f32_16x16x32_bf16 v[82:85], v[164:167], v[188:191], v[82:85]
	v_mfma_f32_16x16x32_bf16 v[70:73], v[156:159], v[202:205], v[70:73]
	v_mfma_f32_16x16x32_bf16 v[66:69], v[164:167], v[202:205], v[66:69]
	v_mfma_f32_16x16x32_bf16 v[118:121], v[160:163], v[176:179], v[118:121]
	v_mfma_f32_16x16x32_bf16 v[114:117], v[168:171], v[176:179], v[114:117]
	v_mfma_f32_16x16x32_bf16 v[102:105], v[160:163], v[184:187], v[102:105]
	v_mfma_f32_16x16x32_bf16 v[98:101], v[168:171], v[184:187], v[98:101]
	v_mfma_f32_16x16x32_bf16 v[86:89], v[160:163], v[198:201], v[86:89]
	v_mfma_f32_16x16x32_bf16 v[82:85], v[168:171], v[198:201], v[82:85]
	v_mfma_f32_16x16x32_bf16 v[70:73], v[160:163], v[206:209], v[70:73]
	v_mfma_f32_16x16x32_bf16 v[66:69], v[168:171], v[206:209], v[66:69]
	s_setprio 0
	s_barrier
; #define PG8_STAGE(bufoff, gbase, voff) do { _Pragma("unroll") for (int _i = 0; _i < 2; ++_i) \
;         __builtin_amdgcn_global_load_lds((const unsigned*)((const char*)(gbase) + (voff)[_i]), (PG8_LAS unsigned*)(lds + (bufoff) + ldsw + _i * 8192), 16, 0, 0); } while (0)
; #define PG8_LDA(dst, b, h) do { _Pragma("unroll") for (int m = 0; m < 4; ++m) _Pragma("unroll") for (int k = 0; k < 2; ++k) dst[m][k] = *(const PG8_LAS bf16x8*)(lds + PG8_SA(b, h) + aoff + m * 2048 + k * 1024); } while (0)
; #define PG8_MMA(ai, bj, At, Bt) do { __builtin_amdgcn_s_setprio(1); _Pragma("unroll") for (int m = 0; m < 4; ++m) _Pragma("unroll") for (int n = 0; n < 2; ++n) _Pragma("unroll") for (int k = 0; k < 2; ++k) \
;         acc[ai][bj][m][n] = __builtin_amdgcn_mfma_f32_16x16x32_bf16(Bt[n][k], At[m][k], acc[ai][bj][m][n], 0, 0, 0); __builtin_amdgcn_s_setprio(0); } while (0)
; #define PG8_WAIT_V(n) asm volatile("s_waitcnt vmcnt(" #n ")" ::: "memory")
; #define PG8_WAIT_L(n) asm volatile("s_waitcnt lgkmcnt(" #n ")" ::: "memory")
; #define PG8_BAR __builtin_amdgcn_s_barrier()
; #define PG8_SCHED __builtin_amdgcn_sched_barrier(0)
; template <class Epi, class Sched, bool ALIGN_EPI = false, bool SP2 = false, bool KHOOK = false>
; __device__ __forceinline__ void gemm_phase(PG8_LAS unsigned char* lds, const Gemm g, const Sched& S, const Epi& E, const int tid_in) {
;     ...
;             PG8_LDA(At, 1, 1); PG8_STAGE(PG8_SB(1, 0), b3, voffB); PG8_STAGE(PG8_SB(1, 1), b3 + hstep, voffB); PG8_STAGE(PG8_SA(1, 0), a3, voffA);
;             PG8_WAIT_V(8); PG8_WAIT_L(0); PG8_BAR; PG8_MMA(1, 0, At, B0); PG8_MMA(1, 1, At, B1); PG8_BAR; PG8_SCHED;
	s_add_i32 s47, s47, s33
	v_lshl_add_u64 v[192:193], v[192:193], 0, s[90:91]
	s_mov_b32 m0, s47
	ds_read_b128 v[172:175], v139 offset:49152
	ds_read_b128 v[176:179], v139 offset:50176
	ds_read_b128 v[180:183], v139 offset:51200
	ds_read_b128 v[184:187], v139 offset:52224
	ds_read_b128 v[188:191], v139 offset:53248
	ds_read_b128 v[198:201], v139 offset:54272
	ds_read_b128 v[202:205], v139 offset:55296
	ds_read_b128 v[206:209], v139 offset:56320
	global_load_lds_dwordx4 v[192:193], off
	s_add_i32 m0, s47, 0x2000
	s_add_u32 s30, s30, 0x80080
	v_lshl_add_u64 v[192:193], v[210:211], 0, s[90:91]
	s_addc_u32 s31, s31, 0
	s_add_i32 s47, s50, s33
	global_load_lds_dwordx4 v[192:193], off
	s_mov_b32 m0, s47
	v_lshl_add_u64 v[192:193], s[30:31], 0, v[32:33]
	global_load_lds_dwordx4 v[192:193], off
	s_add_i32 m0, s47, 0x2000
	v_lshl_add_u64 v[192:193], s[30:31], 0, v[130:131]
	global_load_lds_dwordx4 v[192:193], off
	s_mov_b32 m0, s40
	v_lshl_add_u64 v[192:193], v[212:213], 0, s[90:91]
	global_load_lds_dwordx4 v[192:193], off
	s_mov_b32 m0, s41
	v_lshl_add_u64 v[192:193], v[214:215], 0, s[90:91]
	global_load_lds_dwordx4 v[192:193], off
	s_waitcnt vmcnt(8)
	s_waitcnt lgkmcnt(0)
	s_barrier
	s_setprio 1
	v_mfma_f32_16x16x32_bf16 v[62:65], v[140:143], v[172:175], v[62:65]
	v_mfma_f32_16x16x32_bf16 v[58:61], v[148:151], v[172:175], v[58:61]
	v_mfma_f32_16x16x32_bf16 v[46:49], v[140:143], v[180:183], v[46:49]
	v_mfma_f32_16x16x32_bf16 v[42:45], v[148:151], v[180:183], v[42:45]
	v_mfma_f32_16x16x32_bf16 v[28:31], v[140:143], v[188:191], v[28:31]
	v_mfma_f32_16x16x32_bf16 v[24:27], v[148:151], v[188:191], v[24:27]
	v_mfma_f32_16x16x32_bf16 v[12:15], v[140:143], v[202:205], v[12:15]
	v_mfma_f32_16x16x32_bf16 v[8:11], v[148:151], v[202:205], v[8:11]
	v_mfma_f32_16x16x32_bf16 v[62:65], v[144:147], v[176:179], v[62:65]
	v_mfma_f32_16x16x32_bf16 v[58:61], v[152:155], v[176:179], v[58:61]
	v_mfma_f32_16x16x32_bf16 v[46:49], v[144:147], v[184:187], v[46:49]
	v_mfma_f32_16x16x32_bf16 v[42:45], v[152:155], v[184:187], v[42:45]
	v_mfma_f32_16x16x32_bf16 v[28:31], v[144:147], v[198:201], v[28:31]
	v_mfma_f32_16x16x32_bf16 v[24:27], v[152:155], v[198:201], v[24:27]
	v_mfma_f32_16x16x32_bf16 v[12:15], v[144:147], v[206:209], v[12:15]
	v_mfma_f32_16x16x32_bf16 v[8:11], v[152:155], v[206:209], v[8:11]
	s_setprio 0
	s_setprio 1
	v_mfma_f32_16x16x32_bf16 v[54:57], v[156:159], v[172:175], v[54:57]
	v_mfma_f32_16x16x32_bf16 v[50:53], v[164:167], v[172:175], v[50:53]
	v_mfma_f32_16x16x32_bf16 v[38:41], v[156:159], v[180:183], v[38:41]
	v_mfma_f32_16x16x32_bf16 v[34:37], v[164:167], v[180:183], v[34:37]
	v_mfma_f32_16x16x32_bf16 v[20:23], v[156:159], v[188:191], v[20:23]
	v_mfma_f32_16x16x32_bf16 v[16:19], v[164:167], v[188:191], v[16:19]
	v_mfma_f32_16x16x32_bf16 v[4:7], v[156:159], v[202:205], v[4:7]
	v_mfma_f32_16x16x32_bf16 v[0:3], v[164:167], v[202:205], v[0:3]
	v_mfma_f32_16x16x32_bf16 v[54:57], v[160:163], v[176:179], v[54:57]
	v_mfma_f32_16x16x32_bf16 v[50:53], v[168:171], v[176:179], v[50:53]
	v_mfma_f32_16x16x32_bf16 v[38:41], v[160:163], v[184:187], v[38:41]
	v_mfma_f32_16x16x32_bf16 v[34:37], v[168:171], v[184:187], v[34:37]
	v_mfma_f32_16x16x32_bf16 v[20:23], v[160:163], v[198:201], v[20:23]
	v_mfma_f32_16x16x32_bf16 v[16:19], v[168:171], v[198:201], v[16:19]
	v_mfma_f32_16x16x32_bf16 v[4:7], v[160:163], v[206:209], v[4:7]
	v_mfma_f32_16x16x32_bf16 v[0:3], v[168:171], v[206:209], v[0:3]
	s_setprio 0
	s_barrier
	s_add_i32 s46, s46, 2
	s_add_u32 s26, s26, 0x100
	s_addc_u32 s27, s27, 0
	s_add_u32 s44, s44, 0x100
	s_addc_u32 s45, s45, 0
	s_cmp_gt_u32 s46, 29
	s_cbranch_scc0 .LBB0_1063
	s_and_b64 vcc, exec, s[4:5]
	s_cbranch_vccz .LBB0_1066
	s_barrier

; #define PG8_STAGE(bufoff, gbase, voff) do { _Pragma("unroll") for (int _i = 0; _i < 2; ++_i) \
;         __builtin_amdgcn_global_load_lds((const unsigned*)((const char*)(gbase) + (voff)[_i]), (PG8_LAS unsigned*)(lds + (bufoff) + ldsw + _i * 8192), 16, 0, 0); } while (0)
; #define PG8_LDA(dst, b, h) do { _Pragma("unroll") for (int m = 0; m < 4; ++m) _Pragma("unroll") for (int k = 0; k < 2; ++k) dst[m][k] = *(const PG8_LAS bf16x8*)(lds + PG8_SA(b, h) + aoff + m * 2048 + k * 1024); } while (0)
; #define PG8_LDB(dst, b, h) do { _Pragma("unroll") for (int n = 0; n < 2; ++n) _Pragma("unroll") for (int k = 0; k < 2; ++k) dst[n][k] = *(const PG8_LAS bf16x8*)(lds + PG8_SB(b, h) + boff + n * 2048 + k * 1024); } while (0)
; #define PG8_MMA(ai, bj, At, Bt) do { __builtin_amdgcn_s_setprio(1); _Pragma("unroll") for (int m = 0; m < 4; ++m) _Pragma("unroll") for (int n = 0; n < 2; ++n) _Pragma("unroll") for (int k = 0; k < 2; ++k) \
;         acc[ai][bj][m][n] = __builtin_amdgcn_mfma_f32_16x16x32_bf16(Bt[n][k], At[m][k], acc[ai][bj][m][n], 0, 0, 0); __builtin_amdgcn_s_setprio(0); } while (0)
; #define PG8_WAIT_V(n) asm volatile("s_waitcnt vmcnt(" #n ")" ::: "memory")
; #define PG8_WAIT_L(n) asm volatile("s_waitcnt lgkmcnt(" #n ")" ::: "memory")
; #define PG8_BAR __builtin_amdgcn_s_barrier()
; #define PG8_SCHED __builtin_amdgcn_sched_barrier(0)
; template <class Epi, class Sched, bool ALIGN_EPI = false, bool SP2 = false, bool KHOOK = false>
; __device__ __forceinline__ void gemm_phase(PG8_LAS unsigned char* lds, const Gemm g, const Sched& S, const Epi& E, const int tid_in) {
;     ...
;             PG8_LDB(B0, 0, 0); PG8_LDB(B1, 0, 1); PG8_SCHED; PG8_LDA(At, 0, 0); PG8_STAGE(PG8_SA(1, 1), a1 + hstep, voffA);
;             PG8_WAIT_V(8); PG8_WAIT_L(0); PG8_BAR; PG8_MMA(0, 0, At, B0); PG8_MMA(0, 1, At, B1); PG8_BAR; PG8_SCHED;
;             PG8_LDA(At, 0, 1); PG8_STAGE(PG8_SB(0, 0), b2, voffB); PG8_STAGE(PG8_SB(0, 1), b2 + hstep, voffB); PG8_STAGE(PG8_SA(0, 0), a2, voffA);
;             PG8_WAIT_V(8); PG8_WAIT_L(0); PG8_BAR; PG8_MMA(1, 0, At, B0); PG8_MMA(1, 1, At, B1); PG8_BAR; PG8_SCHED;
;             PG8_LDB(B0, 1, 0); PG8_LDB(B1, 1, 1); PG8_SCHED; PG8_LDA(At, 1, 0); PG8_STAGE(PG8_SA(0, 1), a2 + hstep, voffA);
;             PG8_WAIT_V(8); PG8_WAIT_L(0); PG8_BAR; PG8_MMA(0, 0, At, B0); PG8_MMA(0, 1, At, B1); PG8_BAR; PG8_SCHED;
.LBB0_1086:
	v_cndmask_b32_e64 v172, 0, 1, s[56:57]
	s_add_u32 s56, s14, s46
	s_addc_u32 s57, s15, 0
	s_add_u32 s47, s56, 0x100
	s_addc_u32 s58, s57, 0
	s_and_b64 s[50:51], s[52:53], exec
	s_cselect_b32 s59, s18, s58
	s_cselect_b32 s58, s19, s47
	s_add_u32 s46, s12, s46
	s_addc_u32 s47, s13, 0
	s_add_u32 s50, s46, 0x100
	s_addc_u32 s51, s47, 0
	s_add_i32 s75, 0, 0x10000
	s_and_b64 s[46:47], s[52:53], exec
	s_cselect_b32 s65, s17, s51
	s_cselect_b32 s64, s23, s50
	s_add_i32 s53, 0, 0x14000
	s_add_u32 s70, s56, 0x10080
	s_addc_u32 s71, s57, 0
	s_add_i32 s74, s75, s37
	s_add_i32 m0, s38, 0xc000
	s_add_i32 s81, s38, 0xe000
	s_add_i32 s60, s74, 0x2000
	s_add_u32 s68, s64, 0x10000
	v_add_u32_e32 v152, s75, v137
	v_add_u32_e32 v168, s53, v137
	s_addc_u32 s69, s65, 0
	s_add_i32 s66, s53, s37
	ds_read_b128 v[140:143], v152
	ds_read_b128 v[144:147], v152 offset:1024
	ds_read_b128 v[148:151], v152 offset:2048
	ds_read_b128 v[152:155], v152 offset:3072
	ds_read_b128 v[156:159], v168
	ds_read_b128 v[160:163], v168 offset:1024
	ds_read_b128 v[164:167], v168 offset:2048
	ds_read_b128 v[168:171], v168 offset:3072
	s_add_i32 s61, s66, 0x2000
	s_add_i32 s51, 0, 0x18000
	s_add_i32 s50, 0, 0x1c000
	s_add_u32 s56, s58, 0x10000
	s_addc_u32 s57, s59, 0
	s_add_i32 s47, s51, s37
	s_add_i32 s46, s47, 0x2000
	s_add_u32 s52, s64, 0x10080
	s_addc_u32 s53, s65, 0
	s_add_i32 s79, s50, s37
	s_add_i32 s75, s79, 0x2000
	v_cmp_ne_u32_e32 vcc, 1, v172
	v_lshl_add_u64 v[192:193], s[70:71], 0, v[134:135]
	ds_read_b128 v[172:175], v139
	ds_read_b128 v[176:179], v139 offset:1024
	ds_read_b128 v[180:183], v139 offset:2048
	ds_read_b128 v[184:187], v139 offset:3072
	ds_read_b128 v[188:191], v139 offset:4096
	ds_read_b128 v[198:201], v139 offset:5120
	ds_read_b128 v[202:205], v139 offset:6144
	ds_read_b128 v[206:209], v139 offset:7168
	global_load_lds_dwordx4 v[192:193], off
	s_mov_b32 m0, s81
	v_lshl_add_u64 v[192:193], s[70:71], 0, v[132:133]
	global_load_lds_dwordx4 v[192:193], off
	s_waitcnt vmcnt(8)
	s_waitcnt lgkmcnt(0)
	s_barrier
	s_setprio 1
	v_mfma_f32_16x16x32_bf16 v[126:129], v[140:143], v[172:175], v[126:129]
	v_mfma_f32_16x16x32_bf16 v[122:125], v[148:151], v[172:175], v[122:125]
	v_mfma_f32_16x16x32_bf16 v[118:121], v[140:143], v[180:183], v[118:121]
	v_mfma_f32_16x16x32_bf16 v[114:117], v[148:151], v[180:183], v[114:117]
	v_mfma_f32_16x16x32_bf16 v[102:105], v[140:143], v[188:191], v[102:105]
	v_mfma_f32_16x16x32_bf16 v[98:101], v[148:151], v[188:191], v[98:101]
	v_mfma_f32_16x16x32_bf16 v[86:89], v[140:143], v[202:205], v[86:89]
	v_mfma_f32_16x16x32_bf16 v[82:85], v[148:151], v[202:205], v[82:85]
	v_mfma_f32_16x16x32_bf16 v[126:129], v[144:147], v[176:179], v[126:129]
	v_mfma_f32_16x16x32_bf16 v[122:125], v[152:155], v[176:179], v[122:125]
	v_mfma_f32_16x16x32_bf16 v[118:121], v[144:147], v[184:187], v[118:121]
	v_mfma_f32_16x16x32_bf16 v[114:117], v[152:155], v[184:187], v[114:117]
	v_mfma_f32_16x16x32_bf16 v[102:105], v[144:147], v[198:201], v[102:105]
	v_mfma_f32_16x16x32_bf16 v[98:101], v[152:155], v[198:201], v[98:101]
	v_mfma_f32_16x16x32_bf16 v[86:89], v[144:147], v[206:209], v[86:89]
	v_mfma_f32_16x16x32_bf16 v[82:85], v[152:155], v[206:209], v[82:85]
	s_setprio 0
	s_setprio 1
	v_mfma_f32_16x16x32_bf16 v[110:113], v[156:159], v[172:175], v[110:113]
	v_mfma_f32_16x16x32_bf16 v[106:109], v[164:167], v[172:175], v[106:109]
	v_mfma_f32_16x16x32_bf16 v[94:97], v[156:159], v[180:183], v[94:97]
	v_mfma_f32_16x16x32_bf16 v[90:93], v[164:167], v[180:183], v[90:93]
	v_mfma_f32_16x16x32_bf16 v[78:81], v[156:159], v[188:191], v[78:81]
	v_mfma_f32_16x16x32_bf16 v[74:77], v[164:167], v[188:191], v[74:77]
	v_mfma_f32_16x16x32_bf16 v[70:73], v[156:159], v[202:205], v[70:73]
	v_mfma_f32_16x16x32_bf16 v[66:69], v[164:167], v[202:205], v[66:69]
	v_mfma_f32_16x16x32_bf16 v[110:113], v[160:163], v[176:179], v[110:113]
	v_mfma_f32_16x16x32_bf16 v[106:109], v[168:171], v[176:179], v[106:109]
	v_mfma_f32_16x16x32_bf16 v[94:97], v[160:163], v[184:187], v[94:97]
	v_mfma_f32_16x16x32_bf16 v[90:93], v[168:171], v[184:187], v[90:93]
	v_mfma_f32_16x16x32_bf16 v[78:81], v[160:163], v[198:201], v[78:81]
	v_mfma_f32_16x16x32_bf16 v[74:77], v[168:171], v[198:201], v[74:77]
	v_mfma_f32_16x16x32_bf16 v[70:73], v[160:163], v[206:209], v[70:73]
	v_mfma_f32_16x16x32_bf16 v[66:69], v[168:171], v[206:209], v[66:69]
	s_setprio 0
	s_barrier
	s_mov_b32 m0, s74
	v_lshl_add_u64 v[192:193], s[64:65], 0, v[32:33]
	ds_read_b128 v[172:175], v139 offset:16384
	ds_read_b128 v[176:179], v139 offset:17408
	ds_read_b128 v[180:183], v139 offset:18432
	ds_read_b128 v[184:187], v139 offset:19456
	ds_read_b128 v[188:191], v139 offset:20480
	ds_read_b128 v[198:201], v139 offset:21504
	ds_read_b128 v[202:205], v139 offset:22528
	ds_read_b128 v[206:209], v139 offset:23552
	global_load_lds_dwordx4 v[192:193], off
	v_lshl_add_u64 v[210:211], s[64:65], 0, v[130:131]
	s_mov_b32 m0, s60
	v_lshl_add_u64 v[212:213], s[68:69], 0, v[32:33]
	global_load_lds_dwordx4 v[210:211], off
	s_mov_b32 m0, s66
	v_lshl_add_u64 v[214:215], s[58:59], 0, v[132:133]
	global_load_lds_dwordx4 v[212:213], off
	s_mov_b32 m0, s61
	v_lshl_add_u64 v[212:213], s[68:69], 0, v[130:131]
	global_load_lds_dwordx4 v[212:213], off
	s_mov_b32 m0, s38
	v_lshl_add_u64 v[212:213], s[58:59], 0, v[134:135]
	global_load_lds_dwordx4 v[212:213], off
	s_mov_b32 m0, s39
	s_nop 0
	global_load_lds_dwordx4 v[214:215], off
	s_waitcnt vmcnt(8)
	s_waitcnt lgkmcnt(0)
	s_barrier
; #define PG8_STAGE(bufoff, gbase, voff) do { _Pragma("unroll") for (int _i = 0; _i < 2; ++_i) \
;         __builtin_amdgcn_global_load_lds((const unsigned*)((const char*)(gbase) + (voff)[_i]), (PG8_LAS unsigned*)(lds + (bufoff) + ldsw + _i * 8192), 16, 0, 0); } while (0)
; #define PG8_LDA(dst, b, h) do { _Pragma("unroll") for (int m = 0; m < 4; ++m) _Pragma("unroll") for (int k = 0; k < 2; ++k) dst[m][k] = *(const PG8_LAS bf16x8*)(lds + PG8_SA(b, h) + aoff + m * 2048 + k * 1024); } while (0)
; #define PG8_LDB(dst, b, h) do { _Pragma("unroll") for (int n = 0; n < 2; ++n) _Pragma("unroll") for (int k = 0; k < 2; ++k) dst[n][k] = *(const PG8_LAS bf16x8*)(lds + PG8_SB(b, h) + boff + n * 2048 + k * 1024); } while (0)
; #define PG8_MMA(ai, bj, At, Bt) do { __builtin_amdgcn_s_setprio(1); _Pragma("unroll") for (int m = 0; m < 4; ++m) _Pragma("unroll") for (int n = 0; n < 2; ++n) _Pragma("unroll") for (int k = 0; k < 2; ++k) \
;         acc[ai][bj][m][n] = __builtin_amdgcn_mfma_f32_16x16x32_bf16(Bt[n][k], At[m][k], acc[ai][bj][m][n], 0, 0, 0); __builtin_amdgcn_s_setprio(0); } while (0)
; #define PG8_WAIT_V(n) asm volatile("s_waitcnt vmcnt(" #n ")" ::: "memory")
; #define PG8_WAIT_L(n) asm volatile("s_waitcnt lgkmcnt(" #n ")" ::: "memory")
; #define PG8_BAR __builtin_amdgcn_s_barrier()
; #define PG8_SCHED __builtin_amdgcn_sched_barrier(0)
; template <class Epi, class Sched, bool ALIGN_EPI = false, bool SP2 = false, bool KHOOK = false>
; __device__ __forceinline__ void gemm_phase(PG8_LAS unsigned char* lds, const Gemm g, const Sched& S, const Epi& E, const int tid_in) {
;     ...
;             PG8_WAIT_V(8); PG8_WAIT_L(0); PG8_BAR; PG8_MMA(1, 0, At, B0); PG8_MMA(1, 1, At, B1); PG8_BAR; PG8_SCHED;
;             PG8_LDB(B0, 1, 0); PG8_LDB(B1, 1, 1); PG8_SCHED; PG8_LDA(At, 1, 0); PG8_STAGE(PG8_SA(0, 1), a2 + hstep, voffA);
;             PG8_WAIT_V(8); PG8_WAIT_L(0); PG8_BAR; PG8_MMA(0, 0, At, B0); PG8_MMA(0, 1, At, B1); PG8_BAR; PG8_SCHED;
	s_setprio 1
	v_mfma_f32_16x16x32_bf16 v[62:65], v[140:143], v[172:175], v[62:65]
	v_mfma_f32_16x16x32_bf16 v[58:61], v[148:151], v[172:175], v[58:61]
	v_mfma_f32_16x16x32_bf16 v[54:57], v[140:143], v[180:183], v[54:57]
	v_mfma_f32_16x16x32_bf16 v[50:53], v[148:151], v[180:183], v[50:53]
	v_mfma_f32_16x16x32_bf16 v[38:41], v[140:143], v[188:191], v[38:41]
	v_mfma_f32_16x16x32_bf16 v[34:37], v[148:151], v[188:191], v[34:37]
	v_mfma_f32_16x16x32_bf16 v[20:23], v[140:143], v[202:205], v[20:23]
	v_mfma_f32_16x16x32_bf16 v[16:19], v[148:151], v[202:205], v[16:19]
	v_mfma_f32_16x16x32_bf16 v[62:65], v[144:147], v[176:179], v[62:65]
	v_mfma_f32_16x16x32_bf16 v[58:61], v[152:155], v[176:179], v[58:61]
	v_mfma_f32_16x16x32_bf16 v[54:57], v[144:147], v[184:187], v[54:57]
	v_mfma_f32_16x16x32_bf16 v[50:53], v[152:155], v[184:187], v[50:53]
	v_mfma_f32_16x16x32_bf16 v[38:41], v[144:147], v[198:201], v[38:41]
	v_mfma_f32_16x16x32_bf16 v[34:37], v[152:155], v[198:201], v[34:37]
	v_mfma_f32_16x16x32_bf16 v[20:23], v[144:147], v[206:209], v[20:23]
	v_mfma_f32_16x16x32_bf16 v[16:19], v[152:155], v[206:209], v[16:19]
	s_setprio 0
	s_setprio 1
	v_mfma_f32_16x16x32_bf16 v[46:49], v[156:159], v[172:175], v[46:49]
	v_mfma_f32_16x16x32_bf16 v[42:45], v[164:167], v[172:175], v[42:45]
	v_mfma_f32_16x16x32_bf16 v[28:31], v[156:159], v[180:183], v[28:31]
	v_mfma_f32_16x16x32_bf16 v[24:27], v[164:167], v[180:183], v[24:27]
	v_mfma_f32_16x16x32_bf16 v[12:15], v[156:159], v[188:191], v[12:15]
	v_mfma_f32_16x16x32_bf16 v[8:11], v[164:167], v[188:191], v[8:11]
	v_mfma_f32_16x16x32_bf16 v[4:7], v[156:159], v[202:205], v[4:7]
	v_mfma_f32_16x16x32_bf16 v[0:3], v[164:167], v[202:205], v[0:3]
	v_mfma_f32_16x16x32_bf16 v[46:49], v[160:163], v[176:179], v[46:49]
	v_mfma_f32_16x16x32_bf16 v[42:45], v[168:171], v[176:179], v[42:45]
	v_mfma_f32_16x16x32_bf16 v[28:31], v[160:163], v[184:187], v[28:31]
	v_mfma_f32_16x16x32_bf16 v[24:27], v[168:171], v[184:187], v[24:27]
	v_mfma_f32_16x16x32_bf16 v[12:15], v[160:163], v[198:201], v[12:15]
	v_mfma_f32_16x16x32_bf16 v[8:11], v[168:171], v[198:201], v[8:11]
	v_mfma_f32_16x16x32_bf16 v[4:7], v[160:163], v[206:209], v[4:7]
	v_mfma_f32_16x16x32_bf16 v[0:3], v[168:171], v[206:209], v[0:3]
	s_setprio 0
	s_barrier
	v_add_u32_e32 v152, s51, v137
	v_add_u32_e32 v168, s50, v137
	ds_read_b128 v[140:143], v152
	ds_read_b128 v[144:147], v152 offset:1024
	ds_read_b128 v[148:151], v152 offset:2048
	ds_read_b128 v[152:155], v152 offset:3072
	ds_read_b128 v[156:159], v168
	ds_read_b128 v[160:163], v168 offset:1024
	ds_read_b128 v[164:167], v168 offset:2048
	ds_read_b128 v[168:171], v168 offset:3072
	s_mov_b32 m0, s40
	v_lshl_add_u64 v[216:217], s[56:57], 0, v[134:135]
	ds_read_b128 v[172:175], v139 offset:32768
	ds_read_b128 v[176:179], v139 offset:33792
	ds_read_b128 v[180:183], v139 offset:34816
	ds_read_b128 v[184:187], v139 offset:35840
	ds_read_b128 v[188:191], v139 offset:36864
	ds_read_b128 v[198:201], v139 offset:37888
	ds_read_b128 v[202:205], v139 offset:38912
	ds_read_b128 v[206:209], v139 offset:39936
	global_load_lds_dwordx4 v[216:217], off
	s_mov_b32 m0, s41
	v_lshl_add_u64 v[216:217], s[56:57], 0, v[132:133]
	global_load_lds_dwordx4 v[216:217], off
	s_waitcnt vmcnt(8)
	s_waitcnt lgkmcnt(0)
	s_barrier
	s_setprio 1
	v_mfma_f32_16x16x32_bf16 v[126:129], v[140:143], v[172:175], v[126:129]
	v_mfma_f32_16x16x32_bf16 v[122:125], v[148:151], v[172:175], v[122:125]
	v_mfma_f32_16x16x32_bf16 v[118:121], v[140:143], v[180:183], v[118:121]
	v_mfma_f32_16x16x32_bf16 v[114:117], v[148:151], v[180:183], v[114:117]
	v_mfma_f32_16x16x32_bf16 v[102:105], v[140:143], v[188:191], v[102:105]
	v_mfma_f32_16x16x32_bf16 v[98:101], v[148:151], v[188:191], v[98:101]
	v_mfma_f32_16x16x32_bf16 v[86:89], v[140:143], v[202:205], v[86:89]
	v_mfma_f32_16x16x32_bf16 v[82:85], v[148:151], v[202:205], v[82:85]
	v_mfma_f32_16x16x32_bf16 v[126:129], v[144:147], v[176:179], v[126:129]
	v_mfma_f32_16x16x32_bf16 v[122:125], v[152:155], v[176:179], v[122:125]
	v_mfma_f32_16x16x32_bf16 v[118:121], v[144:147], v[184:187], v[118:121]
	v_mfma_f32_16x16x32_bf16 v[114:117], v[152:155], v[184:187], v[114:117]
	v_mfma_f32_16x16x32_bf16 v[102:105], v[144:147], v[198:201], v[102:105]
	v_mfma_f32_16x16x32_bf16 v[98:101], v[152:155], v[198:201], v[98:101]
	v_mfma_f32_16x16x32_bf16 v[86:89], v[144:147], v[206:209], v[86:89]
	v_mfma_f32_16x16x32_bf16 v[82:85], v[152:155], v[206:209], v[82:85]
	s_setprio 0
	s_setprio 1
	v_mfma_f32_16x16x32_bf16 v[110:113], v[156:159], v[172:175], v[110:113]
	v_mfma_f32_16x16x32_bf16 v[106:109], v[164:167], v[172:175], v[106:109]
	v_mfma_f32_16x16x32_bf16 v[94:97], v[156:159], v[180:183], v[94:97]
	v_mfma_f32_16x16x32_bf16 v[90:93], v[164:167], v[180:183], v[90:93]
	v_mfma_f32_16x16x32_bf16 v[78:81], v[156:159], v[188:191], v[78:81]
	v_mfma_f32_16x16x32_bf16 v[74:77], v[164:167], v[188:191], v[74:77]
	v_mfma_f32_16x16x32_bf16 v[70:73], v[156:159], v[202:205], v[70:73]
	v_mfma_f32_16x16x32_bf16 v[66:69], v[164:167], v[202:205], v[66:69]
	v_mfma_f32_16x16x32_bf16 v[110:113], v[160:163], v[176:179], v[110:113]
	v_mfma_f32_16x16x32_bf16 v[106:109], v[168:171], v[176:179], v[106:109]
	v_mfma_f32_16x16x32_bf16 v[94:97], v[160:163], v[184:187], v[94:97]
	v_mfma_f32_16x16x32_bf16 v[90:93], v[168:171], v[184:187], v[90:93]
	v_mfma_f32_16x16x32_bf16 v[78:81], v[160:163], v[198:201], v[78:81]
	v_mfma_f32_16x16x32_bf16 v[74:77], v[168:171], v[198:201], v[74:77]
	v_mfma_f32_16x16x32_bf16 v[70:73], v[160:163], v[206:209], v[70:73]
	v_mfma_f32_16x16x32_bf16 v[66:69], v[168:171], v[206:209], v[66:69]
	s_setprio 0
	s_barrier
; #define PG8_STAGE(bufoff, gbase, voff) do { _Pragma("unroll") for (int _i = 0; _i < 2; ++_i) \
;         __builtin_amdgcn_global_load_lds((const unsigned*)((const char*)(gbase) + (voff)[_i]), (PG8_LAS unsigned*)(lds + (bufoff) + ldsw + _i * 8192), 16, 0, 0); } while (0)
; #define PG8_LDA(dst, b, h) do { _Pragma("unroll") for (int m = 0; m < 4; ++m) _Pragma("unroll") for (int k = 0; k < 2; ++k) dst[m][k] = *(const PG8_LAS bf16x8*)(lds + PG8_SA(b, h) + aoff + m * 2048 + k * 1024); } while (0)
; #define PG8_MMA(ai, bj, At, Bt) do { __builtin_amdgcn_s_setprio(1); _Pragma("unroll") for (int m = 0; m < 4; ++m) _Pragma("unroll") for (int n = 0; n < 2; ++n) _Pragma("unroll") for (int k = 0; k < 2; ++k) \
;         acc[ai][bj][m][n] = __builtin_amdgcn_mfma_f32_16x16x32_bf16(Bt[n][k], At[m][k], acc[ai][bj][m][n], 0, 0, 0); __builtin_amdgcn_s_setprio(0); } while (0)
; #define PG8_WAIT_V(n) asm volatile("s_waitcnt vmcnt(" #n ")" ::: "memory")
; #define PG8_WAIT_L(n) asm volatile("s_waitcnt lgkmcnt(" #n ")" ::: "memory")
; #define PG8_BAR __builtin_amdgcn_s_barrier()
; #define PG8_SCHED __builtin_amdgcn_sched_barrier(0)
; template <class Epi, class Sched, bool ALIGN_EPI = false, bool SP2 = false, bool KHOOK = false>
; __device__ __forceinline__ void gemm_phase(PG8_LAS unsigned char* lds, const Gemm g, const Sched& S, const Epi& E, const int tid_in) {
;     ...
;             PG8_LDA(At, 1, 1); PG8_STAGE(PG8_SB(1, 0), b3, voffB); PG8_STAGE(PG8_SB(1, 1), b3 + hstep, voffB); PG8_STAGE(PG8_SA(1, 0), a3, voffA);
;             PG8_WAIT_V(8); PG8_WAIT_L(0); PG8_BAR; PG8_MMA(1, 0, At, B0); PG8_MMA(1, 1, At, B1); PG8_BAR; PG8_SCHED;
	s_mov_b32 m0, s47
	v_lshl_add_u64 v[192:193], v[192:193], 0, s[90:91]
	ds_read_b128 v[172:175], v139 offset:49152
	ds_read_b128 v[176:179], v139 offset:50176
	ds_read_b128 v[180:183], v139 offset:51200
	ds_read_b128 v[184:187], v139 offset:52224
	ds_read_b128 v[188:191], v139 offset:53248
	ds_read_b128 v[198:201], v139 offset:54272
	ds_read_b128 v[202:205], v139 offset:55296
	ds_read_b128 v[206:209], v139 offset:56320
	global_load_lds_dwordx4 v[192:193], off
	s_mov_b32 m0, s46
	v_lshl_add_u64 v[192:193], v[210:211], 0, s[90:91]
	global_load_lds_dwordx4 v[192:193], off
	s_mov_b32 m0, s79
	v_lshl_add_u64 v[192:193], s[52:53], 0, v[32:33]
	global_load_lds_dwordx4 v[192:193], off
	s_mov_b32 m0, s75
	v_lshl_add_u64 v[192:193], s[52:53], 0, v[130:131]
	global_load_lds_dwordx4 v[192:193], off
	s_mov_b32 m0, s24
	v_lshl_add_u64 v[192:193], v[212:213], 0, s[90:91]
	global_load_lds_dwordx4 v[192:193], off
	s_mov_b32 m0, s25
	v_lshl_add_u64 v[192:193], v[214:215], 0, s[90:91]
	global_load_lds_dwordx4 v[192:193], off
	s_waitcnt vmcnt(8)
	s_waitcnt lgkmcnt(0)
	s_barrier
	s_setprio 1
	v_mfma_f32_16x16x32_bf16 v[62:65], v[140:143], v[172:175], v[62:65]
	v_mfma_f32_16x16x32_bf16 v[58:61], v[148:151], v[172:175], v[58:61]
	v_mfma_f32_16x16x32_bf16 v[54:57], v[140:143], v[180:183], v[54:57]
	v_mfma_f32_16x16x32_bf16 v[50:53], v[148:151], v[180:183], v[50:53]
	v_mfma_f32_16x16x32_bf16 v[38:41], v[140:143], v[188:191], v[38:41]
	v_mfma_f32_16x16x32_bf16 v[34:37], v[148:151], v[188:191], v[34:37]
	v_mfma_f32_16x16x32_bf16 v[20:23], v[140:143], v[202:205], v[20:23]
	v_mfma_f32_16x16x32_bf16 v[16:19], v[148:151], v[202:205], v[16:19]
	v_mfma_f32_16x16x32_bf16 v[62:65], v[144:147], v[176:179], v[62:65]
	v_mfma_f32_16x16x32_bf16 v[58:61], v[152:155], v[176:179], v[58:61]
	v_mfma_f32_16x16x32_bf16 v[54:57], v[144:147], v[184:187], v[54:57]
	v_mfma_f32_16x16x32_bf16 v[50:53], v[152:155], v[184:187], v[50:53]
	v_mfma_f32_16x16x32_bf16 v[38:41], v[144:147], v[198:201], v[38:41]
	v_mfma_f32_16x16x32_bf16 v[34:37], v[152:155], v[198:201], v[34:37]
	v_mfma_f32_16x16x32_bf16 v[20:23], v[144:147], v[206:209], v[20:23]
	v_mfma_f32_16x16x32_bf16 v[16:19], v[152:155], v[206:209], v[16:19]
	s_setprio 0
	s_setprio 1
	v_mfma_f32_16x16x32_bf16 v[46:49], v[156:159], v[172:175], v[46:49]
	v_mfma_f32_16x16x32_bf16 v[42:45], v[164:167], v[172:175], v[42:45]
	v_mfma_f32_16x16x32_bf16 v[28:31], v[156:159], v[180:183], v[28:31]
	v_mfma_f32_16x16x32_bf16 v[24:27], v[164:167], v[180:183], v[24:27]
	v_mfma_f32_16x16x32_bf16 v[12:15], v[156:159], v[188:191], v[12:15]
	v_mfma_f32_16x16x32_bf16 v[8:11], v[164:167], v[188:191], v[8:11]
	v_mfma_f32_16x16x32_bf16 v[4:7], v[156:159], v[202:205], v[4:7]
	v_mfma_f32_16x16x32_bf16 v[0:3], v[164:167], v[202:205], v[0:3]
	v_mfma_f32_16x16x32_bf16 v[46:49], v[160:163], v[176:179], v[46:49]
	v_mfma_f32_16x16x32_bf16 v[42:45], v[168:171], v[176:179], v[42:45]
	v_mfma_f32_16x16x32_bf16 v[28:31], v[160:163], v[184:187], v[28:31]
	v_mfma_f32_16x16x32_bf16 v[24:27], v[168:171], v[184:187], v[24:27]
	v_mfma_f32_16x16x32_bf16 v[12:15], v[160:163], v[198:201], v[12:15]
	v_mfma_f32_16x16x32_bf16 v[8:11], v[168:171], v[198:201], v[8:11]
	v_mfma_f32_16x16x32_bf16 v[4:7], v[160:163], v[206:209], v[4:7]
	v_mfma_f32_16x16x32_bf16 v[0:3], v[168:171], v[206:209], v[0:3]
	s_setprio 0
	s_barrier
	s_movk_i32 s46, 0x100
	s_mov_b64 s[56:57], 0
	s_mov_b64 s[52:53], -1
	s_cbranch_vccz .LBB0_1086
	s_and_b64 vcc, exec, s[10:11]
	s_cbranch_vccz .LBB0_1089
	s_barrier

; #define PG8_STAGE(bufoff, gbase, voff) do { _Pragma("unroll") for (int _i = 0; _i < 2; ++_i) \
;         __builtin_amdgcn_global_load_lds((const unsigned*)((const char*)(gbase) + (voff)[_i]), (PG8_LAS unsigned*)(lds + (bufoff) + ldsw + _i * 8192), 16, 0, 0); } while (0)
; #define PG8_LDA(dst, b, h) do { _Pragma("unroll") for (int m = 0; m < 4; ++m) _Pragma("unroll") for (int k = 0; k < 2; ++k) dst[m][k] = *(const PG8_LAS bf16x8*)(lds + PG8_SA(b, h) + aoff + m * 2048 + k * 1024); } while (0)
; #define PG8_LDB(dst, b, h) do { _Pragma("unroll") for (int n = 0; n < 2; ++n) _Pragma("unroll") for (int k = 0; k < 2; ++k) dst[n][k] = *(const PG8_LAS bf16x8*)(lds + PG8_SB(b, h) + boff + n * 2048 + k * 1024); } while (0)
; #define PG8_MMA(ai, bj, At, Bt) do { __builtin_amdgcn_s_setprio(1); _Pragma("unroll") for (int m = 0; m < 4; ++m) _Pragma("unroll") for (int n = 0; n < 2; ++n) _Pragma("unroll") for (int k = 0; k < 2; ++k) \
;         acc[ai][bj][m][n] = __builtin_amdgcn_mfma_f32_16x16x32_bf16(Bt[n][k], At[m][k], acc[ai][bj][m][n], 0, 0, 0); __builtin_amdgcn_s_setprio(0); } while (0)
; #define PG8_WAIT_V(n) asm volatile("s_waitcnt vmcnt(" #n ")" ::: "memory")
; template <class Epi, class Sched, bool ALIGN_EPI = false, bool SP2 = false, bool KHOOK = false>
; __device__ __forceinline__ void gemm_phase(PG8_LAS unsigned char* lds, const Gemm g, const Sched& S, const Epi& E, const int tid_in) {
;     ...
;         for (int t = 0; t < nt; t += 2) {
;             const bool last = (t == nt - 2);
;             const char* a1 = cA + (size_t)(t + 1) * kstep;
;             const char* a2 = last ? nA : cA + (size_t)(t + 2) * kstep; const char* b2 = last ? nB : cB + (size_t)(t + 2) * kstep;
;             const char* a3 = a2 + kstep; const char* b3 = b2 + kstep;
;             if (last && has_next) S.a_ready(nxt);
;             if constexpr (SP2) {
;             PG8_LDB(B0, 0, 0); PG8_LDB(B1, 0, 1); PG8_SCHED; PG8_LDA(At, 0, 0); PG8_STAGE(PG8_SA(1, 1), a1 + hstep, voffA);
;             PG8_WAIT_V(8); PG8_WAIT_L(0); PG8_BAR; PG8_MMA(0, 0, At, B0); PG8_MMA(0, 1, At, B1); PG8_BAR; PG8_SCHED;
;             PG8_LDA(At, 0, 1); PG8_STAGE(PG8_SB(0, 0), b2, voffB); PG8_STAGE(PG8_SB(0, 1), b2 + hstep, voffB); PG8_STAGE(PG8_SA(0, 0), a2, voffA);
;             PG8_WAIT_V(8); PG8_WAIT_L(0); PG8_BAR; PG8_MMA(1, 0, At, B0); PG8_MMA(1, 1, At, B1); PG8_BAR; PG8_SCHED;
.LBB0_1170:
	s_add_u32 s26, s10, s22
	s_addc_u32 s27, s11, s23
	s_add_u32 s26, s26, 0x100
	s_addc_u32 s27, s27, 0
	s_add_u32 s51, s18, s22
	s_addc_u32 s52, s19, s23
	s_add_i32 s53, 0, 0x10000
	s_cmpk_eq_i32 s22, 0x2b00
	s_cselect_b32 s31, s17, s27
	s_cselect_b32 s30, s16, s26
	s_cselect_b32 s27, s15, s52
	s_cselect_b32 s26, s14, s51
	s_add_i32 s51, 0, 0x14000
	v_add_u32_e32 v158, s53, v144
	v_add_u32_e32 v170, s51, v144
	ds_read_b128 v[146:149], v158
	ds_read_b128 v[150:153], v158 offset:1024
	ds_read_b128 v[154:157], v158 offset:2048
	ds_read_b128 v[158:161], v158 offset:3072
	ds_read_b128 v[162:165], v170
	ds_read_b128 v[166:169], v170 offset:1024
	ds_read_b128 v[176:179], v170 offset:2048
	ds_read_b128 v[180:183], v170 offset:3072
	v_lshl_add_u64 v[170:171], v[140:141], 0, s[22:23]
	s_add_i32 m0, s40, 0xc000
	ds_read_b128 v[184:187], v145
	ds_read_b128 v[188:191], v145 offset:1024
	ds_read_b128 v[198:201], v145 offset:2048
	ds_read_b128 v[202:205], v145 offset:3072
	ds_read_b128 v[206:209], v145 offset:4096
	ds_read_b128 v[210:213], v145 offset:5120
	ds_read_b128 v[214:217], v145 offset:6144
	ds_read_b128 v[218:221], v145 offset:7168
	global_load_lds_dwordx4 v[170:171], off
	s_add_i32 m0, s40, 0xe000
	v_lshl_add_u64 v[170:171], v[142:143], 0, s[22:23]
	global_load_lds_dwordx4 v[170:171], off
	s_waitcnt vmcnt(8)
	s_waitcnt lgkmcnt(0)
	s_barrier
	s_setprio 1
	v_mfma_f32_16x16x32_bf16 v[118:121], v[146:149], v[184:187], v[118:121]
	v_mfma_f32_16x16x32_bf16 v[114:117], v[154:157], v[184:187], v[114:117]
	v_mfma_f32_16x16x32_bf16 v[134:137], v[146:149], v[198:201], v[134:137]
	v_mfma_f32_16x16x32_bf16 v[130:133], v[154:157], v[198:201], v[130:133]
	v_mfma_f32_16x16x32_bf16 v[94:97], v[146:149], v[206:209], v[94:97]
	v_mfma_f32_16x16x32_bf16 v[90:93], v[154:157], v[206:209], v[90:93]
	v_mfma_f32_16x16x32_bf16 v[78:81], v[146:149], v[214:217], v[78:81]
	v_mfma_f32_16x16x32_bf16 v[74:77], v[154:157], v[214:217], v[74:77]
	v_mfma_f32_16x16x32_bf16 v[118:121], v[150:153], v[188:191], v[118:121]
	v_mfma_f32_16x16x32_bf16 v[114:117], v[158:161], v[188:191], v[114:117]
	v_mfma_f32_16x16x32_bf16 v[134:137], v[150:153], v[202:205], v[134:137]
	v_mfma_f32_16x16x32_bf16 v[130:133], v[158:161], v[202:205], v[130:133]
	v_mfma_f32_16x16x32_bf16 v[94:97], v[150:153], v[210:213], v[94:97]
	v_mfma_f32_16x16x32_bf16 v[90:93], v[158:161], v[210:213], v[90:93]
	v_mfma_f32_16x16x32_bf16 v[78:81], v[150:153], v[218:221], v[78:81]
	v_mfma_f32_16x16x32_bf16 v[74:77], v[158:161], v[218:221], v[74:77]
	s_setprio 0
	s_setprio 1
	v_mfma_f32_16x16x32_bf16 v[102:105], v[162:165], v[184:187], v[102:105]
	v_mfma_f32_16x16x32_bf16 v[98:101], v[176:179], v[184:187], v[98:101]
	v_mfma_f32_16x16x32_bf16 v[110:113], v[162:165], v[198:201], v[110:113]
	v_mfma_f32_16x16x32_bf16 v[106:109], v[176:179], v[198:201], v[106:109]
	v_mfma_f32_16x16x32_bf16 v[86:89], v[162:165], v[206:209], v[86:89]
	v_mfma_f32_16x16x32_bf16 v[82:85], v[176:179], v[206:209], v[82:85]
	v_mfma_f32_16x16x32_bf16 v[70:73], v[162:165], v[214:217], v[70:73]
	v_mfma_f32_16x16x32_bf16 v[66:69], v[176:179], v[214:217], v[66:69]
	v_mfma_f32_16x16x32_bf16 v[102:105], v[166:169], v[188:191], v[102:105]
	v_mfma_f32_16x16x32_bf16 v[98:101], v[180:183], v[188:191], v[98:101]
	v_mfma_f32_16x16x32_bf16 v[110:113], v[166:169], v[202:205], v[110:113]
	v_mfma_f32_16x16x32_bf16 v[106:109], v[180:183], v[202:205], v[106:109]
	v_mfma_f32_16x16x32_bf16 v[86:89], v[166:169], v[210:213], v[86:89]
	v_mfma_f32_16x16x32_bf16 v[82:85], v[180:183], v[210:213], v[82:85]
	v_mfma_f32_16x16x32_bf16 v[70:73], v[166:169], v[218:221], v[70:73]
	v_mfma_f32_16x16x32_bf16 v[66:69], v[180:183], v[218:221], v[66:69]
	s_setprio 0
	s_barrier
	s_add_i32 s52, s53, s39
	v_lshl_add_u64 v[170:171], s[26:27], 0, v[32:33]
	s_mov_b32 m0, s52
	ds_read_b128 v[184:187], v145 offset:16384
	ds_read_b128 v[188:191], v145 offset:17408
	ds_read_b128 v[198:201], v145 offset:18432
	ds_read_b128 v[202:205], v145 offset:19456
	ds_read_b128 v[206:209], v145 offset:20480
	ds_read_b128 v[210:213], v145 offset:21504
	ds_read_b128 v[214:217], v145 offset:22528
	ds_read_b128 v[218:221], v145 offset:23552
	global_load_lds_dwordx4 v[170:171], off
	s_add_i32 m0, s52, 0x2000
	s_add_u32 s52, s26, 0x160000
	v_lshl_add_u64 v[192:193], s[26:27], 0, v[122:123]
	s_addc_u32 s53, s27, 0
	s_add_i32 s51, s51, s39
	global_load_lds_dwordx4 v[192:193], off
	v_lshl_add_u64 v[222:223], s[52:53], 0, v[32:33]
	s_mov_b32 m0, s51
	v_lshl_add_u64 v[224:225], s[30:31], 0, v[124:125]
	global_load_lds_dwordx4 v[222:223], off
	s_add_i32 m0, s51, 0x2000
	v_lshl_add_u64 v[222:223], s[52:53], 0, v[122:123]
	global_load_lds_dwordx4 v[222:223], off
	s_mov_b32 m0, s40
	v_lshl_add_u64 v[222:223], s[30:31], 0, v[126:127]
	global_load_lds_dwordx4 v[222:223], off
	s_mov_b32 m0, s41
	s_nop 0
	global_load_lds_dwordx4 v[224:225], off
	s_waitcnt vmcnt(8)
	s_waitcnt lgkmcnt(0)
	s_barrier
; #define PG8_STAGE(bufoff, gbase, voff) do { _Pragma("unroll") for (int _i = 0; _i < 2; ++_i) \
;         __builtin_amdgcn_global_load_lds((const unsigned*)((const char*)(gbase) + (voff)[_i]), (PG8_LAS unsigned*)(lds + (bufoff) + ldsw + _i * 8192), 16, 0, 0); } while (0)
; #define PG8_LDA(dst, b, h) do { _Pragma("unroll") for (int m = 0; m < 4; ++m) _Pragma("unroll") for (int k = 0; k < 2; ++k) dst[m][k] = *(const PG8_LAS bf16x8*)(lds + PG8_SA(b, h) + aoff + m * 2048 + k * 1024); } while (0)
; #define PG8_LDB(dst, b, h) do { _Pragma("unroll") for (int n = 0; n < 2; ++n) _Pragma("unroll") for (int k = 0; k < 2; ++k) dst[n][k] = *(const PG8_LAS bf16x8*)(lds + PG8_SB(b, h) + boff + n * 2048 + k * 1024); } while (0)
; #define PG8_MMA(ai, bj, At, Bt) do { __builtin_amdgcn_s_setprio(1); _Pragma("unroll") for (int m = 0; m < 4; ++m) _Pragma("unroll") for (int n = 0; n < 2; ++n) _Pragma("unroll") for (int k = 0; k < 2; ++k) \
;         acc[ai][bj][m][n] = __builtin_amdgcn_mfma_f32_16x16x32_bf16(Bt[n][k], At[m][k], acc[ai][bj][m][n], 0, 0, 0); __builtin_amdgcn_s_setprio(0); } while (0)
; #define PG8_WAIT_V(n) asm volatile("s_waitcnt vmcnt(" #n ")" ::: "memory")
; #define PG8_WAIT_L(n) asm volatile("s_waitcnt lgkmcnt(" #n ")" ::: "memory")
; #define PG8_BAR __builtin_amdgcn_s_barrier()
; #define PG8_SCHED __builtin_amdgcn_sched_barrier(0)
; template <class Epi, class Sched, bool ALIGN_EPI = false, bool SP2 = false, bool KHOOK = false>
; __device__ __forceinline__ void gemm_phase(PG8_LAS unsigned char* lds, const Gemm g, const Sched& S, const Epi& E, const int tid_in) {
;     ...
;             PG8_WAIT_V(8); PG8_WAIT_L(0); PG8_BAR; PG8_MMA(1, 0, At, B0); PG8_MMA(1, 1, At, B1); PG8_BAR; PG8_SCHED;
;             PG8_LDB(B0, 1, 0); PG8_LDB(B1, 1, 1); PG8_SCHED; PG8_LDA(At, 1, 0); PG8_STAGE(PG8_SA(0, 1), a2 + hstep, voffA);
;             PG8_WAIT_V(8); PG8_WAIT_L(0); PG8_BAR; PG8_MMA(0, 0, At, B0); PG8_MMA(0, 1, At, B1); PG8_BAR; PG8_SCHED;
	s_setprio 1
	v_mfma_f32_16x16x32_bf16 v[62:65], v[146:149], v[184:187], v[62:65]
	v_mfma_f32_16x16x32_bf16 v[58:61], v[154:157], v[184:187], v[58:61]
	v_mfma_f32_16x16x32_bf16 v[46:49], v[146:149], v[198:201], v[46:49]
	v_mfma_f32_16x16x32_bf16 v[42:45], v[154:157], v[198:201], v[42:45]
	v_mfma_f32_16x16x32_bf16 v[28:31], v[146:149], v[206:209], v[28:31]
	v_mfma_f32_16x16x32_bf16 v[24:27], v[154:157], v[206:209], v[24:27]
	v_mfma_f32_16x16x32_bf16 v[12:15], v[146:149], v[214:217], v[12:15]
	v_mfma_f32_16x16x32_bf16 v[8:11], v[154:157], v[214:217], v[8:11]
	v_mfma_f32_16x16x32_bf16 v[62:65], v[150:153], v[188:191], v[62:65]
	v_mfma_f32_16x16x32_bf16 v[58:61], v[158:161], v[188:191], v[58:61]
	v_mfma_f32_16x16x32_bf16 v[46:49], v[150:153], v[202:205], v[46:49]
	v_mfma_f32_16x16x32_bf16 v[42:45], v[158:161], v[202:205], v[42:45]
	v_mfma_f32_16x16x32_bf16 v[28:31], v[150:153], v[210:213], v[28:31]
	v_mfma_f32_16x16x32_bf16 v[24:27], v[158:161], v[210:213], v[24:27]
	v_mfma_f32_16x16x32_bf16 v[12:15], v[150:153], v[218:221], v[12:15]
	v_mfma_f32_16x16x32_bf16 v[8:11], v[158:161], v[218:221], v[8:11]
	s_setprio 0
	s_setprio 1
	v_mfma_f32_16x16x32_bf16 v[54:57], v[162:165], v[184:187], v[54:57]
	v_mfma_f32_16x16x32_bf16 v[50:53], v[176:179], v[184:187], v[50:53]
	v_mfma_f32_16x16x32_bf16 v[38:41], v[162:165], v[198:201], v[38:41]
	v_mfma_f32_16x16x32_bf16 v[34:37], v[176:179], v[198:201], v[34:37]
	v_mfma_f32_16x16x32_bf16 v[20:23], v[162:165], v[206:209], v[20:23]
	v_mfma_f32_16x16x32_bf16 v[16:19], v[176:179], v[206:209], v[16:19]
	v_mfma_f32_16x16x32_bf16 v[4:7], v[162:165], v[214:217], v[4:7]
	v_mfma_f32_16x16x32_bf16 v[0:3], v[176:179], v[214:217], v[0:3]
	v_mfma_f32_16x16x32_bf16 v[54:57], v[166:169], v[188:191], v[54:57]
	v_mfma_f32_16x16x32_bf16 v[50:53], v[180:183], v[188:191], v[50:53]
	v_mfma_f32_16x16x32_bf16 v[38:41], v[166:169], v[202:205], v[38:41]
	v_mfma_f32_16x16x32_bf16 v[34:37], v[180:183], v[202:205], v[34:37]
	v_mfma_f32_16x16x32_bf16 v[20:23], v[166:169], v[210:213], v[20:23]
	v_mfma_f32_16x16x32_bf16 v[16:19], v[180:183], v[210:213], v[16:19]
	v_mfma_f32_16x16x32_bf16 v[4:7], v[166:169], v[218:221], v[4:7]
	v_mfma_f32_16x16x32_bf16 v[0:3], v[180:183], v[218:221], v[0:3]
	s_setprio 0
	s_barrier
	s_add_i32 s51, 0, 0x18000
	s_add_i32 s52, 0, 0x1c000
	v_add_u32_e32 v158, s51, v144
	v_add_u32_e32 v175, s52, v144
	ds_read_b128 v[146:149], v158
	ds_read_b128 v[150:153], v158 offset:1024
	ds_read_b128 v[154:157], v158 offset:2048
	ds_read_b128 v[158:161], v158 offset:3072
	ds_read_b128 v[162:165], v175
	ds_read_b128 v[166:169], v175 offset:1024
	ds_read_b128 v[176:179], v175 offset:2048
	ds_read_b128 v[180:183], v175 offset:3072
	s_add_u32 s30, s30, 0x160000
	s_addc_u32 s31, s31, 0
	s_mov_b32 m0, s42
	v_lshl_add_u64 v[226:227], s[30:31], 0, v[126:127]
	ds_read_b128 v[184:187], v145 offset:32768
	ds_read_b128 v[188:191], v145 offset:33792
	ds_read_b128 v[198:201], v145 offset:34816
	ds_read_b128 v[202:205], v145 offset:35840
	ds_read_b128 v[206:209], v145 offset:36864
	ds_read_b128 v[210:213], v145 offset:37888
	ds_read_b128 v[214:217], v145 offset:38912
	ds_read_b128 v[218:221], v145 offset:39936
	global_load_lds_dwordx4 v[226:227], off
	s_mov_b32 m0, s44
	v_lshl_add_u64 v[226:227], s[30:31], 0, v[124:125]
	global_load_lds_dwordx4 v[226:227], off
	s_waitcnt vmcnt(8)
	s_waitcnt lgkmcnt(0)
	s_barrier
	s_setprio 1
	v_mfma_f32_16x16x32_bf16 v[118:121], v[146:149], v[184:187], v[118:121]
	v_mfma_f32_16x16x32_bf16 v[114:117], v[154:157], v[184:187], v[114:117]
	v_mfma_f32_16x16x32_bf16 v[134:137], v[146:149], v[198:201], v[134:137]
	v_mfma_f32_16x16x32_bf16 v[130:133], v[154:157], v[198:201], v[130:133]
	v_mfma_f32_16x16x32_bf16 v[94:97], v[146:149], v[206:209], v[94:97]
	v_mfma_f32_16x16x32_bf16 v[90:93], v[154:157], v[206:209], v[90:93]
	v_mfma_f32_16x16x32_bf16 v[78:81], v[146:149], v[214:217], v[78:81]
	v_mfma_f32_16x16x32_bf16 v[74:77], v[154:157], v[214:217], v[74:77]
	v_mfma_f32_16x16x32_bf16 v[118:121], v[150:153], v[188:191], v[118:121]
	v_mfma_f32_16x16x32_bf16 v[114:117], v[158:161], v[188:191], v[114:117]
	v_mfma_f32_16x16x32_bf16 v[134:137], v[150:153], v[202:205], v[134:137]
	v_mfma_f32_16x16x32_bf16 v[130:133], v[158:161], v[202:205], v[130:133]
	v_mfma_f32_16x16x32_bf16 v[94:97], v[150:153], v[210:213], v[94:97]
	v_mfma_f32_16x16x32_bf16 v[90:93], v[158:161], v[210:213], v[90:93]
	v_mfma_f32_16x16x32_bf16 v[78:81], v[150:153], v[218:221], v[78:81]
	v_mfma_f32_16x16x32_bf16 v[74:77], v[158:161], v[218:221], v[74:77]
	s_setprio 0
	s_setprio 1
	v_mfma_f32_16x16x32_bf16 v[102:105], v[162:165], v[184:187], v[102:105]
	v_mfma_f32_16x16x32_bf16 v[98:101], v[176:179], v[184:187], v[98:101]
	v_mfma_f32_16x16x32_bf16 v[110:113], v[162:165], v[198:201], v[110:113]
	v_mfma_f32_16x16x32_bf16 v[106:109], v[176:179], v[198:201], v[106:109]
	v_mfma_f32_16x16x32_bf16 v[86:89], v[162:165], v[206:209], v[86:89]
	v_mfma_f32_16x16x32_bf16 v[82:85], v[176:179], v[206:209], v[82:85]
	v_mfma_f32_16x16x32_bf16 v[70:73], v[162:165], v[214:217], v[70:73]
	v_mfma_f32_16x16x32_bf16 v[66:69], v[176:179], v[214:217], v[66:69]
	v_mfma_f32_16x16x32_bf16 v[102:105], v[166:169], v[188:191], v[102:105]
	v_mfma_f32_16x16x32_bf16 v[98:101], v[180:183], v[188:191], v[98:101]
	v_mfma_f32_16x16x32_bf16 v[110:113], v[166:169], v[202:205], v[110:113]
	v_mfma_f32_16x16x32_bf16 v[106:109], v[180:183], v[202:205], v[106:109]
	v_mfma_f32_16x16x32_bf16 v[86:89], v[166:169], v[210:213], v[86:89]
	v_mfma_f32_16x16x32_bf16 v[82:85], v[180:183], v[210:213], v[82:85]
	v_mfma_f32_16x16x32_bf16 v[70:73], v[166:169], v[218:221], v[70:73]
	v_mfma_f32_16x16x32_bf16 v[66:69], v[180:183], v[218:221], v[66:69]
	s_setprio 0
	s_barrier
; #define PG8_STAGE(bufoff, gbase, voff) do { _Pragma("unroll") for (int _i = 0; _i < 2; ++_i) \
;         __builtin_amdgcn_global_load_lds((const unsigned*)((const char*)(gbase) + (voff)[_i]), (PG8_LAS unsigned*)(lds + (bufoff) + ldsw + _i * 8192), 16, 0, 0); } while (0)
; #define PG8_LDA(dst, b, h) do { _Pragma("unroll") for (int m = 0; m < 4; ++m) _Pragma("unroll") for (int k = 0; k < 2; ++k) dst[m][k] = *(const PG8_LAS bf16x8*)(lds + PG8_SA(b, h) + aoff + m * 2048 + k * 1024); } while (0)
; #define PG8_MMA(ai, bj, At, Bt) do { __builtin_amdgcn_s_setprio(1); _Pragma("unroll") for (int m = 0; m < 4; ++m) _Pragma("unroll") for (int n = 0; n < 2; ++n) _Pragma("unroll") for (int k = 0; k < 2; ++k) \
;         acc[ai][bj][m][n] = __builtin_amdgcn_mfma_f32_16x16x32_bf16(Bt[n][k], At[m][k], acc[ai][bj][m][n], 0, 0, 0); __builtin_amdgcn_s_setprio(0); } while (0)
; #define PG8_WAIT_V(n) asm volatile("s_waitcnt vmcnt(" #n ")" ::: "memory")
; #define PG8_WAIT_L(n) asm volatile("s_waitcnt lgkmcnt(" #n ")" ::: "memory")
; #define PG8_BAR __builtin_amdgcn_s_barrier()
; #define PG8_SCHED __builtin_amdgcn_sched_barrier(0)
; template <class Epi, class Sched, bool ALIGN_EPI = false, bool SP2 = false, bool KHOOK = false>
; __device__ __forceinline__ void gemm_phase(PG8_LAS unsigned char* lds, const Gemm g, const Sched& S, const Epi& E, const int tid_in) {
;     ...
;             PG8_LDA(At, 1, 1); PG8_STAGE(PG8_SB(1, 0), b3, voffB); PG8_STAGE(PG8_SB(1, 1), b3 + hstep, voffB); PG8_STAGE(PG8_SA(1, 0), a3, voffA);
;             PG8_WAIT_V(8); PG8_WAIT_L(0); PG8_BAR; PG8_MMA(1, 0, At, B0); PG8_MMA(1, 1, At, B1); PG8_BAR; PG8_SCHED;
;     ...
;         if (!has_next) break;
; #pragma unroll
;         for (int a = 0; a < 2; ++a)
; #pragma unroll
;             for (int b = 0; b < 2; ++b)
; #pragma unroll
;                 for (int m = 0; m < 4; ++m)
; #pragma unroll
;                     for (int n = 0; n < 2; ++n) acc[a][b][m][n] = (f32x4){0.f, 0.f, 0.f, 0.f};
;         cur = nxt; cA = nA; cB = nB; ++ui; load_rr(cur);
	s_add_i32 s30, s51, s39
	v_lshl_add_u64 v[170:171], v[170:171], 0, s[90:91]
	s_mov_b32 m0, s30
	ds_read_b128 v[184:187], v145 offset:49152
	ds_read_b128 v[188:191], v145 offset:50176
	ds_read_b128 v[198:201], v145 offset:51200
	ds_read_b128 v[202:205], v145 offset:52224
	ds_read_b128 v[206:209], v145 offset:53248
	ds_read_b128 v[210:213], v145 offset:54272
	ds_read_b128 v[214:217], v145 offset:55296
	ds_read_b128 v[218:221], v145 offset:56320
	global_load_lds_dwordx4 v[170:171], off
	s_add_i32 m0, s30, 0x2000
	s_add_u32 s26, s26, 0x160080
	v_lshl_add_u64 v[170:171], v[192:193], 0, s[90:91]
	s_addc_u32 s27, s27, 0
	s_add_i32 s30, s52, s39
	global_load_lds_dwordx4 v[170:171], off
	s_mov_b32 m0, s30
	v_lshl_add_u64 v[170:171], s[26:27], 0, v[32:33]
	global_load_lds_dwordx4 v[170:171], off
	s_add_i32 m0, s30, 0x2000
	v_lshl_add_u64 v[170:171], s[26:27], 0, v[122:123]
	global_load_lds_dwordx4 v[170:171], off
	s_mov_b32 m0, s46
	v_lshl_add_u64 v[170:171], v[222:223], 0, s[90:91]
	global_load_lds_dwordx4 v[170:171], off
	s_mov_b32 m0, s47
	v_lshl_add_u64 v[170:171], v[224:225], 0, s[90:91]
	global_load_lds_dwordx4 v[170:171], off
	s_waitcnt vmcnt(8)
	s_waitcnt lgkmcnt(0)
	s_barrier
	s_setprio 1
	v_mfma_f32_16x16x32_bf16 v[62:65], v[146:149], v[184:187], v[62:65]
	v_mfma_f32_16x16x32_bf16 v[58:61], v[154:157], v[184:187], v[58:61]
	v_mfma_f32_16x16x32_bf16 v[46:49], v[146:149], v[198:201], v[46:49]
	v_mfma_f32_16x16x32_bf16 v[42:45], v[154:157], v[198:201], v[42:45]
	v_mfma_f32_16x16x32_bf16 v[28:31], v[146:149], v[206:209], v[28:31]
	v_mfma_f32_16x16x32_bf16 v[24:27], v[154:157], v[206:209], v[24:27]
	v_mfma_f32_16x16x32_bf16 v[12:15], v[146:149], v[214:217], v[12:15]
	v_mfma_f32_16x16x32_bf16 v[8:11], v[154:157], v[214:217], v[8:11]
	v_mfma_f32_16x16x32_bf16 v[62:65], v[150:153], v[188:191], v[62:65]
	v_mfma_f32_16x16x32_bf16 v[58:61], v[158:161], v[188:191], v[58:61]
	v_mfma_f32_16x16x32_bf16 v[46:49], v[150:153], v[202:205], v[46:49]
	v_mfma_f32_16x16x32_bf16 v[42:45], v[158:161], v[202:205], v[42:45]
	v_mfma_f32_16x16x32_bf16 v[28:31], v[150:153], v[210:213], v[28:31]
	v_mfma_f32_16x16x32_bf16 v[24:27], v[158:161], v[210:213], v[24:27]
	v_mfma_f32_16x16x32_bf16 v[12:15], v[150:153], v[218:221], v[12:15]
	v_mfma_f32_16x16x32_bf16 v[8:11], v[158:161], v[218:221], v[8:11]
	s_setprio 0
	s_setprio 1
	v_mfma_f32_16x16x32_bf16 v[54:57], v[162:165], v[184:187], v[54:57]
	v_mfma_f32_16x16x32_bf16 v[50:53], v[176:179], v[184:187], v[50:53]
	v_mfma_f32_16x16x32_bf16 v[38:41], v[162:165], v[198:201], v[38:41]
	v_mfma_f32_16x16x32_bf16 v[34:37], v[176:179], v[198:201], v[34:37]
	v_mfma_f32_16x16x32_bf16 v[20:23], v[162:165], v[206:209], v[20:23]
	v_mfma_f32_16x16x32_bf16 v[16:19], v[176:179], v[206:209], v[16:19]
	v_mfma_f32_16x16x32_bf16 v[4:7], v[162:165], v[214:217], v[4:7]
	v_mfma_f32_16x16x32_bf16 v[0:3], v[176:179], v[214:217], v[0:3]
	v_mfma_f32_16x16x32_bf16 v[54:57], v[166:169], v[188:191], v[54:57]
	v_mfma_f32_16x16x32_bf16 v[50:53], v[180:183], v[188:191], v[50:53]
	v_mfma_f32_16x16x32_bf16 v[38:41], v[166:169], v[202:205], v[38:41]
	v_mfma_f32_16x16x32_bf16 v[34:37], v[180:183], v[202:205], v[34:37]
	v_mfma_f32_16x16x32_bf16 v[20:23], v[166:169], v[210:213], v[20:23]
	v_mfma_f32_16x16x32_bf16 v[16:19], v[180:183], v[210:213], v[16:19]
	v_mfma_f32_16x16x32_bf16 v[4:7], v[166:169], v[218:221], v[4:7]
	v_mfma_f32_16x16x32_bf16 v[0:3], v[180:183], v[218:221], v[0:3]
	s_setprio 0
	s_barrier
	s_add_i32 s25, s25, 2
	s_add_u32 s22, s22, 0x100
	s_addc_u32 s23, s23, 0
	s_cmpk_gt_u32 s25, 0x55
	s_cbranch_scc0 .LBB0_1170
	s_add_u32 s18, s18, 0xffffff00
	s_addc_u32 s19, s19, -1
	s_and_b64 vcc, exec, s[4:5]
	s_cbranch_vccnz .LBB0_1173
	v_mov_b32_e32 v0, 0
	s_mov_b32 s33, s50
	s_mov_b32 s0, s49
	s_mov_b64 s[10:11], s[16:17]
	s_mov_b32 s48, s24
	v_mov_b32_e32 v1, v0
	v_mov_b32_e32 v2, v0
	v_mov_b32_e32 v3, v0
	v_mov_b32_e32 v4, v0
	v_mov_b32_e32 v5, v0
	v_mov_b32_e32 v6, v0
	v_mov_b32_e32 v7, v0
	v_mov_b32_e32 v16, v0
	v_mov_b32_e32 v17, v0
	v_mov_b32_e32 v18, v0
	v_mov_b32_e32 v19, v0
	v_mov_b32_e32 v20, v0
	v_mov_b32_e32 v21, v0
	v_mov_b32_e32 v22, v0
	v_mov_b32_e32 v23, v0
	v_mov_b32_e32 v34, v0
	v_mov_b32_e32 v35, v0
	v_mov_b32_e32 v36, v0
	v_mov_b32_e32 v37, v0
	v_mov_b32_e32 v38, v0
	v_mov_b32_e32 v39, v0
	v_mov_b32_e32 v40, v0
	v_mov_b32_e32 v41, v0
	v_mov_b32_e32 v50, v0
	v_mov_b32_e32 v51, v0
	v_mov_b32_e32 v52, v0
	v_mov_b32_e32 v53, v0
	v_mov_b32_e32 v54, v0
	v_mov_b32_e32 v55, v0
	v_mov_b32_e32 v56, v0
	v_mov_b32_e32 v57, v0
	v_mov_b32_e32 v8, v0
	v_mov_b32_e32 v9, v0
	v_mov_b32_e32 v10, v0
	v_mov_b32_e32 v11, v0
	v_mov_b32_e32 v12, v0
	v_mov_b32_e32 v13, v0
	v_mov_b32_e32 v14, v0
	v_mov_b32_e32 v15, v0
	v_mov_b32_e32 v24, v0
	v_mov_b32_e32 v25, v0
	v_mov_b32_e32 v26, v0
	v_mov_b32_e32 v27, v0
	v_mov_b32_e32 v28, v0
	v_mov_b32_e32 v29, v0
	v_mov_b32_e32 v30, v0
	v_mov_b32_e32 v31, v0
	v_mov_b32_e32 v42, v0
	v_mov_b32_e32 v43, v0
	v_mov_b32_e32 v44, v0
	v_mov_b32_e32 v45, v0
	v_mov_b32_e32 v46, v0
	v_mov_b32_e32 v47, v0
	v_mov_b32_e32 v48, v0
	v_mov_b32_e32 v49, v0
	v_mov_b32_e32 v58, v0
	v_mov_b32_e32 v59, v0
	v_mov_b32_e32 v60, v0
	v_mov_b32_e32 v61, v0
	v_mov_b32_e32 v62, v0
	v_mov_b32_e32 v63, v0
	v_mov_b32_e32 v64, v0
	v_mov_b32_e32 v65, v0
	v_mov_b32_e32 v66, v0
	v_mov_b32_e32 v67, v0
	v_mov_b32_e32 v68, v0
	v_mov_b32_e32 v69, v0
	v_mov_b32_e32 v70, v0
	v_mov_b32_e32 v71, v0
	v_mov_b32_e32 v72, v0
	v_mov_b32_e32 v73, v0
	v_mov_b32_e32 v82, v0
	v_mov_b32_e32 v83, v0
	v_mov_b32_e32 v84, v0
	v_mov_b32_e32 v85, v0
	v_mov_b32_e32 v86, v0
	v_mov_b32_e32 v87, v0
	v_mov_b32_e32 v88, v0
	v_mov_b32_e32 v89, v0
	v_mov_b32_e32 v106, v0
	v_mov_b32_e32 v107, v0
	v_mov_b32_e32 v108, v0
	v_mov_b32_e32 v109, v0
	v_mov_b32_e32 v110, v0
	v_mov_b32_e32 v111, v0
	v_mov_b32_e32 v112, v0
	v_mov_b32_e32 v113, v0
	v_mov_b32_e32 v98, v0
	v_mov_b32_e32 v99, v0
	v_mov_b32_e32 v100, v0
	v_mov_b32_e32 v101, v0
	v_mov_b32_e32 v102, v0
	v_mov_b32_e32 v103, v0
	v_mov_b32_e32 v104, v0
	v_mov_b32_e32 v105, v0
	v_mov_b32_e32 v74, v0
	v_mov_b32_e32 v75, v0
	v_mov_b32_e32 v76, v0
	v_mov_b32_e32 v77, v0
	v_mov_b32_e32 v78, v0
	v_mov_b32_e32 v79, v0
	v_mov_b32_e32 v80, v0
	v_mov_b32_e32 v81, v0
	v_mov_b32_e32 v90, v0
	v_mov_b32_e32 v91, v0
	v_mov_b32_e32 v92, v0
	v_mov_b32_e32 v93, v0
	v_mov_b32_e32 v94, v0
	v_mov_b32_e32 v95, v0
	v_mov_b32_e32 v96, v0
	v_mov_b32_e32 v97, v0
	v_mov_b32_e32 v130, v0
	v_mov_b32_e32 v131, v0
	v_mov_b32_e32 v132, v0
	v_mov_b32_e32 v133, v0
	v_mov_b32_e32 v134, v0
	v_mov_b32_e32 v135, v0
	v_mov_b32_e32 v136, v0
	v_mov_b32_e32 v137, v0
	v_mov_b32_e32 v114, v0
	v_mov_b32_e32 v115, v0
	v_mov_b32_e32 v116, v0
	v_mov_b32_e32 v117, v0
	v_mov_b32_e32 v118, v0
	v_mov_b32_e32 v119, v0
	v_mov_b32_e32 v120, v0
	v_mov_b32_e32 v121, v0
	s_andn2_b64 vcc, exec, s[12:13]
	s_cbranch_vccnz .LBB0_1174
	s_branch .LBB0_1175

; #define PG8_STAGE(bufoff, gbase, voff) do { _Pragma("unroll") for (int _i = 0; _i < 2; ++_i) \
;         __builtin_amdgcn_global_load_lds((const unsigned*)((const char*)(gbase) + (voff)[_i]), (PG8_LAS unsigned*)(lds + (bufoff) + ldsw + _i * 8192), 16, 0, 0); } while (0)
; #define PG8_LDA(dst, b, h) do { _Pragma("unroll") for (int m = 0; m < 4; ++m) _Pragma("unroll") for (int k = 0; k < 2; ++k) dst[m][k] = *(const PG8_LAS bf16x8*)(lds + PG8_SA(b, h) + aoff + m * 2048 + k * 1024); } while (0)
; #define PG8_LDB(dst, b, h) do { _Pragma("unroll") for (int n = 0; n < 2; ++n) _Pragma("unroll") for (int k = 0; k < 2; ++k) dst[n][k] = *(const PG8_LAS bf16x8*)(lds + PG8_SB(b, h) + boff + n * 2048 + k * 1024); } while (0)
; #define PG8_MMA(ai, bj, At, Bt) do { __builtin_amdgcn_s_setprio(1); _Pragma("unroll") for (int m = 0; m < 4; ++m) _Pragma("unroll") for (int n = 0; n < 2; ++n) _Pragma("unroll") for (int k = 0; k < 2; ++k) \
;         acc[ai][bj][m][n] = __builtin_amdgcn_mfma_f32_16x16x32_bf16(Bt[n][k], At[m][k], acc[ai][bj][m][n], 0, 0, 0); __builtin_amdgcn_s_setprio(0); } while (0)
; #define PG8_WAIT_V(n) asm volatile("s_waitcnt vmcnt(" #n ")" ::: "memory")
; template <class Epi, class Sched, bool ALIGN_EPI = false, bool SP2 = false, bool KHOOK = false>
; __device__ __forceinline__ void gemm_phase(PG8_LAS unsigned char* lds, const Gemm g, const Sched& S, const Epi& E, const int tid_in) {
;     ...
;         for (int t = 0; t < nt; t += 2) {
;             const bool last = (t == nt - 2);
;             const char* a1 = cA + (size_t)(t + 1) * kstep;
;             const char* a2 = last ? nA : cA + (size_t)(t + 2) * kstep; const char* b2 = last ? nB : cB + (size_t)(t + 2) * kstep;
;             const char* a3 = a2 + kstep; const char* b3 = b2 + kstep;
;             if (last && has_next) S.a_ready(nxt);
;             if constexpr (SP2) {
;             PG8_LDB(B0, 0, 0); PG8_LDB(B1, 0, 1); PG8_SCHED; PG8_LDA(At, 0, 0); PG8_STAGE(PG8_SA(1, 1), a1 + hstep, voffA);
;             PG8_WAIT_V(8); PG8_WAIT_L(0); PG8_BAR; PG8_MMA(0, 0, At, B0); PG8_MMA(0, 1, At, B1); PG8_BAR; PG8_SCHED;
;             PG8_LDA(At, 0, 1); PG8_STAGE(PG8_SB(0, 0), b2, voffB); PG8_STAGE(PG8_SB(0, 1), b2 + hstep, voffB); PG8_STAGE(PG8_SA(0, 0), a2, voffA);
;             PG8_WAIT_V(8); PG8_WAIT_L(0); PG8_BAR; PG8_MMA(1, 0, At, B0); PG8_MMA(1, 1, At, B1); PG8_BAR; PG8_SCHED;
.LBB0_1287:
	s_add_u32 s30, s4, s16
	s_addc_u32 s31, s5, s17
	s_add_u32 s30, s30, 0x100
	s_addc_u32 s31, s31, 0
	s_add_u32 s53, s25, s16
	s_addc_u32 s56, s47, s17
	s_add_i32 s57, 0, 0x10000
	s_cmpk_eq_i32 s16, 0xf00
	s_cselect_b32 s49, s11, s31
	s_cselect_b32 s48, s50, s30
	s_cselect_b32 s31, s9, s56
	s_cselect_b32 s30, s51, s53
	s_add_i32 s53, 0, 0x14000
	v_add_u32_e32 v158, s57, v144
	v_add_u32_e32 v174, s53, v144
	ds_read_b128 v[146:149], v158
	ds_read_b128 v[150:153], v158 offset:1024
	ds_read_b128 v[154:157], v158 offset:2048
	ds_read_b128 v[158:161], v158 offset:3072
	ds_read_b128 v[162:165], v174
	ds_read_b128 v[166:169], v174 offset:1024
	ds_read_b128 v[170:173], v174 offset:2048
	ds_read_b128 v[174:177], v174 offset:3072
	v_lshl_add_u64 v[218:219], v[140:141], 0, s[16:17]
	s_add_i32 m0, s38, 0xc000
	ds_read_b128 v[178:181], v145
	ds_read_b128 v[182:185], v145 offset:1024
	ds_read_b128 v[186:189], v145 offset:2048
	ds_read_b128 v[190:193], v145 offset:3072
	ds_read_b128 v[198:201], v145 offset:4096
	ds_read_b128 v[202:205], v145 offset:5120
	ds_read_b128 v[206:209], v145 offset:6144
	ds_read_b128 v[210:213], v145 offset:7168
	global_load_lds_dwordx4 v[218:219], off
	s_add_i32 m0, s38, 0xe000
	v_lshl_add_u64 v[218:219], v[142:143], 0, s[16:17]
	global_load_lds_dwordx4 v[218:219], off
	s_waitcnt vmcnt(8)
	s_waitcnt lgkmcnt(0)
	s_barrier
	s_setprio 1
	v_mfma_f32_16x16x32_bf16 v[54:57], v[146:149], v[178:181], v[54:57]
	v_mfma_f32_16x16x32_bf16 v[62:65], v[154:157], v[178:181], v[62:65]
	v_mfma_f32_16x16x32_bf16 v[82:85], v[146:149], v[186:189], v[82:85]
	v_mfma_f32_16x16x32_bf16 v[86:89], v[154:157], v[186:189], v[86:89]
	v_mfma_f32_16x16x32_bf16 v[106:109], v[146:149], v[198:201], v[106:109]
	v_mfma_f32_16x16x32_bf16 v[110:113], v[154:157], v[198:201], v[110:113]
	v_mfma_f32_16x16x32_bf16 v[126:129], v[146:149], v[206:209], v[126:129]
	v_mfma_f32_16x16x32_bf16 v[122:125], v[154:157], v[206:209], v[122:125]
	v_mfma_f32_16x16x32_bf16 v[54:57], v[150:153], v[182:185], v[54:57]
	v_mfma_f32_16x16x32_bf16 v[62:65], v[158:161], v[182:185], v[62:65]
	v_mfma_f32_16x16x32_bf16 v[82:85], v[150:153], v[190:193], v[82:85]
	v_mfma_f32_16x16x32_bf16 v[86:89], v[158:161], v[190:193], v[86:89]
	v_mfma_f32_16x16x32_bf16 v[106:109], v[150:153], v[202:205], v[106:109]
	v_mfma_f32_16x16x32_bf16 v[110:113], v[158:161], v[202:205], v[110:113]
	v_mfma_f32_16x16x32_bf16 v[126:129], v[150:153], v[210:213], v[126:129]
	v_mfma_f32_16x16x32_bf16 v[122:125], v[158:161], v[210:213], v[122:125]
	s_setprio 0
	s_setprio 1
	v_mfma_f32_16x16x32_bf16 v[70:73], v[162:165], v[178:181], v[70:73]
	v_mfma_f32_16x16x32_bf16 v[78:81], v[170:173], v[178:181], v[78:81]
	v_mfma_f32_16x16x32_bf16 v[90:93], v[162:165], v[186:189], v[90:93]
	v_mfma_f32_16x16x32_bf16 v[98:101], v[170:173], v[186:189], v[98:101]
	v_mfma_f32_16x16x32_bf16 v[114:117], v[162:165], v[198:201], v[114:117]
	v_mfma_f32_16x16x32_bf16 v[118:121], v[170:173], v[198:201], v[118:121]
	v_mfma_f32_16x16x32_bf16 v[102:105], v[162:165], v[206:209], v[102:105]
	v_mfma_f32_16x16x32_bf16 v[94:97], v[170:173], v[206:209], v[94:97]
	v_mfma_f32_16x16x32_bf16 v[70:73], v[166:169], v[182:185], v[70:73]
	v_mfma_f32_16x16x32_bf16 v[78:81], v[174:177], v[182:185], v[78:81]
	v_mfma_f32_16x16x32_bf16 v[90:93], v[166:169], v[190:193], v[90:93]
	v_mfma_f32_16x16x32_bf16 v[98:101], v[174:177], v[190:193], v[98:101]
	v_mfma_f32_16x16x32_bf16 v[114:117], v[166:169], v[202:205], v[114:117]
	v_mfma_f32_16x16x32_bf16 v[118:121], v[174:177], v[202:205], v[118:121]
	v_mfma_f32_16x16x32_bf16 v[102:105], v[166:169], v[210:213], v[102:105]
	v_mfma_f32_16x16x32_bf16 v[94:97], v[174:177], v[210:213], v[94:97]
	s_setprio 0
	s_barrier
	s_add_i32 s56, s57, s37
	v_lshl_add_u64 v[218:219], s[30:31], 0, v[32:33]
	s_mov_b32 m0, s56
	ds_read_b128 v[178:181], v145 offset:16384
	ds_read_b128 v[182:185], v145 offset:17408
	ds_read_b128 v[186:189], v145 offset:18432
	ds_read_b128 v[190:193], v145 offset:19456
	ds_read_b128 v[198:201], v145 offset:20480
	ds_read_b128 v[202:205], v145 offset:21504
	ds_read_b128 v[206:209], v145 offset:22528
	ds_read_b128 v[210:213], v145 offset:23552
	global_load_lds_dwordx4 v[218:219], off
	s_add_i32 m0, s56, 0x2000
	s_add_u32 s56, s30, 0x80000
	v_lshl_add_u64 v[220:221], s[30:31], 0, v[130:131]
	s_addc_u32 s57, s31, 0
	s_add_i32 s53, s53, s37
	global_load_lds_dwordx4 v[220:221], off
	v_lshl_add_u64 v[222:223], s[56:57], 0, v[32:33]
	s_mov_b32 m0, s53
	v_lshl_add_u64 v[224:225], s[48:49], 0, v[132:133]
	global_load_lds_dwordx4 v[222:223], off
	s_add_i32 m0, s53, 0x2000
	v_lshl_add_u64 v[222:223], s[56:57], 0, v[130:131]
	global_load_lds_dwordx4 v[222:223], off
	s_mov_b32 m0, s38
	v_lshl_add_u64 v[222:223], s[48:49], 0, v[134:135]
	global_load_lds_dwordx4 v[222:223], off
	s_mov_b32 m0, s39
	s_nop 0
	global_load_lds_dwordx4 v[224:225], off
	s_waitcnt vmcnt(8)
	s_waitcnt lgkmcnt(0)
	s_barrier
; #define PG8_STAGE(bufoff, gbase, voff) do { _Pragma("unroll") for (int _i = 0; _i < 2; ++_i) \
;         __builtin_amdgcn_global_load_lds((const unsigned*)((const char*)(gbase) + (voff)[_i]), (PG8_LAS unsigned*)(lds + (bufoff) + ldsw + _i * 8192), 16, 0, 0); } while (0)
; #define PG8_LDA(dst, b, h) do { _Pragma("unroll") for (int m = 0; m < 4; ++m) _Pragma("unroll") for (int k = 0; k < 2; ++k) dst[m][k] = *(const PG8_LAS bf16x8*)(lds + PG8_SA(b, h) + aoff + m * 2048 + k * 1024); } while (0)
; #define PG8_LDB(dst, b, h) do { _Pragma("unroll") for (int n = 0; n < 2; ++n) _Pragma("unroll") for (int k = 0; k < 2; ++k) dst[n][k] = *(const PG8_LAS bf16x8*)(lds + PG8_SB(b, h) + boff + n * 2048 + k * 1024); } while (0)
; #define PG8_MMA(ai, bj, At, Bt) do { __builtin_amdgcn_s_setprio(1); _Pragma("unroll") for (int m = 0; m < 4; ++m) _Pragma("unroll") for (int n = 0; n < 2; ++n) _Pragma("unroll") for (int k = 0; k < 2; ++k) \
;         acc[ai][bj][m][n] = __builtin_amdgcn_mfma_f32_16x16x32_bf16(Bt[n][k], At[m][k], acc[ai][bj][m][n], 0, 0, 0); __builtin_amdgcn_s_setprio(0); } while (0)
; #define PG8_WAIT_V(n) asm volatile("s_waitcnt vmcnt(" #n ")" ::: "memory")
; #define PG8_WAIT_L(n) asm volatile("s_waitcnt lgkmcnt(" #n ")" ::: "memory")
; #define PG8_BAR __builtin_amdgcn_s_barrier()
; #define PG8_SCHED __builtin_amdgcn_sched_barrier(0)
; template <class Epi, class Sched, bool ALIGN_EPI = false, bool SP2 = false, bool KHOOK = false>
; __device__ __forceinline__ void gemm_phase(PG8_LAS unsigned char* lds, const Gemm g, const Sched& S, const Epi& E, const int tid_in) {
;     ...
;             PG8_WAIT_V(8); PG8_WAIT_L(0); PG8_BAR; PG8_MMA(1, 0, At, B0); PG8_MMA(1, 1, At, B1); PG8_BAR; PG8_SCHED;
;             PG8_LDB(B0, 1, 0); PG8_LDB(B1, 1, 1); PG8_SCHED; PG8_LDA(At, 1, 0); PG8_STAGE(PG8_SA(0, 1), a2 + hstep, voffA);
;             PG8_WAIT_V(8); PG8_WAIT_L(0); PG8_BAR; PG8_MMA(0, 0, At, B0); PG8_MMA(0, 1, At, B1); PG8_BAR; PG8_SCHED;
	s_setprio 1
	v_mfma_f32_16x16x32_bf16 v[74:77], v[146:149], v[178:181], v[74:77]
	v_mfma_f32_16x16x32_bf16 v[66:69], v[154:157], v[178:181], v[66:69]
	v_mfma_f32_16x16x32_bf16 v[46:49], v[146:149], v[186:189], v[46:49]
	v_mfma_f32_16x16x32_bf16 v[42:45], v[154:157], v[186:189], v[42:45]
	v_mfma_f32_16x16x32_bf16 v[28:31], v[146:149], v[198:201], v[28:31]
	v_mfma_f32_16x16x32_bf16 v[24:27], v[154:157], v[198:201], v[24:27]
	v_mfma_f32_16x16x32_bf16 v[12:15], v[146:149], v[206:209], v[12:15]
	v_mfma_f32_16x16x32_bf16 v[8:11], v[154:157], v[206:209], v[8:11]
	v_mfma_f32_16x16x32_bf16 v[74:77], v[150:153], v[182:185], v[74:77]
	v_mfma_f32_16x16x32_bf16 v[66:69], v[158:161], v[182:185], v[66:69]
	v_mfma_f32_16x16x32_bf16 v[46:49], v[150:153], v[190:193], v[46:49]
	v_mfma_f32_16x16x32_bf16 v[42:45], v[158:161], v[190:193], v[42:45]
	v_mfma_f32_16x16x32_bf16 v[28:31], v[150:153], v[202:205], v[28:31]
	v_mfma_f32_16x16x32_bf16 v[24:27], v[158:161], v[202:205], v[24:27]
	v_mfma_f32_16x16x32_bf16 v[12:15], v[150:153], v[210:213], v[12:15]
	v_mfma_f32_16x16x32_bf16 v[8:11], v[158:161], v[210:213], v[8:11]
	s_setprio 0
	s_setprio 1
	v_mfma_f32_16x16x32_bf16 v[58:61], v[162:165], v[178:181], v[58:61]
	v_mfma_f32_16x16x32_bf16 v[50:53], v[170:173], v[178:181], v[50:53]
	v_mfma_f32_16x16x32_bf16 v[38:41], v[162:165], v[186:189], v[38:41]
	v_mfma_f32_16x16x32_bf16 v[34:37], v[170:173], v[186:189], v[34:37]
	v_mfma_f32_16x16x32_bf16 v[20:23], v[162:165], v[198:201], v[20:23]
	v_mfma_f32_16x16x32_bf16 v[16:19], v[170:173], v[198:201], v[16:19]
	v_mfma_f32_16x16x32_bf16 v[4:7], v[162:165], v[206:209], v[4:7]
	v_mfma_f32_16x16x32_bf16 v[0:3], v[170:173], v[206:209], v[0:3]
	v_mfma_f32_16x16x32_bf16 v[58:61], v[166:169], v[182:185], v[58:61]
	v_mfma_f32_16x16x32_bf16 v[50:53], v[174:177], v[182:185], v[50:53]
	v_mfma_f32_16x16x32_bf16 v[38:41], v[166:169], v[190:193], v[38:41]
	v_mfma_f32_16x16x32_bf16 v[34:37], v[174:177], v[190:193], v[34:37]
	v_mfma_f32_16x16x32_bf16 v[20:23], v[166:169], v[202:205], v[20:23]
	v_mfma_f32_16x16x32_bf16 v[16:19], v[174:177], v[202:205], v[16:19]
	v_mfma_f32_16x16x32_bf16 v[4:7], v[166:169], v[210:213], v[4:7]
	v_mfma_f32_16x16x32_bf16 v[0:3], v[174:177], v[210:213], v[0:3]
	s_setprio 0
	s_barrier
	s_add_i32 s53, 0, 0x18000
	s_add_i32 s56, 0, 0x1c000
	v_add_u32_e32 v158, s53, v144
	v_add_u32_e32 v174, s56, v144
	ds_read_b128 v[146:149], v158
	ds_read_b128 v[150:153], v158 offset:1024
	ds_read_b128 v[154:157], v158 offset:2048
	ds_read_b128 v[158:161], v158 offset:3072
	ds_read_b128 v[162:165], v174
	ds_read_b128 v[166:169], v174 offset:1024
	ds_read_b128 v[170:173], v174 offset:2048
	ds_read_b128 v[174:177], v174 offset:3072
	s_add_u32 s48, s48, 0x80000
	s_addc_u32 s49, s49, 0
	s_mov_b32 m0, s40
	v_lshl_add_u64 v[226:227], s[48:49], 0, v[134:135]
	ds_read_b128 v[178:181], v145 offset:32768
	ds_read_b128 v[182:185], v145 offset:33792
	ds_read_b128 v[186:189], v145 offset:34816
	ds_read_b128 v[190:193], v145 offset:35840
	ds_read_b128 v[198:201], v145 offset:36864
	ds_read_b128 v[202:205], v145 offset:37888
	ds_read_b128 v[206:209], v145 offset:38912
	ds_read_b128 v[210:213], v145 offset:39936
	global_load_lds_dwordx4 v[226:227], off
	s_mov_b32 m0, s42
	v_lshl_add_u64 v[226:227], s[48:49], 0, v[132:133]
	global_load_lds_dwordx4 v[226:227], off
	s_waitcnt vmcnt(8)
	s_waitcnt lgkmcnt(0)
	s_barrier
	s_setprio 1
	v_mfma_f32_16x16x32_bf16 v[54:57], v[146:149], v[178:181], v[54:57]
	v_mfma_f32_16x16x32_bf16 v[62:65], v[154:157], v[178:181], v[62:65]
	v_mfma_f32_16x16x32_bf16 v[82:85], v[146:149], v[186:189], v[82:85]
	v_mfma_f32_16x16x32_bf16 v[86:89], v[154:157], v[186:189], v[86:89]
	v_mfma_f32_16x16x32_bf16 v[106:109], v[146:149], v[198:201], v[106:109]
	v_mfma_f32_16x16x32_bf16 v[110:113], v[154:157], v[198:201], v[110:113]
	v_mfma_f32_16x16x32_bf16 v[126:129], v[146:149], v[206:209], v[126:129]
	v_mfma_f32_16x16x32_bf16 v[122:125], v[154:157], v[206:209], v[122:125]
	v_mfma_f32_16x16x32_bf16 v[54:57], v[150:153], v[182:185], v[54:57]
	v_mfma_f32_16x16x32_bf16 v[62:65], v[158:161], v[182:185], v[62:65]
	v_mfma_f32_16x16x32_bf16 v[82:85], v[150:153], v[190:193], v[82:85]
	v_mfma_f32_16x16x32_bf16 v[86:89], v[158:161], v[190:193], v[86:89]
	v_mfma_f32_16x16x32_bf16 v[106:109], v[150:153], v[202:205], v[106:109]
	v_mfma_f32_16x16x32_bf16 v[110:113], v[158:161], v[202:205], v[110:113]
	v_mfma_f32_16x16x32_bf16 v[126:129], v[150:153], v[210:213], v[126:129]
	v_mfma_f32_16x16x32_bf16 v[122:125], v[158:161], v[210:213], v[122:125]
	s_setprio 0
	s_setprio 1
	v_mfma_f32_16x16x32_bf16 v[70:73], v[162:165], v[178:181], v[70:73]
	v_mfma_f32_16x16x32_bf16 v[78:81], v[170:173], v[178:181], v[78:81]
	v_mfma_f32_16x16x32_bf16 v[90:93], v[162:165], v[186:189], v[90:93]
	v_mfma_f32_16x16x32_bf16 v[98:101], v[170:173], v[186:189], v[98:101]
	v_mfma_f32_16x16x32_bf16 v[114:117], v[162:165], v[198:201], v[114:117]
	v_mfma_f32_16x16x32_bf16 v[118:121], v[170:173], v[198:201], v[118:121]
	v_mfma_f32_16x16x32_bf16 v[102:105], v[162:165], v[206:209], v[102:105]
	v_mfma_f32_16x16x32_bf16 v[94:97], v[170:173], v[206:209], v[94:97]
	v_mfma_f32_16x16x32_bf16 v[70:73], v[166:169], v[182:185], v[70:73]
	v_mfma_f32_16x16x32_bf16 v[78:81], v[174:177], v[182:185], v[78:81]
	v_mfma_f32_16x16x32_bf16 v[90:93], v[166:169], v[190:193], v[90:93]
	v_mfma_f32_16x16x32_bf16 v[98:101], v[174:177], v[190:193], v[98:101]
	v_mfma_f32_16x16x32_bf16 v[114:117], v[166:169], v[202:205], v[114:117]
	v_mfma_f32_16x16x32_bf16 v[118:121], v[174:177], v[202:205], v[118:121]
	v_mfma_f32_16x16x32_bf16 v[102:105], v[166:169], v[210:213], v[102:105]
	v_mfma_f32_16x16x32_bf16 v[94:97], v[174:177], v[210:213], v[94:97]
	s_setprio 0
	s_barrier
; #define PG8_STAGE(bufoff, gbase, voff) do { _Pragma("unroll") for (int _i = 0; _i < 2; ++_i) \
;         __builtin_amdgcn_global_load_lds((const unsigned*)((const char*)(gbase) + (voff)[_i]), (PG8_LAS unsigned*)(lds + (bufoff) + ldsw + _i * 8192), 16, 0, 0); } while (0)
; #define PG8_LDA(dst, b, h) do { _Pragma("unroll") for (int m = 0; m < 4; ++m) _Pragma("unroll") for (int k = 0; k < 2; ++k) dst[m][k] = *(const PG8_LAS bf16x8*)(lds + PG8_SA(b, h) + aoff + m * 2048 + k * 1024); } while (0)
; #define PG8_MMA(ai, bj, At, Bt) do { __builtin_amdgcn_s_setprio(1); _Pragma("unroll") for (int m = 0; m < 4; ++m) _Pragma("unroll") for (int n = 0; n < 2; ++n) _Pragma("unroll") for (int k = 0; k < 2; ++k) \
;         acc[ai][bj][m][n] = __builtin_amdgcn_mfma_f32_16x16x32_bf16(Bt[n][k], At[m][k], acc[ai][bj][m][n], 0, 0, 0); __builtin_amdgcn_s_setprio(0); } while (0)
; #define PG8_WAIT_V(n) asm volatile("s_waitcnt vmcnt(" #n ")" ::: "memory")
; #define PG8_WAIT_L(n) asm volatile("s_waitcnt lgkmcnt(" #n ")" ::: "memory")
; #define PG8_BAR __builtin_amdgcn_s_barrier()
; #define PG8_SCHED __builtin_amdgcn_sched_barrier(0)
; template <class Epi, class Sched, bool ALIGN_EPI = false, bool SP2 = false, bool KHOOK = false>
; __device__ __forceinline__ void gemm_phase(PG8_LAS unsigned char* lds, const Gemm g, const Sched& S, const Epi& E, const int tid_in) {
;     ...
;             PG8_LDA(At, 1, 1); PG8_STAGE(PG8_SB(1, 0), b3, voffB); PG8_STAGE(PG8_SB(1, 1), b3 + hstep, voffB); PG8_STAGE(PG8_SA(1, 0), a3, voffA);
;             PG8_WAIT_V(8); PG8_WAIT_L(0); PG8_BAR; PG8_MMA(1, 0, At, B0); PG8_MMA(1, 1, At, B1); PG8_BAR; PG8_SCHED;
;     ...
;         if (!has_next) break;
; #pragma unroll
;         for (int a = 0; a < 2; ++a)
; #pragma unroll
;             for (int b = 0; b < 2; ++b)
; #pragma unroll
;                 for (int m = 0; m < 4; ++m)
; #pragma unroll
;                     for (int n = 0; n < 2; ++n) acc[a][b][m][n] = (f32x4){0.f, 0.f, 0.f, 0.f};
;         cur = nxt; cA = nA; cB = nB; ++ui; load_rr(cur);
	s_add_i32 s48, s53, s37
	v_lshl_add_u64 v[218:219], v[218:219], 0, s[90:91]
	s_mov_b32 m0, s48
	ds_read_b128 v[178:181], v145 offset:49152
	ds_read_b128 v[182:185], v145 offset:50176
	ds_read_b128 v[186:189], v145 offset:51200
	ds_read_b128 v[190:193], v145 offset:52224
	ds_read_b128 v[198:201], v145 offset:53248
	ds_read_b128 v[202:205], v145 offset:54272
	ds_read_b128 v[206:209], v145 offset:55296
	ds_read_b128 v[210:213], v145 offset:56320
	global_load_lds_dwordx4 v[218:219], off
	s_add_i32 m0, s48, 0x2000
	s_add_u32 s30, s30, 0x80080
	v_lshl_add_u64 v[218:219], v[220:221], 0, s[90:91]
	s_addc_u32 s31, s31, 0
	s_add_i32 s48, s56, s37
	global_load_lds_dwordx4 v[218:219], off
	s_mov_b32 m0, s48
	v_lshl_add_u64 v[218:219], s[30:31], 0, v[32:33]
	global_load_lds_dwordx4 v[218:219], off
	s_add_i32 m0, s48, 0x2000
	v_lshl_add_u64 v[218:219], s[30:31], 0, v[130:131]
	global_load_lds_dwordx4 v[218:219], off
	s_mov_b32 m0, s44
	v_lshl_add_u64 v[218:219], v[222:223], 0, s[90:91]
	global_load_lds_dwordx4 v[218:219], off
	s_mov_b32 m0, s45
	v_lshl_add_u64 v[218:219], v[224:225], 0, s[90:91]
	global_load_lds_dwordx4 v[218:219], off
	s_waitcnt vmcnt(8)
	s_waitcnt lgkmcnt(0)
	s_barrier
	s_setprio 1
	v_mfma_f32_16x16x32_bf16 v[74:77], v[146:149], v[178:181], v[74:77]
	v_mfma_f32_16x16x32_bf16 v[66:69], v[154:157], v[178:181], v[66:69]
	v_mfma_f32_16x16x32_bf16 v[46:49], v[146:149], v[186:189], v[46:49]
	v_mfma_f32_16x16x32_bf16 v[42:45], v[154:157], v[186:189], v[42:45]
	v_mfma_f32_16x16x32_bf16 v[28:31], v[146:149], v[198:201], v[28:31]
	v_mfma_f32_16x16x32_bf16 v[24:27], v[154:157], v[198:201], v[24:27]
	v_mfma_f32_16x16x32_bf16 v[12:15], v[146:149], v[206:209], v[12:15]
	v_mfma_f32_16x16x32_bf16 v[8:11], v[154:157], v[206:209], v[8:11]
	v_mfma_f32_16x16x32_bf16 v[74:77], v[150:153], v[182:185], v[74:77]
	v_mfma_f32_16x16x32_bf16 v[66:69], v[158:161], v[182:185], v[66:69]
	v_mfma_f32_16x16x32_bf16 v[46:49], v[150:153], v[190:193], v[46:49]
	v_mfma_f32_16x16x32_bf16 v[42:45], v[158:161], v[190:193], v[42:45]
	v_mfma_f32_16x16x32_bf16 v[28:31], v[150:153], v[202:205], v[28:31]
	v_mfma_f32_16x16x32_bf16 v[24:27], v[158:161], v[202:205], v[24:27]
	v_mfma_f32_16x16x32_bf16 v[12:15], v[150:153], v[210:213], v[12:15]
	v_mfma_f32_16x16x32_bf16 v[8:11], v[158:161], v[210:213], v[8:11]
	s_setprio 0
	s_setprio 1
	v_mfma_f32_16x16x32_bf16 v[58:61], v[162:165], v[178:181], v[58:61]
	v_mfma_f32_16x16x32_bf16 v[50:53], v[170:173], v[178:181], v[50:53]
	v_mfma_f32_16x16x32_bf16 v[38:41], v[162:165], v[186:189], v[38:41]
	v_mfma_f32_16x16x32_bf16 v[34:37], v[170:173], v[186:189], v[34:37]
	v_mfma_f32_16x16x32_bf16 v[20:23], v[162:165], v[198:201], v[20:23]
	v_mfma_f32_16x16x32_bf16 v[16:19], v[170:173], v[198:201], v[16:19]
	v_mfma_f32_16x16x32_bf16 v[4:7], v[162:165], v[206:209], v[4:7]
	v_mfma_f32_16x16x32_bf16 v[0:3], v[170:173], v[206:209], v[0:3]
	v_mfma_f32_16x16x32_bf16 v[58:61], v[166:169], v[182:185], v[58:61]
	v_mfma_f32_16x16x32_bf16 v[50:53], v[174:177], v[182:185], v[50:53]
	v_mfma_f32_16x16x32_bf16 v[38:41], v[166:169], v[190:193], v[38:41]
	v_mfma_f32_16x16x32_bf16 v[34:37], v[174:177], v[190:193], v[34:37]
	v_mfma_f32_16x16x32_bf16 v[20:23], v[166:169], v[202:205], v[20:23]
	v_mfma_f32_16x16x32_bf16 v[16:19], v[174:177], v[202:205], v[16:19]
	v_mfma_f32_16x16x32_bf16 v[4:7], v[166:169], v[210:213], v[4:7]
	v_mfma_f32_16x16x32_bf16 v[0:3], v[174:177], v[210:213], v[0:3]
	s_setprio 0
	s_barrier
	s_add_i32 s52, s52, 2
	s_add_u32 s16, s16, 0x100
	s_addc_u32 s17, s17, 0
	s_cmp_gt_u32 s52, 29
	s_cbranch_scc0 .LBB0_1287
	s_add_u32 s16, s25, 0xffffff00
	s_addc_u32 s17, s47, -1
	s_andn2_b64 vcc, exec, s[22:23]
	s_cbranch_vccnz .LBB0_1290
	v_mov_b32_e32 v0, 0
	s_mov_b32 s20, s10
	s_mov_b32 s0, s8
	s_mov_b64 s[4:5], s[26:27]
	s_mov_b32 s46, s24
	v_mov_b32_e32 v1, v0
	v_mov_b32_e32 v2, v0
	v_mov_b32_e32 v3, v0
	v_mov_b32_e32 v4, v0
	v_mov_b32_e32 v5, v0
	v_mov_b32_e32 v6, v0
	v_mov_b32_e32 v7, v0
	v_mov_b32_e32 v16, v0
	v_mov_b32_e32 v17, v0
	v_mov_b32_e32 v18, v0
	v_mov_b32_e32 v19, v0
	v_mov_b32_e32 v20, v0
	v_mov_b32_e32 v21, v0
	v_mov_b32_e32 v22, v0
	v_mov_b32_e32 v23, v0
	v_mov_b32_e32 v34, v0
	v_mov_b32_e32 v35, v0
	v_mov_b32_e32 v36, v0
	v_mov_b32_e32 v37, v0
	v_mov_b32_e32 v38, v0
	v_mov_b32_e32 v39, v0
	v_mov_b32_e32 v40, v0
	v_mov_b32_e32 v41, v0
	v_mov_b32_e32 v50, v0
	v_mov_b32_e32 v51, v0
	v_mov_b32_e32 v52, v0
	v_mov_b32_e32 v53, v0
	v_mov_b32_e32 v58, v0
	v_mov_b32_e32 v59, v0
	v_mov_b32_e32 v60, v0
	v_mov_b32_e32 v61, v0
	v_mov_b32_e32 v8, v0
	v_mov_b32_e32 v9, v0
	v_mov_b32_e32 v10, v0
	v_mov_b32_e32 v11, v0
	v_mov_b32_e32 v12, v0
	v_mov_b32_e32 v13, v0
	v_mov_b32_e32 v14, v0
	v_mov_b32_e32 v15, v0
	v_mov_b32_e32 v24, v0
	v_mov_b32_e32 v25, v0
	v_mov_b32_e32 v26, v0
	v_mov_b32_e32 v27, v0
	v_mov_b32_e32 v28, v0
	v_mov_b32_e32 v29, v0
	v_mov_b32_e32 v30, v0
	v_mov_b32_e32 v31, v0
	v_mov_b32_e32 v42, v0
	v_mov_b32_e32 v43, v0
	v_mov_b32_e32 v44, v0
	v_mov_b32_e32 v45, v0
	v_mov_b32_e32 v46, v0
	v_mov_b32_e32 v47, v0
	v_mov_b32_e32 v48, v0
	v_mov_b32_e32 v49, v0
	v_mov_b32_e32 v66, v0
	v_mov_b32_e32 v67, v0
	v_mov_b32_e32 v68, v0
	v_mov_b32_e32 v69, v0
	v_mov_b32_e32 v74, v0
	v_mov_b32_e32 v75, v0
	v_mov_b32_e32 v76, v0
	v_mov_b32_e32 v77, v0
	v_mov_b32_e32 v94, v0
	v_mov_b32_e32 v95, v0
	v_mov_b32_e32 v96, v0
	v_mov_b32_e32 v97, v0
	v_mov_b32_e32 v102, v0
	v_mov_b32_e32 v103, v0
	v_mov_b32_e32 v104, v0
	v_mov_b32_e32 v105, v0
	v_mov_b32_e32 v118, v0
	v_mov_b32_e32 v119, v0
	v_mov_b32_e32 v120, v0
	v_mov_b32_e32 v121, v0
	v_mov_b32_e32 v114, v0
	v_mov_b32_e32 v115, v0
	v_mov_b32_e32 v116, v0
	v_mov_b32_e32 v117, v0
	v_mov_b32_e32 v98, v0
	v_mov_b32_e32 v99, v0
	v_mov_b32_e32 v100, v0
	v_mov_b32_e32 v101, v0
	v_mov_b32_e32 v90, v0
	v_mov_b32_e32 v91, v0
	v_mov_b32_e32 v92, v0
	v_mov_b32_e32 v93, v0
	v_mov_b32_e32 v78, v0
	v_mov_b32_e32 v79, v0
	v_mov_b32_e32 v80, v0
	v_mov_b32_e32 v81, v0
	v_mov_b32_e32 v70, v0
	v_mov_b32_e32 v71, v0
	v_mov_b32_e32 v72, v0
	v_mov_b32_e32 v73, v0
	v_mov_b32_e32 v122, v0
	v_mov_b32_e32 v123, v0
	v_mov_b32_e32 v124, v0
	v_mov_b32_e32 v125, v0
	v_mov_b32_e32 v126, v0
	v_mov_b32_e32 v127, v0
	v_mov_b32_e32 v128, v0
	v_mov_b32_e32 v129, v0
	v_mov_b32_e32 v110, v0
	v_mov_b32_e32 v111, v0
	v_mov_b32_e32 v112, v0
	v_mov_b32_e32 v113, v0
	v_mov_b32_e32 v106, v0
	v_mov_b32_e32 v107, v0
	v_mov_b32_e32 v108, v0
	v_mov_b32_e32 v109, v0
	v_mov_b32_e32 v86, v0
	v_mov_b32_e32 v87, v0
	v_mov_b32_e32 v88, v0
	v_mov_b32_e32 v89, v0
	v_mov_b32_e32 v82, v0
	v_mov_b32_e32 v83, v0
	v_mov_b32_e32 v84, v0
	v_mov_b32_e32 v85, v0
	v_mov_b32_e32 v62, v0
	v_mov_b32_e32 v63, v0
	v_mov_b32_e32 v64, v0
	v_mov_b32_e32 v65, v0
	v_mov_b32_e32 v54, v0
	v_mov_b32_e32 v55, v0
	v_mov_b32_e32 v56, v0
	v_mov_b32_e32 v57, v0
	s_andn2_b64 vcc, exec, s[12:13]
	s_cbranch_vccnz .LBB0_1291
	s_branch .LBB0_1292
